# pipelined norm fast paths (norm1 f32+bf16, norm2): 16 latent rows per wave unrolled, prefetch distance 3, exact vmcnt
# speedup vs baseline: 1.0250x; 1.0250x over previous
; __device__ __forceinline__ void norm_phase(const void* src_lat, int lat_f32, const float* src_ctx, int nrows, const float* gvec, const float* mods_l, int sh_off, int sc_off, bf16_t* U, const float* part, int nparts, float* ctx_out) {
;     ...
;     const int gw = blockIdx.x * 8 + w, ngw = gridDim.x * 8;
;     f32x4 gv[4];
; #pragma unroll
;     for (int j = 0; j < 4; ++j) gv[j] = *(const f32x4*)(gvec + 4 * lane + 256 * j);
;     for (int row = gw; row < nrows; row += ngw) {
;         const int s = row < MLAT ? (row >> 13) : 4;
;         f32x4 v[4]; float ss = 0.f;
;         if (row < MLAT && !lat_f32) { const bf16_t* src = (const bf16_t*)src_lat + (size_t)row * DM + 4 * lane;
; #pragma unroll
;             for (int j = 0; j < 4; ++j) { const u32x2 w = *(const u32x2*)(src + 256 * j);
;                 v[j] = (f32x4){__uint_as_float(w.x << 16), __uint_as_float(w.x & 0xffff0000u), __uint_as_float(w.y << 16), __uint_as_float(w.y & 0xffff0000u)}; } }
;         else { const float* src = row < MLAT ? (const float*)src_lat + (size_t)row * DM : src_ctx + (size_t)(row - MLAT) * DM;
; #pragma unroll
;             for (int j = 0; j < 4; ++j) v[j] = *(const f32x4*)(src + 4 * lane + 256 * j); }
;     ...
;         const float* shp = mods_l + s * 6144 + sh_off + 4 * lane; const float* scp = mods_l + s * 6144 + sc_off + 4 * lane;
;         bf16_t* up = U + (size_t)row * DM + 4 * lane;
; #pragma unroll
;         for (int j = 0; j < 4; ++j) { const f32x4 sh = *(const f32x4*)(shp + 256 * j), sc = *(const f32x4*)(scp + 256 * j);
.LBB0_138:
	global_load_dwordx2 v[0:1], v155, s[78:79] offset:48
	v_readlane_b32 s0, v240, 36
	v_readlane_b32 s1, v240, 37
	s_xor_b64 s[0:1], s[0:1], -1
	v_writelane_b32 v240, s0, 38
	v_readlane_b32 s6, v241, 5
	v_mov_b32_e32 v16, v152
	v_writelane_b32 v240, s1, 39
	s_mov_b32 s9, s83
	v_readlane_b32 s0, v240, 16
	s_mul_i32 s82, s0, 0x7800
	s_lshl_b32 s8, s0, 10
	s_lshl_b64 s[0:1], s[82:83], 2
	s_add_u32 s0, s6, s0
	v_writelane_b32 v240, s0, 42
	v_readlane_b32 s0, v241, 6
	s_addc_u32 s0, s0, s1
	s_nop 0
	v_writelane_b32 v240, s0, 43
	v_readfirstlane_b32 s0, v16
	s_ashr_i32 s1, s0, 6
	v_readlane_b32 s0, v241, 4
	s_add_i32 s0, s1, s0
	s_cmp_gt_i32 s0, 0x83ff
	v_writelane_b32 v240, s8, 44
	s_nop 1
	v_writelane_b32 v240, s9, 45
	s_cbranch_scc1 .LBB0_150
	v_readlane_b32 s6, v240, 44
	v_readlane_b32 s7, v240, 45
	v_lshlrev_b32_e32 v2, 2, v16
	s_lshl_b64 s[6:7], s[6:7], 2
	v_and_b32_e32 v36, 0xfc, v2
	s_waitcnt vmcnt(0)
	v_lshl_add_u64 v[0:1], v[0:1], 0, s[6:7]
	v_lshlrev_b32_e32 v154, 2, v36
	v_lshl_add_u64 v[12:13], v[0:1], 0, v[154:155]
	flat_load_dwordx4 v[0:3], v[12:13]
	flat_load_dwordx4 v[4:7], v[12:13] offset:1024
	flat_load_dwordx4 v[8:11], v[12:13] offset:2048
	s_nop 0
	flat_load_dwordx4 v[12:15], v[12:13] offset:3072
	v_and_b32_e32 v16, 63, v16
	v_readlane_b32 s6, v240, 9
	v_lshl_add_u64 v[40:41], s[72:73], 0, v[154:155]
	v_lshlrev_b32_e32 v154, 4, v16
	v_readlane_b32 s7, v240, 10
	v_lshlrev_b32_e32 v18, 1, v36
	v_mov_b32_e32 v19, v155
	v_lshl_add_u64 v[44:45], s[6:7], 0, v[154:155]
	v_readlane_b32 s6, v240, 13
	v_lshl_add_u64 v[38:39], v[32:33], 0, v[18:19]
	v_lshl_add_u64 v[42:43], s[94:95], 0, v[18:19]
	s_add_i32 s82, s6, s1
	s_cmp_lg_u32 s56, 0x800
	s_cbranch_scc1 .LBB0_142
	v_readlane_b32 s37, v240, 36
	s_nop 0
	s_cmp_eq_u32 s37, 0
	s_cbranch_scc1 .Lnorm1_bf16
	v_and_b32_e32 v102, 63, v152
	v_lshlrev_b32_e32 v103, 4, v102
	v_lshlrev_b32_e32 v102, 3, v102
	v_readfirstlane_b32 s38, v32
	v_readfirstlane_b32 s39, v33
	v_readlane_b32 s34, v240, 42
	v_readlane_b32 s35, v240, 43
	s_nop 0
	s_lshl_b32 s36, s0, 12
	s_add_u32 s38, s38, s36
	s_addc_u32 s39, s39, 0
	s_lshl_b32 s36, s0, 11
	s_add_u32 s40, s94, s36
	s_addc_u32 s41, s95, 0
	s_add_u32 s42, s34, 0x0
	s_addc_u32 s43, s35, 0
	s_add_u32 s44, s34, 0x1000
	s_addc_u32 s45, s35, 0
	global_load_dwordx4 v[112:115], v103, s[42:43]
	global_load_dwordx4 v[116:119], v103, s[42:43] offset:1024
	global_load_dwordx4 v[120:123], v103, s[42:43] offset:2048
	global_load_dwordx4 v[124:127], v103, s[42:43] offset:3072
	global_load_dwordx4 v[128:131], v103, s[44:45]
	global_load_dwordx4 v[132:135], v103, s[44:45] offset:1024
	global_load_dwordx4 v[136:139], v103, s[44:45] offset:2048
	global_load_dwordx4 v[140:143], v103, s[44:45] offset:3072
	s_add_u32 s42, s42, 0x6000
	s_addc_u32 s43, s43, 0
	s_add_u32 s44, s44, 0x6000
	s_addc_u32 s45, s45, 0
	global_load_dwordx4 v[158:161], v103, s[38:39]
	global_load_dwordx4 v[162:165], v103, s[38:39] offset:1024
	global_load_dwordx4 v[166:169], v103, s[38:39] offset:2048
	global_load_dwordx4 v[170:173], v103, s[38:39] offset:3072
	s_add_u32 s38, s38, 0x800000
	s_addc_u32 s39, s39, 0
	global_load_dwordx4 v[174:177], v103, s[38:39]
	global_load_dwordx4 v[178:181], v103, s[38:39] offset:1024
	global_load_dwordx4 v[182:185], v103, s[38:39] offset:2048
	global_load_dwordx4 v[186:189], v103, s[38:39] offset:3072
	s_add_u32 s38, s38, 0x800000
	s_addc_u32 s39, s39, 0
	global_load_dwordx4 v[198:201], v103, s[38:39]
	global_load_dwordx4 v[202:205], v103, s[38:39] offset:1024
	global_load_dwordx4 v[206:209], v103, s[38:39] offset:2048
	global_load_dwordx4 v[210:213], v103, s[38:39] offset:3072
	s_add_u32 s38, s38, 0x800000
	s_addc_u32 s39, s39, 0
	global_load_dwordx4 v[214:217], v103, s[38:39]
	global_load_dwordx4 v[218:221], v103, s[38:39] offset:1024
	global_load_dwordx4 v[222:225], v103, s[38:39] offset:2048
	global_load_dwordx4 v[226:229], v103, s[38:39] offset:3072
	s_add_u32 s38, s38, 0x800000
	s_addc_u32 s39, s39, 0
	s_waitcnt vmcnt(16)
	v_pk_add_f32 v[128:129], v[128:129], 1.0 op_sel_hi:[1,0]
	v_pk_add_f32 v[130:131], v[130:131], 1.0 op_sel_hi:[1,0]
	v_pk_add_f32 v[132:133], v[132:133], 1.0 op_sel_hi:[1,0]
	v_pk_add_f32 v[134:135], v[134:135], 1.0 op_sel_hi:[1,0]
	v_pk_add_f32 v[136:137], v[136:137], 1.0 op_sel_hi:[1,0]
	v_pk_add_f32 v[138:139], v[138:139], 1.0 op_sel_hi:[1,0]
	v_pk_add_f32 v[140:141], v[140:141], 1.0 op_sel_hi:[1,0]
	v_pk_add_f32 v[142:143], v[142:143], 1.0 op_sel_hi:[1,0]
	s_waitcnt vmcnt(12)
; __device__ __forceinline__ unsigned pkbf(float lo, float hi) { f32x2_t v = {lo, hi}; bf16x2_t b = __builtin_convertvector(v, bf16x2_t); return __builtin_bit_cast(unsigned, b); }
; __device__ __forceinline__ void norm_phase(const void* src_lat, int lat_f32, const float* src_ctx, int nrows, const float* gvec, const float* mods_l, int sh_off, int sc_off, bf16_t* U, const float* part, int nparts, float* ctx_out) {
;     ...
;         else { const float* src = row < MLAT ? (const float*)src_lat + (size_t)row * DM : src_ctx + (size_t)(row - MLAT) * DM;
; #pragma unroll
;             for (int j = 0; j < 4; ++j) v[j] = *(const f32x4*)(src + 4 * lane + 256 * j); }
; #pragma unroll
;         for (int j = 0; j < 4; ++j) { ss += (v[j][0] * v[j][0] + v[j][1] * v[j][1]) + (v[j][2] * v[j][2] + v[j][3] * v[j][3]); }
;         if (nparts != 0 && row >= MLAT) {
;             for (int ch = 0; ch < nparts; ch += 4) {
;                 f32x4 pv[4][4];
; #pragma unroll
;                 for (int c4 = 0; c4 < 4; ++c4) { const float* pr = part + ((size_t)(ch + c4) * MCTX + (row - MLAT)) * DM + 4 * lane;
; #pragma unroll
;                     for (int j = 0; j < 4; ++j) pv[c4][j] = *(const f32x4*)(pr + 256 * j); }
; #pragma unroll
;                 for (int c4 = 0; c4 < 4; ++c4)
; #pragma unroll
;                     for (int j = 0; j < 4; ++j) v[j] = v[j] + pv[c4][j]; }
;             ss = 0.f;
; #pragma unroll
;             for (int j = 0; j < 4; ++j) { *(f32x4*)(ctx_out + (size_t)(row - MLAT) * DM + 4 * lane + 256 * j) = v[j]; ss += (v[j][0] * v[j][0] + v[j][1] * v[j][1]) + (v[j][2] * v[j][2] + v[j][3] * v[j][3]); }
;         }
;         const float rs = rsqrtf(wave_sum64(ss) * (1.0f / DM) + EPS);
;         const float* shp = mods_l + s * 6144 + sh_off + 4 * lane; const float* scp = mods_l + s * 6144 + sc_off + 4 * lane;
;         bf16_t* up = U + (size_t)row * DM + 4 * lane;
; #pragma unroll
;         for (int j = 0; j < 4; ++j) { const f32x4 sh = *(const f32x4*)(shp + 256 * j), sc = *(const f32x4*)(scp + 256 * j);
;             const f32x4 y = v[j] * rs * gv[j] * (sc + 1.0f) + sh;
;             u32x2 o; o.x = pkbf(y[0], y[1]); o.y = pkbf(y[2], y[3]); *(u32x2*)(up + 256 * j) = o; }
	v_mul_f32_e32 v96, v159, v159
	v_mul_f32_e32 v97, v161, v161
	v_fmac_f32_e32 v96, v158, v158
	v_fmac_f32_e32 v97, v160, v160
	v_add_f32_e32 v98, v96, v97
	v_mul_f32_e32 v96, v163, v163
	v_mul_f32_e32 v97, v165, v165
	v_fmac_f32_e32 v96, v162, v162
	v_fmac_f32_e32 v97, v164, v164
	v_add_f32_e32 v96, v96, v97
	v_add_f32_e32 v98, v98, v96
	v_mul_f32_e32 v96, v167, v167
	v_mul_f32_e32 v97, v169, v169
	v_fmac_f32_e32 v96, v166, v166
	v_fmac_f32_e32 v97, v168, v168
	v_add_f32_e32 v96, v96, v97
	v_add_f32_e32 v98, v98, v96
	v_mul_f32_e32 v96, v171, v171
	v_mul_f32_e32 v97, v173, v173
	v_fmac_f32_e32 v96, v170, v170
	v_fmac_f32_e32 v97, v172, v172
	v_add_f32_e32 v96, v96, v97
	v_add_f32_e32 v98, v98, v96
	s_nop 1
	v_add_f32_dpp v98, v98, v98 quad_perm:[1,0,3,2] row_mask:0xf bank_mask:0xf bound_ctrl:1
	s_nop 1
	v_add_f32_dpp v98, v98, v98 quad_perm:[2,3,0,1] row_mask:0xf bank_mask:0xf bound_ctrl:1
	s_nop 1
	v_add_f32_dpp v98, v98, v98 row_half_mirror row_mask:0xf bank_mask:0xf bound_ctrl:1
	s_nop 1
	v_add_f32_dpp v98, v98, v98 row_mirror row_mask:0xf bank_mask:0xf bound_ctrl:1
	v_mov_b32_e32 v96, v98
	s_nop 1
	v_permlane16_swap_b32_e32 v98, v96
	v_add_f32_e32 v98, v98, v96
	v_mov_b32_e32 v96, v98
	s_nop 1
	v_permlane32_swap_b32_e32 v98, v96
	v_add_f32_e32 v98, v98, v96
	v_fmamk_f32 v100, v98, 0x3a800000, v153
	v_rsq_f32_e32 v100, v100
	s_nop 0
	v_pk_mul_f32 v[158:159], v[158:159], v[100:101] op_sel_hi:[1,0]
	v_pk_mul_f32 v[160:161], v[160:161], v[100:101] op_sel_hi:[1,0]
	v_pk_mul_f32 v[162:163], v[162:163], v[100:101] op_sel_hi:[1,0]
	v_pk_mul_f32 v[164:165], v[164:165], v[100:101] op_sel_hi:[1,0]
	v_pk_mul_f32 v[166:167], v[166:167], v[100:101] op_sel_hi:[1,0]
	v_pk_mul_f32 v[168:169], v[168:169], v[100:101] op_sel_hi:[1,0]
	v_pk_mul_f32 v[170:171], v[170:171], v[100:101] op_sel_hi:[1,0]
	v_pk_mul_f32 v[172:173], v[172:173], v[100:101] op_sel_hi:[1,0]
	v_pk_mul_f32 v[158:159], v[0:1], v[158:159]
	v_pk_mul_f32 v[160:161], v[2:3], v[160:161]
	v_pk_mul_f32 v[162:163], v[4:5], v[162:163]
	v_pk_mul_f32 v[164:165], v[6:7], v[164:165]
	v_pk_mul_f32 v[166:167], v[8:9], v[166:167]
	v_pk_mul_f32 v[168:169], v[10:11], v[168:169]
	v_pk_mul_f32 v[170:171], v[12:13], v[170:171]
	v_pk_mul_f32 v[172:173], v[14:15], v[172:173]
	v_pk_fma_f32 v[158:159], v[128:129], v[158:159], v[112:113]
	v_pk_fma_f32 v[160:161], v[130:131], v[160:161], v[114:115]
	v_pk_fma_f32 v[162:163], v[132:133], v[162:163], v[116:117]
	v_pk_fma_f32 v[164:165], v[134:135], v[164:165], v[118:119]
	v_pk_fma_f32 v[166:167], v[136:137], v[166:167], v[120:121]
	v_pk_fma_f32 v[168:169], v[138:139], v[168:169], v[122:123]
	v_pk_fma_f32 v[170:171], v[140:141], v[170:171], v[124:125]
	v_pk_fma_f32 v[172:173], v[142:143], v[172:173], v[126:127]
	v_cvt_pk_bf16_f32 v158, v158, v159
	v_cvt_pk_bf16_f32 v159, v160, v161
	v_cvt_pk_bf16_f32 v162, v162, v163
	v_cvt_pk_bf16_f32 v163, v164, v165
	v_cvt_pk_bf16_f32 v166, v166, v167
	v_cvt_pk_bf16_f32 v167, v168, v169
	v_cvt_pk_bf16_f32 v170, v170, v171
	v_cvt_pk_bf16_f32 v171, v172, v173
	global_store_dwordx2 v102, v[158:159], s[40:41]
	global_store_dwordx2 v102, v[162:163], s[40:41] offset:512
	global_store_dwordx2 v102, v[166:167], s[40:41] offset:1024
	global_store_dwordx2 v102, v[170:171], s[40:41] offset:1536
	s_add_u32 s40, s40, 0x400000
	s_addc_u32 s41, s41, 0
	global_load_dwordx4 v[158:161], v103, s[38:39]
	global_load_dwordx4 v[162:165], v103, s[38:39] offset:1024
	global_load_dwordx4 v[166:169], v103, s[38:39] offset:2048
	global_load_dwordx4 v[170:173], v103, s[38:39] offset:3072
	s_add_u32 s38, s38, 0x800000
	s_addc_u32 s39, s39, 0
	global_load_dwordx4 v[48:51], v103, s[42:43]
	global_load_dwordx4 v[52:55], v103, s[42:43] offset:1024
	global_load_dwordx4 v[56:59], v103, s[42:43] offset:2048
	global_load_dwordx4 v[60:63], v103, s[42:43] offset:3072
	global_load_dwordx4 v[64:67], v103, s[44:45]
	global_load_dwordx4 v[68:71], v103, s[44:45] offset:1024
	global_load_dwordx4 v[72:75], v103, s[44:45] offset:2048
	global_load_dwordx4 v[76:79], v103, s[44:45] offset:3072
	s_add_u32 s42, s42, 0x6000
	s_addc_u32 s43, s43, 0
	s_add_u32 s44, s44, 0x6000
	s_addc_u32 s45, s45, 0
	s_waitcnt vmcnt(24)
	v_mul_f32_e32 v96, v175, v175
	v_mul_f32_e32 v97, v177, v177
	v_fmac_f32_e32 v96, v174, v174
	v_fmac_f32_e32 v97, v176, v176
	v_add_f32_e32 v98, v96, v97
	v_mul_f32_e32 v96, v179, v179
	v_mul_f32_e32 v97, v181, v181
	v_fmac_f32_e32 v96, v178, v178
	v_fmac_f32_e32 v97, v180, v180
	v_add_f32_e32 v96, v96, v97
	v_add_f32_e32 v98, v98, v96
	v_mul_f32_e32 v96, v183, v183
	v_mul_f32_e32 v97, v185, v185
	v_fmac_f32_e32 v96, v182, v182
	v_fmac_f32_e32 v97, v184, v184
	v_add_f32_e32 v96, v96, v97
	v_add_f32_e32 v98, v98, v96
	v_mul_f32_e32 v96, v187, v187
	v_mul_f32_e32 v97, v189, v189
	v_fmac_f32_e32 v96, v186, v186
	v_fmac_f32_e32 v97, v188, v188
	v_add_f32_e32 v96, v96, v97
	v_add_f32_e32 v98, v98, v96
	s_nop 1
	v_add_f32_dpp v98, v98, v98 quad_perm:[1,0,3,2] row_mask:0xf bank_mask:0xf bound_ctrl:1
	s_nop 1
	v_add_f32_dpp v98, v98, v98 quad_perm:[2,3,0,1] row_mask:0xf bank_mask:0xf bound_ctrl:1
	s_nop 1
	v_add_f32_dpp v98, v98, v98 row_half_mirror row_mask:0xf bank_mask:0xf bound_ctrl:1
	s_nop 1
	v_add_f32_dpp v98, v98, v98 row_mirror row_mask:0xf bank_mask:0xf bound_ctrl:1
	v_mov_b32_e32 v96, v98
	s_nop 1
	v_permlane16_swap_b32_e32 v98, v96
	v_add_f32_e32 v98, v98, v96
	v_mov_b32_e32 v96, v98
	s_nop 1
	v_permlane32_swap_b32_e32 v98, v96
	v_add_f32_e32 v98, v98, v96
	v_fmamk_f32 v100, v98, 0x3a800000, v153
	v_rsq_f32_e32 v100, v100
	s_nop 0
	v_pk_mul_f32 v[174:175], v[174:175], v[100:101] op_sel_hi:[1,0]
	v_pk_mul_f32 v[176:177], v[176:177], v[100:101] op_sel_hi:[1,0]
; __device__ __forceinline__ unsigned pkbf(float lo, float hi) { f32x2_t v = {lo, hi}; bf16x2_t b = __builtin_convertvector(v, bf16x2_t); return __builtin_bit_cast(unsigned, b); }
; __device__ __forceinline__ void norm_phase(const void* src_lat, int lat_f32, const float* src_ctx, int nrows, const float* gvec, const float* mods_l, int sh_off, int sc_off, bf16_t* U, const float* part, int nparts, float* ctx_out) {
;     ...
;         else { const float* src = row < MLAT ? (const float*)src_lat + (size_t)row * DM : src_ctx + (size_t)(row - MLAT) * DM;
; #pragma unroll
;             for (int j = 0; j < 4; ++j) v[j] = *(const f32x4*)(src + 4 * lane + 256 * j); }
; #pragma unroll
;         for (int j = 0; j < 4; ++j) { ss += (v[j][0] * v[j][0] + v[j][1] * v[j][1]) + (v[j][2] * v[j][2] + v[j][3] * v[j][3]); }
;         if (nparts != 0 && row >= MLAT) {
;             for (int ch = 0; ch < nparts; ch += 4) {
;                 f32x4 pv[4][4];
; #pragma unroll
;                 for (int c4 = 0; c4 < 4; ++c4) { const float* pr = part + ((size_t)(ch + c4) * MCTX + (row - MLAT)) * DM + 4 * lane;
; #pragma unroll
;                     for (int j = 0; j < 4; ++j) pv[c4][j] = *(const f32x4*)(pr + 256 * j); }
; #pragma unroll
;                 for (int c4 = 0; c4 < 4; ++c4)
; #pragma unroll
;                     for (int j = 0; j < 4; ++j) v[j] = v[j] + pv[c4][j]; }
;             ss = 0.f;
; #pragma unroll
;             for (int j = 0; j < 4; ++j) { *(f32x4*)(ctx_out + (size_t)(row - MLAT) * DM + 4 * lane + 256 * j) = v[j]; ss += (v[j][0] * v[j][0] + v[j][1] * v[j][1]) + (v[j][2] * v[j][2] + v[j][3] * v[j][3]); }
;         }
;         const float rs = rsqrtf(wave_sum64(ss) * (1.0f / DM) + EPS);
;         const float* shp = mods_l + s * 6144 + sh_off + 4 * lane; const float* scp = mods_l + s * 6144 + sc_off + 4 * lane;
;         bf16_t* up = U + (size_t)row * DM + 4 * lane;
; #pragma unroll
;         for (int j = 0; j < 4; ++j) { const f32x4 sh = *(const f32x4*)(shp + 256 * j), sc = *(const f32x4*)(scp + 256 * j);
;             const f32x4 y = v[j] * rs * gv[j] * (sc + 1.0f) + sh;
;             u32x2 o; o.x = pkbf(y[0], y[1]); o.y = pkbf(y[2], y[3]); *(u32x2*)(up + 256 * j) = o; }
	v_pk_mul_f32 v[178:179], v[178:179], v[100:101] op_sel_hi:[1,0]
	v_pk_mul_f32 v[180:181], v[180:181], v[100:101] op_sel_hi:[1,0]
	v_pk_mul_f32 v[182:183], v[182:183], v[100:101] op_sel_hi:[1,0]
	v_pk_mul_f32 v[184:185], v[184:185], v[100:101] op_sel_hi:[1,0]
	v_pk_mul_f32 v[186:187], v[186:187], v[100:101] op_sel_hi:[1,0]
	v_pk_mul_f32 v[188:189], v[188:189], v[100:101] op_sel_hi:[1,0]
	v_pk_mul_f32 v[174:175], v[0:1], v[174:175]
	v_pk_mul_f32 v[176:177], v[2:3], v[176:177]
	v_pk_mul_f32 v[178:179], v[4:5], v[178:179]
	v_pk_mul_f32 v[180:181], v[6:7], v[180:181]
	v_pk_mul_f32 v[182:183], v[8:9], v[182:183]
	v_pk_mul_f32 v[184:185], v[10:11], v[184:185]
	v_pk_mul_f32 v[186:187], v[12:13], v[186:187]
	v_pk_mul_f32 v[188:189], v[14:15], v[188:189]
	v_pk_fma_f32 v[174:175], v[128:129], v[174:175], v[112:113]
	v_pk_fma_f32 v[176:177], v[130:131], v[176:177], v[114:115]
	v_pk_fma_f32 v[178:179], v[132:133], v[178:179], v[116:117]
	v_pk_fma_f32 v[180:181], v[134:135], v[180:181], v[118:119]
	v_pk_fma_f32 v[182:183], v[136:137], v[182:183], v[120:121]
	v_pk_fma_f32 v[184:185], v[138:139], v[184:185], v[122:123]
	v_pk_fma_f32 v[186:187], v[140:141], v[186:187], v[124:125]
	v_pk_fma_f32 v[188:189], v[142:143], v[188:189], v[126:127]
	v_cvt_pk_bf16_f32 v174, v174, v175
	v_cvt_pk_bf16_f32 v175, v176, v177
	v_cvt_pk_bf16_f32 v178, v178, v179
	v_cvt_pk_bf16_f32 v179, v180, v181
	v_cvt_pk_bf16_f32 v182, v182, v183
	v_cvt_pk_bf16_f32 v183, v184, v185
	v_cvt_pk_bf16_f32 v186, v186, v187
	v_cvt_pk_bf16_f32 v187, v188, v189
	global_store_dwordx2 v102, v[174:175], s[40:41]
	global_store_dwordx2 v102, v[178:179], s[40:41] offset:512
	global_store_dwordx2 v102, v[182:183], s[40:41] offset:1024
	global_store_dwordx2 v102, v[186:187], s[40:41] offset:1536
	s_add_u32 s40, s40, 0x400000
	s_addc_u32 s41, s41, 0
	global_load_dwordx4 v[174:177], v103, s[38:39]
	global_load_dwordx4 v[178:181], v103, s[38:39] offset:1024
	global_load_dwordx4 v[182:185], v103, s[38:39] offset:2048
	global_load_dwordx4 v[186:189], v103, s[38:39] offset:3072
	s_add_u32 s38, s38, 0x800000
	s_addc_u32 s39, s39, 0
	s_waitcnt vmcnt(28)
	v_mul_f32_e32 v96, v199, v199
	v_mul_f32_e32 v97, v201, v201
	v_fmac_f32_e32 v96, v198, v198
	v_fmac_f32_e32 v97, v200, v200
	v_add_f32_e32 v98, v96, v97
	v_mul_f32_e32 v96, v203, v203
	v_mul_f32_e32 v97, v205, v205
	v_fmac_f32_e32 v96, v202, v202
	v_fmac_f32_e32 v97, v204, v204
	v_add_f32_e32 v96, v96, v97
	v_add_f32_e32 v98, v98, v96
	v_mul_f32_e32 v96, v207, v207
	v_mul_f32_e32 v97, v209, v209
	v_fmac_f32_e32 v96, v206, v206
	v_fmac_f32_e32 v97, v208, v208
	v_add_f32_e32 v96, v96, v97
	v_add_f32_e32 v98, v98, v96
	v_mul_f32_e32 v96, v211, v211
	v_mul_f32_e32 v97, v213, v213
	v_fmac_f32_e32 v96, v210, v210
	v_fmac_f32_e32 v97, v212, v212
	v_add_f32_e32 v96, v96, v97
	v_add_f32_e32 v98, v98, v96
	s_nop 1
	v_add_f32_dpp v98, v98, v98 quad_perm:[1,0,3,2] row_mask:0xf bank_mask:0xf bound_ctrl:1
	s_nop 1
	v_add_f32_dpp v98, v98, v98 quad_perm:[2,3,0,1] row_mask:0xf bank_mask:0xf bound_ctrl:1
	s_nop 1
	v_add_f32_dpp v98, v98, v98 row_half_mirror row_mask:0xf bank_mask:0xf bound_ctrl:1
	s_nop 1
	v_add_f32_dpp v98, v98, v98 row_mirror row_mask:0xf bank_mask:0xf bound_ctrl:1
	v_mov_b32_e32 v96, v98
	s_nop 1
	v_permlane16_swap_b32_e32 v98, v96
	v_add_f32_e32 v98, v98, v96
	v_mov_b32_e32 v96, v98
	s_nop 1
	v_permlane32_swap_b32_e32 v98, v96
	v_add_f32_e32 v98, v98, v96
	v_fmamk_f32 v100, v98, 0x3a800000, v153
	v_rsq_f32_e32 v100, v100
	s_nop 0
	v_pk_mul_f32 v[198:199], v[198:199], v[100:101] op_sel_hi:[1,0]
	v_pk_mul_f32 v[200:201], v[200:201], v[100:101] op_sel_hi:[1,0]
	v_pk_mul_f32 v[202:203], v[202:203], v[100:101] op_sel_hi:[1,0]
	v_pk_mul_f32 v[204:205], v[204:205], v[100:101] op_sel_hi:[1,0]
	v_pk_mul_f32 v[206:207], v[206:207], v[100:101] op_sel_hi:[1,0]
	v_pk_mul_f32 v[208:209], v[208:209], v[100:101] op_sel_hi:[1,0]
	v_pk_mul_f32 v[210:211], v[210:211], v[100:101] op_sel_hi:[1,0]
	v_pk_mul_f32 v[212:213], v[212:213], v[100:101] op_sel_hi:[1,0]
	v_pk_mul_f32 v[198:199], v[0:1], v[198:199]
	v_pk_mul_f32 v[200:201], v[2:3], v[200:201]
	v_pk_mul_f32 v[202:203], v[4:5], v[202:203]
	v_pk_mul_f32 v[204:205], v[6:7], v[204:205]
	v_pk_mul_f32 v[206:207], v[8:9], v[206:207]
	v_pk_mul_f32 v[208:209], v[10:11], v[208:209]
	v_pk_mul_f32 v[210:211], v[12:13], v[210:211]
	v_pk_mul_f32 v[212:213], v[14:15], v[212:213]
	v_pk_fma_f32 v[198:199], v[128:129], v[198:199], v[112:113]
	v_pk_fma_f32 v[200:201], v[130:131], v[200:201], v[114:115]
	v_pk_fma_f32 v[202:203], v[132:133], v[202:203], v[116:117]
	v_pk_fma_f32 v[204:205], v[134:135], v[204:205], v[118:119]
	v_pk_fma_f32 v[206:207], v[136:137], v[206:207], v[120:121]
	v_pk_fma_f32 v[208:209], v[138:139], v[208:209], v[122:123]
	v_pk_fma_f32 v[210:211], v[140:141], v[210:211], v[124:125]
	v_pk_fma_f32 v[212:213], v[142:143], v[212:213], v[126:127]
	v_cvt_pk_bf16_f32 v198, v198, v199
	v_cvt_pk_bf16_f32 v199, v200, v201
	v_cvt_pk_bf16_f32 v202, v202, v203
	v_cvt_pk_bf16_f32 v203, v204, v205
	v_cvt_pk_bf16_f32 v206, v206, v207
	v_cvt_pk_bf16_f32 v207, v208, v209
	v_cvt_pk_bf16_f32 v210, v210, v211
	v_cvt_pk_bf16_f32 v211, v212, v213
	global_store_dwordx2 v102, v[198:199], s[40:41]
	global_store_dwordx2 v102, v[202:203], s[40:41] offset:512
	global_store_dwordx2 v102, v[206:207], s[40:41] offset:1024
	global_store_dwordx2 v102, v[210:211], s[40:41] offset:1536
	s_add_u32 s40, s40, 0x400000
	s_addc_u32 s41, s41, 0
	global_load_dwordx4 v[198:201], v103, s[38:39]
	global_load_dwordx4 v[202:205], v103, s[38:39] offset:1024
	global_load_dwordx4 v[206:209], v103, s[38:39] offset:2048
	global_load_dwordx4 v[210:213], v103, s[38:39] offset:3072
	s_add_u32 s38, s38, 0x800000
	s_addc_u32 s39, s39, 0
	s_waitcnt vmcnt(32)
; __device__ __forceinline__ unsigned pkbf(float lo, float hi) { f32x2_t v = {lo, hi}; bf16x2_t b = __builtin_convertvector(v, bf16x2_t); return __builtin_bit_cast(unsigned, b); }
; __device__ __forceinline__ void norm_phase(const void* src_lat, int lat_f32, const float* src_ctx, int nrows, const float* gvec, const float* mods_l, int sh_off, int sc_off, bf16_t* U, const float* part, int nparts, float* ctx_out) {
;     ...
;         else { const float* src = row < MLAT ? (const float*)src_lat + (size_t)row * DM : src_ctx + (size_t)(row - MLAT) * DM;
; #pragma unroll
;             for (int j = 0; j < 4; ++j) v[j] = *(const f32x4*)(src + 4 * lane + 256 * j); }
; #pragma unroll
;         for (int j = 0; j < 4; ++j) { ss += (v[j][0] * v[j][0] + v[j][1] * v[j][1]) + (v[j][2] * v[j][2] + v[j][3] * v[j][3]); }
;         if (nparts != 0 && row >= MLAT) {
;             for (int ch = 0; ch < nparts; ch += 4) {
;                 f32x4 pv[4][4];
; #pragma unroll
;                 for (int c4 = 0; c4 < 4; ++c4) { const float* pr = part + ((size_t)(ch + c4) * MCTX + (row - MLAT)) * DM + 4 * lane;
; #pragma unroll
;                     for (int j = 0; j < 4; ++j) pv[c4][j] = *(const f32x4*)(pr + 256 * j); }
; #pragma unroll
;                 for (int c4 = 0; c4 < 4; ++c4)
; #pragma unroll
;                     for (int j = 0; j < 4; ++j) v[j] = v[j] + pv[c4][j]; }
;             ss = 0.f;
; #pragma unroll
;             for (int j = 0; j < 4; ++j) { *(f32x4*)(ctx_out + (size_t)(row - MLAT) * DM + 4 * lane + 256 * j) = v[j]; ss += (v[j][0] * v[j][0] + v[j][1] * v[j][1]) + (v[j][2] * v[j][2] + v[j][3] * v[j][3]); }
;         }
;         const float rs = rsqrtf(wave_sum64(ss) * (1.0f / DM) + EPS);
;         const float* shp = mods_l + s * 6144 + sh_off + 4 * lane; const float* scp = mods_l + s * 6144 + sc_off + 4 * lane;
;         bf16_t* up = U + (size_t)row * DM + 4 * lane;
; #pragma unroll
;         for (int j = 0; j < 4; ++j) { const f32x4 sh = *(const f32x4*)(shp + 256 * j), sc = *(const f32x4*)(scp + 256 * j);
;             const f32x4 y = v[j] * rs * gv[j] * (sc + 1.0f) + sh;
;             u32x2 o; o.x = pkbf(y[0], y[1]); o.y = pkbf(y[2], y[3]); *(u32x2*)(up + 256 * j) = o; }
	v_mul_f32_e32 v96, v215, v215
	v_mul_f32_e32 v97, v217, v217
	v_fmac_f32_e32 v96, v214, v214
	v_fmac_f32_e32 v97, v216, v216
	v_add_f32_e32 v98, v96, v97
	v_mul_f32_e32 v96, v219, v219
	v_mul_f32_e32 v97, v221, v221
	v_fmac_f32_e32 v96, v218, v218
	v_fmac_f32_e32 v97, v220, v220
	v_add_f32_e32 v96, v96, v97
	v_add_f32_e32 v98, v98, v96
	v_mul_f32_e32 v96, v223, v223
	v_mul_f32_e32 v97, v225, v225
	v_fmac_f32_e32 v96, v222, v222
	v_fmac_f32_e32 v97, v224, v224
	v_add_f32_e32 v96, v96, v97
	v_add_f32_e32 v98, v98, v96
	v_mul_f32_e32 v96, v227, v227
	v_mul_f32_e32 v97, v229, v229
	v_fmac_f32_e32 v96, v226, v226
	v_fmac_f32_e32 v97, v228, v228
	v_add_f32_e32 v96, v96, v97
	v_add_f32_e32 v98, v98, v96
	s_nop 1
	v_add_f32_dpp v98, v98, v98 quad_perm:[1,0,3,2] row_mask:0xf bank_mask:0xf bound_ctrl:1
	s_nop 1
	v_add_f32_dpp v98, v98, v98 quad_perm:[2,3,0,1] row_mask:0xf bank_mask:0xf bound_ctrl:1
	s_nop 1
	v_add_f32_dpp v98, v98, v98 row_half_mirror row_mask:0xf bank_mask:0xf bound_ctrl:1
	s_nop 1
	v_add_f32_dpp v98, v98, v98 row_mirror row_mask:0xf bank_mask:0xf bound_ctrl:1
	v_mov_b32_e32 v96, v98
	s_nop 1
	v_permlane16_swap_b32_e32 v98, v96
	v_add_f32_e32 v98, v98, v96
	v_mov_b32_e32 v96, v98
	s_nop 1
	v_permlane32_swap_b32_e32 v98, v96
	v_add_f32_e32 v98, v98, v96
	v_fmamk_f32 v100, v98, 0x3a800000, v153
	v_rsq_f32_e32 v100, v100
	s_nop 0
	v_pk_mul_f32 v[214:215], v[214:215], v[100:101] op_sel_hi:[1,0]
	v_pk_mul_f32 v[216:217], v[216:217], v[100:101] op_sel_hi:[1,0]
	v_pk_mul_f32 v[218:219], v[218:219], v[100:101] op_sel_hi:[1,0]
	v_pk_mul_f32 v[220:221], v[220:221], v[100:101] op_sel_hi:[1,0]
	v_pk_mul_f32 v[222:223], v[222:223], v[100:101] op_sel_hi:[1,0]
	v_pk_mul_f32 v[224:225], v[224:225], v[100:101] op_sel_hi:[1,0]
	v_pk_mul_f32 v[226:227], v[226:227], v[100:101] op_sel_hi:[1,0]
	v_pk_mul_f32 v[228:229], v[228:229], v[100:101] op_sel_hi:[1,0]
	v_pk_mul_f32 v[214:215], v[0:1], v[214:215]
	v_pk_mul_f32 v[216:217], v[2:3], v[216:217]
	v_pk_mul_f32 v[218:219], v[4:5], v[218:219]
	v_pk_mul_f32 v[220:221], v[6:7], v[220:221]
	v_pk_mul_f32 v[222:223], v[8:9], v[222:223]
	v_pk_mul_f32 v[224:225], v[10:11], v[224:225]
	v_pk_mul_f32 v[226:227], v[12:13], v[226:227]
	v_pk_mul_f32 v[228:229], v[14:15], v[228:229]
	v_pk_fma_f32 v[214:215], v[128:129], v[214:215], v[112:113]
	v_pk_fma_f32 v[216:217], v[130:131], v[216:217], v[114:115]
	v_pk_fma_f32 v[218:219], v[132:133], v[218:219], v[116:117]
	v_pk_fma_f32 v[220:221], v[134:135], v[220:221], v[118:119]
	v_pk_fma_f32 v[222:223], v[136:137], v[222:223], v[120:121]
	v_pk_fma_f32 v[224:225], v[138:139], v[224:225], v[122:123]
	v_pk_fma_f32 v[226:227], v[140:141], v[226:227], v[124:125]
	v_pk_fma_f32 v[228:229], v[142:143], v[228:229], v[126:127]
	v_cvt_pk_bf16_f32 v214, v214, v215
	v_cvt_pk_bf16_f32 v215, v216, v217
	v_cvt_pk_bf16_f32 v218, v218, v219
	v_cvt_pk_bf16_f32 v219, v220, v221
	v_cvt_pk_bf16_f32 v222, v222, v223
	v_cvt_pk_bf16_f32 v223, v224, v225
	v_cvt_pk_bf16_f32 v226, v226, v227
	v_cvt_pk_bf16_f32 v227, v228, v229
	global_store_dwordx2 v102, v[214:215], s[40:41]
	global_store_dwordx2 v102, v[218:219], s[40:41] offset:512
	global_store_dwordx2 v102, v[222:223], s[40:41] offset:1024
	global_store_dwordx2 v102, v[226:227], s[40:41] offset:1536
	s_add_u32 s40, s40, 0x400000
	s_addc_u32 s41, s41, 0
	global_load_dwordx4 v[214:217], v103, s[38:39]
	global_load_dwordx4 v[218:221], v103, s[38:39] offset:1024
	global_load_dwordx4 v[222:225], v103, s[38:39] offset:2048
	global_load_dwordx4 v[226:229], v103, s[38:39] offset:3072
	s_add_u32 s38, s38, 0x800000
	s_addc_u32 s39, s39, 0
	s_waitcnt vmcnt(24)
	v_pk_add_f32 v[64:65], v[64:65], 1.0 op_sel_hi:[1,0]
	v_pk_add_f32 v[66:67], v[66:67], 1.0 op_sel_hi:[1,0]
	v_pk_add_f32 v[68:69], v[68:69], 1.0 op_sel_hi:[1,0]
	v_pk_add_f32 v[70:71], v[70:71], 1.0 op_sel_hi:[1,0]
	v_pk_add_f32 v[72:73], v[72:73], 1.0 op_sel_hi:[1,0]
	v_pk_add_f32 v[74:75], v[74:75], 1.0 op_sel_hi:[1,0]
	v_pk_add_f32 v[76:77], v[76:77], 1.0 op_sel_hi:[1,0]
	v_pk_add_f32 v[78:79], v[78:79], 1.0 op_sel_hi:[1,0]
	v_mul_f32_e32 v96, v159, v159
	v_mul_f32_e32 v97, v161, v161
	v_fmac_f32_e32 v96, v158, v158
	v_fmac_f32_e32 v97, v160, v160
	v_add_f32_e32 v98, v96, v97
	v_mul_f32_e32 v96, v163, v163
	v_mul_f32_e32 v97, v165, v165
	v_fmac_f32_e32 v96, v162, v162
	v_fmac_f32_e32 v97, v164, v164
	v_add_f32_e32 v96, v96, v97
	v_add_f32_e32 v98, v98, v96
	v_mul_f32_e32 v96, v167, v167
	v_mul_f32_e32 v97, v169, v169
	v_fmac_f32_e32 v96, v166, v166
	v_fmac_f32_e32 v97, v168, v168
	v_add_f32_e32 v96, v96, v97
	v_add_f32_e32 v98, v98, v96
	v_mul_f32_e32 v96, v171, v171
	v_mul_f32_e32 v97, v173, v173
	v_fmac_f32_e32 v96, v170, v170
	v_fmac_f32_e32 v97, v172, v172
	v_add_f32_e32 v96, v96, v97
	v_add_f32_e32 v98, v98, v96
	s_nop 1
	v_add_f32_dpp v98, v98, v98 quad_perm:[1,0,3,2] row_mask:0xf bank_mask:0xf bound_ctrl:1
	s_nop 1
	v_add_f32_dpp v98, v98, v98 quad_perm:[2,3,0,1] row_mask:0xf bank_mask:0xf bound_ctrl:1
	s_nop 1
	v_add_f32_dpp v98, v98, v98 row_half_mirror row_mask:0xf bank_mask:0xf bound_ctrl:1
	s_nop 1
	v_add_f32_dpp v98, v98, v98 row_mirror row_mask:0xf bank_mask:0xf bound_ctrl:1
	v_mov_b32_e32 v96, v98
	s_nop 1
	v_permlane16_swap_b32_e32 v98, v96
	v_add_f32_e32 v98, v98, v96
	v_mov_b32_e32 v96, v98
	s_nop 1
	v_permlane32_swap_b32_e32 v98, v96
	v_add_f32_e32 v98, v98, v96
	v_fmamk_f32 v100, v98, 0x3a800000, v153
	v_rsq_f32_e32 v100, v100
	s_nop 0
	v_pk_mul_f32 v[158:159], v[158:159], v[100:101] op_sel_hi:[1,0]
	v_pk_mul_f32 v[160:161], v[160:161], v[100:101] op_sel_hi:[1,0]
	v_pk_mul_f32 v[162:163], v[162:163], v[100:101] op_sel_hi:[1,0]
	v_pk_mul_f32 v[164:165], v[164:165], v[100:101] op_sel_hi:[1,0]
; __device__ __forceinline__ unsigned pkbf(float lo, float hi) { f32x2_t v = {lo, hi}; bf16x2_t b = __builtin_convertvector(v, bf16x2_t); return __builtin_bit_cast(unsigned, b); }
; __device__ __forceinline__ void norm_phase(const void* src_lat, int lat_f32, const float* src_ctx, int nrows, const float* gvec, const float* mods_l, int sh_off, int sc_off, bf16_t* U, const float* part, int nparts, float* ctx_out) {
;     ...
;         else { const float* src = row < MLAT ? (const float*)src_lat + (size_t)row * DM : src_ctx + (size_t)(row - MLAT) * DM;
; #pragma unroll
;             for (int j = 0; j < 4; ++j) v[j] = *(const f32x4*)(src + 4 * lane + 256 * j); }
; #pragma unroll
;         for (int j = 0; j < 4; ++j) { ss += (v[j][0] * v[j][0] + v[j][1] * v[j][1]) + (v[j][2] * v[j][2] + v[j][3] * v[j][3]); }
;         if (nparts != 0 && row >= MLAT) {
;             for (int ch = 0; ch < nparts; ch += 4) {
;                 f32x4 pv[4][4];
; #pragma unroll
;                 for (int c4 = 0; c4 < 4; ++c4) { const float* pr = part + ((size_t)(ch + c4) * MCTX + (row - MLAT)) * DM + 4 * lane;
; #pragma unroll
;                     for (int j = 0; j < 4; ++j) pv[c4][j] = *(const f32x4*)(pr + 256 * j); }
; #pragma unroll
;                 for (int c4 = 0; c4 < 4; ++c4)
; #pragma unroll
;                     for (int j = 0; j < 4; ++j) v[j] = v[j] + pv[c4][j]; }
;             ss = 0.f;
; #pragma unroll
;             for (int j = 0; j < 4; ++j) { *(f32x4*)(ctx_out + (size_t)(row - MLAT) * DM + 4 * lane + 256 * j) = v[j]; ss += (v[j][0] * v[j][0] + v[j][1] * v[j][1]) + (v[j][2] * v[j][2] + v[j][3] * v[j][3]); }
;         }
;         const float rs = rsqrtf(wave_sum64(ss) * (1.0f / DM) + EPS);
;         const float* shp = mods_l + s * 6144 + sh_off + 4 * lane; const float* scp = mods_l + s * 6144 + sc_off + 4 * lane;
;         bf16_t* up = U + (size_t)row * DM + 4 * lane;
; #pragma unroll
;         for (int j = 0; j < 4; ++j) { const f32x4 sh = *(const f32x4*)(shp + 256 * j), sc = *(const f32x4*)(scp + 256 * j);
;             const f32x4 y = v[j] * rs * gv[j] * (sc + 1.0f) + sh;
;             u32x2 o; o.x = pkbf(y[0], y[1]); o.y = pkbf(y[2], y[3]); *(u32x2*)(up + 256 * j) = o; }
	v_pk_mul_f32 v[166:167], v[166:167], v[100:101] op_sel_hi:[1,0]
	v_pk_mul_f32 v[168:169], v[168:169], v[100:101] op_sel_hi:[1,0]
	v_pk_mul_f32 v[170:171], v[170:171], v[100:101] op_sel_hi:[1,0]
	v_pk_mul_f32 v[172:173], v[172:173], v[100:101] op_sel_hi:[1,0]
	v_pk_mul_f32 v[158:159], v[0:1], v[158:159]
	v_pk_mul_f32 v[160:161], v[2:3], v[160:161]
	v_pk_mul_f32 v[162:163], v[4:5], v[162:163]
	v_pk_mul_f32 v[164:165], v[6:7], v[164:165]
	v_pk_mul_f32 v[166:167], v[8:9], v[166:167]
	v_pk_mul_f32 v[168:169], v[10:11], v[168:169]
	v_pk_mul_f32 v[170:171], v[12:13], v[170:171]
	v_pk_mul_f32 v[172:173], v[14:15], v[172:173]
	v_pk_fma_f32 v[158:159], v[64:65], v[158:159], v[48:49]
	v_pk_fma_f32 v[160:161], v[66:67], v[160:161], v[50:51]
	v_pk_fma_f32 v[162:163], v[68:69], v[162:163], v[52:53]
	v_pk_fma_f32 v[164:165], v[70:71], v[164:165], v[54:55]
	v_pk_fma_f32 v[166:167], v[72:73], v[166:167], v[56:57]
	v_pk_fma_f32 v[168:169], v[74:75], v[168:169], v[58:59]
	v_pk_fma_f32 v[170:171], v[76:77], v[170:171], v[60:61]
	v_pk_fma_f32 v[172:173], v[78:79], v[172:173], v[62:63]
	v_cvt_pk_bf16_f32 v158, v158, v159
	v_cvt_pk_bf16_f32 v159, v160, v161
	v_cvt_pk_bf16_f32 v162, v162, v163
	v_cvt_pk_bf16_f32 v163, v164, v165
	v_cvt_pk_bf16_f32 v166, v166, v167
	v_cvt_pk_bf16_f32 v167, v168, v169
	v_cvt_pk_bf16_f32 v170, v170, v171
	v_cvt_pk_bf16_f32 v171, v172, v173
	global_store_dwordx2 v102, v[158:159], s[40:41]
	global_store_dwordx2 v102, v[162:163], s[40:41] offset:512
	global_store_dwordx2 v102, v[166:167], s[40:41] offset:1024
	global_store_dwordx2 v102, v[170:171], s[40:41] offset:1536
	s_add_u32 s40, s40, 0x400000
	s_addc_u32 s41, s41, 0
	global_load_dwordx4 v[158:161], v103, s[38:39]
	global_load_dwordx4 v[162:165], v103, s[38:39] offset:1024
	global_load_dwordx4 v[166:169], v103, s[38:39] offset:2048
	global_load_dwordx4 v[170:173], v103, s[38:39] offset:3072
	s_add_u32 s38, s38, 0x800000
	s_addc_u32 s39, s39, 0
	global_load_dwordx4 v[112:115], v103, s[42:43]
	global_load_dwordx4 v[116:119], v103, s[42:43] offset:1024
	global_load_dwordx4 v[120:123], v103, s[42:43] offset:2048
	global_load_dwordx4 v[124:127], v103, s[42:43] offset:3072
	global_load_dwordx4 v[128:131], v103, s[44:45]
	global_load_dwordx4 v[132:135], v103, s[44:45] offset:1024
	global_load_dwordx4 v[136:139], v103, s[44:45] offset:2048
	global_load_dwordx4 v[140:143], v103, s[44:45] offset:3072
	s_add_u32 s42, s42, 0x6000
	s_addc_u32 s43, s43, 0
	s_add_u32 s44, s44, 0x6000
	s_addc_u32 s45, s45, 0
	s_waitcnt vmcnt(32)
	v_mul_f32_e32 v96, v175, v175
	v_mul_f32_e32 v97, v177, v177
	v_fmac_f32_e32 v96, v174, v174
	v_fmac_f32_e32 v97, v176, v176
	v_add_f32_e32 v98, v96, v97
	v_mul_f32_e32 v96, v179, v179
	v_mul_f32_e32 v97, v181, v181
	v_fmac_f32_e32 v96, v178, v178
	v_fmac_f32_e32 v97, v180, v180
	v_add_f32_e32 v96, v96, v97
	v_add_f32_e32 v98, v98, v96
	v_mul_f32_e32 v96, v183, v183
	v_mul_f32_e32 v97, v185, v185
	v_fmac_f32_e32 v96, v182, v182
	v_fmac_f32_e32 v97, v184, v184
	v_add_f32_e32 v96, v96, v97
	v_add_f32_e32 v98, v98, v96
	v_mul_f32_e32 v96, v187, v187
	v_mul_f32_e32 v97, v189, v189
	v_fmac_f32_e32 v96, v186, v186
	v_fmac_f32_e32 v97, v188, v188
	v_add_f32_e32 v96, v96, v97
	v_add_f32_e32 v98, v98, v96
	s_nop 1
	v_add_f32_dpp v98, v98, v98 quad_perm:[1,0,3,2] row_mask:0xf bank_mask:0xf bound_ctrl:1
	s_nop 1
	v_add_f32_dpp v98, v98, v98 quad_perm:[2,3,0,1] row_mask:0xf bank_mask:0xf bound_ctrl:1
	s_nop 1
	v_add_f32_dpp v98, v98, v98 row_half_mirror row_mask:0xf bank_mask:0xf bound_ctrl:1
	s_nop 1
	v_add_f32_dpp v98, v98, v98 row_mirror row_mask:0xf bank_mask:0xf bound_ctrl:1
	v_mov_b32_e32 v96, v98
	s_nop 1
	v_permlane16_swap_b32_e32 v98, v96
	v_add_f32_e32 v98, v98, v96
	v_mov_b32_e32 v96, v98
	s_nop 1
	v_permlane32_swap_b32_e32 v98, v96
	v_add_f32_e32 v98, v98, v96
	v_fmamk_f32 v100, v98, 0x3a800000, v153
	v_rsq_f32_e32 v100, v100
	s_nop 0
	v_pk_mul_f32 v[174:175], v[174:175], v[100:101] op_sel_hi:[1,0]
	v_pk_mul_f32 v[176:177], v[176:177], v[100:101] op_sel_hi:[1,0]
	v_pk_mul_f32 v[178:179], v[178:179], v[100:101] op_sel_hi:[1,0]
	v_pk_mul_f32 v[180:181], v[180:181], v[100:101] op_sel_hi:[1,0]
	v_pk_mul_f32 v[182:183], v[182:183], v[100:101] op_sel_hi:[1,0]
	v_pk_mul_f32 v[184:185], v[184:185], v[100:101] op_sel_hi:[1,0]
	v_pk_mul_f32 v[186:187], v[186:187], v[100:101] op_sel_hi:[1,0]
	v_pk_mul_f32 v[188:189], v[188:189], v[100:101] op_sel_hi:[1,0]
	v_pk_mul_f32 v[174:175], v[0:1], v[174:175]
	v_pk_mul_f32 v[176:177], v[2:3], v[176:177]
	v_pk_mul_f32 v[178:179], v[4:5], v[178:179]
	v_pk_mul_f32 v[180:181], v[6:7], v[180:181]
	v_pk_mul_f32 v[182:183], v[8:9], v[182:183]
	v_pk_mul_f32 v[184:185], v[10:11], v[184:185]
	v_pk_mul_f32 v[186:187], v[12:13], v[186:187]
	v_pk_mul_f32 v[188:189], v[14:15], v[188:189]
	v_pk_fma_f32 v[174:175], v[64:65], v[174:175], v[48:49]
	v_pk_fma_f32 v[176:177], v[66:67], v[176:177], v[50:51]
	v_pk_fma_f32 v[178:179], v[68:69], v[178:179], v[52:53]
	v_pk_fma_f32 v[180:181], v[70:71], v[180:181], v[54:55]
	v_pk_fma_f32 v[182:183], v[72:73], v[182:183], v[56:57]
	v_pk_fma_f32 v[184:185], v[74:75], v[184:185], v[58:59]
	v_pk_fma_f32 v[186:187], v[76:77], v[186:187], v[60:61]
	v_pk_fma_f32 v[188:189], v[78:79], v[188:189], v[62:63]
	v_cvt_pk_bf16_f32 v174, v174, v175
	v_cvt_pk_bf16_f32 v175, v176, v177
	v_cvt_pk_bf16_f32 v178, v178, v179
	v_cvt_pk_bf16_f32 v179, v180, v181
	v_cvt_pk_bf16_f32 v182, v182, v183
	v_cvt_pk_bf16_f32 v183, v184, v185
	v_cvt_pk_bf16_f32 v186, v186, v187
	v_cvt_pk_bf16_f32 v187, v188, v189
	global_store_dwordx2 v102, v[174:175], s[40:41]
	global_store_dwordx2 v102, v[178:179], s[40:41] offset:512
	global_store_dwordx2 v102, v[182:183], s[40:41] offset:1024
	global_store_dwordx2 v102, v[186:187], s[40:41] offset:1536
	s_add_u32 s40, s40, 0x400000
	s_addc_u32 s41, s41, 0
	global_load_dwordx4 v[174:177], v103, s[38:39]
	global_load_dwordx4 v[178:181], v103, s[38:39] offset:1024
	global_load_dwordx4 v[182:185], v103, s[38:39] offset:2048
	global_load_dwordx4 v[186:189], v103, s[38:39] offset:3072
	s_add_u32 s38, s38, 0x800000
	s_addc_u32 s39, s39, 0
	s_waitcnt vmcnt(32)
; __device__ __forceinline__ unsigned pkbf(float lo, float hi) { f32x2_t v = {lo, hi}; bf16x2_t b = __builtin_convertvector(v, bf16x2_t); return __builtin_bit_cast(unsigned, b); }
; __device__ __forceinline__ void norm_phase(const void* src_lat, int lat_f32, const float* src_ctx, int nrows, const float* gvec, const float* mods_l, int sh_off, int sc_off, bf16_t* U, const float* part, int nparts, float* ctx_out) {
;     ...
;         else { const float* src = row < MLAT ? (const float*)src_lat + (size_t)row * DM : src_ctx + (size_t)(row - MLAT) * DM;
; #pragma unroll
;             for (int j = 0; j < 4; ++j) v[j] = *(const f32x4*)(src + 4 * lane + 256 * j); }
; #pragma unroll
;         for (int j = 0; j < 4; ++j) { ss += (v[j][0] * v[j][0] + v[j][1] * v[j][1]) + (v[j][2] * v[j][2] + v[j][3] * v[j][3]); }
;         if (nparts != 0 && row >= MLAT) {
;             for (int ch = 0; ch < nparts; ch += 4) {
;                 f32x4 pv[4][4];
; #pragma unroll
;                 for (int c4 = 0; c4 < 4; ++c4) { const float* pr = part + ((size_t)(ch + c4) * MCTX + (row - MLAT)) * DM + 4 * lane;
; #pragma unroll
;                     for (int j = 0; j < 4; ++j) pv[c4][j] = *(const f32x4*)(pr + 256 * j); }
; #pragma unroll
;                 for (int c4 = 0; c4 < 4; ++c4)
; #pragma unroll
;                     for (int j = 0; j < 4; ++j) v[j] = v[j] + pv[c4][j]; }
;             ss = 0.f;
; #pragma unroll
;             for (int j = 0; j < 4; ++j) { *(f32x4*)(ctx_out + (size_t)(row - MLAT) * DM + 4 * lane + 256 * j) = v[j]; ss += (v[j][0] * v[j][0] + v[j][1] * v[j][1]) + (v[j][2] * v[j][2] + v[j][3] * v[j][3]); }
;         }
;         const float rs = rsqrtf(wave_sum64(ss) * (1.0f / DM) + EPS);
;         const float* shp = mods_l + s * 6144 + sh_off + 4 * lane; const float* scp = mods_l + s * 6144 + sc_off + 4 * lane;
;         bf16_t* up = U + (size_t)row * DM + 4 * lane;
; #pragma unroll
;         for (int j = 0; j < 4; ++j) { const f32x4 sh = *(const f32x4*)(shp + 256 * j), sc = *(const f32x4*)(scp + 256 * j);
;             const f32x4 y = v[j] * rs * gv[j] * (sc + 1.0f) + sh;
;             u32x2 o; o.x = pkbf(y[0], y[1]); o.y = pkbf(y[2], y[3]); *(u32x2*)(up + 256 * j) = o; }
	v_mul_f32_e32 v96, v199, v199
	v_mul_f32_e32 v97, v201, v201
	v_fmac_f32_e32 v96, v198, v198
	v_fmac_f32_e32 v97, v200, v200
	v_add_f32_e32 v98, v96, v97
	v_mul_f32_e32 v96, v203, v203
	v_mul_f32_e32 v97, v205, v205
	v_fmac_f32_e32 v96, v202, v202
	v_fmac_f32_e32 v97, v204, v204
	v_add_f32_e32 v96, v96, v97
	v_add_f32_e32 v98, v98, v96
	v_mul_f32_e32 v96, v207, v207
	v_mul_f32_e32 v97, v209, v209
	v_fmac_f32_e32 v96, v206, v206
	v_fmac_f32_e32 v97, v208, v208
	v_add_f32_e32 v96, v96, v97
	v_add_f32_e32 v98, v98, v96
	v_mul_f32_e32 v96, v211, v211
	v_mul_f32_e32 v97, v213, v213
	v_fmac_f32_e32 v96, v210, v210
	v_fmac_f32_e32 v97, v212, v212
	v_add_f32_e32 v96, v96, v97
	v_add_f32_e32 v98, v98, v96
	s_nop 1
	v_add_f32_dpp v98, v98, v98 quad_perm:[1,0,3,2] row_mask:0xf bank_mask:0xf bound_ctrl:1
	s_nop 1
	v_add_f32_dpp v98, v98, v98 quad_perm:[2,3,0,1] row_mask:0xf bank_mask:0xf bound_ctrl:1
	s_nop 1
	v_add_f32_dpp v98, v98, v98 row_half_mirror row_mask:0xf bank_mask:0xf bound_ctrl:1
	s_nop 1
	v_add_f32_dpp v98, v98, v98 row_mirror row_mask:0xf bank_mask:0xf bound_ctrl:1
	v_mov_b32_e32 v96, v98
	s_nop 1
	v_permlane16_swap_b32_e32 v98, v96
	v_add_f32_e32 v98, v98, v96
	v_mov_b32_e32 v96, v98
	s_nop 1
	v_permlane32_swap_b32_e32 v98, v96
	v_add_f32_e32 v98, v98, v96
	v_fmamk_f32 v100, v98, 0x3a800000, v153
	v_rsq_f32_e32 v100, v100
	s_nop 0
	v_pk_mul_f32 v[198:199], v[198:199], v[100:101] op_sel_hi:[1,0]
	v_pk_mul_f32 v[200:201], v[200:201], v[100:101] op_sel_hi:[1,0]
	v_pk_mul_f32 v[202:203], v[202:203], v[100:101] op_sel_hi:[1,0]
	v_pk_mul_f32 v[204:205], v[204:205], v[100:101] op_sel_hi:[1,0]
	v_pk_mul_f32 v[206:207], v[206:207], v[100:101] op_sel_hi:[1,0]
	v_pk_mul_f32 v[208:209], v[208:209], v[100:101] op_sel_hi:[1,0]
	v_pk_mul_f32 v[210:211], v[210:211], v[100:101] op_sel_hi:[1,0]
	v_pk_mul_f32 v[212:213], v[212:213], v[100:101] op_sel_hi:[1,0]
	v_pk_mul_f32 v[198:199], v[0:1], v[198:199]
	v_pk_mul_f32 v[200:201], v[2:3], v[200:201]
	v_pk_mul_f32 v[202:203], v[4:5], v[202:203]
	v_pk_mul_f32 v[204:205], v[6:7], v[204:205]
	v_pk_mul_f32 v[206:207], v[8:9], v[206:207]
	v_pk_mul_f32 v[208:209], v[10:11], v[208:209]
	v_pk_mul_f32 v[210:211], v[12:13], v[210:211]
	v_pk_mul_f32 v[212:213], v[14:15], v[212:213]
	v_pk_fma_f32 v[198:199], v[64:65], v[198:199], v[48:49]
	v_pk_fma_f32 v[200:201], v[66:67], v[200:201], v[50:51]
	v_pk_fma_f32 v[202:203], v[68:69], v[202:203], v[52:53]
	v_pk_fma_f32 v[204:205], v[70:71], v[204:205], v[54:55]
	v_pk_fma_f32 v[206:207], v[72:73], v[206:207], v[56:57]
	v_pk_fma_f32 v[208:209], v[74:75], v[208:209], v[58:59]
	v_pk_fma_f32 v[210:211], v[76:77], v[210:211], v[60:61]
	v_pk_fma_f32 v[212:213], v[78:79], v[212:213], v[62:63]
	v_cvt_pk_bf16_f32 v198, v198, v199
	v_cvt_pk_bf16_f32 v199, v200, v201
	v_cvt_pk_bf16_f32 v202, v202, v203
	v_cvt_pk_bf16_f32 v203, v204, v205
	v_cvt_pk_bf16_f32 v206, v206, v207
	v_cvt_pk_bf16_f32 v207, v208, v209
	v_cvt_pk_bf16_f32 v210, v210, v211
	v_cvt_pk_bf16_f32 v211, v212, v213
	global_store_dwordx2 v102, v[198:199], s[40:41]
	global_store_dwordx2 v102, v[202:203], s[40:41] offset:512
	global_store_dwordx2 v102, v[206:207], s[40:41] offset:1024
	global_store_dwordx2 v102, v[210:211], s[40:41] offset:1536
	s_add_u32 s40, s40, 0x400000
	s_addc_u32 s41, s41, 0
	global_load_dwordx4 v[198:201], v103, s[38:39]
	global_load_dwordx4 v[202:205], v103, s[38:39] offset:1024
	global_load_dwordx4 v[206:209], v103, s[38:39] offset:2048
	global_load_dwordx4 v[210:213], v103, s[38:39] offset:3072
	s_add_u32 s38, s38, 0x800000
	s_addc_u32 s39, s39, 0
	s_waitcnt vmcnt(32)
	v_mul_f32_e32 v96, v215, v215
	v_mul_f32_e32 v97, v217, v217
	v_fmac_f32_e32 v96, v214, v214
	v_fmac_f32_e32 v97, v216, v216
	v_add_f32_e32 v98, v96, v97
	v_mul_f32_e32 v96, v219, v219
	v_mul_f32_e32 v97, v221, v221
	v_fmac_f32_e32 v96, v218, v218
	v_fmac_f32_e32 v97, v220, v220
	v_add_f32_e32 v96, v96, v97
	v_add_f32_e32 v98, v98, v96
	v_mul_f32_e32 v96, v223, v223
	v_mul_f32_e32 v97, v225, v225
	v_fmac_f32_e32 v96, v222, v222
	v_fmac_f32_e32 v97, v224, v224
	v_add_f32_e32 v96, v96, v97
	v_add_f32_e32 v98, v98, v96
	v_mul_f32_e32 v96, v227, v227
	v_mul_f32_e32 v97, v229, v229
	v_fmac_f32_e32 v96, v226, v226
	v_fmac_f32_e32 v97, v228, v228
	v_add_f32_e32 v96, v96, v97
	v_add_f32_e32 v98, v98, v96
	s_nop 1
	v_add_f32_dpp v98, v98, v98 quad_perm:[1,0,3,2] row_mask:0xf bank_mask:0xf bound_ctrl:1
	s_nop 1
	v_add_f32_dpp v98, v98, v98 quad_perm:[2,3,0,1] row_mask:0xf bank_mask:0xf bound_ctrl:1
	s_nop 1
	v_add_f32_dpp v98, v98, v98 row_half_mirror row_mask:0xf bank_mask:0xf bound_ctrl:1
	s_nop 1
	v_add_f32_dpp v98, v98, v98 row_mirror row_mask:0xf bank_mask:0xf bound_ctrl:1
	v_mov_b32_e32 v96, v98
	s_nop 1
	v_permlane16_swap_b32_e32 v98, v96
	v_add_f32_e32 v98, v98, v96
	v_mov_b32_e32 v96, v98
	s_nop 1
	v_permlane32_swap_b32_e32 v98, v96
	v_add_f32_e32 v98, v98, v96
	v_fmamk_f32 v100, v98, 0x3a800000, v153
	v_rsq_f32_e32 v100, v100
	s_nop 0
	v_pk_mul_f32 v[214:215], v[214:215], v[100:101] op_sel_hi:[1,0]
	v_pk_mul_f32 v[216:217], v[216:217], v[100:101] op_sel_hi:[1,0]
	v_pk_mul_f32 v[218:219], v[218:219], v[100:101] op_sel_hi:[1,0]
	v_pk_mul_f32 v[220:221], v[220:221], v[100:101] op_sel_hi:[1,0]
	v_pk_mul_f32 v[222:223], v[222:223], v[100:101] op_sel_hi:[1,0]
	v_pk_mul_f32 v[224:225], v[224:225], v[100:101] op_sel_hi:[1,0]
	v_pk_mul_f32 v[226:227], v[226:227], v[100:101] op_sel_hi:[1,0]
	v_pk_mul_f32 v[228:229], v[228:229], v[100:101] op_sel_hi:[1,0]
	v_pk_mul_f32 v[214:215], v[0:1], v[214:215]
	v_pk_mul_f32 v[216:217], v[2:3], v[216:217]
	v_pk_mul_f32 v[218:219], v[4:5], v[218:219]
	v_pk_mul_f32 v[220:221], v[6:7], v[220:221]
; __device__ __forceinline__ unsigned pkbf(float lo, float hi) { f32x2_t v = {lo, hi}; bf16x2_t b = __builtin_convertvector(v, bf16x2_t); return __builtin_bit_cast(unsigned, b); }
; __device__ __forceinline__ void norm_phase(const void* src_lat, int lat_f32, const float* src_ctx, int nrows, const float* gvec, const float* mods_l, int sh_off, int sc_off, bf16_t* U, const float* part, int nparts, float* ctx_out) {
;     ...
;         else { const float* src = row < MLAT ? (const float*)src_lat + (size_t)row * DM : src_ctx + (size_t)(row - MLAT) * DM;
; #pragma unroll
;             for (int j = 0; j < 4; ++j) v[j] = *(const f32x4*)(src + 4 * lane + 256 * j); }
; #pragma unroll
;         for (int j = 0; j < 4; ++j) { ss += (v[j][0] * v[j][0] + v[j][1] * v[j][1]) + (v[j][2] * v[j][2] + v[j][3] * v[j][3]); }
;         if (nparts != 0 && row >= MLAT) {
;             for (int ch = 0; ch < nparts; ch += 4) {
;                 f32x4 pv[4][4];
; #pragma unroll
;                 for (int c4 = 0; c4 < 4; ++c4) { const float* pr = part + ((size_t)(ch + c4) * MCTX + (row - MLAT)) * DM + 4 * lane;
; #pragma unroll
;                     for (int j = 0; j < 4; ++j) pv[c4][j] = *(const f32x4*)(pr + 256 * j); }
; #pragma unroll
;                 for (int c4 = 0; c4 < 4; ++c4)
; #pragma unroll
;                     for (int j = 0; j < 4; ++j) v[j] = v[j] + pv[c4][j]; }
;             ss = 0.f;
; #pragma unroll
;             for (int j = 0; j < 4; ++j) { *(f32x4*)(ctx_out + (size_t)(row - MLAT) * DM + 4 * lane + 256 * j) = v[j]; ss += (v[j][0] * v[j][0] + v[j][1] * v[j][1]) + (v[j][2] * v[j][2] + v[j][3] * v[j][3]); }
;         }
;         const float rs = rsqrtf(wave_sum64(ss) * (1.0f / DM) + EPS);
;         const float* shp = mods_l + s * 6144 + sh_off + 4 * lane; const float* scp = mods_l + s * 6144 + sc_off + 4 * lane;
;         bf16_t* up = U + (size_t)row * DM + 4 * lane;
; #pragma unroll
;         for (int j = 0; j < 4; ++j) { const f32x4 sh = *(const f32x4*)(shp + 256 * j), sc = *(const f32x4*)(scp + 256 * j);
;             const f32x4 y = v[j] * rs * gv[j] * (sc + 1.0f) + sh;
;             u32x2 o; o.x = pkbf(y[0], y[1]); o.y = pkbf(y[2], y[3]); *(u32x2*)(up + 256 * j) = o; }
	v_pk_mul_f32 v[222:223], v[8:9], v[222:223]
	v_pk_mul_f32 v[224:225], v[10:11], v[224:225]
	v_pk_mul_f32 v[226:227], v[12:13], v[226:227]
	v_pk_mul_f32 v[228:229], v[14:15], v[228:229]
	v_pk_fma_f32 v[214:215], v[64:65], v[214:215], v[48:49]
	v_pk_fma_f32 v[216:217], v[66:67], v[216:217], v[50:51]
	v_pk_fma_f32 v[218:219], v[68:69], v[218:219], v[52:53]
	v_pk_fma_f32 v[220:221], v[70:71], v[220:221], v[54:55]
	v_pk_fma_f32 v[222:223], v[72:73], v[222:223], v[56:57]
	v_pk_fma_f32 v[224:225], v[74:75], v[224:225], v[58:59]
	v_pk_fma_f32 v[226:227], v[76:77], v[226:227], v[60:61]
	v_pk_fma_f32 v[228:229], v[78:79], v[228:229], v[62:63]
	v_cvt_pk_bf16_f32 v214, v214, v215
	v_cvt_pk_bf16_f32 v215, v216, v217
	v_cvt_pk_bf16_f32 v218, v218, v219
	v_cvt_pk_bf16_f32 v219, v220, v221
	v_cvt_pk_bf16_f32 v222, v222, v223
	v_cvt_pk_bf16_f32 v223, v224, v225
	v_cvt_pk_bf16_f32 v226, v226, v227
	v_cvt_pk_bf16_f32 v227, v228, v229
	global_store_dwordx2 v102, v[214:215], s[40:41]
	global_store_dwordx2 v102, v[218:219], s[40:41] offset:512
	global_store_dwordx2 v102, v[222:223], s[40:41] offset:1024
	global_store_dwordx2 v102, v[226:227], s[40:41] offset:1536
	s_add_u32 s40, s40, 0x400000
	s_addc_u32 s41, s41, 0
	global_load_dwordx4 v[214:217], v103, s[38:39]
	global_load_dwordx4 v[218:221], v103, s[38:39] offset:1024
	global_load_dwordx4 v[222:225], v103, s[38:39] offset:2048
	global_load_dwordx4 v[226:229], v103, s[38:39] offset:3072
	s_add_u32 s38, s38, 0x800000
	s_addc_u32 s39, s39, 0
	s_waitcnt vmcnt(24)
	v_pk_add_f32 v[128:129], v[128:129], 1.0 op_sel_hi:[1,0]
	v_pk_add_f32 v[130:131], v[130:131], 1.0 op_sel_hi:[1,0]
	v_pk_add_f32 v[132:133], v[132:133], 1.0 op_sel_hi:[1,0]
	v_pk_add_f32 v[134:135], v[134:135], 1.0 op_sel_hi:[1,0]
	v_pk_add_f32 v[136:137], v[136:137], 1.0 op_sel_hi:[1,0]
	v_pk_add_f32 v[138:139], v[138:139], 1.0 op_sel_hi:[1,0]
	v_pk_add_f32 v[140:141], v[140:141], 1.0 op_sel_hi:[1,0]
	v_pk_add_f32 v[142:143], v[142:143], 1.0 op_sel_hi:[1,0]
	v_mul_f32_e32 v96, v159, v159
	v_mul_f32_e32 v97, v161, v161
	v_fmac_f32_e32 v96, v158, v158
	v_fmac_f32_e32 v97, v160, v160
	v_add_f32_e32 v98, v96, v97
	v_mul_f32_e32 v96, v163, v163
	v_mul_f32_e32 v97, v165, v165
	v_fmac_f32_e32 v96, v162, v162
	v_fmac_f32_e32 v97, v164, v164
	v_add_f32_e32 v96, v96, v97
	v_add_f32_e32 v98, v98, v96
	v_mul_f32_e32 v96, v167, v167
	v_mul_f32_e32 v97, v169, v169
	v_fmac_f32_e32 v96, v166, v166
	v_fmac_f32_e32 v97, v168, v168
	v_add_f32_e32 v96, v96, v97
	v_add_f32_e32 v98, v98, v96
	v_mul_f32_e32 v96, v171, v171
	v_mul_f32_e32 v97, v173, v173
	v_fmac_f32_e32 v96, v170, v170
	v_fmac_f32_e32 v97, v172, v172
	v_add_f32_e32 v96, v96, v97
	v_add_f32_e32 v98, v98, v96
	s_nop 1
	v_add_f32_dpp v98, v98, v98 quad_perm:[1,0,3,2] row_mask:0xf bank_mask:0xf bound_ctrl:1
	s_nop 1
	v_add_f32_dpp v98, v98, v98 quad_perm:[2,3,0,1] row_mask:0xf bank_mask:0xf bound_ctrl:1
	s_nop 1
	v_add_f32_dpp v98, v98, v98 row_half_mirror row_mask:0xf bank_mask:0xf bound_ctrl:1
	s_nop 1
	v_add_f32_dpp v98, v98, v98 row_mirror row_mask:0xf bank_mask:0xf bound_ctrl:1
	v_mov_b32_e32 v96, v98
	s_nop 1
	v_permlane16_swap_b32_e32 v98, v96
	v_add_f32_e32 v98, v98, v96
	v_mov_b32_e32 v96, v98
	s_nop 1
	v_permlane32_swap_b32_e32 v98, v96
	v_add_f32_e32 v98, v98, v96
	v_fmamk_f32 v100, v98, 0x3a800000, v153
	v_rsq_f32_e32 v100, v100
	s_nop 0
	v_pk_mul_f32 v[158:159], v[158:159], v[100:101] op_sel_hi:[1,0]
	v_pk_mul_f32 v[160:161], v[160:161], v[100:101] op_sel_hi:[1,0]
	v_pk_mul_f32 v[162:163], v[162:163], v[100:101] op_sel_hi:[1,0]
	v_pk_mul_f32 v[164:165], v[164:165], v[100:101] op_sel_hi:[1,0]
	v_pk_mul_f32 v[166:167], v[166:167], v[100:101] op_sel_hi:[1,0]
	v_pk_mul_f32 v[168:169], v[168:169], v[100:101] op_sel_hi:[1,0]
	v_pk_mul_f32 v[170:171], v[170:171], v[100:101] op_sel_hi:[1,0]
	v_pk_mul_f32 v[172:173], v[172:173], v[100:101] op_sel_hi:[1,0]
	v_pk_mul_f32 v[158:159], v[0:1], v[158:159]
	v_pk_mul_f32 v[160:161], v[2:3], v[160:161]
	v_pk_mul_f32 v[162:163], v[4:5], v[162:163]
	v_pk_mul_f32 v[164:165], v[6:7], v[164:165]
	v_pk_mul_f32 v[166:167], v[8:9], v[166:167]
	v_pk_mul_f32 v[168:169], v[10:11], v[168:169]
	v_pk_mul_f32 v[170:171], v[12:13], v[170:171]
	v_pk_mul_f32 v[172:173], v[14:15], v[172:173]
	v_pk_fma_f32 v[158:159], v[128:129], v[158:159], v[112:113]
	v_pk_fma_f32 v[160:161], v[130:131], v[160:161], v[114:115]
	v_pk_fma_f32 v[162:163], v[132:133], v[162:163], v[116:117]
	v_pk_fma_f32 v[164:165], v[134:135], v[164:165], v[118:119]
	v_pk_fma_f32 v[166:167], v[136:137], v[166:167], v[120:121]
	v_pk_fma_f32 v[168:169], v[138:139], v[168:169], v[122:123]
	v_pk_fma_f32 v[170:171], v[140:141], v[170:171], v[124:125]
	v_pk_fma_f32 v[172:173], v[142:143], v[172:173], v[126:127]
	v_cvt_pk_bf16_f32 v158, v158, v159
	v_cvt_pk_bf16_f32 v159, v160, v161
	v_cvt_pk_bf16_f32 v162, v162, v163
	v_cvt_pk_bf16_f32 v163, v164, v165
	v_cvt_pk_bf16_f32 v166, v166, v167
	v_cvt_pk_bf16_f32 v167, v168, v169
	v_cvt_pk_bf16_f32 v170, v170, v171
	v_cvt_pk_bf16_f32 v171, v172, v173
	global_store_dwordx2 v102, v[158:159], s[40:41]
	global_store_dwordx2 v102, v[162:163], s[40:41] offset:512
	global_store_dwordx2 v102, v[166:167], s[40:41] offset:1024
	global_store_dwordx2 v102, v[170:171], s[40:41] offset:1536
	s_add_u32 s40, s40, 0x400000
	s_addc_u32 s41, s41, 0
	global_load_dwordx4 v[158:161], v103, s[38:39]
	global_load_dwordx4 v[162:165], v103, s[38:39] offset:1024
	global_load_dwordx4 v[166:169], v103, s[38:39] offset:2048
	global_load_dwordx4 v[170:173], v103, s[38:39] offset:3072
	s_add_u32 s38, s38, 0x800000
	s_addc_u32 s39, s39, 0
	global_load_dwordx4 v[48:51], v103, s[42:43]
	global_load_dwordx4 v[52:55], v103, s[42:43] offset:1024
	global_load_dwordx4 v[56:59], v103, s[42:43] offset:2048
	global_load_dwordx4 v[60:63], v103, s[42:43] offset:3072
	global_load_dwordx4 v[64:67], v103, s[44:45]
	global_load_dwordx4 v[68:71], v103, s[44:45] offset:1024
	global_load_dwordx4 v[72:75], v103, s[44:45] offset:2048
	global_load_dwordx4 v[76:79], v103, s[44:45] offset:3072
	s_add_u32 s42, s42, 0x6000
	s_addc_u32 s43, s43, 0
	s_add_u32 s44, s44, 0x6000
	s_addc_u32 s45, s45, 0
	s_waitcnt vmcnt(32)
; __device__ __forceinline__ unsigned pkbf(float lo, float hi) { f32x2_t v = {lo, hi}; bf16x2_t b = __builtin_convertvector(v, bf16x2_t); return __builtin_bit_cast(unsigned, b); }
; __device__ __forceinline__ void norm_phase(const void* src_lat, int lat_f32, const float* src_ctx, int nrows, const float* gvec, const float* mods_l, int sh_off, int sc_off, bf16_t* U, const float* part, int nparts, float* ctx_out) {
;     ...
;         else { const float* src = row < MLAT ? (const float*)src_lat + (size_t)row * DM : src_ctx + (size_t)(row - MLAT) * DM;
; #pragma unroll
;             for (int j = 0; j < 4; ++j) v[j] = *(const f32x4*)(src + 4 * lane + 256 * j); }
; #pragma unroll
;         for (int j = 0; j < 4; ++j) { ss += (v[j][0] * v[j][0] + v[j][1] * v[j][1]) + (v[j][2] * v[j][2] + v[j][3] * v[j][3]); }
;         if (nparts != 0 && row >= MLAT) {
;             for (int ch = 0; ch < nparts; ch += 4) {
;                 f32x4 pv[4][4];
; #pragma unroll
;                 for (int c4 = 0; c4 < 4; ++c4) { const float* pr = part + ((size_t)(ch + c4) * MCTX + (row - MLAT)) * DM + 4 * lane;
; #pragma unroll
;                     for (int j = 0; j < 4; ++j) pv[c4][j] = *(const f32x4*)(pr + 256 * j); }
; #pragma unroll
;                 for (int c4 = 0; c4 < 4; ++c4)
; #pragma unroll
;                     for (int j = 0; j < 4; ++j) v[j] = v[j] + pv[c4][j]; }
;             ss = 0.f;
; #pragma unroll
;             for (int j = 0; j < 4; ++j) { *(f32x4*)(ctx_out + (size_t)(row - MLAT) * DM + 4 * lane + 256 * j) = v[j]; ss += (v[j][0] * v[j][0] + v[j][1] * v[j][1]) + (v[j][2] * v[j][2] + v[j][3] * v[j][3]); }
;         }
;         const float rs = rsqrtf(wave_sum64(ss) * (1.0f / DM) + EPS);
;         const float* shp = mods_l + s * 6144 + sh_off + 4 * lane; const float* scp = mods_l + s * 6144 + sc_off + 4 * lane;
;         bf16_t* up = U + (size_t)row * DM + 4 * lane;
; #pragma unroll
;         for (int j = 0; j < 4; ++j) { const f32x4 sh = *(const f32x4*)(shp + 256 * j), sc = *(const f32x4*)(scp + 256 * j);
;             const f32x4 y = v[j] * rs * gv[j] * (sc + 1.0f) + sh;
;             u32x2 o; o.x = pkbf(y[0], y[1]); o.y = pkbf(y[2], y[3]); *(u32x2*)(up + 256 * j) = o; }
	v_mul_f32_e32 v96, v175, v175
	v_mul_f32_e32 v97, v177, v177
	v_fmac_f32_e32 v96, v174, v174
	v_fmac_f32_e32 v97, v176, v176
	v_add_f32_e32 v98, v96, v97
	v_mul_f32_e32 v96, v179, v179
	v_mul_f32_e32 v97, v181, v181
	v_fmac_f32_e32 v96, v178, v178
	v_fmac_f32_e32 v97, v180, v180
	v_add_f32_e32 v96, v96, v97
	v_add_f32_e32 v98, v98, v96
	v_mul_f32_e32 v96, v183, v183
	v_mul_f32_e32 v97, v185, v185
	v_fmac_f32_e32 v96, v182, v182
	v_fmac_f32_e32 v97, v184, v184
	v_add_f32_e32 v96, v96, v97
	v_add_f32_e32 v98, v98, v96
	v_mul_f32_e32 v96, v187, v187
	v_mul_f32_e32 v97, v189, v189
	v_fmac_f32_e32 v96, v186, v186
	v_fmac_f32_e32 v97, v188, v188
	v_add_f32_e32 v96, v96, v97
	v_add_f32_e32 v98, v98, v96
	s_nop 1
	v_add_f32_dpp v98, v98, v98 quad_perm:[1,0,3,2] row_mask:0xf bank_mask:0xf bound_ctrl:1
	s_nop 1
	v_add_f32_dpp v98, v98, v98 quad_perm:[2,3,0,1] row_mask:0xf bank_mask:0xf bound_ctrl:1
	s_nop 1
	v_add_f32_dpp v98, v98, v98 row_half_mirror row_mask:0xf bank_mask:0xf bound_ctrl:1
	s_nop 1
	v_add_f32_dpp v98, v98, v98 row_mirror row_mask:0xf bank_mask:0xf bound_ctrl:1
	v_mov_b32_e32 v96, v98
	s_nop 1
	v_permlane16_swap_b32_e32 v98, v96
	v_add_f32_e32 v98, v98, v96
	v_mov_b32_e32 v96, v98
	s_nop 1
	v_permlane32_swap_b32_e32 v98, v96
	v_add_f32_e32 v98, v98, v96
	v_fmamk_f32 v100, v98, 0x3a800000, v153
	v_rsq_f32_e32 v100, v100
	s_nop 0
	v_pk_mul_f32 v[174:175], v[174:175], v[100:101] op_sel_hi:[1,0]
	v_pk_mul_f32 v[176:177], v[176:177], v[100:101] op_sel_hi:[1,0]
	v_pk_mul_f32 v[178:179], v[178:179], v[100:101] op_sel_hi:[1,0]
	v_pk_mul_f32 v[180:181], v[180:181], v[100:101] op_sel_hi:[1,0]
	v_pk_mul_f32 v[182:183], v[182:183], v[100:101] op_sel_hi:[1,0]
	v_pk_mul_f32 v[184:185], v[184:185], v[100:101] op_sel_hi:[1,0]
	v_pk_mul_f32 v[186:187], v[186:187], v[100:101] op_sel_hi:[1,0]
	v_pk_mul_f32 v[188:189], v[188:189], v[100:101] op_sel_hi:[1,0]
	v_pk_mul_f32 v[174:175], v[0:1], v[174:175]
	v_pk_mul_f32 v[176:177], v[2:3], v[176:177]
	v_pk_mul_f32 v[178:179], v[4:5], v[178:179]
	v_pk_mul_f32 v[180:181], v[6:7], v[180:181]
	v_pk_mul_f32 v[182:183], v[8:9], v[182:183]
	v_pk_mul_f32 v[184:185], v[10:11], v[184:185]
	v_pk_mul_f32 v[186:187], v[12:13], v[186:187]
	v_pk_mul_f32 v[188:189], v[14:15], v[188:189]
	v_pk_fma_f32 v[174:175], v[128:129], v[174:175], v[112:113]
	v_pk_fma_f32 v[176:177], v[130:131], v[176:177], v[114:115]
	v_pk_fma_f32 v[178:179], v[132:133], v[178:179], v[116:117]
	v_pk_fma_f32 v[180:181], v[134:135], v[180:181], v[118:119]
	v_pk_fma_f32 v[182:183], v[136:137], v[182:183], v[120:121]
	v_pk_fma_f32 v[184:185], v[138:139], v[184:185], v[122:123]
	v_pk_fma_f32 v[186:187], v[140:141], v[186:187], v[124:125]
	v_pk_fma_f32 v[188:189], v[142:143], v[188:189], v[126:127]
	v_cvt_pk_bf16_f32 v174, v174, v175
	v_cvt_pk_bf16_f32 v175, v176, v177
	v_cvt_pk_bf16_f32 v178, v178, v179
	v_cvt_pk_bf16_f32 v179, v180, v181
	v_cvt_pk_bf16_f32 v182, v182, v183
	v_cvt_pk_bf16_f32 v183, v184, v185
	v_cvt_pk_bf16_f32 v186, v186, v187
	v_cvt_pk_bf16_f32 v187, v188, v189
	global_store_dwordx2 v102, v[174:175], s[40:41]
	global_store_dwordx2 v102, v[178:179], s[40:41] offset:512
	global_store_dwordx2 v102, v[182:183], s[40:41] offset:1024
	global_store_dwordx2 v102, v[186:187], s[40:41] offset:1536
	s_add_u32 s40, s40, 0x400000
	s_addc_u32 s41, s41, 0
	global_load_dwordx4 v[174:177], v103, s[38:39]
	global_load_dwordx4 v[178:181], v103, s[38:39] offset:1024
	global_load_dwordx4 v[182:185], v103, s[38:39] offset:2048
	global_load_dwordx4 v[186:189], v103, s[38:39] offset:3072
	s_add_u32 s38, s38, 0x800000
	s_addc_u32 s39, s39, 0
	s_waitcnt vmcnt(32)
	v_mul_f32_e32 v96, v199, v199
	v_mul_f32_e32 v97, v201, v201
	v_fmac_f32_e32 v96, v198, v198
	v_fmac_f32_e32 v97, v200, v200
	v_add_f32_e32 v98, v96, v97
	v_mul_f32_e32 v96, v203, v203
	v_mul_f32_e32 v97, v205, v205
	v_fmac_f32_e32 v96, v202, v202
	v_fmac_f32_e32 v97, v204, v204
	v_add_f32_e32 v96, v96, v97
	v_add_f32_e32 v98, v98, v96
	v_mul_f32_e32 v96, v207, v207
	v_mul_f32_e32 v97, v209, v209
	v_fmac_f32_e32 v96, v206, v206
	v_fmac_f32_e32 v97, v208, v208
	v_add_f32_e32 v96, v96, v97
	v_add_f32_e32 v98, v98, v96
	v_mul_f32_e32 v96, v211, v211
	v_mul_f32_e32 v97, v213, v213
	v_fmac_f32_e32 v96, v210, v210
	v_fmac_f32_e32 v97, v212, v212
	v_add_f32_e32 v96, v96, v97
	v_add_f32_e32 v98, v98, v96
	s_nop 1
	v_add_f32_dpp v98, v98, v98 quad_perm:[1,0,3,2] row_mask:0xf bank_mask:0xf bound_ctrl:1
	s_nop 1
	v_add_f32_dpp v98, v98, v98 quad_perm:[2,3,0,1] row_mask:0xf bank_mask:0xf bound_ctrl:1
	s_nop 1
	v_add_f32_dpp v98, v98, v98 row_half_mirror row_mask:0xf bank_mask:0xf bound_ctrl:1
	s_nop 1
	v_add_f32_dpp v98, v98, v98 row_mirror row_mask:0xf bank_mask:0xf bound_ctrl:1
	v_mov_b32_e32 v96, v98
	s_nop 1
	v_permlane16_swap_b32_e32 v98, v96
	v_add_f32_e32 v98, v98, v96
	v_mov_b32_e32 v96, v98
	s_nop 1
	v_permlane32_swap_b32_e32 v98, v96
	v_add_f32_e32 v98, v98, v96
	v_fmamk_f32 v100, v98, 0x3a800000, v153
	v_rsq_f32_e32 v100, v100
	s_nop 0
	v_pk_mul_f32 v[198:199], v[198:199], v[100:101] op_sel_hi:[1,0]
	v_pk_mul_f32 v[200:201], v[200:201], v[100:101] op_sel_hi:[1,0]
	v_pk_mul_f32 v[202:203], v[202:203], v[100:101] op_sel_hi:[1,0]
	v_pk_mul_f32 v[204:205], v[204:205], v[100:101] op_sel_hi:[1,0]
	v_pk_mul_f32 v[206:207], v[206:207], v[100:101] op_sel_hi:[1,0]
	v_pk_mul_f32 v[208:209], v[208:209], v[100:101] op_sel_hi:[1,0]
	v_pk_mul_f32 v[210:211], v[210:211], v[100:101] op_sel_hi:[1,0]
	v_pk_mul_f32 v[212:213], v[212:213], v[100:101] op_sel_hi:[1,0]
	v_pk_mul_f32 v[198:199], v[0:1], v[198:199]
	v_pk_mul_f32 v[200:201], v[2:3], v[200:201]
	v_pk_mul_f32 v[202:203], v[4:5], v[202:203]
; __device__ __forceinline__ unsigned pkbf(float lo, float hi) { f32x2_t v = {lo, hi}; bf16x2_t b = __builtin_convertvector(v, bf16x2_t); return __builtin_bit_cast(unsigned, b); }
; __device__ __forceinline__ void norm_phase(const void* src_lat, int lat_f32, const float* src_ctx, int nrows, const float* gvec, const float* mods_l, int sh_off, int sc_off, bf16_t* U, const float* part, int nparts, float* ctx_out) {
;     ...
;         else { const float* src = row < MLAT ? (const float*)src_lat + (size_t)row * DM : src_ctx + (size_t)(row - MLAT) * DM;
; #pragma unroll
;             for (int j = 0; j < 4; ++j) v[j] = *(const f32x4*)(src + 4 * lane + 256 * j); }
; #pragma unroll
;         for (int j = 0; j < 4; ++j) { ss += (v[j][0] * v[j][0] + v[j][1] * v[j][1]) + (v[j][2] * v[j][2] + v[j][3] * v[j][3]); }
;         if (nparts != 0 && row >= MLAT) {
;             for (int ch = 0; ch < nparts; ch += 4) {
;                 f32x4 pv[4][4];
; #pragma unroll
;                 for (int c4 = 0; c4 < 4; ++c4) { const float* pr = part + ((size_t)(ch + c4) * MCTX + (row - MLAT)) * DM + 4 * lane;
; #pragma unroll
;                     for (int j = 0; j < 4; ++j) pv[c4][j] = *(const f32x4*)(pr + 256 * j); }
; #pragma unroll
;                 for (int c4 = 0; c4 < 4; ++c4)
; #pragma unroll
;                     for (int j = 0; j < 4; ++j) v[j] = v[j] + pv[c4][j]; }
;             ss = 0.f;
; #pragma unroll
;             for (int j = 0; j < 4; ++j) { *(f32x4*)(ctx_out + (size_t)(row - MLAT) * DM + 4 * lane + 256 * j) = v[j]; ss += (v[j][0] * v[j][0] + v[j][1] * v[j][1]) + (v[j][2] * v[j][2] + v[j][3] * v[j][3]); }
;         }
;         const float rs = rsqrtf(wave_sum64(ss) * (1.0f / DM) + EPS);
;         const float* shp = mods_l + s * 6144 + sh_off + 4 * lane; const float* scp = mods_l + s * 6144 + sc_off + 4 * lane;
;         bf16_t* up = U + (size_t)row * DM + 4 * lane;
; #pragma unroll
;         for (int j = 0; j < 4; ++j) { const f32x4 sh = *(const f32x4*)(shp + 256 * j), sc = *(const f32x4*)(scp + 256 * j);
;             const f32x4 y = v[j] * rs * gv[j] * (sc + 1.0f) + sh;
;             u32x2 o; o.x = pkbf(y[0], y[1]); o.y = pkbf(y[2], y[3]); *(u32x2*)(up + 256 * j) = o; }
	v_pk_mul_f32 v[204:205], v[6:7], v[204:205]
	v_pk_mul_f32 v[206:207], v[8:9], v[206:207]
	v_pk_mul_f32 v[208:209], v[10:11], v[208:209]
	v_pk_mul_f32 v[210:211], v[12:13], v[210:211]
	v_pk_mul_f32 v[212:213], v[14:15], v[212:213]
	v_pk_fma_f32 v[198:199], v[128:129], v[198:199], v[112:113]
	v_pk_fma_f32 v[200:201], v[130:131], v[200:201], v[114:115]
	v_pk_fma_f32 v[202:203], v[132:133], v[202:203], v[116:117]
	v_pk_fma_f32 v[204:205], v[134:135], v[204:205], v[118:119]
	v_pk_fma_f32 v[206:207], v[136:137], v[206:207], v[120:121]
	v_pk_fma_f32 v[208:209], v[138:139], v[208:209], v[122:123]
	v_pk_fma_f32 v[210:211], v[140:141], v[210:211], v[124:125]
	v_pk_fma_f32 v[212:213], v[142:143], v[212:213], v[126:127]
	v_cvt_pk_bf16_f32 v198, v198, v199
	v_cvt_pk_bf16_f32 v199, v200, v201
	v_cvt_pk_bf16_f32 v202, v202, v203
	v_cvt_pk_bf16_f32 v203, v204, v205
	v_cvt_pk_bf16_f32 v206, v206, v207
	v_cvt_pk_bf16_f32 v207, v208, v209
	v_cvt_pk_bf16_f32 v210, v210, v211
	v_cvt_pk_bf16_f32 v211, v212, v213
	global_store_dwordx2 v102, v[198:199], s[40:41]
	global_store_dwordx2 v102, v[202:203], s[40:41] offset:512
	global_store_dwordx2 v102, v[206:207], s[40:41] offset:1024
	global_store_dwordx2 v102, v[210:211], s[40:41] offset:1536
	s_add_u32 s40, s40, 0x400000
	s_addc_u32 s41, s41, 0
	global_load_dwordx4 v[198:201], v103, s[38:39]
	global_load_dwordx4 v[202:205], v103, s[38:39] offset:1024
	global_load_dwordx4 v[206:209], v103, s[38:39] offset:2048
	global_load_dwordx4 v[210:213], v103, s[38:39] offset:3072
	s_add_u32 s38, s38, 0x800000
	s_addc_u32 s39, s39, 0
	s_waitcnt vmcnt(32)
	v_mul_f32_e32 v96, v215, v215
	v_mul_f32_e32 v97, v217, v217
	v_fmac_f32_e32 v96, v214, v214
	v_fmac_f32_e32 v97, v216, v216
	v_add_f32_e32 v98, v96, v97
	v_mul_f32_e32 v96, v219, v219
	v_mul_f32_e32 v97, v221, v221
	v_fmac_f32_e32 v96, v218, v218
	v_fmac_f32_e32 v97, v220, v220
	v_add_f32_e32 v96, v96, v97
	v_add_f32_e32 v98, v98, v96
	v_mul_f32_e32 v96, v223, v223
	v_mul_f32_e32 v97, v225, v225
	v_fmac_f32_e32 v96, v222, v222
	v_fmac_f32_e32 v97, v224, v224
	v_add_f32_e32 v96, v96, v97
	v_add_f32_e32 v98, v98, v96
	v_mul_f32_e32 v96, v227, v227
	v_mul_f32_e32 v97, v229, v229
	v_fmac_f32_e32 v96, v226, v226
	v_fmac_f32_e32 v97, v228, v228
	v_add_f32_e32 v96, v96, v97
	v_add_f32_e32 v98, v98, v96
	s_nop 1
	v_add_f32_dpp v98, v98, v98 quad_perm:[1,0,3,2] row_mask:0xf bank_mask:0xf bound_ctrl:1
	s_nop 1
	v_add_f32_dpp v98, v98, v98 quad_perm:[2,3,0,1] row_mask:0xf bank_mask:0xf bound_ctrl:1
	s_nop 1
	v_add_f32_dpp v98, v98, v98 row_half_mirror row_mask:0xf bank_mask:0xf bound_ctrl:1
	s_nop 1
	v_add_f32_dpp v98, v98, v98 row_mirror row_mask:0xf bank_mask:0xf bound_ctrl:1
	v_mov_b32_e32 v96, v98
	s_nop 1
	v_permlane16_swap_b32_e32 v98, v96
	v_add_f32_e32 v98, v98, v96
	v_mov_b32_e32 v96, v98
	s_nop 1
	v_permlane32_swap_b32_e32 v98, v96
	v_add_f32_e32 v98, v98, v96
	v_fmamk_f32 v100, v98, 0x3a800000, v153
	v_rsq_f32_e32 v100, v100
	s_nop 0
	v_pk_mul_f32 v[214:215], v[214:215], v[100:101] op_sel_hi:[1,0]
	v_pk_mul_f32 v[216:217], v[216:217], v[100:101] op_sel_hi:[1,0]
	v_pk_mul_f32 v[218:219], v[218:219], v[100:101] op_sel_hi:[1,0]
	v_pk_mul_f32 v[220:221], v[220:221], v[100:101] op_sel_hi:[1,0]
	v_pk_mul_f32 v[222:223], v[222:223], v[100:101] op_sel_hi:[1,0]
	v_pk_mul_f32 v[224:225], v[224:225], v[100:101] op_sel_hi:[1,0]
	v_pk_mul_f32 v[226:227], v[226:227], v[100:101] op_sel_hi:[1,0]
	v_pk_mul_f32 v[228:229], v[228:229], v[100:101] op_sel_hi:[1,0]
	v_pk_mul_f32 v[214:215], v[0:1], v[214:215]
	v_pk_mul_f32 v[216:217], v[2:3], v[216:217]
	v_pk_mul_f32 v[218:219], v[4:5], v[218:219]
	v_pk_mul_f32 v[220:221], v[6:7], v[220:221]
	v_pk_mul_f32 v[222:223], v[8:9], v[222:223]
	v_pk_mul_f32 v[224:225], v[10:11], v[224:225]
	v_pk_mul_f32 v[226:227], v[12:13], v[226:227]
	v_pk_mul_f32 v[228:229], v[14:15], v[228:229]
	v_pk_fma_f32 v[214:215], v[128:129], v[214:215], v[112:113]
	v_pk_fma_f32 v[216:217], v[130:131], v[216:217], v[114:115]
	v_pk_fma_f32 v[218:219], v[132:133], v[218:219], v[116:117]
	v_pk_fma_f32 v[220:221], v[134:135], v[220:221], v[118:119]
	v_pk_fma_f32 v[222:223], v[136:137], v[222:223], v[120:121]
	v_pk_fma_f32 v[224:225], v[138:139], v[224:225], v[122:123]
	v_pk_fma_f32 v[226:227], v[140:141], v[226:227], v[124:125]
	v_pk_fma_f32 v[228:229], v[142:143], v[228:229], v[126:127]
	v_cvt_pk_bf16_f32 v214, v214, v215
	v_cvt_pk_bf16_f32 v215, v216, v217
	v_cvt_pk_bf16_f32 v218, v218, v219
	v_cvt_pk_bf16_f32 v219, v220, v221
	v_cvt_pk_bf16_f32 v222, v222, v223
	v_cvt_pk_bf16_f32 v223, v224, v225
	v_cvt_pk_bf16_f32 v226, v226, v227
	v_cvt_pk_bf16_f32 v227, v228, v229
	global_store_dwordx2 v102, v[214:215], s[40:41]
	global_store_dwordx2 v102, v[218:219], s[40:41] offset:512
	global_store_dwordx2 v102, v[222:223], s[40:41] offset:1024
	global_store_dwordx2 v102, v[226:227], s[40:41] offset:1536
	s_add_u32 s40, s40, 0x400000
	s_addc_u32 s41, s41, 0
	global_load_dwordx4 v[214:217], v103, s[38:39]
	global_load_dwordx4 v[218:221], v103, s[38:39] offset:1024
	global_load_dwordx4 v[222:225], v103, s[38:39] offset:2048
	global_load_dwordx4 v[226:229], v103, s[38:39] offset:3072
	s_add_u32 s38, s38, 0x800000
	s_addc_u32 s39, s39, 0
	s_waitcnt vmcnt(24)
; __device__ __forceinline__ unsigned pkbf(float lo, float hi) { f32x2_t v = {lo, hi}; bf16x2_t b = __builtin_convertvector(v, bf16x2_t); return __builtin_bit_cast(unsigned, b); }
; __device__ __forceinline__ void norm_phase(const void* src_lat, int lat_f32, const float* src_ctx, int nrows, const float* gvec, const float* mods_l, int sh_off, int sc_off, bf16_t* U, const float* part, int nparts, float* ctx_out) {
;     ...
;         else { const float* src = row < MLAT ? (const float*)src_lat + (size_t)row * DM : src_ctx + (size_t)(row - MLAT) * DM;
; #pragma unroll
;             for (int j = 0; j < 4; ++j) v[j] = *(const f32x4*)(src + 4 * lane + 256 * j); }
; #pragma unroll
;         for (int j = 0; j < 4; ++j) { ss += (v[j][0] * v[j][0] + v[j][1] * v[j][1]) + (v[j][2] * v[j][2] + v[j][3] * v[j][3]); }
;         if (nparts != 0 && row >= MLAT) {
;             for (int ch = 0; ch < nparts; ch += 4) {
;                 f32x4 pv[4][4];
; #pragma unroll
;                 for (int c4 = 0; c4 < 4; ++c4) { const float* pr = part + ((size_t)(ch + c4) * MCTX + (row - MLAT)) * DM + 4 * lane;
; #pragma unroll
;                     for (int j = 0; j < 4; ++j) pv[c4][j] = *(const f32x4*)(pr + 256 * j); }
; #pragma unroll
;                 for (int c4 = 0; c4 < 4; ++c4)
; #pragma unroll
;                     for (int j = 0; j < 4; ++j) v[j] = v[j] + pv[c4][j]; }
;             ss = 0.f;
; #pragma unroll
;             for (int j = 0; j < 4; ++j) { *(f32x4*)(ctx_out + (size_t)(row - MLAT) * DM + 4 * lane + 256 * j) = v[j]; ss += (v[j][0] * v[j][0] + v[j][1] * v[j][1]) + (v[j][2] * v[j][2] + v[j][3] * v[j][3]); }
;         }
;         const float rs = rsqrtf(wave_sum64(ss) * (1.0f / DM) + EPS);
;         const float* shp = mods_l + s * 6144 + sh_off + 4 * lane; const float* scp = mods_l + s * 6144 + sc_off + 4 * lane;
;         bf16_t* up = U + (size_t)row * DM + 4 * lane;
; #pragma unroll
;         for (int j = 0; j < 4; ++j) { const f32x4 sh = *(const f32x4*)(shp + 256 * j), sc = *(const f32x4*)(scp + 256 * j);
;             const f32x4 y = v[j] * rs * gv[j] * (sc + 1.0f) + sh;
;             u32x2 o; o.x = pkbf(y[0], y[1]); o.y = pkbf(y[2], y[3]); *(u32x2*)(up + 256 * j) = o; }
	v_pk_add_f32 v[64:65], v[64:65], 1.0 op_sel_hi:[1,0]
	v_pk_add_f32 v[66:67], v[66:67], 1.0 op_sel_hi:[1,0]
	v_pk_add_f32 v[68:69], v[68:69], 1.0 op_sel_hi:[1,0]
	v_pk_add_f32 v[70:71], v[70:71], 1.0 op_sel_hi:[1,0]
	v_pk_add_f32 v[72:73], v[72:73], 1.0 op_sel_hi:[1,0]
	v_pk_add_f32 v[74:75], v[74:75], 1.0 op_sel_hi:[1,0]
	v_pk_add_f32 v[76:77], v[76:77], 1.0 op_sel_hi:[1,0]
	v_pk_add_f32 v[78:79], v[78:79], 1.0 op_sel_hi:[1,0]
	v_mul_f32_e32 v96, v159, v159
	v_mul_f32_e32 v97, v161, v161
	v_fmac_f32_e32 v96, v158, v158
	v_fmac_f32_e32 v97, v160, v160
	v_add_f32_e32 v98, v96, v97
	v_mul_f32_e32 v96, v163, v163
	v_mul_f32_e32 v97, v165, v165
	v_fmac_f32_e32 v96, v162, v162
	v_fmac_f32_e32 v97, v164, v164
	v_add_f32_e32 v96, v96, v97
	v_add_f32_e32 v98, v98, v96
	v_mul_f32_e32 v96, v167, v167
	v_mul_f32_e32 v97, v169, v169
	v_fmac_f32_e32 v96, v166, v166
	v_fmac_f32_e32 v97, v168, v168
	v_add_f32_e32 v96, v96, v97
	v_add_f32_e32 v98, v98, v96
	v_mul_f32_e32 v96, v171, v171
	v_mul_f32_e32 v97, v173, v173
	v_fmac_f32_e32 v96, v170, v170
	v_fmac_f32_e32 v97, v172, v172
	v_add_f32_e32 v96, v96, v97
	v_add_f32_e32 v98, v98, v96
	s_nop 1
	v_add_f32_dpp v98, v98, v98 quad_perm:[1,0,3,2] row_mask:0xf bank_mask:0xf bound_ctrl:1
	s_nop 1
	v_add_f32_dpp v98, v98, v98 quad_perm:[2,3,0,1] row_mask:0xf bank_mask:0xf bound_ctrl:1
	s_nop 1
	v_add_f32_dpp v98, v98, v98 row_half_mirror row_mask:0xf bank_mask:0xf bound_ctrl:1
	s_nop 1
	v_add_f32_dpp v98, v98, v98 row_mirror row_mask:0xf bank_mask:0xf bound_ctrl:1
	v_mov_b32_e32 v96, v98
	s_nop 1
	v_permlane16_swap_b32_e32 v98, v96
	v_add_f32_e32 v98, v98, v96
	v_mov_b32_e32 v96, v98
	s_nop 1
	v_permlane32_swap_b32_e32 v98, v96
	v_add_f32_e32 v98, v98, v96
	v_fmamk_f32 v100, v98, 0x3a800000, v153
	v_rsq_f32_e32 v100, v100
	s_nop 0
	v_pk_mul_f32 v[158:159], v[158:159], v[100:101] op_sel_hi:[1,0]
	v_pk_mul_f32 v[160:161], v[160:161], v[100:101] op_sel_hi:[1,0]
	v_pk_mul_f32 v[162:163], v[162:163], v[100:101] op_sel_hi:[1,0]
	v_pk_mul_f32 v[164:165], v[164:165], v[100:101] op_sel_hi:[1,0]
	v_pk_mul_f32 v[166:167], v[166:167], v[100:101] op_sel_hi:[1,0]
	v_pk_mul_f32 v[168:169], v[168:169], v[100:101] op_sel_hi:[1,0]
	v_pk_mul_f32 v[170:171], v[170:171], v[100:101] op_sel_hi:[1,0]
	v_pk_mul_f32 v[172:173], v[172:173], v[100:101] op_sel_hi:[1,0]
	v_pk_mul_f32 v[158:159], v[0:1], v[158:159]
	v_pk_mul_f32 v[160:161], v[2:3], v[160:161]
	v_pk_mul_f32 v[162:163], v[4:5], v[162:163]
	v_pk_mul_f32 v[164:165], v[6:7], v[164:165]
	v_pk_mul_f32 v[166:167], v[8:9], v[166:167]
	v_pk_mul_f32 v[168:169], v[10:11], v[168:169]
	v_pk_mul_f32 v[170:171], v[12:13], v[170:171]
	v_pk_mul_f32 v[172:173], v[14:15], v[172:173]
	v_pk_fma_f32 v[158:159], v[64:65], v[158:159], v[48:49]
	v_pk_fma_f32 v[160:161], v[66:67], v[160:161], v[50:51]
	v_pk_fma_f32 v[162:163], v[68:69], v[162:163], v[52:53]
	v_pk_fma_f32 v[164:165], v[70:71], v[164:165], v[54:55]
	v_pk_fma_f32 v[166:167], v[72:73], v[166:167], v[56:57]
	v_pk_fma_f32 v[168:169], v[74:75], v[168:169], v[58:59]
	v_pk_fma_f32 v[170:171], v[76:77], v[170:171], v[60:61]
	v_pk_fma_f32 v[172:173], v[78:79], v[172:173], v[62:63]
	v_cvt_pk_bf16_f32 v158, v158, v159
	v_cvt_pk_bf16_f32 v159, v160, v161
	v_cvt_pk_bf16_f32 v162, v162, v163
	v_cvt_pk_bf16_f32 v163, v164, v165
	v_cvt_pk_bf16_f32 v166, v166, v167
	v_cvt_pk_bf16_f32 v167, v168, v169
	v_cvt_pk_bf16_f32 v170, v170, v171
	v_cvt_pk_bf16_f32 v171, v172, v173
	global_store_dwordx2 v102, v[158:159], s[40:41]
	global_store_dwordx2 v102, v[162:163], s[40:41] offset:512
	global_store_dwordx2 v102, v[166:167], s[40:41] offset:1024
	global_store_dwordx2 v102, v[170:171], s[40:41] offset:1536
	s_add_u32 s40, s40, 0x400000
	s_addc_u32 s41, s41, 0
	s_waitcnt vmcnt(20)
	v_mul_f32_e32 v96, v175, v175
	v_mul_f32_e32 v97, v177, v177
	v_fmac_f32_e32 v96, v174, v174
	v_fmac_f32_e32 v97, v176, v176
	v_add_f32_e32 v98, v96, v97
	v_mul_f32_e32 v96, v179, v179
	v_mul_f32_e32 v97, v181, v181
	v_fmac_f32_e32 v96, v178, v178
	v_fmac_f32_e32 v97, v180, v180
	v_add_f32_e32 v96, v96, v97
	v_add_f32_e32 v98, v98, v96
	v_mul_f32_e32 v96, v183, v183
	v_mul_f32_e32 v97, v185, v185
	v_fmac_f32_e32 v96, v182, v182
	v_fmac_f32_e32 v97, v184, v184
	v_add_f32_e32 v96, v96, v97
	v_add_f32_e32 v98, v98, v96
	v_mul_f32_e32 v96, v187, v187
	v_mul_f32_e32 v97, v189, v189
	v_fmac_f32_e32 v96, v186, v186
	v_fmac_f32_e32 v97, v188, v188
	v_add_f32_e32 v96, v96, v97
	v_add_f32_e32 v98, v98, v96
	s_nop 1
	v_add_f32_dpp v98, v98, v98 quad_perm:[1,0,3,2] row_mask:0xf bank_mask:0xf bound_ctrl:1
	s_nop 1
	v_add_f32_dpp v98, v98, v98 quad_perm:[2,3,0,1] row_mask:0xf bank_mask:0xf bound_ctrl:1
	s_nop 1
	v_add_f32_dpp v98, v98, v98 row_half_mirror row_mask:0xf bank_mask:0xf bound_ctrl:1
	s_nop 1
	v_add_f32_dpp v98, v98, v98 row_mirror row_mask:0xf bank_mask:0xf bound_ctrl:1
	v_mov_b32_e32 v96, v98
	s_nop 1
	v_permlane16_swap_b32_e32 v98, v96
	v_add_f32_e32 v98, v98, v96
	v_mov_b32_e32 v96, v98
	s_nop 1
	v_permlane32_swap_b32_e32 v98, v96
	v_add_f32_e32 v98, v98, v96
	v_fmamk_f32 v100, v98, 0x3a800000, v153
	v_rsq_f32_e32 v100, v100
	s_nop 0
	v_pk_mul_f32 v[174:175], v[174:175], v[100:101] op_sel_hi:[1,0]
	v_pk_mul_f32 v[176:177], v[176:177], v[100:101] op_sel_hi:[1,0]
	v_pk_mul_f32 v[178:179], v[178:179], v[100:101] op_sel_hi:[1,0]
	v_pk_mul_f32 v[180:181], v[180:181], v[100:101] op_sel_hi:[1,0]
	v_pk_mul_f32 v[182:183], v[182:183], v[100:101] op_sel_hi:[1,0]
	v_pk_mul_f32 v[184:185], v[184:185], v[100:101] op_sel_hi:[1,0]
	v_pk_mul_f32 v[186:187], v[186:187], v[100:101] op_sel_hi:[1,0]
	v_pk_mul_f32 v[188:189], v[188:189], v[100:101] op_sel_hi:[1,0]
	v_pk_mul_f32 v[174:175], v[0:1], v[174:175]
	v_pk_mul_f32 v[176:177], v[2:3], v[176:177]
	v_pk_mul_f32 v[178:179], v[4:5], v[178:179]
	v_pk_mul_f32 v[180:181], v[6:7], v[180:181]
	v_pk_mul_f32 v[182:183], v[8:9], v[182:183]
	v_pk_mul_f32 v[184:185], v[10:11], v[184:185]
	v_pk_mul_f32 v[186:187], v[12:13], v[186:187]
	v_pk_mul_f32 v[188:189], v[14:15], v[188:189]
	v_pk_fma_f32 v[174:175], v[64:65], v[174:175], v[48:49]
	v_pk_fma_f32 v[176:177], v[66:67], v[176:177], v[50:51]
	v_pk_fma_f32 v[178:179], v[68:69], v[178:179], v[52:53]
	v_pk_fma_f32 v[180:181], v[70:71], v[180:181], v[54:55]
	v_pk_fma_f32 v[182:183], v[72:73], v[182:183], v[56:57]
	v_pk_fma_f32 v[184:185], v[74:75], v[184:185], v[58:59]
	v_pk_fma_f32 v[186:187], v[76:77], v[186:187], v[60:61]
	v_pk_fma_f32 v[188:189], v[78:79], v[188:189], v[62:63]
	v_cvt_pk_bf16_f32 v174, v174, v175
	v_cvt_pk_bf16_f32 v175, v176, v177
	v_cvt_pk_bf16_f32 v178, v178, v179
	v_cvt_pk_bf16_f32 v179, v180, v181
	v_cvt_pk_bf16_f32 v182, v182, v183
	v_cvt_pk_bf16_f32 v183, v184, v185
	v_cvt_pk_bf16_f32 v186, v186, v187
	v_cvt_pk_bf16_f32 v187, v188, v189
	global_store_dwordx2 v102, v[174:175], s[40:41]
	global_store_dwordx2 v102, v[178:179], s[40:41] offset:512
	global_store_dwordx2 v102, v[182:183], s[40:41] offset:1024
	global_store_dwordx2 v102, v[186:187], s[40:41] offset:1536
	s_add_u32 s40, s40, 0x400000
	s_addc_u32 s41, s41, 0
	s_waitcnt vmcnt(16)
; __device__ __forceinline__ void norm_phase(const void* src_lat, int lat_f32, const float* src_ctx, int nrows, const float* gvec, const float* mods_l, int sh_off, int sc_off, bf16_t* U, const float* part, int nparts, float* ctx_out) {
;     ...
;     for (int row = gw; row < nrows; row += ngw) {
;         const int s = row < MLAT ? (row >> 13) : 4;
;         f32x4 v[4]; float ss = 0.f;
;         if (row < MLAT && !lat_f32) { const bf16_t* src = (const bf16_t*)src_lat + (size_t)row * DM + 4 * lane;
; #pragma unroll
;             for (int j = 0; j < 4; ++j) { const u32x2 w = *(const u32x2*)(src + 256 * j);
;                 v[j] = (f32x4){__uint_as_float(w.x << 16), __uint_as_float(w.x & 0xffff0000u), __uint_as_float(w.y << 16), __uint_as_float(w.y & 0xffff0000u)}; } }
;         else { const float* src = row < MLAT ? (const float*)src_lat + (size_t)row * DM : src_ctx + (size_t)(row - MLAT) * DM;
; #pragma unroll
;             for (int j = 0; j < 4; ++j) v[j] = *(const f32x4*)(src + 4 * lane + 256 * j); }
; #pragma unroll
;         for (int j = 0; j < 4; ++j) { ss += (v[j][0] * v[j][0] + v[j][1] * v[j][1]) + (v[j][2] * v[j][2] + v[j][3] * v[j][3]); }
;         if (nparts != 0 && row >= MLAT) {
;             for (int ch = 0; ch < nparts; ch += 4) {
;                 f32x4 pv[4][4];
; #pragma unroll
;                 for (int c4 = 0; c4 < 4; ++c4) { const float* pr = part + ((size_t)(ch + c4) * MCTX + (row - MLAT)) * DM + 4 * lane;
; #pragma unroll
;                     for (int j = 0; j < 4; ++j) pv[c4][j] = *(const f32x4*)(pr + 256 * j); }
; #pragma unroll
;                 for (int c4 = 0; c4 < 4; ++c4)
; #pragma unroll
;                     for (int j = 0; j < 4; ++j) v[j] = v[j] + pv[c4][j]; }
;             ss = 0.f;
; #pragma unroll
;             for (int j = 0; j < 4; ++j) { *(f32x4*)(ctx_out + (size_t)(row - MLAT) * DM + 4 * lane + 256 * j) = v[j]; ss += (v[j][0] * v[j][0] + v[j][1] * v[j][1]) + (v[j][2] * v[j][2] + v[j][3] * v[j][3]); }
;         }
;         const float rs = rsqrtf(wave_sum64(ss) * (1.0f / DM) + EPS);
;         const float* shp = mods_l + s * 6144 + sh_off + 4 * lane; const float* scp = mods_l + s * 6144 + sc_off + 4 * lane;
;         bf16_t* up = U + (size_t)row * DM + 4 * lane;
; #pragma unroll
;         for (int j = 0; j < 4; ++j) { const f32x4 sh = *(const f32x4*)(shp + 256 * j), sc = *(const f32x4*)(scp + 256 * j);
	v_mul_f32_e32 v96, v199, v199
	v_mul_f32_e32 v97, v201, v201
	v_fmac_f32_e32 v96, v198, v198
	v_fmac_f32_e32 v97, v200, v200
	v_add_f32_e32 v98, v96, v97
	v_mul_f32_e32 v96, v203, v203
	v_mul_f32_e32 v97, v205, v205
	v_fmac_f32_e32 v96, v202, v202
	v_fmac_f32_e32 v97, v204, v204
	v_add_f32_e32 v96, v96, v97
	v_add_f32_e32 v98, v98, v96
	v_mul_f32_e32 v96, v207, v207
	v_mul_f32_e32 v97, v209, v209
	v_fmac_f32_e32 v96, v206, v206
	v_fmac_f32_e32 v97, v208, v208
	v_add_f32_e32 v96, v96, v97
	v_add_f32_e32 v98, v98, v96
	v_mul_f32_e32 v96, v211, v211
	v_mul_f32_e32 v97, v213, v213
	v_fmac_f32_e32 v96, v210, v210
	v_fmac_f32_e32 v97, v212, v212
	v_add_f32_e32 v96, v96, v97
	v_add_f32_e32 v98, v98, v96
	s_nop 1
	v_add_f32_dpp v98, v98, v98 quad_perm:[1,0,3,2] row_mask:0xf bank_mask:0xf bound_ctrl:1
	s_nop 1
	v_add_f32_dpp v98, v98, v98 quad_perm:[2,3,0,1] row_mask:0xf bank_mask:0xf bound_ctrl:1
	s_nop 1
	v_add_f32_dpp v98, v98, v98 row_half_mirror row_mask:0xf bank_mask:0xf bound_ctrl:1
	s_nop 1
	v_add_f32_dpp v98, v98, v98 row_mirror row_mask:0xf bank_mask:0xf bound_ctrl:1
	v_mov_b32_e32 v96, v98
	s_nop 1
	v_permlane16_swap_b32_e32 v98, v96
	v_add_f32_e32 v98, v98, v96
	v_mov_b32_e32 v96, v98
	s_nop 1
	v_permlane32_swap_b32_e32 v98, v96
	v_add_f32_e32 v98, v98, v96
	v_fmamk_f32 v100, v98, 0x3a800000, v153
	v_rsq_f32_e32 v100, v100
	s_nop 0
	v_pk_mul_f32 v[198:199], v[198:199], v[100:101] op_sel_hi:[1,0]
	v_pk_mul_f32 v[200:201], v[200:201], v[100:101] op_sel_hi:[1,0]
	v_pk_mul_f32 v[202:203], v[202:203], v[100:101] op_sel_hi:[1,0]
	v_pk_mul_f32 v[204:205], v[204:205], v[100:101] op_sel_hi:[1,0]
	v_pk_mul_f32 v[206:207], v[206:207], v[100:101] op_sel_hi:[1,0]
	v_pk_mul_f32 v[208:209], v[208:209], v[100:101] op_sel_hi:[1,0]
	v_pk_mul_f32 v[210:211], v[210:211], v[100:101] op_sel_hi:[1,0]
	v_pk_mul_f32 v[212:213], v[212:213], v[100:101] op_sel_hi:[1,0]
	v_pk_mul_f32 v[198:199], v[0:1], v[198:199]
	v_pk_mul_f32 v[200:201], v[2:3], v[200:201]
	v_pk_mul_f32 v[202:203], v[4:5], v[202:203]
	v_pk_mul_f32 v[204:205], v[6:7], v[204:205]
	v_pk_mul_f32 v[206:207], v[8:9], v[206:207]
	v_pk_mul_f32 v[208:209], v[10:11], v[208:209]
	v_pk_mul_f32 v[210:211], v[12:13], v[210:211]
	v_pk_mul_f32 v[212:213], v[14:15], v[212:213]
	v_pk_fma_f32 v[198:199], v[64:65], v[198:199], v[48:49]
	v_pk_fma_f32 v[200:201], v[66:67], v[200:201], v[50:51]
	v_pk_fma_f32 v[202:203], v[68:69], v[202:203], v[52:53]
	v_pk_fma_f32 v[204:205], v[70:71], v[204:205], v[54:55]
	v_pk_fma_f32 v[206:207], v[72:73], v[206:207], v[56:57]
	v_pk_fma_f32 v[208:209], v[74:75], v[208:209], v[58:59]
	v_pk_fma_f32 v[210:211], v[76:77], v[210:211], v[60:61]
	v_pk_fma_f32 v[212:213], v[78:79], v[212:213], v[62:63]
	v_cvt_pk_bf16_f32 v198, v198, v199
	v_cvt_pk_bf16_f32 v199, v200, v201
	v_cvt_pk_bf16_f32 v202, v202, v203
	v_cvt_pk_bf16_f32 v203, v204, v205
	v_cvt_pk_bf16_f32 v206, v206, v207
	v_cvt_pk_bf16_f32 v207, v208, v209
	v_cvt_pk_bf16_f32 v210, v210, v211
	v_cvt_pk_bf16_f32 v211, v212, v213
	global_store_dwordx2 v102, v[198:199], s[40:41]
	global_store_dwordx2 v102, v[202:203], s[40:41] offset:512
	global_store_dwordx2 v102, v[206:207], s[40:41] offset:1024
	global_store_dwordx2 v102, v[210:211], s[40:41] offset:1536
	s_add_u32 s40, s40, 0x400000
	s_addc_u32 s41, s41, 0
	s_waitcnt vmcnt(12)
	v_mul_f32_e32 v96, v215, v215
	v_mul_f32_e32 v97, v217, v217
	v_fmac_f32_e32 v96, v214, v214
	v_fmac_f32_e32 v97, v216, v216
	v_add_f32_e32 v98, v96, v97
	v_mul_f32_e32 v96, v219, v219
	v_mul_f32_e32 v97, v221, v221
	v_fmac_f32_e32 v96, v218, v218
	v_fmac_f32_e32 v97, v220, v220
	v_add_f32_e32 v96, v96, v97
	v_add_f32_e32 v98, v98, v96
	v_mul_f32_e32 v96, v223, v223
	v_mul_f32_e32 v97, v225, v225
	v_fmac_f32_e32 v96, v222, v222
	v_fmac_f32_e32 v97, v224, v224
	v_add_f32_e32 v96, v96, v97
	v_add_f32_e32 v98, v98, v96
	v_mul_f32_e32 v96, v227, v227
	v_mul_f32_e32 v97, v229, v229
	v_fmac_f32_e32 v96, v226, v226
	v_fmac_f32_e32 v97, v228, v228
	v_add_f32_e32 v96, v96, v97
	v_add_f32_e32 v98, v98, v96
	s_nop 1
	v_add_f32_dpp v98, v98, v98 quad_perm:[1,0,3,2] row_mask:0xf bank_mask:0xf bound_ctrl:1
	s_nop 1
	v_add_f32_dpp v98, v98, v98 quad_perm:[2,3,0,1] row_mask:0xf bank_mask:0xf bound_ctrl:1
	s_nop 1
	v_add_f32_dpp v98, v98, v98 row_half_mirror row_mask:0xf bank_mask:0xf bound_ctrl:1
	s_nop 1
	v_add_f32_dpp v98, v98, v98 row_mirror row_mask:0xf bank_mask:0xf bound_ctrl:1
	v_mov_b32_e32 v96, v98
	s_nop 1
	v_permlane16_swap_b32_e32 v98, v96
	v_add_f32_e32 v98, v98, v96
	v_mov_b32_e32 v96, v98
	s_nop 1
	v_permlane32_swap_b32_e32 v98, v96
	v_add_f32_e32 v98, v98, v96
	v_fmamk_f32 v100, v98, 0x3a800000, v153
	v_rsq_f32_e32 v100, v100
	s_nop 0
	v_pk_mul_f32 v[214:215], v[214:215], v[100:101] op_sel_hi:[1,0]
	v_pk_mul_f32 v[216:217], v[216:217], v[100:101] op_sel_hi:[1,0]
	v_pk_mul_f32 v[218:219], v[218:219], v[100:101] op_sel_hi:[1,0]
	v_pk_mul_f32 v[220:221], v[220:221], v[100:101] op_sel_hi:[1,0]
	v_pk_mul_f32 v[222:223], v[222:223], v[100:101] op_sel_hi:[1,0]
	v_pk_mul_f32 v[224:225], v[224:225], v[100:101] op_sel_hi:[1,0]
	v_pk_mul_f32 v[226:227], v[226:227], v[100:101] op_sel_hi:[1,0]
	v_pk_mul_f32 v[228:229], v[228:229], v[100:101] op_sel_hi:[1,0]
	v_pk_mul_f32 v[214:215], v[0:1], v[214:215]
	v_pk_mul_f32 v[216:217], v[2:3], v[216:217]
	v_pk_mul_f32 v[218:219], v[4:5], v[218:219]
	v_pk_mul_f32 v[220:221], v[6:7], v[220:221]
	v_pk_mul_f32 v[222:223], v[8:9], v[222:223]
	v_pk_mul_f32 v[224:225], v[10:11], v[224:225]
	v_pk_mul_f32 v[226:227], v[12:13], v[226:227]
	v_pk_mul_f32 v[228:229], v[14:15], v[228:229]
	v_pk_fma_f32 v[214:215], v[64:65], v[214:215], v[48:49]
	v_pk_fma_f32 v[216:217], v[66:67], v[216:217], v[50:51]
	v_pk_fma_f32 v[218:219], v[68:69], v[218:219], v[52:53]
	v_pk_fma_f32 v[220:221], v[70:71], v[220:221], v[54:55]
	v_pk_fma_f32 v[222:223], v[72:73], v[222:223], v[56:57]
	v_pk_fma_f32 v[224:225], v[74:75], v[224:225], v[58:59]
	v_pk_fma_f32 v[226:227], v[76:77], v[226:227], v[60:61]
	v_pk_fma_f32 v[228:229], v[78:79], v[228:229], v[62:63]
	v_cvt_pk_bf16_f32 v214, v214, v215
	v_cvt_pk_bf16_f32 v215, v216, v217
	v_cvt_pk_bf16_f32 v218, v218, v219
	v_cvt_pk_bf16_f32 v219, v220, v221
	v_cvt_pk_bf16_f32 v222, v222, v223
	v_cvt_pk_bf16_f32 v223, v224, v225
	v_cvt_pk_bf16_f32 v226, v226, v227
	v_cvt_pk_bf16_f32 v227, v228, v229
	global_store_dwordx2 v102, v[214:215], s[40:41]
	global_store_dwordx2 v102, v[218:219], s[40:41] offset:512
	global_store_dwordx2 v102, v[222:223], s[40:41] offset:1024
	global_store_dwordx2 v102, v[226:227], s[40:41] offset:1536
	s_add_u32 s40, s40, 0x400000
	s_addc_u32 s41, s41, 0
	s_add_i32 s0, s0, 0x8000
	s_add_i32 s82, s82, 0x8000
	s_cmp_lt_i32 s0, 0x8400
	s_cbranch_scc1 .LBB0_142
	s_branch .LBB0_150
; __device__ __forceinline__ unsigned pkbf(float lo, float hi) { f32x2_t v = {lo, hi}; bf16x2_t b = __builtin_convertvector(v, bf16x2_t); return __builtin_bit_cast(unsigned, b); }
; __device__ __forceinline__ void norm_phase(const void* src_lat, int lat_f32, const float* src_ctx, int nrows, const float* gvec, const float* mods_l, int sh_off, int sc_off, bf16_t* U, const float* part, int nparts, float* ctx_out) {
;     ...
;         if (row < MLAT && !lat_f32) { const bf16_t* src = (const bf16_t*)src_lat + (size_t)row * DM + 4 * lane;
; #pragma unroll
;             for (int j = 0; j < 4; ++j) { const u32x2 w = *(const u32x2*)(src + 256 * j);
;                 v[j] = (f32x4){__uint_as_float(w.x << 16), __uint_as_float(w.x & 0xffff0000u), __uint_as_float(w.y << 16), __uint_as_float(w.y & 0xffff0000u)}; } }
;     ...
;         for (int j = 0; j < 4; ++j) { ss += (v[j][0] * v[j][0] + v[j][1] * v[j][1]) + (v[j][2] * v[j][2] + v[j][3] * v[j][3]); }
;         if (nparts != 0 && row >= MLAT) {
;             for (int ch = 0; ch < nparts; ch += 4) {
;                 f32x4 pv[4][4];
; #pragma unroll
;                 for (int c4 = 0; c4 < 4; ++c4) { const float* pr = part + ((size_t)(ch + c4) * MCTX + (row - MLAT)) * DM + 4 * lane;
; #pragma unroll
;                     for (int j = 0; j < 4; ++j) pv[c4][j] = *(const f32x4*)(pr + 256 * j); }
; #pragma unroll
;                 for (int c4 = 0; c4 < 4; ++c4)
; #pragma unroll
;                     for (int j = 0; j < 4; ++j) v[j] = v[j] + pv[c4][j]; }
;             ss = 0.f;
; #pragma unroll
;             for (int j = 0; j < 4; ++j) { *(f32x4*)(ctx_out + (size_t)(row - MLAT) * DM + 4 * lane + 256 * j) = v[j]; ss += (v[j][0] * v[j][0] + v[j][1] * v[j][1]) + (v[j][2] * v[j][2] + v[j][3] * v[j][3]); }
;         }
;         const float rs = rsqrtf(wave_sum64(ss) * (1.0f / DM) + EPS);
;         const float* shp = mods_l + s * 6144 + sh_off + 4 * lane; const float* scp = mods_l + s * 6144 + sc_off + 4 * lane;
;         bf16_t* up = U + (size_t)row * DM + 4 * lane;
; #pragma unroll
;         for (int j = 0; j < 4; ++j) { const f32x4 sh = *(const f32x4*)(shp + 256 * j), sc = *(const f32x4*)(scp + 256 * j);
;             const f32x4 y = v[j] * rs * gv[j] * (sc + 1.0f) + sh;
;             u32x2 o; o.x = pkbf(y[0], y[1]); o.y = pkbf(y[2], y[3]); *(u32x2*)(up + 256 * j) = o; }
.Lnorm1_bf16:
	v_and_b32_e32 v102, 63, v152
	v_lshlrev_b32_e32 v103, 4, v102
	v_lshlrev_b32_e32 v102, 3, v102
	v_readfirstlane_b32 s38, v32
	v_readfirstlane_b32 s39, v33
	v_readlane_b32 s34, v240, 42
	v_readlane_b32 s35, v240, 43
	s_nop 0
	s_lshl_b32 s36, s0, 11
	s_add_u32 s38, s38, s36
	s_addc_u32 s39, s39, 0
	s_add_u32 s40, s94, s36
	s_addc_u32 s41, s95, 0
	s_add_u32 s42, s34, 0x0
	s_addc_u32 s43, s35, 0
	s_add_u32 s44, s34, 0x1000
	s_addc_u32 s45, s35, 0
	global_load_dwordx4 v[112:115], v103, s[42:43]
	global_load_dwordx4 v[116:119], v103, s[42:43] offset:1024
	global_load_dwordx4 v[120:123], v103, s[42:43] offset:2048
	global_load_dwordx4 v[124:127], v103, s[42:43] offset:3072
	global_load_dwordx4 v[128:131], v103, s[44:45]
	global_load_dwordx4 v[132:135], v103, s[44:45] offset:1024
	global_load_dwordx4 v[136:139], v103, s[44:45] offset:2048
	global_load_dwordx4 v[140:143], v103, s[44:45] offset:3072
	s_add_u32 s42, s42, 0x6000
	s_addc_u32 s43, s43, 0
	s_add_u32 s44, s44, 0x6000
	s_addc_u32 s45, s45, 0
	global_load_dwordx2 v[158:159], v102, s[38:39]
	global_load_dwordx2 v[160:161], v102, s[38:39] offset:512
	global_load_dwordx2 v[162:163], v102, s[38:39] offset:1024
	global_load_dwordx2 v[164:165], v102, s[38:39] offset:1536
	s_add_u32 s38, s38, 0x400000
	s_addc_u32 s39, s39, 0
	global_load_dwordx2 v[166:167], v102, s[38:39]
	global_load_dwordx2 v[168:169], v102, s[38:39] offset:512
	global_load_dwordx2 v[170:171], v102, s[38:39] offset:1024
	global_load_dwordx2 v[172:173], v102, s[38:39] offset:1536
	s_add_u32 s38, s38, 0x400000
	s_addc_u32 s39, s39, 0
	global_load_dwordx2 v[174:175], v102, s[38:39]
	global_load_dwordx2 v[176:177], v102, s[38:39] offset:512
	global_load_dwordx2 v[178:179], v102, s[38:39] offset:1024
	global_load_dwordx2 v[180:181], v102, s[38:39] offset:1536
	s_add_u32 s38, s38, 0x400000
	s_addc_u32 s39, s39, 0
	global_load_dwordx2 v[182:183], v102, s[38:39]
	global_load_dwordx2 v[184:185], v102, s[38:39] offset:512
	global_load_dwordx2 v[186:187], v102, s[38:39] offset:1024
	global_load_dwordx2 v[188:189], v102, s[38:39] offset:1536
	s_add_u32 s38, s38, 0x400000
	s_addc_u32 s39, s39, 0
	s_waitcnt vmcnt(16)
	v_pk_add_f32 v[128:129], v[128:129], 1.0 op_sel_hi:[1,0]
	v_pk_add_f32 v[130:131], v[130:131], 1.0 op_sel_hi:[1,0]
	v_pk_add_f32 v[132:133], v[132:133], 1.0 op_sel_hi:[1,0]
	v_pk_add_f32 v[134:135], v[134:135], 1.0 op_sel_hi:[1,0]
	v_pk_add_f32 v[136:137], v[136:137], 1.0 op_sel_hi:[1,0]
	v_pk_add_f32 v[138:139], v[138:139], 1.0 op_sel_hi:[1,0]
	v_pk_add_f32 v[140:141], v[140:141], 1.0 op_sel_hi:[1,0]
	v_pk_add_f32 v[142:143], v[142:143], 1.0 op_sel_hi:[1,0]
	s_waitcnt vmcnt(12)
	v_lshlrev_b32_e32 v80, 16, v158
	v_and_b32_e32 v81, 0xffff0000, v158
	v_lshlrev_b32_e32 v82, 16, v159
	v_and_b32_e32 v83, 0xffff0000, v159
	v_lshlrev_b32_e32 v84, 16, v160
	v_and_b32_e32 v85, 0xffff0000, v160
	v_lshlrev_b32_e32 v86, 16, v161
	v_and_b32_e32 v87, 0xffff0000, v161
	v_lshlrev_b32_e32 v88, 16, v162
	v_and_b32_e32 v89, 0xffff0000, v162
	v_lshlrev_b32_e32 v90, 16, v163
	v_and_b32_e32 v91, 0xffff0000, v163
	v_lshlrev_b32_e32 v92, 16, v164
	v_and_b32_e32 v93, 0xffff0000, v164
	v_lshlrev_b32_e32 v94, 16, v165
	v_and_b32_e32 v95, 0xffff0000, v165
	v_mul_f32_e32 v96, v81, v81
	v_mul_f32_e32 v97, v83, v83
	v_fmac_f32_e32 v96, v80, v80
	v_fmac_f32_e32 v97, v82, v82
	v_add_f32_e32 v98, v96, v97
	v_mul_f32_e32 v96, v85, v85
	v_mul_f32_e32 v97, v87, v87
	v_fmac_f32_e32 v96, v84, v84
	v_fmac_f32_e32 v97, v86, v86
	v_add_f32_e32 v96, v96, v97
	v_add_f32_e32 v98, v98, v96
	v_mul_f32_e32 v96, v89, v89
	v_mul_f32_e32 v97, v91, v91
	v_fmac_f32_e32 v96, v88, v88
	v_fmac_f32_e32 v97, v90, v90
	v_add_f32_e32 v96, v96, v97
	v_add_f32_e32 v98, v98, v96
	v_mul_f32_e32 v96, v93, v93
	v_mul_f32_e32 v97, v95, v95
	v_fmac_f32_e32 v96, v92, v92
	v_fmac_f32_e32 v97, v94, v94
	v_add_f32_e32 v96, v96, v97
	v_add_f32_e32 v98, v98, v96
	s_nop 1
	v_add_f32_dpp v98, v98, v98 quad_perm:[1,0,3,2] row_mask:0xf bank_mask:0xf bound_ctrl:1
	s_nop 1
	v_add_f32_dpp v98, v98, v98 quad_perm:[2,3,0,1] row_mask:0xf bank_mask:0xf bound_ctrl:1
	s_nop 1
	v_add_f32_dpp v98, v98, v98 row_half_mirror row_mask:0xf bank_mask:0xf bound_ctrl:1
	s_nop 1
	v_add_f32_dpp v98, v98, v98 row_mirror row_mask:0xf bank_mask:0xf bound_ctrl:1
	v_mov_b32_e32 v96, v98
	s_nop 1
	v_permlane16_swap_b32_e32 v98, v96
	v_add_f32_e32 v98, v98, v96
	v_mov_b32_e32 v96, v98
	s_nop 1
	v_permlane32_swap_b32_e32 v98, v96
	v_add_f32_e32 v98, v98, v96
	v_fmamk_f32 v100, v98, 0x3a800000, v153
	v_rsq_f32_e32 v100, v100
	s_nop 0
	v_pk_mul_f32 v[80:81], v[80:81], v[100:101] op_sel_hi:[1,0]
	v_pk_mul_f32 v[82:83], v[82:83], v[100:101] op_sel_hi:[1,0]
	v_pk_mul_f32 v[84:85], v[84:85], v[100:101] op_sel_hi:[1,0]
	v_pk_mul_f32 v[86:87], v[86:87], v[100:101] op_sel_hi:[1,0]
	v_pk_mul_f32 v[88:89], v[88:89], v[100:101] op_sel_hi:[1,0]
	v_pk_mul_f32 v[90:91], v[90:91], v[100:101] op_sel_hi:[1,0]
	v_pk_mul_f32 v[92:93], v[92:93], v[100:101] op_sel_hi:[1,0]
	v_pk_mul_f32 v[94:95], v[94:95], v[100:101] op_sel_hi:[1,0]
	v_pk_mul_f32 v[80:81], v[0:1], v[80:81]
	v_pk_mul_f32 v[82:83], v[2:3], v[82:83]
	v_pk_mul_f32 v[84:85], v[4:5], v[84:85]
	v_pk_mul_f32 v[86:87], v[6:7], v[86:87]
	v_pk_mul_f32 v[88:89], v[8:9], v[88:89]
	v_pk_mul_f32 v[90:91], v[10:11], v[90:91]
	v_pk_mul_f32 v[92:93], v[12:13], v[92:93]
	v_pk_mul_f32 v[94:95], v[14:15], v[94:95]
	v_pk_fma_f32 v[80:81], v[128:129], v[80:81], v[112:113]
	v_pk_fma_f32 v[82:83], v[130:131], v[82:83], v[114:115]
	v_pk_fma_f32 v[84:85], v[132:133], v[84:85], v[116:117]
	v_pk_fma_f32 v[86:87], v[134:135], v[86:87], v[118:119]
	v_pk_fma_f32 v[88:89], v[136:137], v[88:89], v[120:121]
; __device__ __forceinline__ unsigned pkbf(float lo, float hi) { f32x2_t v = {lo, hi}; bf16x2_t b = __builtin_convertvector(v, bf16x2_t); return __builtin_bit_cast(unsigned, b); }
; __device__ __forceinline__ void norm_phase(const void* src_lat, int lat_f32, const float* src_ctx, int nrows, const float* gvec, const float* mods_l, int sh_off, int sc_off, bf16_t* U, const float* part, int nparts, float* ctx_out) {
;     ...
;         if (row < MLAT && !lat_f32) { const bf16_t* src = (const bf16_t*)src_lat + (size_t)row * DM + 4 * lane;
; #pragma unroll
;             for (int j = 0; j < 4; ++j) { const u32x2 w = *(const u32x2*)(src + 256 * j);
;                 v[j] = (f32x4){__uint_as_float(w.x << 16), __uint_as_float(w.x & 0xffff0000u), __uint_as_float(w.y << 16), __uint_as_float(w.y & 0xffff0000u)}; } }
;     ...
;         for (int j = 0; j < 4; ++j) { ss += (v[j][0] * v[j][0] + v[j][1] * v[j][1]) + (v[j][2] * v[j][2] + v[j][3] * v[j][3]); }
;         if (nparts != 0 && row >= MLAT) {
;             for (int ch = 0; ch < nparts; ch += 4) {
;                 f32x4 pv[4][4];
; #pragma unroll
;                 for (int c4 = 0; c4 < 4; ++c4) { const float* pr = part + ((size_t)(ch + c4) * MCTX + (row - MLAT)) * DM + 4 * lane;
; #pragma unroll
;                     for (int j = 0; j < 4; ++j) pv[c4][j] = *(const f32x4*)(pr + 256 * j); }
; #pragma unroll
;                 for (int c4 = 0; c4 < 4; ++c4)
; #pragma unroll
;                     for (int j = 0; j < 4; ++j) v[j] = v[j] + pv[c4][j]; }
;             ss = 0.f;
; #pragma unroll
;             for (int j = 0; j < 4; ++j) { *(f32x4*)(ctx_out + (size_t)(row - MLAT) * DM + 4 * lane + 256 * j) = v[j]; ss += (v[j][0] * v[j][0] + v[j][1] * v[j][1]) + (v[j][2] * v[j][2] + v[j][3] * v[j][3]); }
;         }
;         const float rs = rsqrtf(wave_sum64(ss) * (1.0f / DM) + EPS);
;         const float* shp = mods_l + s * 6144 + sh_off + 4 * lane; const float* scp = mods_l + s * 6144 + sc_off + 4 * lane;
;         bf16_t* up = U + (size_t)row * DM + 4 * lane;
; #pragma unroll
;         for (int j = 0; j < 4; ++j) { const f32x4 sh = *(const f32x4*)(shp + 256 * j), sc = *(const f32x4*)(scp + 256 * j);
;             const f32x4 y = v[j] * rs * gv[j] * (sc + 1.0f) + sh;
;             u32x2 o; o.x = pkbf(y[0], y[1]); o.y = pkbf(y[2], y[3]); *(u32x2*)(up + 256 * j) = o; }
	v_pk_fma_f32 v[90:91], v[138:139], v[90:91], v[122:123]
	v_pk_fma_f32 v[92:93], v[140:141], v[92:93], v[124:125]
	v_pk_fma_f32 v[94:95], v[142:143], v[94:95], v[126:127]
	v_cvt_pk_bf16_f32 v80, v80, v81
	v_cvt_pk_bf16_f32 v81, v82, v83
	v_cvt_pk_bf16_f32 v84, v84, v85
	v_cvt_pk_bf16_f32 v85, v86, v87
	v_cvt_pk_bf16_f32 v88, v88, v89
	v_cvt_pk_bf16_f32 v89, v90, v91
	v_cvt_pk_bf16_f32 v92, v92, v93
	v_cvt_pk_bf16_f32 v93, v94, v95
	global_store_dwordx2 v102, v[80:81], s[40:41]
	global_store_dwordx2 v102, v[84:85], s[40:41] offset:512
	global_store_dwordx2 v102, v[88:89], s[40:41] offset:1024
	global_store_dwordx2 v102, v[92:93], s[40:41] offset:1536
	s_add_u32 s40, s40, 0x400000
	s_addc_u32 s41, s41, 0
	global_load_dwordx2 v[158:159], v102, s[38:39]
	global_load_dwordx2 v[160:161], v102, s[38:39] offset:512
	global_load_dwordx2 v[162:163], v102, s[38:39] offset:1024
	global_load_dwordx2 v[164:165], v102, s[38:39] offset:1536
	s_add_u32 s38, s38, 0x400000
	s_addc_u32 s39, s39, 0
	global_load_dwordx4 v[48:51], v103, s[42:43]
	global_load_dwordx4 v[52:55], v103, s[42:43] offset:1024
	global_load_dwordx4 v[56:59], v103, s[42:43] offset:2048
	global_load_dwordx4 v[60:63], v103, s[42:43] offset:3072
	global_load_dwordx4 v[64:67], v103, s[44:45]
	global_load_dwordx4 v[68:71], v103, s[44:45] offset:1024
	global_load_dwordx4 v[72:75], v103, s[44:45] offset:2048
	global_load_dwordx4 v[76:79], v103, s[44:45] offset:3072
	s_add_u32 s42, s42, 0x6000
	s_addc_u32 s43, s43, 0
	s_add_u32 s44, s44, 0x6000
	s_addc_u32 s45, s45, 0
	s_waitcnt vmcnt(24)
	v_lshlrev_b32_e32 v80, 16, v166
	v_and_b32_e32 v81, 0xffff0000, v166
	v_lshlrev_b32_e32 v82, 16, v167
	v_and_b32_e32 v83, 0xffff0000, v167
	v_lshlrev_b32_e32 v84, 16, v168
	v_and_b32_e32 v85, 0xffff0000, v168
	v_lshlrev_b32_e32 v86, 16, v169
	v_and_b32_e32 v87, 0xffff0000, v169
	v_lshlrev_b32_e32 v88, 16, v170
	v_and_b32_e32 v89, 0xffff0000, v170
	v_lshlrev_b32_e32 v90, 16, v171
	v_and_b32_e32 v91, 0xffff0000, v171
	v_lshlrev_b32_e32 v92, 16, v172
	v_and_b32_e32 v93, 0xffff0000, v172
	v_lshlrev_b32_e32 v94, 16, v173
	v_and_b32_e32 v95, 0xffff0000, v173
	v_mul_f32_e32 v96, v81, v81
	v_mul_f32_e32 v97, v83, v83
	v_fmac_f32_e32 v96, v80, v80
	v_fmac_f32_e32 v97, v82, v82
	v_add_f32_e32 v98, v96, v97
	v_mul_f32_e32 v96, v85, v85
	v_mul_f32_e32 v97, v87, v87
	v_fmac_f32_e32 v96, v84, v84
	v_fmac_f32_e32 v97, v86, v86
	v_add_f32_e32 v96, v96, v97
	v_add_f32_e32 v98, v98, v96
	v_mul_f32_e32 v96, v89, v89
	v_mul_f32_e32 v97, v91, v91
	v_fmac_f32_e32 v96, v88, v88
	v_fmac_f32_e32 v97, v90, v90
	v_add_f32_e32 v96, v96, v97
	v_add_f32_e32 v98, v98, v96
	v_mul_f32_e32 v96, v93, v93
	v_mul_f32_e32 v97, v95, v95
	v_fmac_f32_e32 v96, v92, v92
	v_fmac_f32_e32 v97, v94, v94
	v_add_f32_e32 v96, v96, v97
	v_add_f32_e32 v98, v98, v96
	s_nop 1
	v_add_f32_dpp v98, v98, v98 quad_perm:[1,0,3,2] row_mask:0xf bank_mask:0xf bound_ctrl:1
	s_nop 1
	v_add_f32_dpp v98, v98, v98 quad_perm:[2,3,0,1] row_mask:0xf bank_mask:0xf bound_ctrl:1
	s_nop 1
	v_add_f32_dpp v98, v98, v98 row_half_mirror row_mask:0xf bank_mask:0xf bound_ctrl:1
	s_nop 1
	v_add_f32_dpp v98, v98, v98 row_mirror row_mask:0xf bank_mask:0xf bound_ctrl:1
	v_mov_b32_e32 v96, v98
	s_nop 1
	v_permlane16_swap_b32_e32 v98, v96
	v_add_f32_e32 v98, v98, v96
	v_mov_b32_e32 v96, v98
	s_nop 1
	v_permlane32_swap_b32_e32 v98, v96
	v_add_f32_e32 v98, v98, v96
	v_fmamk_f32 v100, v98, 0x3a800000, v153
	v_rsq_f32_e32 v100, v100
	s_nop 0
	v_pk_mul_f32 v[80:81], v[80:81], v[100:101] op_sel_hi:[1,0]
	v_pk_mul_f32 v[82:83], v[82:83], v[100:101] op_sel_hi:[1,0]
	v_pk_mul_f32 v[84:85], v[84:85], v[100:101] op_sel_hi:[1,0]
	v_pk_mul_f32 v[86:87], v[86:87], v[100:101] op_sel_hi:[1,0]
	v_pk_mul_f32 v[88:89], v[88:89], v[100:101] op_sel_hi:[1,0]
	v_pk_mul_f32 v[90:91], v[90:91], v[100:101] op_sel_hi:[1,0]
	v_pk_mul_f32 v[92:93], v[92:93], v[100:101] op_sel_hi:[1,0]
	v_pk_mul_f32 v[94:95], v[94:95], v[100:101] op_sel_hi:[1,0]
	v_pk_mul_f32 v[80:81], v[0:1], v[80:81]
	v_pk_mul_f32 v[82:83], v[2:3], v[82:83]
	v_pk_mul_f32 v[84:85], v[4:5], v[84:85]
	v_pk_mul_f32 v[86:87], v[6:7], v[86:87]
	v_pk_mul_f32 v[88:89], v[8:9], v[88:89]
	v_pk_mul_f32 v[90:91], v[10:11], v[90:91]
	v_pk_mul_f32 v[92:93], v[12:13], v[92:93]
	v_pk_mul_f32 v[94:95], v[14:15], v[94:95]
	v_pk_fma_f32 v[80:81], v[128:129], v[80:81], v[112:113]
	v_pk_fma_f32 v[82:83], v[130:131], v[82:83], v[114:115]
	v_pk_fma_f32 v[84:85], v[132:133], v[84:85], v[116:117]
	v_pk_fma_f32 v[86:87], v[134:135], v[86:87], v[118:119]
	v_pk_fma_f32 v[88:89], v[136:137], v[88:89], v[120:121]
	v_pk_fma_f32 v[90:91], v[138:139], v[90:91], v[122:123]
	v_pk_fma_f32 v[92:93], v[140:141], v[92:93], v[124:125]
	v_pk_fma_f32 v[94:95], v[142:143], v[94:95], v[126:127]
	v_cvt_pk_bf16_f32 v80, v80, v81
	v_cvt_pk_bf16_f32 v81, v82, v83
	v_cvt_pk_bf16_f32 v84, v84, v85
	v_cvt_pk_bf16_f32 v85, v86, v87
	v_cvt_pk_bf16_f32 v88, v88, v89
	v_cvt_pk_bf16_f32 v89, v90, v91
	v_cvt_pk_bf16_f32 v92, v92, v93
	v_cvt_pk_bf16_f32 v93, v94, v95
	global_store_dwordx2 v102, v[80:81], s[40:41]
	global_store_dwordx2 v102, v[84:85], s[40:41] offset:512
	global_store_dwordx2 v102, v[88:89], s[40:41] offset:1024
	global_store_dwordx2 v102, v[92:93], s[40:41] offset:1536
	s_add_u32 s40, s40, 0x400000
	s_addc_u32 s41, s41, 0
	global_load_dwordx2 v[166:167], v102, s[38:39]
	global_load_dwordx2 v[168:169], v102, s[38:39] offset:512
	global_load_dwordx2 v[170:171], v102, s[38:39] offset:1024
	global_load_dwordx2 v[172:173], v102, s[38:39] offset:1536
	s_add_u32 s38, s38, 0x400000
	s_addc_u32 s39, s39, 0
	s_waitcnt vmcnt(28)
; __device__ __forceinline__ unsigned pkbf(float lo, float hi) { f32x2_t v = {lo, hi}; bf16x2_t b = __builtin_convertvector(v, bf16x2_t); return __builtin_bit_cast(unsigned, b); }
; __device__ __forceinline__ void norm_phase(const void* src_lat, int lat_f32, const float* src_ctx, int nrows, const float* gvec, const float* mods_l, int sh_off, int sc_off, bf16_t* U, const float* part, int nparts, float* ctx_out) {
;     ...
;         if (row < MLAT && !lat_f32) { const bf16_t* src = (const bf16_t*)src_lat + (size_t)row * DM + 4 * lane;
; #pragma unroll
;             for (int j = 0; j < 4; ++j) { const u32x2 w = *(const u32x2*)(src + 256 * j);
;                 v[j] = (f32x4){__uint_as_float(w.x << 16), __uint_as_float(w.x & 0xffff0000u), __uint_as_float(w.y << 16), __uint_as_float(w.y & 0xffff0000u)}; } }
;     ...
;         for (int j = 0; j < 4; ++j) { ss += (v[j][0] * v[j][0] + v[j][1] * v[j][1]) + (v[j][2] * v[j][2] + v[j][3] * v[j][3]); }
;         if (nparts != 0 && row >= MLAT) {
;             for (int ch = 0; ch < nparts; ch += 4) {
;                 f32x4 pv[4][4];
; #pragma unroll
;                 for (int c4 = 0; c4 < 4; ++c4) { const float* pr = part + ((size_t)(ch + c4) * MCTX + (row - MLAT)) * DM + 4 * lane;
; #pragma unroll
;                     for (int j = 0; j < 4; ++j) pv[c4][j] = *(const f32x4*)(pr + 256 * j); }
; #pragma unroll
;                 for (int c4 = 0; c4 < 4; ++c4)
; #pragma unroll
;                     for (int j = 0; j < 4; ++j) v[j] = v[j] + pv[c4][j]; }
;             ss = 0.f;
; #pragma unroll
;             for (int j = 0; j < 4; ++j) { *(f32x4*)(ctx_out + (size_t)(row - MLAT) * DM + 4 * lane + 256 * j) = v[j]; ss += (v[j][0] * v[j][0] + v[j][1] * v[j][1]) + (v[j][2] * v[j][2] + v[j][3] * v[j][3]); }
;         }
;         const float rs = rsqrtf(wave_sum64(ss) * (1.0f / DM) + EPS);
;         const float* shp = mods_l + s * 6144 + sh_off + 4 * lane; const float* scp = mods_l + s * 6144 + sc_off + 4 * lane;
;         bf16_t* up = U + (size_t)row * DM + 4 * lane;
; #pragma unroll
;         for (int j = 0; j < 4; ++j) { const f32x4 sh = *(const f32x4*)(shp + 256 * j), sc = *(const f32x4*)(scp + 256 * j);
;             const f32x4 y = v[j] * rs * gv[j] * (sc + 1.0f) + sh;
;             u32x2 o; o.x = pkbf(y[0], y[1]); o.y = pkbf(y[2], y[3]); *(u32x2*)(up + 256 * j) = o; }
	v_lshlrev_b32_e32 v80, 16, v174
	v_and_b32_e32 v81, 0xffff0000, v174
	v_lshlrev_b32_e32 v82, 16, v175
	v_and_b32_e32 v83, 0xffff0000, v175
	v_lshlrev_b32_e32 v84, 16, v176
	v_and_b32_e32 v85, 0xffff0000, v176
	v_lshlrev_b32_e32 v86, 16, v177
	v_and_b32_e32 v87, 0xffff0000, v177
	v_lshlrev_b32_e32 v88, 16, v178
	v_and_b32_e32 v89, 0xffff0000, v178
	v_lshlrev_b32_e32 v90, 16, v179
	v_and_b32_e32 v91, 0xffff0000, v179
	v_lshlrev_b32_e32 v92, 16, v180
	v_and_b32_e32 v93, 0xffff0000, v180
	v_lshlrev_b32_e32 v94, 16, v181
	v_and_b32_e32 v95, 0xffff0000, v181
	v_mul_f32_e32 v96, v81, v81
	v_mul_f32_e32 v97, v83, v83
	v_fmac_f32_e32 v96, v80, v80
	v_fmac_f32_e32 v97, v82, v82
	v_add_f32_e32 v98, v96, v97
	v_mul_f32_e32 v96, v85, v85
	v_mul_f32_e32 v97, v87, v87
	v_fmac_f32_e32 v96, v84, v84
	v_fmac_f32_e32 v97, v86, v86
	v_add_f32_e32 v96, v96, v97
	v_add_f32_e32 v98, v98, v96
	v_mul_f32_e32 v96, v89, v89
	v_mul_f32_e32 v97, v91, v91
	v_fmac_f32_e32 v96, v88, v88
	v_fmac_f32_e32 v97, v90, v90
	v_add_f32_e32 v96, v96, v97
	v_add_f32_e32 v98, v98, v96
	v_mul_f32_e32 v96, v93, v93
	v_mul_f32_e32 v97, v95, v95
	v_fmac_f32_e32 v96, v92, v92
	v_fmac_f32_e32 v97, v94, v94
	v_add_f32_e32 v96, v96, v97
	v_add_f32_e32 v98, v98, v96
	s_nop 1
	v_add_f32_dpp v98, v98, v98 quad_perm:[1,0,3,2] row_mask:0xf bank_mask:0xf bound_ctrl:1
	s_nop 1
	v_add_f32_dpp v98, v98, v98 quad_perm:[2,3,0,1] row_mask:0xf bank_mask:0xf bound_ctrl:1
	s_nop 1
	v_add_f32_dpp v98, v98, v98 row_half_mirror row_mask:0xf bank_mask:0xf bound_ctrl:1
	s_nop 1
	v_add_f32_dpp v98, v98, v98 row_mirror row_mask:0xf bank_mask:0xf bound_ctrl:1
	v_mov_b32_e32 v96, v98
	s_nop 1
	v_permlane16_swap_b32_e32 v98, v96
	v_add_f32_e32 v98, v98, v96
	v_mov_b32_e32 v96, v98
	s_nop 1
	v_permlane32_swap_b32_e32 v98, v96
	v_add_f32_e32 v98, v98, v96
	v_fmamk_f32 v100, v98, 0x3a800000, v153
	v_rsq_f32_e32 v100, v100
	s_nop 0
	v_pk_mul_f32 v[80:81], v[80:81], v[100:101] op_sel_hi:[1,0]
	v_pk_mul_f32 v[82:83], v[82:83], v[100:101] op_sel_hi:[1,0]
	v_pk_mul_f32 v[84:85], v[84:85], v[100:101] op_sel_hi:[1,0]
	v_pk_mul_f32 v[86:87], v[86:87], v[100:101] op_sel_hi:[1,0]
	v_pk_mul_f32 v[88:89], v[88:89], v[100:101] op_sel_hi:[1,0]
	v_pk_mul_f32 v[90:91], v[90:91], v[100:101] op_sel_hi:[1,0]
	v_pk_mul_f32 v[92:93], v[92:93], v[100:101] op_sel_hi:[1,0]
	v_pk_mul_f32 v[94:95], v[94:95], v[100:101] op_sel_hi:[1,0]
	v_pk_mul_f32 v[80:81], v[0:1], v[80:81]
	v_pk_mul_f32 v[82:83], v[2:3], v[82:83]
	v_pk_mul_f32 v[84:85], v[4:5], v[84:85]
	v_pk_mul_f32 v[86:87], v[6:7], v[86:87]
	v_pk_mul_f32 v[88:89], v[8:9], v[88:89]
	v_pk_mul_f32 v[90:91], v[10:11], v[90:91]
	v_pk_mul_f32 v[92:93], v[12:13], v[92:93]
	v_pk_mul_f32 v[94:95], v[14:15], v[94:95]
	v_pk_fma_f32 v[80:81], v[128:129], v[80:81], v[112:113]
	v_pk_fma_f32 v[82:83], v[130:131], v[82:83], v[114:115]
	v_pk_fma_f32 v[84:85], v[132:133], v[84:85], v[116:117]
	v_pk_fma_f32 v[86:87], v[134:135], v[86:87], v[118:119]
	v_pk_fma_f32 v[88:89], v[136:137], v[88:89], v[120:121]
	v_pk_fma_f32 v[90:91], v[138:139], v[90:91], v[122:123]
	v_pk_fma_f32 v[92:93], v[140:141], v[92:93], v[124:125]
	v_pk_fma_f32 v[94:95], v[142:143], v[94:95], v[126:127]
	v_cvt_pk_bf16_f32 v80, v80, v81
	v_cvt_pk_bf16_f32 v81, v82, v83
	v_cvt_pk_bf16_f32 v84, v84, v85
	v_cvt_pk_bf16_f32 v85, v86, v87
	v_cvt_pk_bf16_f32 v88, v88, v89
	v_cvt_pk_bf16_f32 v89, v90, v91
	v_cvt_pk_bf16_f32 v92, v92, v93
	v_cvt_pk_bf16_f32 v93, v94, v95
	global_store_dwordx2 v102, v[80:81], s[40:41]
	global_store_dwordx2 v102, v[84:85], s[40:41] offset:512
	global_store_dwordx2 v102, v[88:89], s[40:41] offset:1024
	global_store_dwordx2 v102, v[92:93], s[40:41] offset:1536
	s_add_u32 s40, s40, 0x400000
	s_addc_u32 s41, s41, 0
	global_load_dwordx2 v[174:175], v102, s[38:39]
	global_load_dwordx2 v[176:177], v102, s[38:39] offset:512
	global_load_dwordx2 v[178:179], v102, s[38:39] offset:1024
	global_load_dwordx2 v[180:181], v102, s[38:39] offset:1536
	s_add_u32 s38, s38, 0x400000
	s_addc_u32 s39, s39, 0
	s_waitcnt vmcnt(32)
	v_lshlrev_b32_e32 v80, 16, v182
	v_and_b32_e32 v81, 0xffff0000, v182
	v_lshlrev_b32_e32 v82, 16, v183
	v_and_b32_e32 v83, 0xffff0000, v183
	v_lshlrev_b32_e32 v84, 16, v184
	v_and_b32_e32 v85, 0xffff0000, v184
	v_lshlrev_b32_e32 v86, 16, v185
	v_and_b32_e32 v87, 0xffff0000, v185
	v_lshlrev_b32_e32 v88, 16, v186
	v_and_b32_e32 v89, 0xffff0000, v186
	v_lshlrev_b32_e32 v90, 16, v187
	v_and_b32_e32 v91, 0xffff0000, v187
	v_lshlrev_b32_e32 v92, 16, v188
	v_and_b32_e32 v93, 0xffff0000, v188
	v_lshlrev_b32_e32 v94, 16, v189
	v_and_b32_e32 v95, 0xffff0000, v189
	v_mul_f32_e32 v96, v81, v81
	v_mul_f32_e32 v97, v83, v83
	v_fmac_f32_e32 v96, v80, v80
	v_fmac_f32_e32 v97, v82, v82
	v_add_f32_e32 v98, v96, v97
	v_mul_f32_e32 v96, v85, v85
	v_mul_f32_e32 v97, v87, v87
	v_fmac_f32_e32 v96, v84, v84
	v_fmac_f32_e32 v97, v86, v86
	v_add_f32_e32 v96, v96, v97
	v_add_f32_e32 v98, v98, v96
	v_mul_f32_e32 v96, v89, v89
	v_mul_f32_e32 v97, v91, v91
	v_fmac_f32_e32 v96, v88, v88
	v_fmac_f32_e32 v97, v90, v90
	v_add_f32_e32 v96, v96, v97
	v_add_f32_e32 v98, v98, v96
	v_mul_f32_e32 v96, v93, v93
	v_mul_f32_e32 v97, v95, v95
	v_fmac_f32_e32 v96, v92, v92
	v_fmac_f32_e32 v97, v94, v94
	v_add_f32_e32 v96, v96, v97
	v_add_f32_e32 v98, v98, v96
	s_nop 1
	v_add_f32_dpp v98, v98, v98 quad_perm:[1,0,3,2] row_mask:0xf bank_mask:0xf bound_ctrl:1
	s_nop 1
	v_add_f32_dpp v98, v98, v98 quad_perm:[2,3,0,1] row_mask:0xf bank_mask:0xf bound_ctrl:1
	s_nop 1
	v_add_f32_dpp v98, v98, v98 row_half_mirror row_mask:0xf bank_mask:0xf bound_ctrl:1
	s_nop 1
	v_add_f32_dpp v98, v98, v98 row_mirror row_mask:0xf bank_mask:0xf bound_ctrl:1
	v_mov_b32_e32 v96, v98
; __device__ __forceinline__ unsigned pkbf(float lo, float hi) { f32x2_t v = {lo, hi}; bf16x2_t b = __builtin_convertvector(v, bf16x2_t); return __builtin_bit_cast(unsigned, b); }
; __device__ __forceinline__ void norm_phase(const void* src_lat, int lat_f32, const float* src_ctx, int nrows, const float* gvec, const float* mods_l, int sh_off, int sc_off, bf16_t* U, const float* part, int nparts, float* ctx_out) {
;     ...
;         if (row < MLAT && !lat_f32) { const bf16_t* src = (const bf16_t*)src_lat + (size_t)row * DM + 4 * lane;
; #pragma unroll
;             for (int j = 0; j < 4; ++j) { const u32x2 w = *(const u32x2*)(src + 256 * j);
;                 v[j] = (f32x4){__uint_as_float(w.x << 16), __uint_as_float(w.x & 0xffff0000u), __uint_as_float(w.y << 16), __uint_as_float(w.y & 0xffff0000u)}; } }
;     ...
;         for (int j = 0; j < 4; ++j) { ss += (v[j][0] * v[j][0] + v[j][1] * v[j][1]) + (v[j][2] * v[j][2] + v[j][3] * v[j][3]); }
;         if (nparts != 0 && row >= MLAT) {
;             for (int ch = 0; ch < nparts; ch += 4) {
;                 f32x4 pv[4][4];
; #pragma unroll
;                 for (int c4 = 0; c4 < 4; ++c4) { const float* pr = part + ((size_t)(ch + c4) * MCTX + (row - MLAT)) * DM + 4 * lane;
; #pragma unroll
;                     for (int j = 0; j < 4; ++j) pv[c4][j] = *(const f32x4*)(pr + 256 * j); }
; #pragma unroll
;                 for (int c4 = 0; c4 < 4; ++c4)
; #pragma unroll
;                     for (int j = 0; j < 4; ++j) v[j] = v[j] + pv[c4][j]; }
;             ss = 0.f;
; #pragma unroll
;             for (int j = 0; j < 4; ++j) { *(f32x4*)(ctx_out + (size_t)(row - MLAT) * DM + 4 * lane + 256 * j) = v[j]; ss += (v[j][0] * v[j][0] + v[j][1] * v[j][1]) + (v[j][2] * v[j][2] + v[j][3] * v[j][3]); }
;         }
;         const float rs = rsqrtf(wave_sum64(ss) * (1.0f / DM) + EPS);
;         const float* shp = mods_l + s * 6144 + sh_off + 4 * lane; const float* scp = mods_l + s * 6144 + sc_off + 4 * lane;
;         bf16_t* up = U + (size_t)row * DM + 4 * lane;
; #pragma unroll
;         for (int j = 0; j < 4; ++j) { const f32x4 sh = *(const f32x4*)(shp + 256 * j), sc = *(const f32x4*)(scp + 256 * j);
;             const f32x4 y = v[j] * rs * gv[j] * (sc + 1.0f) + sh;
;             u32x2 o; o.x = pkbf(y[0], y[1]); o.y = pkbf(y[2], y[3]); *(u32x2*)(up + 256 * j) = o; }
	s_nop 1
	v_permlane16_swap_b32_e32 v98, v96
	v_add_f32_e32 v98, v98, v96
	v_mov_b32_e32 v96, v98
	s_nop 1
	v_permlane32_swap_b32_e32 v98, v96
	v_add_f32_e32 v98, v98, v96
	v_fmamk_f32 v100, v98, 0x3a800000, v153
	v_rsq_f32_e32 v100, v100
	s_nop 0
	v_pk_mul_f32 v[80:81], v[80:81], v[100:101] op_sel_hi:[1,0]
	v_pk_mul_f32 v[82:83], v[82:83], v[100:101] op_sel_hi:[1,0]
	v_pk_mul_f32 v[84:85], v[84:85], v[100:101] op_sel_hi:[1,0]
	v_pk_mul_f32 v[86:87], v[86:87], v[100:101] op_sel_hi:[1,0]
	v_pk_mul_f32 v[88:89], v[88:89], v[100:101] op_sel_hi:[1,0]
	v_pk_mul_f32 v[90:91], v[90:91], v[100:101] op_sel_hi:[1,0]
	v_pk_mul_f32 v[92:93], v[92:93], v[100:101] op_sel_hi:[1,0]
	v_pk_mul_f32 v[94:95], v[94:95], v[100:101] op_sel_hi:[1,0]
	v_pk_mul_f32 v[80:81], v[0:1], v[80:81]
	v_pk_mul_f32 v[82:83], v[2:3], v[82:83]
	v_pk_mul_f32 v[84:85], v[4:5], v[84:85]
	v_pk_mul_f32 v[86:87], v[6:7], v[86:87]
	v_pk_mul_f32 v[88:89], v[8:9], v[88:89]
	v_pk_mul_f32 v[90:91], v[10:11], v[90:91]
	v_pk_mul_f32 v[92:93], v[12:13], v[92:93]
	v_pk_mul_f32 v[94:95], v[14:15], v[94:95]
	v_pk_fma_f32 v[80:81], v[128:129], v[80:81], v[112:113]
	v_pk_fma_f32 v[82:83], v[130:131], v[82:83], v[114:115]
	v_pk_fma_f32 v[84:85], v[132:133], v[84:85], v[116:117]
	v_pk_fma_f32 v[86:87], v[134:135], v[86:87], v[118:119]
	v_pk_fma_f32 v[88:89], v[136:137], v[88:89], v[120:121]
	v_pk_fma_f32 v[90:91], v[138:139], v[90:91], v[122:123]
	v_pk_fma_f32 v[92:93], v[140:141], v[92:93], v[124:125]
	v_pk_fma_f32 v[94:95], v[142:143], v[94:95], v[126:127]
	v_cvt_pk_bf16_f32 v80, v80, v81
	v_cvt_pk_bf16_f32 v81, v82, v83
	v_cvt_pk_bf16_f32 v84, v84, v85
	v_cvt_pk_bf16_f32 v85, v86, v87
	v_cvt_pk_bf16_f32 v88, v88, v89
	v_cvt_pk_bf16_f32 v89, v90, v91
	v_cvt_pk_bf16_f32 v92, v92, v93
	v_cvt_pk_bf16_f32 v93, v94, v95
	global_store_dwordx2 v102, v[80:81], s[40:41]
	global_store_dwordx2 v102, v[84:85], s[40:41] offset:512
	global_store_dwordx2 v102, v[88:89], s[40:41] offset:1024
	global_store_dwordx2 v102, v[92:93], s[40:41] offset:1536
	s_add_u32 s40, s40, 0x400000
	s_addc_u32 s41, s41, 0
	global_load_dwordx2 v[182:183], v102, s[38:39]
	global_load_dwordx2 v[184:185], v102, s[38:39] offset:512
	global_load_dwordx2 v[186:187], v102, s[38:39] offset:1024
	global_load_dwordx2 v[188:189], v102, s[38:39] offset:1536
	s_add_u32 s38, s38, 0x400000
	s_addc_u32 s39, s39, 0
	s_waitcnt vmcnt(24)
	v_pk_add_f32 v[64:65], v[64:65], 1.0 op_sel_hi:[1,0]
	v_pk_add_f32 v[66:67], v[66:67], 1.0 op_sel_hi:[1,0]
	v_pk_add_f32 v[68:69], v[68:69], 1.0 op_sel_hi:[1,0]
	v_pk_add_f32 v[70:71], v[70:71], 1.0 op_sel_hi:[1,0]
	v_pk_add_f32 v[72:73], v[72:73], 1.0 op_sel_hi:[1,0]
	v_pk_add_f32 v[74:75], v[74:75], 1.0 op_sel_hi:[1,0]
	v_pk_add_f32 v[76:77], v[76:77], 1.0 op_sel_hi:[1,0]
	v_pk_add_f32 v[78:79], v[78:79], 1.0 op_sel_hi:[1,0]
	v_lshlrev_b32_e32 v80, 16, v158
	v_and_b32_e32 v81, 0xffff0000, v158
	v_lshlrev_b32_e32 v82, 16, v159
	v_and_b32_e32 v83, 0xffff0000, v159
	v_lshlrev_b32_e32 v84, 16, v160
	v_and_b32_e32 v85, 0xffff0000, v160
	v_lshlrev_b32_e32 v86, 16, v161
	v_and_b32_e32 v87, 0xffff0000, v161
	v_lshlrev_b32_e32 v88, 16, v162
	v_and_b32_e32 v89, 0xffff0000, v162
	v_lshlrev_b32_e32 v90, 16, v163
	v_and_b32_e32 v91, 0xffff0000, v163
	v_lshlrev_b32_e32 v92, 16, v164
	v_and_b32_e32 v93, 0xffff0000, v164
	v_lshlrev_b32_e32 v94, 16, v165
	v_and_b32_e32 v95, 0xffff0000, v165
	v_mul_f32_e32 v96, v81, v81
	v_mul_f32_e32 v97, v83, v83
	v_fmac_f32_e32 v96, v80, v80
	v_fmac_f32_e32 v97, v82, v82
	v_add_f32_e32 v98, v96, v97
	v_mul_f32_e32 v96, v85, v85
	v_mul_f32_e32 v97, v87, v87
	v_fmac_f32_e32 v96, v84, v84
	v_fmac_f32_e32 v97, v86, v86
	v_add_f32_e32 v96, v96, v97
	v_add_f32_e32 v98, v98, v96
	v_mul_f32_e32 v96, v89, v89
	v_mul_f32_e32 v97, v91, v91
	v_fmac_f32_e32 v96, v88, v88
	v_fmac_f32_e32 v97, v90, v90
	v_add_f32_e32 v96, v96, v97
	v_add_f32_e32 v98, v98, v96
	v_mul_f32_e32 v96, v93, v93
	v_mul_f32_e32 v97, v95, v95
	v_fmac_f32_e32 v96, v92, v92
	v_fmac_f32_e32 v97, v94, v94
	v_add_f32_e32 v96, v96, v97
	v_add_f32_e32 v98, v98, v96
	s_nop 1
	v_add_f32_dpp v98, v98, v98 quad_perm:[1,0,3,2] row_mask:0xf bank_mask:0xf bound_ctrl:1
	s_nop 1
	v_add_f32_dpp v98, v98, v98 quad_perm:[2,3,0,1] row_mask:0xf bank_mask:0xf bound_ctrl:1
	s_nop 1
	v_add_f32_dpp v98, v98, v98 row_half_mirror row_mask:0xf bank_mask:0xf bound_ctrl:1
	s_nop 1
	v_add_f32_dpp v98, v98, v98 row_mirror row_mask:0xf bank_mask:0xf bound_ctrl:1
	v_mov_b32_e32 v96, v98
	s_nop 1
	v_permlane16_swap_b32_e32 v98, v96
	v_add_f32_e32 v98, v98, v96
	v_mov_b32_e32 v96, v98
	s_nop 1
	v_permlane32_swap_b32_e32 v98, v96
	v_add_f32_e32 v98, v98, v96
	v_fmamk_f32 v100, v98, 0x3a800000, v153
	v_rsq_f32_e32 v100, v100
	s_nop 0
	v_pk_mul_f32 v[80:81], v[80:81], v[100:101] op_sel_hi:[1,0]
	v_pk_mul_f32 v[82:83], v[82:83], v[100:101] op_sel_hi:[1,0]
	v_pk_mul_f32 v[84:85], v[84:85], v[100:101] op_sel_hi:[1,0]
	v_pk_mul_f32 v[86:87], v[86:87], v[100:101] op_sel_hi:[1,0]
	v_pk_mul_f32 v[88:89], v[88:89], v[100:101] op_sel_hi:[1,0]
	v_pk_mul_f32 v[90:91], v[90:91], v[100:101] op_sel_hi:[1,0]
	v_pk_mul_f32 v[92:93], v[92:93], v[100:101] op_sel_hi:[1,0]
	v_pk_mul_f32 v[94:95], v[94:95], v[100:101] op_sel_hi:[1,0]
	v_pk_mul_f32 v[80:81], v[0:1], v[80:81]
	v_pk_mul_f32 v[82:83], v[2:3], v[82:83]
	v_pk_mul_f32 v[84:85], v[4:5], v[84:85]
	v_pk_mul_f32 v[86:87], v[6:7], v[86:87]
	v_pk_mul_f32 v[88:89], v[8:9], v[88:89]
	v_pk_mul_f32 v[90:91], v[10:11], v[90:91]
	v_pk_mul_f32 v[92:93], v[12:13], v[92:93]
	v_pk_mul_f32 v[94:95], v[14:15], v[94:95]
	v_pk_fma_f32 v[80:81], v[64:65], v[80:81], v[48:49]
	v_pk_fma_f32 v[82:83], v[66:67], v[82:83], v[50:51]
; __device__ __forceinline__ unsigned pkbf(float lo, float hi) { f32x2_t v = {lo, hi}; bf16x2_t b = __builtin_convertvector(v, bf16x2_t); return __builtin_bit_cast(unsigned, b); }
; __device__ __forceinline__ void norm_phase(const void* src_lat, int lat_f32, const float* src_ctx, int nrows, const float* gvec, const float* mods_l, int sh_off, int sc_off, bf16_t* U, const float* part, int nparts, float* ctx_out) {
;     ...
;         if (row < MLAT && !lat_f32) { const bf16_t* src = (const bf16_t*)src_lat + (size_t)row * DM + 4 * lane;
; #pragma unroll
;             for (int j = 0; j < 4; ++j) { const u32x2 w = *(const u32x2*)(src + 256 * j);
;                 v[j] = (f32x4){__uint_as_float(w.x << 16), __uint_as_float(w.x & 0xffff0000u), __uint_as_float(w.y << 16), __uint_as_float(w.y & 0xffff0000u)}; } }
;     ...
;         for (int j = 0; j < 4; ++j) { ss += (v[j][0] * v[j][0] + v[j][1] * v[j][1]) + (v[j][2] * v[j][2] + v[j][3] * v[j][3]); }
;         if (nparts != 0 && row >= MLAT) {
;             for (int ch = 0; ch < nparts; ch += 4) {
;                 f32x4 pv[4][4];
; #pragma unroll
;                 for (int c4 = 0; c4 < 4; ++c4) { const float* pr = part + ((size_t)(ch + c4) * MCTX + (row - MLAT)) * DM + 4 * lane;
; #pragma unroll
;                     for (int j = 0; j < 4; ++j) pv[c4][j] = *(const f32x4*)(pr + 256 * j); }
; #pragma unroll
;                 for (int c4 = 0; c4 < 4; ++c4)
; #pragma unroll
;                     for (int j = 0; j < 4; ++j) v[j] = v[j] + pv[c4][j]; }
;             ss = 0.f;
; #pragma unroll
;             for (int j = 0; j < 4; ++j) { *(f32x4*)(ctx_out + (size_t)(row - MLAT) * DM + 4 * lane + 256 * j) = v[j]; ss += (v[j][0] * v[j][0] + v[j][1] * v[j][1]) + (v[j][2] * v[j][2] + v[j][3] * v[j][3]); }
;         }
;         const float rs = rsqrtf(wave_sum64(ss) * (1.0f / DM) + EPS);
;         const float* shp = mods_l + s * 6144 + sh_off + 4 * lane; const float* scp = mods_l + s * 6144 + sc_off + 4 * lane;
;         bf16_t* up = U + (size_t)row * DM + 4 * lane;
; #pragma unroll
;         for (int j = 0; j < 4; ++j) { const f32x4 sh = *(const f32x4*)(shp + 256 * j), sc = *(const f32x4*)(scp + 256 * j);
;             const f32x4 y = v[j] * rs * gv[j] * (sc + 1.0f) + sh;
;             u32x2 o; o.x = pkbf(y[0], y[1]); o.y = pkbf(y[2], y[3]); *(u32x2*)(up + 256 * j) = o; }
	v_pk_fma_f32 v[84:85], v[68:69], v[84:85], v[52:53]
	v_pk_fma_f32 v[86:87], v[70:71], v[86:87], v[54:55]
	v_pk_fma_f32 v[88:89], v[72:73], v[88:89], v[56:57]
	v_pk_fma_f32 v[90:91], v[74:75], v[90:91], v[58:59]
	v_pk_fma_f32 v[92:93], v[76:77], v[92:93], v[60:61]
	v_pk_fma_f32 v[94:95], v[78:79], v[94:95], v[62:63]
	v_cvt_pk_bf16_f32 v80, v80, v81
	v_cvt_pk_bf16_f32 v81, v82, v83
	v_cvt_pk_bf16_f32 v84, v84, v85
	v_cvt_pk_bf16_f32 v85, v86, v87
	v_cvt_pk_bf16_f32 v88, v88, v89
	v_cvt_pk_bf16_f32 v89, v90, v91
	v_cvt_pk_bf16_f32 v92, v92, v93
	v_cvt_pk_bf16_f32 v93, v94, v95
	global_store_dwordx2 v102, v[80:81], s[40:41]
	global_store_dwordx2 v102, v[84:85], s[40:41] offset:512
	global_store_dwordx2 v102, v[88:89], s[40:41] offset:1024
	global_store_dwordx2 v102, v[92:93], s[40:41] offset:1536
	s_add_u32 s40, s40, 0x400000
	s_addc_u32 s41, s41, 0
	global_load_dwordx2 v[158:159], v102, s[38:39]
	global_load_dwordx2 v[160:161], v102, s[38:39] offset:512
	global_load_dwordx2 v[162:163], v102, s[38:39] offset:1024
	global_load_dwordx2 v[164:165], v102, s[38:39] offset:1536
	s_add_u32 s38, s38, 0x400000
	s_addc_u32 s39, s39, 0
	global_load_dwordx4 v[112:115], v103, s[42:43]
	global_load_dwordx4 v[116:119], v103, s[42:43] offset:1024
	global_load_dwordx4 v[120:123], v103, s[42:43] offset:2048
	global_load_dwordx4 v[124:127], v103, s[42:43] offset:3072
	global_load_dwordx4 v[128:131], v103, s[44:45]
	global_load_dwordx4 v[132:135], v103, s[44:45] offset:1024
	global_load_dwordx4 v[136:139], v103, s[44:45] offset:2048
	global_load_dwordx4 v[140:143], v103, s[44:45] offset:3072
	s_add_u32 s42, s42, 0x6000
	s_addc_u32 s43, s43, 0
	s_add_u32 s44, s44, 0x6000
	s_addc_u32 s45, s45, 0
	s_waitcnt vmcnt(32)
	v_lshlrev_b32_e32 v80, 16, v166
	v_and_b32_e32 v81, 0xffff0000, v166
	v_lshlrev_b32_e32 v82, 16, v167
	v_and_b32_e32 v83, 0xffff0000, v167
	v_lshlrev_b32_e32 v84, 16, v168
	v_and_b32_e32 v85, 0xffff0000, v168
	v_lshlrev_b32_e32 v86, 16, v169
	v_and_b32_e32 v87, 0xffff0000, v169
	v_lshlrev_b32_e32 v88, 16, v170
	v_and_b32_e32 v89, 0xffff0000, v170
	v_lshlrev_b32_e32 v90, 16, v171
	v_and_b32_e32 v91, 0xffff0000, v171
	v_lshlrev_b32_e32 v92, 16, v172
	v_and_b32_e32 v93, 0xffff0000, v172
	v_lshlrev_b32_e32 v94, 16, v173
	v_and_b32_e32 v95, 0xffff0000, v173
	v_mul_f32_e32 v96, v81, v81
	v_mul_f32_e32 v97, v83, v83
	v_fmac_f32_e32 v96, v80, v80
	v_fmac_f32_e32 v97, v82, v82
	v_add_f32_e32 v98, v96, v97
	v_mul_f32_e32 v96, v85, v85
	v_mul_f32_e32 v97, v87, v87
	v_fmac_f32_e32 v96, v84, v84
	v_fmac_f32_e32 v97, v86, v86
	v_add_f32_e32 v96, v96, v97
	v_add_f32_e32 v98, v98, v96
	v_mul_f32_e32 v96, v89, v89
	v_mul_f32_e32 v97, v91, v91
	v_fmac_f32_e32 v96, v88, v88
	v_fmac_f32_e32 v97, v90, v90
	v_add_f32_e32 v96, v96, v97
	v_add_f32_e32 v98, v98, v96
	v_mul_f32_e32 v96, v93, v93
	v_mul_f32_e32 v97, v95, v95
	v_fmac_f32_e32 v96, v92, v92
	v_fmac_f32_e32 v97, v94, v94
	v_add_f32_e32 v96, v96, v97
	v_add_f32_e32 v98, v98, v96
	s_nop 1
	v_add_f32_dpp v98, v98, v98 quad_perm:[1,0,3,2] row_mask:0xf bank_mask:0xf bound_ctrl:1
	s_nop 1
	v_add_f32_dpp v98, v98, v98 quad_perm:[2,3,0,1] row_mask:0xf bank_mask:0xf bound_ctrl:1
	s_nop 1
	v_add_f32_dpp v98, v98, v98 row_half_mirror row_mask:0xf bank_mask:0xf bound_ctrl:1
	s_nop 1
	v_add_f32_dpp v98, v98, v98 row_mirror row_mask:0xf bank_mask:0xf bound_ctrl:1
	v_mov_b32_e32 v96, v98
	s_nop 1
	v_permlane16_swap_b32_e32 v98, v96
	v_add_f32_e32 v98, v98, v96
	v_mov_b32_e32 v96, v98
	s_nop 1
	v_permlane32_swap_b32_e32 v98, v96
	v_add_f32_e32 v98, v98, v96
	v_fmamk_f32 v100, v98, 0x3a800000, v153
	v_rsq_f32_e32 v100, v100
	s_nop 0
	v_pk_mul_f32 v[80:81], v[80:81], v[100:101] op_sel_hi:[1,0]
	v_pk_mul_f32 v[82:83], v[82:83], v[100:101] op_sel_hi:[1,0]
	v_pk_mul_f32 v[84:85], v[84:85], v[100:101] op_sel_hi:[1,0]
	v_pk_mul_f32 v[86:87], v[86:87], v[100:101] op_sel_hi:[1,0]
	v_pk_mul_f32 v[88:89], v[88:89], v[100:101] op_sel_hi:[1,0]
	v_pk_mul_f32 v[90:91], v[90:91], v[100:101] op_sel_hi:[1,0]
	v_pk_mul_f32 v[92:93], v[92:93], v[100:101] op_sel_hi:[1,0]
	v_pk_mul_f32 v[94:95], v[94:95], v[100:101] op_sel_hi:[1,0]
	v_pk_mul_f32 v[80:81], v[0:1], v[80:81]
	v_pk_mul_f32 v[82:83], v[2:3], v[82:83]
	v_pk_mul_f32 v[84:85], v[4:5], v[84:85]
	v_pk_mul_f32 v[86:87], v[6:7], v[86:87]
	v_pk_mul_f32 v[88:89], v[8:9], v[88:89]
	v_pk_mul_f32 v[90:91], v[10:11], v[90:91]
	v_pk_mul_f32 v[92:93], v[12:13], v[92:93]
	v_pk_mul_f32 v[94:95], v[14:15], v[94:95]
	v_pk_fma_f32 v[80:81], v[64:65], v[80:81], v[48:49]
	v_pk_fma_f32 v[82:83], v[66:67], v[82:83], v[50:51]
	v_pk_fma_f32 v[84:85], v[68:69], v[84:85], v[52:53]
	v_pk_fma_f32 v[86:87], v[70:71], v[86:87], v[54:55]
	v_pk_fma_f32 v[88:89], v[72:73], v[88:89], v[56:57]
	v_pk_fma_f32 v[90:91], v[74:75], v[90:91], v[58:59]
	v_pk_fma_f32 v[92:93], v[76:77], v[92:93], v[60:61]
	v_pk_fma_f32 v[94:95], v[78:79], v[94:95], v[62:63]
	v_cvt_pk_bf16_f32 v80, v80, v81
	v_cvt_pk_bf16_f32 v81, v82, v83
	v_cvt_pk_bf16_f32 v84, v84, v85
	v_cvt_pk_bf16_f32 v85, v86, v87
	v_cvt_pk_bf16_f32 v88, v88, v89
	v_cvt_pk_bf16_f32 v89, v90, v91
	v_cvt_pk_bf16_f32 v92, v92, v93
	v_cvt_pk_bf16_f32 v93, v94, v95
	global_store_dwordx2 v102, v[80:81], s[40:41]
	global_store_dwordx2 v102, v[84:85], s[40:41] offset:512
	global_store_dwordx2 v102, v[88:89], s[40:41] offset:1024
	global_store_dwordx2 v102, v[92:93], s[40:41] offset:1536
	s_add_u32 s40, s40, 0x400000
	s_addc_u32 s41, s41, 0
	global_load_dwordx2 v[166:167], v102, s[38:39]
	global_load_dwordx2 v[168:169], v102, s[38:39] offset:512
	global_load_dwordx2 v[170:171], v102, s[38:39] offset:1024
	global_load_dwordx2 v[172:173], v102, s[38:39] offset:1536
	s_add_u32 s38, s38, 0x400000
	s_addc_u32 s39, s39, 0
	s_waitcnt vmcnt(32)
; __device__ __forceinline__ unsigned pkbf(float lo, float hi) { f32x2_t v = {lo, hi}; bf16x2_t b = __builtin_convertvector(v, bf16x2_t); return __builtin_bit_cast(unsigned, b); }
; __device__ __forceinline__ void norm_phase(const void* src_lat, int lat_f32, const float* src_ctx, int nrows, const float* gvec, const float* mods_l, int sh_off, int sc_off, bf16_t* U, const float* part, int nparts, float* ctx_out) {
;     ...
;         if (row < MLAT && !lat_f32) { const bf16_t* src = (const bf16_t*)src_lat + (size_t)row * DM + 4 * lane;
; #pragma unroll
;             for (int j = 0; j < 4; ++j) { const u32x2 w = *(const u32x2*)(src + 256 * j);
;                 v[j] = (f32x4){__uint_as_float(w.x << 16), __uint_as_float(w.x & 0xffff0000u), __uint_as_float(w.y << 16), __uint_as_float(w.y & 0xffff0000u)}; } }
;     ...
;         for (int j = 0; j < 4; ++j) { ss += (v[j][0] * v[j][0] + v[j][1] * v[j][1]) + (v[j][2] * v[j][2] + v[j][3] * v[j][3]); }
;         if (nparts != 0 && row >= MLAT) {
;             for (int ch = 0; ch < nparts; ch += 4) {
;                 f32x4 pv[4][4];
; #pragma unroll
;                 for (int c4 = 0; c4 < 4; ++c4) { const float* pr = part + ((size_t)(ch + c4) * MCTX + (row - MLAT)) * DM + 4 * lane;
; #pragma unroll
;                     for (int j = 0; j < 4; ++j) pv[c4][j] = *(const f32x4*)(pr + 256 * j); }
; #pragma unroll
;                 for (int c4 = 0; c4 < 4; ++c4)
; #pragma unroll
;                     for (int j = 0; j < 4; ++j) v[j] = v[j] + pv[c4][j]; }
;             ss = 0.f;
; #pragma unroll
;             for (int j = 0; j < 4; ++j) { *(f32x4*)(ctx_out + (size_t)(row - MLAT) * DM + 4 * lane + 256 * j) = v[j]; ss += (v[j][0] * v[j][0] + v[j][1] * v[j][1]) + (v[j][2] * v[j][2] + v[j][3] * v[j][3]); }
;         }
;         const float rs = rsqrtf(wave_sum64(ss) * (1.0f / DM) + EPS);
;         const float* shp = mods_l + s * 6144 + sh_off + 4 * lane; const float* scp = mods_l + s * 6144 + sc_off + 4 * lane;
;         bf16_t* up = U + (size_t)row * DM + 4 * lane;
; #pragma unroll
;         for (int j = 0; j < 4; ++j) { const f32x4 sh = *(const f32x4*)(shp + 256 * j), sc = *(const f32x4*)(scp + 256 * j);
;             const f32x4 y = v[j] * rs * gv[j] * (sc + 1.0f) + sh;
;             u32x2 o; o.x = pkbf(y[0], y[1]); o.y = pkbf(y[2], y[3]); *(u32x2*)(up + 256 * j) = o; }
	v_lshlrev_b32_e32 v80, 16, v174
	v_and_b32_e32 v81, 0xffff0000, v174
	v_lshlrev_b32_e32 v82, 16, v175
	v_and_b32_e32 v83, 0xffff0000, v175
	v_lshlrev_b32_e32 v84, 16, v176
	v_and_b32_e32 v85, 0xffff0000, v176
	v_lshlrev_b32_e32 v86, 16, v177
	v_and_b32_e32 v87, 0xffff0000, v177
	v_lshlrev_b32_e32 v88, 16, v178
	v_and_b32_e32 v89, 0xffff0000, v178
	v_lshlrev_b32_e32 v90, 16, v179
	v_and_b32_e32 v91, 0xffff0000, v179
	v_lshlrev_b32_e32 v92, 16, v180
	v_and_b32_e32 v93, 0xffff0000, v180
	v_lshlrev_b32_e32 v94, 16, v181
	v_and_b32_e32 v95, 0xffff0000, v181
	v_mul_f32_e32 v96, v81, v81
	v_mul_f32_e32 v97, v83, v83
	v_fmac_f32_e32 v96, v80, v80
	v_fmac_f32_e32 v97, v82, v82
	v_add_f32_e32 v98, v96, v97
	v_mul_f32_e32 v96, v85, v85
	v_mul_f32_e32 v97, v87, v87
	v_fmac_f32_e32 v96, v84, v84
	v_fmac_f32_e32 v97, v86, v86
	v_add_f32_e32 v96, v96, v97
	v_add_f32_e32 v98, v98, v96
	v_mul_f32_e32 v96, v89, v89
	v_mul_f32_e32 v97, v91, v91
	v_fmac_f32_e32 v96, v88, v88
	v_fmac_f32_e32 v97, v90, v90
	v_add_f32_e32 v96, v96, v97
	v_add_f32_e32 v98, v98, v96
	v_mul_f32_e32 v96, v93, v93
	v_mul_f32_e32 v97, v95, v95
	v_fmac_f32_e32 v96, v92, v92
	v_fmac_f32_e32 v97, v94, v94
	v_add_f32_e32 v96, v96, v97
	v_add_f32_e32 v98, v98, v96
	s_nop 1
	v_add_f32_dpp v98, v98, v98 quad_perm:[1,0,3,2] row_mask:0xf bank_mask:0xf bound_ctrl:1
	s_nop 1
	v_add_f32_dpp v98, v98, v98 quad_perm:[2,3,0,1] row_mask:0xf bank_mask:0xf bound_ctrl:1
	s_nop 1
	v_add_f32_dpp v98, v98, v98 row_half_mirror row_mask:0xf bank_mask:0xf bound_ctrl:1
	s_nop 1
	v_add_f32_dpp v98, v98, v98 row_mirror row_mask:0xf bank_mask:0xf bound_ctrl:1
	v_mov_b32_e32 v96, v98
	s_nop 1
	v_permlane16_swap_b32_e32 v98, v96
	v_add_f32_e32 v98, v98, v96
	v_mov_b32_e32 v96, v98
	s_nop 1
	v_permlane32_swap_b32_e32 v98, v96
	v_add_f32_e32 v98, v98, v96
	v_fmamk_f32 v100, v98, 0x3a800000, v153
	v_rsq_f32_e32 v100, v100
	s_nop 0
	v_pk_mul_f32 v[80:81], v[80:81], v[100:101] op_sel_hi:[1,0]
	v_pk_mul_f32 v[82:83], v[82:83], v[100:101] op_sel_hi:[1,0]
	v_pk_mul_f32 v[84:85], v[84:85], v[100:101] op_sel_hi:[1,0]
	v_pk_mul_f32 v[86:87], v[86:87], v[100:101] op_sel_hi:[1,0]
	v_pk_mul_f32 v[88:89], v[88:89], v[100:101] op_sel_hi:[1,0]
	v_pk_mul_f32 v[90:91], v[90:91], v[100:101] op_sel_hi:[1,0]
	v_pk_mul_f32 v[92:93], v[92:93], v[100:101] op_sel_hi:[1,0]
	v_pk_mul_f32 v[94:95], v[94:95], v[100:101] op_sel_hi:[1,0]
	v_pk_mul_f32 v[80:81], v[0:1], v[80:81]
	v_pk_mul_f32 v[82:83], v[2:3], v[82:83]
	v_pk_mul_f32 v[84:85], v[4:5], v[84:85]
	v_pk_mul_f32 v[86:87], v[6:7], v[86:87]
	v_pk_mul_f32 v[88:89], v[8:9], v[88:89]
	v_pk_mul_f32 v[90:91], v[10:11], v[90:91]
	v_pk_mul_f32 v[92:93], v[12:13], v[92:93]
	v_pk_mul_f32 v[94:95], v[14:15], v[94:95]
	v_pk_fma_f32 v[80:81], v[64:65], v[80:81], v[48:49]
	v_pk_fma_f32 v[82:83], v[66:67], v[82:83], v[50:51]
	v_pk_fma_f32 v[84:85], v[68:69], v[84:85], v[52:53]
	v_pk_fma_f32 v[86:87], v[70:71], v[86:87], v[54:55]
	v_pk_fma_f32 v[88:89], v[72:73], v[88:89], v[56:57]
	v_pk_fma_f32 v[90:91], v[74:75], v[90:91], v[58:59]
	v_pk_fma_f32 v[92:93], v[76:77], v[92:93], v[60:61]
	v_pk_fma_f32 v[94:95], v[78:79], v[94:95], v[62:63]
	v_cvt_pk_bf16_f32 v80, v80, v81
	v_cvt_pk_bf16_f32 v81, v82, v83
	v_cvt_pk_bf16_f32 v84, v84, v85
	v_cvt_pk_bf16_f32 v85, v86, v87
	v_cvt_pk_bf16_f32 v88, v88, v89
	v_cvt_pk_bf16_f32 v89, v90, v91
	v_cvt_pk_bf16_f32 v92, v92, v93
	v_cvt_pk_bf16_f32 v93, v94, v95
	global_store_dwordx2 v102, v[80:81], s[40:41]
	global_store_dwordx2 v102, v[84:85], s[40:41] offset:512
	global_store_dwordx2 v102, v[88:89], s[40:41] offset:1024
	global_store_dwordx2 v102, v[92:93], s[40:41] offset:1536
	s_add_u32 s40, s40, 0x400000
	s_addc_u32 s41, s41, 0
	global_load_dwordx2 v[174:175], v102, s[38:39]
	global_load_dwordx2 v[176:177], v102, s[38:39] offset:512
	global_load_dwordx2 v[178:179], v102, s[38:39] offset:1024
	global_load_dwordx2 v[180:181], v102, s[38:39] offset:1536
	s_add_u32 s38, s38, 0x400000
	s_addc_u32 s39, s39, 0
	s_waitcnt vmcnt(32)
	v_lshlrev_b32_e32 v80, 16, v182
	v_and_b32_e32 v81, 0xffff0000, v182
	v_lshlrev_b32_e32 v82, 16, v183
	v_and_b32_e32 v83, 0xffff0000, v183
	v_lshlrev_b32_e32 v84, 16, v184
	v_and_b32_e32 v85, 0xffff0000, v184
	v_lshlrev_b32_e32 v86, 16, v185
	v_and_b32_e32 v87, 0xffff0000, v185
	v_lshlrev_b32_e32 v88, 16, v186
	v_and_b32_e32 v89, 0xffff0000, v186
	v_lshlrev_b32_e32 v90, 16, v187
	v_and_b32_e32 v91, 0xffff0000, v187
	v_lshlrev_b32_e32 v92, 16, v188
	v_and_b32_e32 v93, 0xffff0000, v188
	v_lshlrev_b32_e32 v94, 16, v189
	v_and_b32_e32 v95, 0xffff0000, v189
	v_mul_f32_e32 v96, v81, v81
	v_mul_f32_e32 v97, v83, v83
	v_fmac_f32_e32 v96, v80, v80
	v_fmac_f32_e32 v97, v82, v82
	v_add_f32_e32 v98, v96, v97
	v_mul_f32_e32 v96, v85, v85
	v_mul_f32_e32 v97, v87, v87
	v_fmac_f32_e32 v96, v84, v84
	v_fmac_f32_e32 v97, v86, v86
	v_add_f32_e32 v96, v96, v97
	v_add_f32_e32 v98, v98, v96
	v_mul_f32_e32 v96, v89, v89
	v_mul_f32_e32 v97, v91, v91
	v_fmac_f32_e32 v96, v88, v88
	v_fmac_f32_e32 v97, v90, v90
	v_add_f32_e32 v96, v96, v97
	v_add_f32_e32 v98, v98, v96
	v_mul_f32_e32 v96, v93, v93
	v_mul_f32_e32 v97, v95, v95
	v_fmac_f32_e32 v96, v92, v92
	v_fmac_f32_e32 v97, v94, v94
	v_add_f32_e32 v96, v96, v97
	v_add_f32_e32 v98, v98, v96
	s_nop 1
	v_add_f32_dpp v98, v98, v98 quad_perm:[1,0,3,2] row_mask:0xf bank_mask:0xf bound_ctrl:1
	s_nop 1
	v_add_f32_dpp v98, v98, v98 quad_perm:[2,3,0,1] row_mask:0xf bank_mask:0xf bound_ctrl:1
	s_nop 1
	v_add_f32_dpp v98, v98, v98 row_half_mirror row_mask:0xf bank_mask:0xf bound_ctrl:1
	s_nop 1
	v_add_f32_dpp v98, v98, v98 row_mirror row_mask:0xf bank_mask:0xf bound_ctrl:1
	v_mov_b32_e32 v96, v98
	s_nop 1
; __device__ __forceinline__ unsigned pkbf(float lo, float hi) { f32x2_t v = {lo, hi}; bf16x2_t b = __builtin_convertvector(v, bf16x2_t); return __builtin_bit_cast(unsigned, b); }
; __device__ __forceinline__ void norm_phase(const void* src_lat, int lat_f32, const float* src_ctx, int nrows, const float* gvec, const float* mods_l, int sh_off, int sc_off, bf16_t* U, const float* part, int nparts, float* ctx_out) {
;     ...
;         if (row < MLAT && !lat_f32) { const bf16_t* src = (const bf16_t*)src_lat + (size_t)row * DM + 4 * lane;
; #pragma unroll
;             for (int j = 0; j < 4; ++j) { const u32x2 w = *(const u32x2*)(src + 256 * j);
;                 v[j] = (f32x4){__uint_as_float(w.x << 16), __uint_as_float(w.x & 0xffff0000u), __uint_as_float(w.y << 16), __uint_as_float(w.y & 0xffff0000u)}; } }
;     ...
;         for (int j = 0; j < 4; ++j) { ss += (v[j][0] * v[j][0] + v[j][1] * v[j][1]) + (v[j][2] * v[j][2] + v[j][3] * v[j][3]); }
;         if (nparts != 0 && row >= MLAT) {
;             for (int ch = 0; ch < nparts; ch += 4) {
;                 f32x4 pv[4][4];
; #pragma unroll
;                 for (int c4 = 0; c4 < 4; ++c4) { const float* pr = part + ((size_t)(ch + c4) * MCTX + (row - MLAT)) * DM + 4 * lane;
; #pragma unroll
;                     for (int j = 0; j < 4; ++j) pv[c4][j] = *(const f32x4*)(pr + 256 * j); }
; #pragma unroll
;                 for (int c4 = 0; c4 < 4; ++c4)
; #pragma unroll
;                     for (int j = 0; j < 4; ++j) v[j] = v[j] + pv[c4][j]; }
;             ss = 0.f;
; #pragma unroll
;             for (int j = 0; j < 4; ++j) { *(f32x4*)(ctx_out + (size_t)(row - MLAT) * DM + 4 * lane + 256 * j) = v[j]; ss += (v[j][0] * v[j][0] + v[j][1] * v[j][1]) + (v[j][2] * v[j][2] + v[j][3] * v[j][3]); }
;         }
;         const float rs = rsqrtf(wave_sum64(ss) * (1.0f / DM) + EPS);
;         const float* shp = mods_l + s * 6144 + sh_off + 4 * lane; const float* scp = mods_l + s * 6144 + sc_off + 4 * lane;
;         bf16_t* up = U + (size_t)row * DM + 4 * lane;
; #pragma unroll
;         for (int j = 0; j < 4; ++j) { const f32x4 sh = *(const f32x4*)(shp + 256 * j), sc = *(const f32x4*)(scp + 256 * j);
;             const f32x4 y = v[j] * rs * gv[j] * (sc + 1.0f) + sh;
;             u32x2 o; o.x = pkbf(y[0], y[1]); o.y = pkbf(y[2], y[3]); *(u32x2*)(up + 256 * j) = o; }
	v_permlane16_swap_b32_e32 v98, v96
	v_add_f32_e32 v98, v98, v96
	v_mov_b32_e32 v96, v98
	s_nop 1
	v_permlane32_swap_b32_e32 v98, v96
	v_add_f32_e32 v98, v98, v96
	v_fmamk_f32 v100, v98, 0x3a800000, v153
	v_rsq_f32_e32 v100, v100
	s_nop 0
	v_pk_mul_f32 v[80:81], v[80:81], v[100:101] op_sel_hi:[1,0]
	v_pk_mul_f32 v[82:83], v[82:83], v[100:101] op_sel_hi:[1,0]
	v_pk_mul_f32 v[84:85], v[84:85], v[100:101] op_sel_hi:[1,0]
	v_pk_mul_f32 v[86:87], v[86:87], v[100:101] op_sel_hi:[1,0]
	v_pk_mul_f32 v[88:89], v[88:89], v[100:101] op_sel_hi:[1,0]
	v_pk_mul_f32 v[90:91], v[90:91], v[100:101] op_sel_hi:[1,0]
	v_pk_mul_f32 v[92:93], v[92:93], v[100:101] op_sel_hi:[1,0]
	v_pk_mul_f32 v[94:95], v[94:95], v[100:101] op_sel_hi:[1,0]
	v_pk_mul_f32 v[80:81], v[0:1], v[80:81]
	v_pk_mul_f32 v[82:83], v[2:3], v[82:83]
	v_pk_mul_f32 v[84:85], v[4:5], v[84:85]
	v_pk_mul_f32 v[86:87], v[6:7], v[86:87]
	v_pk_mul_f32 v[88:89], v[8:9], v[88:89]
	v_pk_mul_f32 v[90:91], v[10:11], v[90:91]
	v_pk_mul_f32 v[92:93], v[12:13], v[92:93]
	v_pk_mul_f32 v[94:95], v[14:15], v[94:95]
	v_pk_fma_f32 v[80:81], v[64:65], v[80:81], v[48:49]
	v_pk_fma_f32 v[82:83], v[66:67], v[82:83], v[50:51]
	v_pk_fma_f32 v[84:85], v[68:69], v[84:85], v[52:53]
	v_pk_fma_f32 v[86:87], v[70:71], v[86:87], v[54:55]
	v_pk_fma_f32 v[88:89], v[72:73], v[88:89], v[56:57]
	v_pk_fma_f32 v[90:91], v[74:75], v[90:91], v[58:59]
	v_pk_fma_f32 v[92:93], v[76:77], v[92:93], v[60:61]
	v_pk_fma_f32 v[94:95], v[78:79], v[94:95], v[62:63]
	v_cvt_pk_bf16_f32 v80, v80, v81
	v_cvt_pk_bf16_f32 v81, v82, v83
	v_cvt_pk_bf16_f32 v84, v84, v85
	v_cvt_pk_bf16_f32 v85, v86, v87
	v_cvt_pk_bf16_f32 v88, v88, v89
	v_cvt_pk_bf16_f32 v89, v90, v91
	v_cvt_pk_bf16_f32 v92, v92, v93
	v_cvt_pk_bf16_f32 v93, v94, v95
	global_store_dwordx2 v102, v[80:81], s[40:41]
	global_store_dwordx2 v102, v[84:85], s[40:41] offset:512
	global_store_dwordx2 v102, v[88:89], s[40:41] offset:1024
	global_store_dwordx2 v102, v[92:93], s[40:41] offset:1536
	s_add_u32 s40, s40, 0x400000
	s_addc_u32 s41, s41, 0
	global_load_dwordx2 v[182:183], v102, s[38:39]
	global_load_dwordx2 v[184:185], v102, s[38:39] offset:512
	global_load_dwordx2 v[186:187], v102, s[38:39] offset:1024
	global_load_dwordx2 v[188:189], v102, s[38:39] offset:1536
	s_add_u32 s38, s38, 0x400000
	s_addc_u32 s39, s39, 0
	s_waitcnt vmcnt(24)
	v_pk_add_f32 v[128:129], v[128:129], 1.0 op_sel_hi:[1,0]
	v_pk_add_f32 v[130:131], v[130:131], 1.0 op_sel_hi:[1,0]
	v_pk_add_f32 v[132:133], v[132:133], 1.0 op_sel_hi:[1,0]
	v_pk_add_f32 v[134:135], v[134:135], 1.0 op_sel_hi:[1,0]
	v_pk_add_f32 v[136:137], v[136:137], 1.0 op_sel_hi:[1,0]
	v_pk_add_f32 v[138:139], v[138:139], 1.0 op_sel_hi:[1,0]
	v_pk_add_f32 v[140:141], v[140:141], 1.0 op_sel_hi:[1,0]
	v_pk_add_f32 v[142:143], v[142:143], 1.0 op_sel_hi:[1,0]
	v_lshlrev_b32_e32 v80, 16, v158
	v_and_b32_e32 v81, 0xffff0000, v158
	v_lshlrev_b32_e32 v82, 16, v159
	v_and_b32_e32 v83, 0xffff0000, v159
	v_lshlrev_b32_e32 v84, 16, v160
	v_and_b32_e32 v85, 0xffff0000, v160
	v_lshlrev_b32_e32 v86, 16, v161
	v_and_b32_e32 v87, 0xffff0000, v161
	v_lshlrev_b32_e32 v88, 16, v162
	v_and_b32_e32 v89, 0xffff0000, v162
	v_lshlrev_b32_e32 v90, 16, v163
	v_and_b32_e32 v91, 0xffff0000, v163
	v_lshlrev_b32_e32 v92, 16, v164
	v_and_b32_e32 v93, 0xffff0000, v164
	v_lshlrev_b32_e32 v94, 16, v165
	v_and_b32_e32 v95, 0xffff0000, v165
	v_mul_f32_e32 v96, v81, v81
	v_mul_f32_e32 v97, v83, v83
	v_fmac_f32_e32 v96, v80, v80
	v_fmac_f32_e32 v97, v82, v82
	v_add_f32_e32 v98, v96, v97
	v_mul_f32_e32 v96, v85, v85
	v_mul_f32_e32 v97, v87, v87
	v_fmac_f32_e32 v96, v84, v84
	v_fmac_f32_e32 v97, v86, v86
	v_add_f32_e32 v96, v96, v97
	v_add_f32_e32 v98, v98, v96
	v_mul_f32_e32 v96, v89, v89
	v_mul_f32_e32 v97, v91, v91
	v_fmac_f32_e32 v96, v88, v88
	v_fmac_f32_e32 v97, v90, v90
	v_add_f32_e32 v96, v96, v97
	v_add_f32_e32 v98, v98, v96
	v_mul_f32_e32 v96, v93, v93
	v_mul_f32_e32 v97, v95, v95
	v_fmac_f32_e32 v96, v92, v92
	v_fmac_f32_e32 v97, v94, v94
	v_add_f32_e32 v96, v96, v97
	v_add_f32_e32 v98, v98, v96
	s_nop 1
	v_add_f32_dpp v98, v98, v98 quad_perm:[1,0,3,2] row_mask:0xf bank_mask:0xf bound_ctrl:1
	s_nop 1
	v_add_f32_dpp v98, v98, v98 quad_perm:[2,3,0,1] row_mask:0xf bank_mask:0xf bound_ctrl:1
	s_nop 1
	v_add_f32_dpp v98, v98, v98 row_half_mirror row_mask:0xf bank_mask:0xf bound_ctrl:1
	s_nop 1
	v_add_f32_dpp v98, v98, v98 row_mirror row_mask:0xf bank_mask:0xf bound_ctrl:1
	v_mov_b32_e32 v96, v98
	s_nop 1
	v_permlane16_swap_b32_e32 v98, v96
	v_add_f32_e32 v98, v98, v96
	v_mov_b32_e32 v96, v98
	s_nop 1
	v_permlane32_swap_b32_e32 v98, v96
	v_add_f32_e32 v98, v98, v96
	v_fmamk_f32 v100, v98, 0x3a800000, v153
	v_rsq_f32_e32 v100, v100
	s_nop 0
	v_pk_mul_f32 v[80:81], v[80:81], v[100:101] op_sel_hi:[1,0]
	v_pk_mul_f32 v[82:83], v[82:83], v[100:101] op_sel_hi:[1,0]
	v_pk_mul_f32 v[84:85], v[84:85], v[100:101] op_sel_hi:[1,0]
	v_pk_mul_f32 v[86:87], v[86:87], v[100:101] op_sel_hi:[1,0]
	v_pk_mul_f32 v[88:89], v[88:89], v[100:101] op_sel_hi:[1,0]
	v_pk_mul_f32 v[90:91], v[90:91], v[100:101] op_sel_hi:[1,0]
	v_pk_mul_f32 v[92:93], v[92:93], v[100:101] op_sel_hi:[1,0]
	v_pk_mul_f32 v[94:95], v[94:95], v[100:101] op_sel_hi:[1,0]
	v_pk_mul_f32 v[80:81], v[0:1], v[80:81]
	v_pk_mul_f32 v[82:83], v[2:3], v[82:83]
	v_pk_mul_f32 v[84:85], v[4:5], v[84:85]
	v_pk_mul_f32 v[86:87], v[6:7], v[86:87]
	v_pk_mul_f32 v[88:89], v[8:9], v[88:89]
	v_pk_mul_f32 v[90:91], v[10:11], v[90:91]
	v_pk_mul_f32 v[92:93], v[12:13], v[92:93]
	v_pk_mul_f32 v[94:95], v[14:15], v[94:95]
	v_pk_fma_f32 v[80:81], v[128:129], v[80:81], v[112:113]
	v_pk_fma_f32 v[82:83], v[130:131], v[82:83], v[114:115]
; __device__ __forceinline__ unsigned pkbf(float lo, float hi) { f32x2_t v = {lo, hi}; bf16x2_t b = __builtin_convertvector(v, bf16x2_t); return __builtin_bit_cast(unsigned, b); }
; __device__ __forceinline__ void norm_phase(const void* src_lat, int lat_f32, const float* src_ctx, int nrows, const float* gvec, const float* mods_l, int sh_off, int sc_off, bf16_t* U, const float* part, int nparts, float* ctx_out) {
;     ...
;         if (row < MLAT && !lat_f32) { const bf16_t* src = (const bf16_t*)src_lat + (size_t)row * DM + 4 * lane;
; #pragma unroll
;             for (int j = 0; j < 4; ++j) { const u32x2 w = *(const u32x2*)(src + 256 * j);
;                 v[j] = (f32x4){__uint_as_float(w.x << 16), __uint_as_float(w.x & 0xffff0000u), __uint_as_float(w.y << 16), __uint_as_float(w.y & 0xffff0000u)}; } }
;     ...
;         for (int j = 0; j < 4; ++j) { ss += (v[j][0] * v[j][0] + v[j][1] * v[j][1]) + (v[j][2] * v[j][2] + v[j][3] * v[j][3]); }
;         if (nparts != 0 && row >= MLAT) {
;             for (int ch = 0; ch < nparts; ch += 4) {
;                 f32x4 pv[4][4];
; #pragma unroll
;                 for (int c4 = 0; c4 < 4; ++c4) { const float* pr = part + ((size_t)(ch + c4) * MCTX + (row - MLAT)) * DM + 4 * lane;
; #pragma unroll
;                     for (int j = 0; j < 4; ++j) pv[c4][j] = *(const f32x4*)(pr + 256 * j); }
; #pragma unroll
;                 for (int c4 = 0; c4 < 4; ++c4)
; #pragma unroll
;                     for (int j = 0; j < 4; ++j) v[j] = v[j] + pv[c4][j]; }
;             ss = 0.f;
; #pragma unroll
;             for (int j = 0; j < 4; ++j) { *(f32x4*)(ctx_out + (size_t)(row - MLAT) * DM + 4 * lane + 256 * j) = v[j]; ss += (v[j][0] * v[j][0] + v[j][1] * v[j][1]) + (v[j][2] * v[j][2] + v[j][3] * v[j][3]); }
;         }
;         const float rs = rsqrtf(wave_sum64(ss) * (1.0f / DM) + EPS);
;         const float* shp = mods_l + s * 6144 + sh_off + 4 * lane; const float* scp = mods_l + s * 6144 + sc_off + 4 * lane;
;         bf16_t* up = U + (size_t)row * DM + 4 * lane;
; #pragma unroll
;         for (int j = 0; j < 4; ++j) { const f32x4 sh = *(const f32x4*)(shp + 256 * j), sc = *(const f32x4*)(scp + 256 * j);
;             const f32x4 y = v[j] * rs * gv[j] * (sc + 1.0f) + sh;
;             u32x2 o; o.x = pkbf(y[0], y[1]); o.y = pkbf(y[2], y[3]); *(u32x2*)(up + 256 * j) = o; }
	v_pk_fma_f32 v[84:85], v[132:133], v[84:85], v[116:117]
	v_pk_fma_f32 v[86:87], v[134:135], v[86:87], v[118:119]
	v_pk_fma_f32 v[88:89], v[136:137], v[88:89], v[120:121]
	v_pk_fma_f32 v[90:91], v[138:139], v[90:91], v[122:123]
	v_pk_fma_f32 v[92:93], v[140:141], v[92:93], v[124:125]
	v_pk_fma_f32 v[94:95], v[142:143], v[94:95], v[126:127]
	v_cvt_pk_bf16_f32 v80, v80, v81
	v_cvt_pk_bf16_f32 v81, v82, v83
	v_cvt_pk_bf16_f32 v84, v84, v85
	v_cvt_pk_bf16_f32 v85, v86, v87
	v_cvt_pk_bf16_f32 v88, v88, v89
	v_cvt_pk_bf16_f32 v89, v90, v91
	v_cvt_pk_bf16_f32 v92, v92, v93
	v_cvt_pk_bf16_f32 v93, v94, v95
	global_store_dwordx2 v102, v[80:81], s[40:41]
	global_store_dwordx2 v102, v[84:85], s[40:41] offset:512
	global_store_dwordx2 v102, v[88:89], s[40:41] offset:1024
	global_store_dwordx2 v102, v[92:93], s[40:41] offset:1536
	s_add_u32 s40, s40, 0x400000
	s_addc_u32 s41, s41, 0
	global_load_dwordx2 v[158:159], v102, s[38:39]
	global_load_dwordx2 v[160:161], v102, s[38:39] offset:512
	global_load_dwordx2 v[162:163], v102, s[38:39] offset:1024
	global_load_dwordx2 v[164:165], v102, s[38:39] offset:1536
	s_add_u32 s38, s38, 0x400000
	s_addc_u32 s39, s39, 0
	global_load_dwordx4 v[48:51], v103, s[42:43]
	global_load_dwordx4 v[52:55], v103, s[42:43] offset:1024
	global_load_dwordx4 v[56:59], v103, s[42:43] offset:2048
	global_load_dwordx4 v[60:63], v103, s[42:43] offset:3072
	global_load_dwordx4 v[64:67], v103, s[44:45]
	global_load_dwordx4 v[68:71], v103, s[44:45] offset:1024
	global_load_dwordx4 v[72:75], v103, s[44:45] offset:2048
	global_load_dwordx4 v[76:79], v103, s[44:45] offset:3072
	s_add_u32 s42, s42, 0x6000
	s_addc_u32 s43, s43, 0
	s_add_u32 s44, s44, 0x6000
	s_addc_u32 s45, s45, 0
	s_waitcnt vmcnt(32)
	v_lshlrev_b32_e32 v80, 16, v166
	v_and_b32_e32 v81, 0xffff0000, v166
	v_lshlrev_b32_e32 v82, 16, v167
	v_and_b32_e32 v83, 0xffff0000, v167
	v_lshlrev_b32_e32 v84, 16, v168
	v_and_b32_e32 v85, 0xffff0000, v168
	v_lshlrev_b32_e32 v86, 16, v169
	v_and_b32_e32 v87, 0xffff0000, v169
	v_lshlrev_b32_e32 v88, 16, v170
	v_and_b32_e32 v89, 0xffff0000, v170
	v_lshlrev_b32_e32 v90, 16, v171
	v_and_b32_e32 v91, 0xffff0000, v171
	v_lshlrev_b32_e32 v92, 16, v172
	v_and_b32_e32 v93, 0xffff0000, v172
	v_lshlrev_b32_e32 v94, 16, v173
	v_and_b32_e32 v95, 0xffff0000, v173
	v_mul_f32_e32 v96, v81, v81
	v_mul_f32_e32 v97, v83, v83
	v_fmac_f32_e32 v96, v80, v80
	v_fmac_f32_e32 v97, v82, v82
	v_add_f32_e32 v98, v96, v97
	v_mul_f32_e32 v96, v85, v85
	v_mul_f32_e32 v97, v87, v87
	v_fmac_f32_e32 v96, v84, v84
	v_fmac_f32_e32 v97, v86, v86
	v_add_f32_e32 v96, v96, v97
	v_add_f32_e32 v98, v98, v96
	v_mul_f32_e32 v96, v89, v89
	v_mul_f32_e32 v97, v91, v91
	v_fmac_f32_e32 v96, v88, v88
	v_fmac_f32_e32 v97, v90, v90
	v_add_f32_e32 v96, v96, v97
	v_add_f32_e32 v98, v98, v96
	v_mul_f32_e32 v96, v93, v93
	v_mul_f32_e32 v97, v95, v95
	v_fmac_f32_e32 v96, v92, v92
	v_fmac_f32_e32 v97, v94, v94
	v_add_f32_e32 v96, v96, v97
	v_add_f32_e32 v98, v98, v96
	s_nop 1
	v_add_f32_dpp v98, v98, v98 quad_perm:[1,0,3,2] row_mask:0xf bank_mask:0xf bound_ctrl:1
	s_nop 1
	v_add_f32_dpp v98, v98, v98 quad_perm:[2,3,0,1] row_mask:0xf bank_mask:0xf bound_ctrl:1
	s_nop 1
	v_add_f32_dpp v98, v98, v98 row_half_mirror row_mask:0xf bank_mask:0xf bound_ctrl:1
	s_nop 1
	v_add_f32_dpp v98, v98, v98 row_mirror row_mask:0xf bank_mask:0xf bound_ctrl:1
	v_mov_b32_e32 v96, v98
	s_nop 1
	v_permlane16_swap_b32_e32 v98, v96
	v_add_f32_e32 v98, v98, v96
	v_mov_b32_e32 v96, v98
	s_nop 1
	v_permlane32_swap_b32_e32 v98, v96
	v_add_f32_e32 v98, v98, v96
	v_fmamk_f32 v100, v98, 0x3a800000, v153
	v_rsq_f32_e32 v100, v100
	s_nop 0
	v_pk_mul_f32 v[80:81], v[80:81], v[100:101] op_sel_hi:[1,0]
	v_pk_mul_f32 v[82:83], v[82:83], v[100:101] op_sel_hi:[1,0]
	v_pk_mul_f32 v[84:85], v[84:85], v[100:101] op_sel_hi:[1,0]
	v_pk_mul_f32 v[86:87], v[86:87], v[100:101] op_sel_hi:[1,0]
	v_pk_mul_f32 v[88:89], v[88:89], v[100:101] op_sel_hi:[1,0]
	v_pk_mul_f32 v[90:91], v[90:91], v[100:101] op_sel_hi:[1,0]
	v_pk_mul_f32 v[92:93], v[92:93], v[100:101] op_sel_hi:[1,0]
	v_pk_mul_f32 v[94:95], v[94:95], v[100:101] op_sel_hi:[1,0]
	v_pk_mul_f32 v[80:81], v[0:1], v[80:81]
	v_pk_mul_f32 v[82:83], v[2:3], v[82:83]
	v_pk_mul_f32 v[84:85], v[4:5], v[84:85]
	v_pk_mul_f32 v[86:87], v[6:7], v[86:87]
	v_pk_mul_f32 v[88:89], v[8:9], v[88:89]
	v_pk_mul_f32 v[90:91], v[10:11], v[90:91]
	v_pk_mul_f32 v[92:93], v[12:13], v[92:93]
	v_pk_mul_f32 v[94:95], v[14:15], v[94:95]
	v_pk_fma_f32 v[80:81], v[128:129], v[80:81], v[112:113]
	v_pk_fma_f32 v[82:83], v[130:131], v[82:83], v[114:115]
	v_pk_fma_f32 v[84:85], v[132:133], v[84:85], v[116:117]
	v_pk_fma_f32 v[86:87], v[134:135], v[86:87], v[118:119]
	v_pk_fma_f32 v[88:89], v[136:137], v[88:89], v[120:121]
	v_pk_fma_f32 v[90:91], v[138:139], v[90:91], v[122:123]
	v_pk_fma_f32 v[92:93], v[140:141], v[92:93], v[124:125]
	v_pk_fma_f32 v[94:95], v[142:143], v[94:95], v[126:127]
	v_cvt_pk_bf16_f32 v80, v80, v81
	v_cvt_pk_bf16_f32 v81, v82, v83
	v_cvt_pk_bf16_f32 v84, v84, v85
	v_cvt_pk_bf16_f32 v85, v86, v87
	v_cvt_pk_bf16_f32 v88, v88, v89
	v_cvt_pk_bf16_f32 v89, v90, v91
	v_cvt_pk_bf16_f32 v92, v92, v93
	v_cvt_pk_bf16_f32 v93, v94, v95
	global_store_dwordx2 v102, v[80:81], s[40:41]
	global_store_dwordx2 v102, v[84:85], s[40:41] offset:512
	global_store_dwordx2 v102, v[88:89], s[40:41] offset:1024
	global_store_dwordx2 v102, v[92:93], s[40:41] offset:1536
	s_add_u32 s40, s40, 0x400000
	s_addc_u32 s41, s41, 0
	global_load_dwordx2 v[166:167], v102, s[38:39]
	global_load_dwordx2 v[168:169], v102, s[38:39] offset:512
	global_load_dwordx2 v[170:171], v102, s[38:39] offset:1024
	global_load_dwordx2 v[172:173], v102, s[38:39] offset:1536
	s_add_u32 s38, s38, 0x400000
	s_addc_u32 s39, s39, 0
	s_waitcnt vmcnt(32)
; __device__ __forceinline__ unsigned pkbf(float lo, float hi) { f32x2_t v = {lo, hi}; bf16x2_t b = __builtin_convertvector(v, bf16x2_t); return __builtin_bit_cast(unsigned, b); }
; __device__ __forceinline__ void norm_phase(const void* src_lat, int lat_f32, const float* src_ctx, int nrows, const float* gvec, const float* mods_l, int sh_off, int sc_off, bf16_t* U, const float* part, int nparts, float* ctx_out) {
;     ...
;         if (row < MLAT && !lat_f32) { const bf16_t* src = (const bf16_t*)src_lat + (size_t)row * DM + 4 * lane;
; #pragma unroll
;             for (int j = 0; j < 4; ++j) { const u32x2 w = *(const u32x2*)(src + 256 * j);
;                 v[j] = (f32x4){__uint_as_float(w.x << 16), __uint_as_float(w.x & 0xffff0000u), __uint_as_float(w.y << 16), __uint_as_float(w.y & 0xffff0000u)}; } }
;     ...
;         for (int j = 0; j < 4; ++j) { ss += (v[j][0] * v[j][0] + v[j][1] * v[j][1]) + (v[j][2] * v[j][2] + v[j][3] * v[j][3]); }
;         if (nparts != 0 && row >= MLAT) {
;             for (int ch = 0; ch < nparts; ch += 4) {
;                 f32x4 pv[4][4];
; #pragma unroll
;                 for (int c4 = 0; c4 < 4; ++c4) { const float* pr = part + ((size_t)(ch + c4) * MCTX + (row - MLAT)) * DM + 4 * lane;
; #pragma unroll
;                     for (int j = 0; j < 4; ++j) pv[c4][j] = *(const f32x4*)(pr + 256 * j); }
; #pragma unroll
;                 for (int c4 = 0; c4 < 4; ++c4)
; #pragma unroll
;                     for (int j = 0; j < 4; ++j) v[j] = v[j] + pv[c4][j]; }
;             ss = 0.f;
; #pragma unroll
;             for (int j = 0; j < 4; ++j) { *(f32x4*)(ctx_out + (size_t)(row - MLAT) * DM + 4 * lane + 256 * j) = v[j]; ss += (v[j][0] * v[j][0] + v[j][1] * v[j][1]) + (v[j][2] * v[j][2] + v[j][3] * v[j][3]); }
;         }
;         const float rs = rsqrtf(wave_sum64(ss) * (1.0f / DM) + EPS);
;         const float* shp = mods_l + s * 6144 + sh_off + 4 * lane; const float* scp = mods_l + s * 6144 + sc_off + 4 * lane;
;         bf16_t* up = U + (size_t)row * DM + 4 * lane;
; #pragma unroll
;         for (int j = 0; j < 4; ++j) { const f32x4 sh = *(const f32x4*)(shp + 256 * j), sc = *(const f32x4*)(scp + 256 * j);
;             const f32x4 y = v[j] * rs * gv[j] * (sc + 1.0f) + sh;
;             u32x2 o; o.x = pkbf(y[0], y[1]); o.y = pkbf(y[2], y[3]); *(u32x2*)(up + 256 * j) = o; }
	v_lshlrev_b32_e32 v80, 16, v174
	v_and_b32_e32 v81, 0xffff0000, v174
	v_lshlrev_b32_e32 v82, 16, v175
	v_and_b32_e32 v83, 0xffff0000, v175
	v_lshlrev_b32_e32 v84, 16, v176
	v_and_b32_e32 v85, 0xffff0000, v176
	v_lshlrev_b32_e32 v86, 16, v177
	v_and_b32_e32 v87, 0xffff0000, v177
	v_lshlrev_b32_e32 v88, 16, v178
	v_and_b32_e32 v89, 0xffff0000, v178
	v_lshlrev_b32_e32 v90, 16, v179
	v_and_b32_e32 v91, 0xffff0000, v179
	v_lshlrev_b32_e32 v92, 16, v180
	v_and_b32_e32 v93, 0xffff0000, v180
	v_lshlrev_b32_e32 v94, 16, v181
	v_and_b32_e32 v95, 0xffff0000, v181
	v_mul_f32_e32 v96, v81, v81
	v_mul_f32_e32 v97, v83, v83
	v_fmac_f32_e32 v96, v80, v80
	v_fmac_f32_e32 v97, v82, v82
	v_add_f32_e32 v98, v96, v97
	v_mul_f32_e32 v96, v85, v85
	v_mul_f32_e32 v97, v87, v87
	v_fmac_f32_e32 v96, v84, v84
	v_fmac_f32_e32 v97, v86, v86
	v_add_f32_e32 v96, v96, v97
	v_add_f32_e32 v98, v98, v96
	v_mul_f32_e32 v96, v89, v89
	v_mul_f32_e32 v97, v91, v91
	v_fmac_f32_e32 v96, v88, v88
	v_fmac_f32_e32 v97, v90, v90
	v_add_f32_e32 v96, v96, v97
	v_add_f32_e32 v98, v98, v96
	v_mul_f32_e32 v96, v93, v93
	v_mul_f32_e32 v97, v95, v95
	v_fmac_f32_e32 v96, v92, v92
	v_fmac_f32_e32 v97, v94, v94
	v_add_f32_e32 v96, v96, v97
	v_add_f32_e32 v98, v98, v96
	s_nop 1
	v_add_f32_dpp v98, v98, v98 quad_perm:[1,0,3,2] row_mask:0xf bank_mask:0xf bound_ctrl:1
	s_nop 1
	v_add_f32_dpp v98, v98, v98 quad_perm:[2,3,0,1] row_mask:0xf bank_mask:0xf bound_ctrl:1
	s_nop 1
	v_add_f32_dpp v98, v98, v98 row_half_mirror row_mask:0xf bank_mask:0xf bound_ctrl:1
	s_nop 1
	v_add_f32_dpp v98, v98, v98 row_mirror row_mask:0xf bank_mask:0xf bound_ctrl:1
	v_mov_b32_e32 v96, v98
	s_nop 1
	v_permlane16_swap_b32_e32 v98, v96
	v_add_f32_e32 v98, v98, v96
	v_mov_b32_e32 v96, v98
	s_nop 1
	v_permlane32_swap_b32_e32 v98, v96
	v_add_f32_e32 v98, v98, v96
	v_fmamk_f32 v100, v98, 0x3a800000, v153
	v_rsq_f32_e32 v100, v100
	s_nop 0
	v_pk_mul_f32 v[80:81], v[80:81], v[100:101] op_sel_hi:[1,0]
	v_pk_mul_f32 v[82:83], v[82:83], v[100:101] op_sel_hi:[1,0]
	v_pk_mul_f32 v[84:85], v[84:85], v[100:101] op_sel_hi:[1,0]
	v_pk_mul_f32 v[86:87], v[86:87], v[100:101] op_sel_hi:[1,0]
	v_pk_mul_f32 v[88:89], v[88:89], v[100:101] op_sel_hi:[1,0]
	v_pk_mul_f32 v[90:91], v[90:91], v[100:101] op_sel_hi:[1,0]
	v_pk_mul_f32 v[92:93], v[92:93], v[100:101] op_sel_hi:[1,0]
	v_pk_mul_f32 v[94:95], v[94:95], v[100:101] op_sel_hi:[1,0]
	v_pk_mul_f32 v[80:81], v[0:1], v[80:81]
	v_pk_mul_f32 v[82:83], v[2:3], v[82:83]
	v_pk_mul_f32 v[84:85], v[4:5], v[84:85]
	v_pk_mul_f32 v[86:87], v[6:7], v[86:87]
	v_pk_mul_f32 v[88:89], v[8:9], v[88:89]
	v_pk_mul_f32 v[90:91], v[10:11], v[90:91]
	v_pk_mul_f32 v[92:93], v[12:13], v[92:93]
	v_pk_mul_f32 v[94:95], v[14:15], v[94:95]
	v_pk_fma_f32 v[80:81], v[128:129], v[80:81], v[112:113]
	v_pk_fma_f32 v[82:83], v[130:131], v[82:83], v[114:115]
	v_pk_fma_f32 v[84:85], v[132:133], v[84:85], v[116:117]
	v_pk_fma_f32 v[86:87], v[134:135], v[86:87], v[118:119]
	v_pk_fma_f32 v[88:89], v[136:137], v[88:89], v[120:121]
	v_pk_fma_f32 v[90:91], v[138:139], v[90:91], v[122:123]
	v_pk_fma_f32 v[92:93], v[140:141], v[92:93], v[124:125]
	v_pk_fma_f32 v[94:95], v[142:143], v[94:95], v[126:127]
	v_cvt_pk_bf16_f32 v80, v80, v81
	v_cvt_pk_bf16_f32 v81, v82, v83
	v_cvt_pk_bf16_f32 v84, v84, v85
	v_cvt_pk_bf16_f32 v85, v86, v87
	v_cvt_pk_bf16_f32 v88, v88, v89
	v_cvt_pk_bf16_f32 v89, v90, v91
	v_cvt_pk_bf16_f32 v92, v92, v93
	v_cvt_pk_bf16_f32 v93, v94, v95
	global_store_dwordx2 v102, v[80:81], s[40:41]
	global_store_dwordx2 v102, v[84:85], s[40:41] offset:512
	global_store_dwordx2 v102, v[88:89], s[40:41] offset:1024
	global_store_dwordx2 v102, v[92:93], s[40:41] offset:1536
	s_add_u32 s40, s40, 0x400000
	s_addc_u32 s41, s41, 0
	global_load_dwordx2 v[174:175], v102, s[38:39]
	global_load_dwordx2 v[176:177], v102, s[38:39] offset:512
	global_load_dwordx2 v[178:179], v102, s[38:39] offset:1024
	global_load_dwordx2 v[180:181], v102, s[38:39] offset:1536
	s_add_u32 s38, s38, 0x400000
	s_addc_u32 s39, s39, 0
	s_waitcnt vmcnt(32)
	v_lshlrev_b32_e32 v80, 16, v182
	v_and_b32_e32 v81, 0xffff0000, v182
	v_lshlrev_b32_e32 v82, 16, v183
	v_and_b32_e32 v83, 0xffff0000, v183
	v_lshlrev_b32_e32 v84, 16, v184
	v_and_b32_e32 v85, 0xffff0000, v184
	v_lshlrev_b32_e32 v86, 16, v185
	v_and_b32_e32 v87, 0xffff0000, v185
	v_lshlrev_b32_e32 v88, 16, v186
	v_and_b32_e32 v89, 0xffff0000, v186
	v_lshlrev_b32_e32 v90, 16, v187
	v_and_b32_e32 v91, 0xffff0000, v187
	v_lshlrev_b32_e32 v92, 16, v188
	v_and_b32_e32 v93, 0xffff0000, v188
	v_lshlrev_b32_e32 v94, 16, v189
	v_and_b32_e32 v95, 0xffff0000, v189
	v_mul_f32_e32 v96, v81, v81
	v_mul_f32_e32 v97, v83, v83
	v_fmac_f32_e32 v96, v80, v80
	v_fmac_f32_e32 v97, v82, v82
	v_add_f32_e32 v98, v96, v97
	v_mul_f32_e32 v96, v85, v85
	v_mul_f32_e32 v97, v87, v87
	v_fmac_f32_e32 v96, v84, v84
	v_fmac_f32_e32 v97, v86, v86
	v_add_f32_e32 v96, v96, v97
	v_add_f32_e32 v98, v98, v96
	v_mul_f32_e32 v96, v89, v89
	v_mul_f32_e32 v97, v91, v91
	v_fmac_f32_e32 v96, v88, v88
	v_fmac_f32_e32 v97, v90, v90
	v_add_f32_e32 v96, v96, v97
	v_add_f32_e32 v98, v98, v96
	v_mul_f32_e32 v96, v93, v93
	v_mul_f32_e32 v97, v95, v95
	v_fmac_f32_e32 v96, v92, v92
	v_fmac_f32_e32 v97, v94, v94
	v_add_f32_e32 v96, v96, v97
	v_add_f32_e32 v98, v98, v96
	s_nop 1
	v_add_f32_dpp v98, v98, v98 quad_perm:[1,0,3,2] row_mask:0xf bank_mask:0xf bound_ctrl:1
	s_nop 1
	v_add_f32_dpp v98, v98, v98 quad_perm:[2,3,0,1] row_mask:0xf bank_mask:0xf bound_ctrl:1
	s_nop 1
	v_add_f32_dpp v98, v98, v98 row_half_mirror row_mask:0xf bank_mask:0xf bound_ctrl:1
	s_nop 1
	v_add_f32_dpp v98, v98, v98 row_mirror row_mask:0xf bank_mask:0xf bound_ctrl:1
	v_mov_b32_e32 v96, v98
; __device__ __forceinline__ unsigned pkbf(float lo, float hi) { f32x2_t v = {lo, hi}; bf16x2_t b = __builtin_convertvector(v, bf16x2_t); return __builtin_bit_cast(unsigned, b); }
; __device__ __forceinline__ void norm_phase(const void* src_lat, int lat_f32, const float* src_ctx, int nrows, const float* gvec, const float* mods_l, int sh_off, int sc_off, bf16_t* U, const float* part, int nparts, float* ctx_out) {
;     ...
;         if (row < MLAT && !lat_f32) { const bf16_t* src = (const bf16_t*)src_lat + (size_t)row * DM + 4 * lane;
; #pragma unroll
;             for (int j = 0; j < 4; ++j) { const u32x2 w = *(const u32x2*)(src + 256 * j);
;                 v[j] = (f32x4){__uint_as_float(w.x << 16), __uint_as_float(w.x & 0xffff0000u), __uint_as_float(w.y << 16), __uint_as_float(w.y & 0xffff0000u)}; } }
;     ...
;         for (int j = 0; j < 4; ++j) { ss += (v[j][0] * v[j][0] + v[j][1] * v[j][1]) + (v[j][2] * v[j][2] + v[j][3] * v[j][3]); }
;         if (nparts != 0 && row >= MLAT) {
;             for (int ch = 0; ch < nparts; ch += 4) {
;                 f32x4 pv[4][4];
; #pragma unroll
;                 for (int c4 = 0; c4 < 4; ++c4) { const float* pr = part + ((size_t)(ch + c4) * MCTX + (row - MLAT)) * DM + 4 * lane;
; #pragma unroll
;                     for (int j = 0; j < 4; ++j) pv[c4][j] = *(const f32x4*)(pr + 256 * j); }
; #pragma unroll
;                 for (int c4 = 0; c4 < 4; ++c4)
; #pragma unroll
;                     for (int j = 0; j < 4; ++j) v[j] = v[j] + pv[c4][j]; }
;             ss = 0.f;
; #pragma unroll
;             for (int j = 0; j < 4; ++j) { *(f32x4*)(ctx_out + (size_t)(row - MLAT) * DM + 4 * lane + 256 * j) = v[j]; ss += (v[j][0] * v[j][0] + v[j][1] * v[j][1]) + (v[j][2] * v[j][2] + v[j][3] * v[j][3]); }
;         }
;         const float rs = rsqrtf(wave_sum64(ss) * (1.0f / DM) + EPS);
;         const float* shp = mods_l + s * 6144 + sh_off + 4 * lane; const float* scp = mods_l + s * 6144 + sc_off + 4 * lane;
;         bf16_t* up = U + (size_t)row * DM + 4 * lane;
; #pragma unroll
;         for (int j = 0; j < 4; ++j) { const f32x4 sh = *(const f32x4*)(shp + 256 * j), sc = *(const f32x4*)(scp + 256 * j);
;             const f32x4 y = v[j] * rs * gv[j] * (sc + 1.0f) + sh;
;             u32x2 o; o.x = pkbf(y[0], y[1]); o.y = pkbf(y[2], y[3]); *(u32x2*)(up + 256 * j) = o; }
	s_nop 1
	v_permlane16_swap_b32_e32 v98, v96
	v_add_f32_e32 v98, v98, v96
	v_mov_b32_e32 v96, v98
	s_nop 1
	v_permlane32_swap_b32_e32 v98, v96
	v_add_f32_e32 v98, v98, v96
	v_fmamk_f32 v100, v98, 0x3a800000, v153
	v_rsq_f32_e32 v100, v100
	s_nop 0
	v_pk_mul_f32 v[80:81], v[80:81], v[100:101] op_sel_hi:[1,0]
	v_pk_mul_f32 v[82:83], v[82:83], v[100:101] op_sel_hi:[1,0]
	v_pk_mul_f32 v[84:85], v[84:85], v[100:101] op_sel_hi:[1,0]
	v_pk_mul_f32 v[86:87], v[86:87], v[100:101] op_sel_hi:[1,0]
	v_pk_mul_f32 v[88:89], v[88:89], v[100:101] op_sel_hi:[1,0]
	v_pk_mul_f32 v[90:91], v[90:91], v[100:101] op_sel_hi:[1,0]
	v_pk_mul_f32 v[92:93], v[92:93], v[100:101] op_sel_hi:[1,0]
	v_pk_mul_f32 v[94:95], v[94:95], v[100:101] op_sel_hi:[1,0]
	v_pk_mul_f32 v[80:81], v[0:1], v[80:81]
	v_pk_mul_f32 v[82:83], v[2:3], v[82:83]
	v_pk_mul_f32 v[84:85], v[4:5], v[84:85]
	v_pk_mul_f32 v[86:87], v[6:7], v[86:87]
	v_pk_mul_f32 v[88:89], v[8:9], v[88:89]
	v_pk_mul_f32 v[90:91], v[10:11], v[90:91]
	v_pk_mul_f32 v[92:93], v[12:13], v[92:93]
	v_pk_mul_f32 v[94:95], v[14:15], v[94:95]
	v_pk_fma_f32 v[80:81], v[128:129], v[80:81], v[112:113]
	v_pk_fma_f32 v[82:83], v[130:131], v[82:83], v[114:115]
	v_pk_fma_f32 v[84:85], v[132:133], v[84:85], v[116:117]
	v_pk_fma_f32 v[86:87], v[134:135], v[86:87], v[118:119]
	v_pk_fma_f32 v[88:89], v[136:137], v[88:89], v[120:121]
	v_pk_fma_f32 v[90:91], v[138:139], v[90:91], v[122:123]
	v_pk_fma_f32 v[92:93], v[140:141], v[92:93], v[124:125]
	v_pk_fma_f32 v[94:95], v[142:143], v[94:95], v[126:127]
	v_cvt_pk_bf16_f32 v80, v80, v81
	v_cvt_pk_bf16_f32 v81, v82, v83
	v_cvt_pk_bf16_f32 v84, v84, v85
	v_cvt_pk_bf16_f32 v85, v86, v87
	v_cvt_pk_bf16_f32 v88, v88, v89
	v_cvt_pk_bf16_f32 v89, v90, v91
	v_cvt_pk_bf16_f32 v92, v92, v93
	v_cvt_pk_bf16_f32 v93, v94, v95
	global_store_dwordx2 v102, v[80:81], s[40:41]
	global_store_dwordx2 v102, v[84:85], s[40:41] offset:512
	global_store_dwordx2 v102, v[88:89], s[40:41] offset:1024
	global_store_dwordx2 v102, v[92:93], s[40:41] offset:1536
	s_add_u32 s40, s40, 0x400000
	s_addc_u32 s41, s41, 0
	global_load_dwordx2 v[182:183], v102, s[38:39]
	global_load_dwordx2 v[184:185], v102, s[38:39] offset:512
	global_load_dwordx2 v[186:187], v102, s[38:39] offset:1024
	global_load_dwordx2 v[188:189], v102, s[38:39] offset:1536
	s_add_u32 s38, s38, 0x400000
	s_addc_u32 s39, s39, 0
	s_waitcnt vmcnt(24)
	v_pk_add_f32 v[64:65], v[64:65], 1.0 op_sel_hi:[1,0]
	v_pk_add_f32 v[66:67], v[66:67], 1.0 op_sel_hi:[1,0]
	v_pk_add_f32 v[68:69], v[68:69], 1.0 op_sel_hi:[1,0]
	v_pk_add_f32 v[70:71], v[70:71], 1.0 op_sel_hi:[1,0]
	v_pk_add_f32 v[72:73], v[72:73], 1.0 op_sel_hi:[1,0]
	v_pk_add_f32 v[74:75], v[74:75], 1.0 op_sel_hi:[1,0]
	v_pk_add_f32 v[76:77], v[76:77], 1.0 op_sel_hi:[1,0]
	v_pk_add_f32 v[78:79], v[78:79], 1.0 op_sel_hi:[1,0]
	v_lshlrev_b32_e32 v80, 16, v158
	v_and_b32_e32 v81, 0xffff0000, v158
	v_lshlrev_b32_e32 v82, 16, v159
	v_and_b32_e32 v83, 0xffff0000, v159
	v_lshlrev_b32_e32 v84, 16, v160
	v_and_b32_e32 v85, 0xffff0000, v160
	v_lshlrev_b32_e32 v86, 16, v161
	v_and_b32_e32 v87, 0xffff0000, v161
	v_lshlrev_b32_e32 v88, 16, v162
	v_and_b32_e32 v89, 0xffff0000, v162
	v_lshlrev_b32_e32 v90, 16, v163
	v_and_b32_e32 v91, 0xffff0000, v163
	v_lshlrev_b32_e32 v92, 16, v164
	v_and_b32_e32 v93, 0xffff0000, v164
	v_lshlrev_b32_e32 v94, 16, v165
	v_and_b32_e32 v95, 0xffff0000, v165
	v_mul_f32_e32 v96, v81, v81
	v_mul_f32_e32 v97, v83, v83
	v_fmac_f32_e32 v96, v80, v80
	v_fmac_f32_e32 v97, v82, v82
	v_add_f32_e32 v98, v96, v97
	v_mul_f32_e32 v96, v85, v85
	v_mul_f32_e32 v97, v87, v87
	v_fmac_f32_e32 v96, v84, v84
	v_fmac_f32_e32 v97, v86, v86
	v_add_f32_e32 v96, v96, v97
	v_add_f32_e32 v98, v98, v96
	v_mul_f32_e32 v96, v89, v89
	v_mul_f32_e32 v97, v91, v91
	v_fmac_f32_e32 v96, v88, v88
	v_fmac_f32_e32 v97, v90, v90
	v_add_f32_e32 v96, v96, v97
	v_add_f32_e32 v98, v98, v96
	v_mul_f32_e32 v96, v93, v93
	v_mul_f32_e32 v97, v95, v95
	v_fmac_f32_e32 v96, v92, v92
	v_fmac_f32_e32 v97, v94, v94
	v_add_f32_e32 v96, v96, v97
	v_add_f32_e32 v98, v98, v96
	s_nop 1
	v_add_f32_dpp v98, v98, v98 quad_perm:[1,0,3,2] row_mask:0xf bank_mask:0xf bound_ctrl:1
	s_nop 1
	v_add_f32_dpp v98, v98, v98 quad_perm:[2,3,0,1] row_mask:0xf bank_mask:0xf bound_ctrl:1
	s_nop 1
	v_add_f32_dpp v98, v98, v98 row_half_mirror row_mask:0xf bank_mask:0xf bound_ctrl:1
	s_nop 1
	v_add_f32_dpp v98, v98, v98 row_mirror row_mask:0xf bank_mask:0xf bound_ctrl:1
	v_mov_b32_e32 v96, v98
	s_nop 1
	v_permlane16_swap_b32_e32 v98, v96
	v_add_f32_e32 v98, v98, v96
	v_mov_b32_e32 v96, v98
	s_nop 1
	v_permlane32_swap_b32_e32 v98, v96
	v_add_f32_e32 v98, v98, v96
	v_fmamk_f32 v100, v98, 0x3a800000, v153
	v_rsq_f32_e32 v100, v100
	s_nop 0
	v_pk_mul_f32 v[80:81], v[80:81], v[100:101] op_sel_hi:[1,0]
	v_pk_mul_f32 v[82:83], v[82:83], v[100:101] op_sel_hi:[1,0]
	v_pk_mul_f32 v[84:85], v[84:85], v[100:101] op_sel_hi:[1,0]
	v_pk_mul_f32 v[86:87], v[86:87], v[100:101] op_sel_hi:[1,0]
	v_pk_mul_f32 v[88:89], v[88:89], v[100:101] op_sel_hi:[1,0]
	v_pk_mul_f32 v[90:91], v[90:91], v[100:101] op_sel_hi:[1,0]
	v_pk_mul_f32 v[92:93], v[92:93], v[100:101] op_sel_hi:[1,0]
	v_pk_mul_f32 v[94:95], v[94:95], v[100:101] op_sel_hi:[1,0]
	v_pk_mul_f32 v[80:81], v[0:1], v[80:81]
	v_pk_mul_f32 v[82:83], v[2:3], v[82:83]
	v_pk_mul_f32 v[84:85], v[4:5], v[84:85]
	v_pk_mul_f32 v[86:87], v[6:7], v[86:87]
	v_pk_mul_f32 v[88:89], v[8:9], v[88:89]
	v_pk_mul_f32 v[90:91], v[10:11], v[90:91]
	v_pk_mul_f32 v[92:93], v[12:13], v[92:93]
	v_pk_mul_f32 v[94:95], v[14:15], v[94:95]
	v_pk_fma_f32 v[80:81], v[64:65], v[80:81], v[48:49]
	v_pk_fma_f32 v[82:83], v[66:67], v[82:83], v[50:51]
	v_pk_fma_f32 v[84:85], v[68:69], v[84:85], v[52:53]
	v_pk_fma_f32 v[86:87], v[70:71], v[86:87], v[54:55]
	v_pk_fma_f32 v[88:89], v[72:73], v[88:89], v[56:57]
	v_pk_fma_f32 v[90:91], v[74:75], v[90:91], v[58:59]
	v_pk_fma_f32 v[92:93], v[76:77], v[92:93], v[60:61]
	v_pk_fma_f32 v[94:95], v[78:79], v[94:95], v[62:63]
	v_cvt_pk_bf16_f32 v80, v80, v81
	v_cvt_pk_bf16_f32 v81, v82, v83
	v_cvt_pk_bf16_f32 v84, v84, v85
	v_cvt_pk_bf16_f32 v85, v86, v87
	v_cvt_pk_bf16_f32 v88, v88, v89
	v_cvt_pk_bf16_f32 v89, v90, v91
	v_cvt_pk_bf16_f32 v92, v92, v93
	v_cvt_pk_bf16_f32 v93, v94, v95
	global_store_dwordx2 v102, v[80:81], s[40:41]
	global_store_dwordx2 v102, v[84:85], s[40:41] offset:512
	global_store_dwordx2 v102, v[88:89], s[40:41] offset:1024
	global_store_dwordx2 v102, v[92:93], s[40:41] offset:1536
	s_add_u32 s40, s40, 0x400000
	s_addc_u32 s41, s41, 0
	s_waitcnt vmcnt(20)
; __device__ __forceinline__ void norm_phase(const void* src_lat, int lat_f32, const float* src_ctx, int nrows, const float* gvec, const float* mods_l, int sh_off, int sc_off, bf16_t* U, const float* part, int nparts, float* ctx_out) {
;     ...
;         if (row < MLAT && !lat_f32) { const bf16_t* src = (const bf16_t*)src_lat + (size_t)row * DM + 4 * lane;
; #pragma unroll
;             for (int j = 0; j < 4; ++j) { const u32x2 w = *(const u32x2*)(src + 256 * j);
;                 v[j] = (f32x4){__uint_as_float(w.x << 16), __uint_as_float(w.x & 0xffff0000u), __uint_as_float(w.y << 16), __uint_as_float(w.y & 0xffff0000u)}; } }
;         else { const float* src = row < MLAT ? (const float*)src_lat + (size_t)row * DM : src_ctx + (size_t)(row - MLAT) * DM;
; #pragma unroll
;             for (int j = 0; j < 4; ++j) v[j] = *(const f32x4*)(src + 4 * lane + 256 * j); }
; #pragma unroll
;         for (int j = 0; j < 4; ++j) { ss += (v[j][0] * v[j][0] + v[j][1] * v[j][1]) + (v[j][2] * v[j][2] + v[j][3] * v[j][3]); }
;         if (nparts != 0 && row >= MLAT) {
;             for (int ch = 0; ch < nparts; ch += 4) {
;                 f32x4 pv[4][4];
; #pragma unroll
;                 for (int c4 = 0; c4 < 4; ++c4) { const float* pr = part + ((size_t)(ch + c4) * MCTX + (row - MLAT)) * DM + 4 * lane;
; #pragma unroll
;                     for (int j = 0; j < 4; ++j) pv[c4][j] = *(const f32x4*)(pr + 256 * j); }
; #pragma unroll
;                 for (int c4 = 0; c4 < 4; ++c4)
; #pragma unroll
;                     for (int j = 0; j < 4; ++j) v[j] = v[j] + pv[c4][j]; }
;             ss = 0.f;
; #pragma unroll
;             for (int j = 0; j < 4; ++j) { *(f32x4*)(ctx_out + (size_t)(row - MLAT) * DM + 4 * lane + 256 * j) = v[j]; ss += (v[j][0] * v[j][0] + v[j][1] * v[j][1]) + (v[j][2] * v[j][2] + v[j][3] * v[j][3]); }
;         }
;         const float rs = rsqrtf(wave_sum64(ss) * (1.0f / DM) + EPS);
;         const float* shp = mods_l + s * 6144 + sh_off + 4 * lane; const float* scp = mods_l + s * 6144 + sc_off + 4 * lane;
;         bf16_t* up = U + (size_t)row * DM + 4 * lane;
; #pragma unroll
;         for (int j = 0; j < 4; ++j) { const f32x4 sh = *(const f32x4*)(shp + 256 * j), sc = *(const f32x4*)(scp + 256 * j);
;             const f32x4 y = v[j] * rs * gv[j] * (sc + 1.0f) + sh;
;             u32x2 o; o.x = pkbf(y[0], y[1]); o.y = pkbf(y[2], y[3]); *(u32x2*)(up + 256 * j) = o; }
	v_lshlrev_b32_e32 v80, 16, v166
	v_and_b32_e32 v81, 0xffff0000, v166
	v_lshlrev_b32_e32 v82, 16, v167
	v_and_b32_e32 v83, 0xffff0000, v167
	v_lshlrev_b32_e32 v84, 16, v168
	v_and_b32_e32 v85, 0xffff0000, v168
	v_lshlrev_b32_e32 v86, 16, v169
	v_and_b32_e32 v87, 0xffff0000, v169
	v_lshlrev_b32_e32 v88, 16, v170
	v_and_b32_e32 v89, 0xffff0000, v170
	v_lshlrev_b32_e32 v90, 16, v171
	v_and_b32_e32 v91, 0xffff0000, v171
	v_lshlrev_b32_e32 v92, 16, v172
	v_and_b32_e32 v93, 0xffff0000, v172
	v_lshlrev_b32_e32 v94, 16, v173
	v_and_b32_e32 v95, 0xffff0000, v173
	v_mul_f32_e32 v96, v81, v81
	v_mul_f32_e32 v97, v83, v83
	v_fmac_f32_e32 v96, v80, v80
	v_fmac_f32_e32 v97, v82, v82
	v_add_f32_e32 v98, v96, v97
	v_mul_f32_e32 v96, v85, v85
	v_mul_f32_e32 v97, v87, v87
	v_fmac_f32_e32 v96, v84, v84
	v_fmac_f32_e32 v97, v86, v86
	v_add_f32_e32 v96, v96, v97
	v_add_f32_e32 v98, v98, v96
	v_mul_f32_e32 v96, v89, v89
	v_mul_f32_e32 v97, v91, v91
	v_fmac_f32_e32 v96, v88, v88
	v_fmac_f32_e32 v97, v90, v90
	v_add_f32_e32 v96, v96, v97
	v_add_f32_e32 v98, v98, v96
	v_mul_f32_e32 v96, v93, v93
	v_mul_f32_e32 v97, v95, v95
	v_fmac_f32_e32 v96, v92, v92
	v_fmac_f32_e32 v97, v94, v94
	v_add_f32_e32 v96, v96, v97
	v_add_f32_e32 v98, v98, v96
	s_nop 1
	v_add_f32_dpp v98, v98, v98 quad_perm:[1,0,3,2] row_mask:0xf bank_mask:0xf bound_ctrl:1
	s_nop 1
	v_add_f32_dpp v98, v98, v98 quad_perm:[2,3,0,1] row_mask:0xf bank_mask:0xf bound_ctrl:1
	s_nop 1
	v_add_f32_dpp v98, v98, v98 row_half_mirror row_mask:0xf bank_mask:0xf bound_ctrl:1
	s_nop 1
	v_add_f32_dpp v98, v98, v98 row_mirror row_mask:0xf bank_mask:0xf bound_ctrl:1
	v_mov_b32_e32 v96, v98
	s_nop 1
	v_permlane16_swap_b32_e32 v98, v96
	v_add_f32_e32 v98, v98, v96
	v_mov_b32_e32 v96, v98
	s_nop 1
	v_permlane32_swap_b32_e32 v98, v96
	v_add_f32_e32 v98, v98, v96
	v_fmamk_f32 v100, v98, 0x3a800000, v153
	v_rsq_f32_e32 v100, v100
	s_nop 0
	v_pk_mul_f32 v[80:81], v[80:81], v[100:101] op_sel_hi:[1,0]
	v_pk_mul_f32 v[82:83], v[82:83], v[100:101] op_sel_hi:[1,0]
	v_pk_mul_f32 v[84:85], v[84:85], v[100:101] op_sel_hi:[1,0]
	v_pk_mul_f32 v[86:87], v[86:87], v[100:101] op_sel_hi:[1,0]
	v_pk_mul_f32 v[88:89], v[88:89], v[100:101] op_sel_hi:[1,0]
	v_pk_mul_f32 v[90:91], v[90:91], v[100:101] op_sel_hi:[1,0]
	v_pk_mul_f32 v[92:93], v[92:93], v[100:101] op_sel_hi:[1,0]
	v_pk_mul_f32 v[94:95], v[94:95], v[100:101] op_sel_hi:[1,0]
	v_pk_mul_f32 v[80:81], v[0:1], v[80:81]
	v_pk_mul_f32 v[82:83], v[2:3], v[82:83]
	v_pk_mul_f32 v[84:85], v[4:5], v[84:85]
	v_pk_mul_f32 v[86:87], v[6:7], v[86:87]
	v_pk_mul_f32 v[88:89], v[8:9], v[88:89]
	v_pk_mul_f32 v[90:91], v[10:11], v[90:91]
	v_pk_mul_f32 v[92:93], v[12:13], v[92:93]
	v_pk_mul_f32 v[94:95], v[14:15], v[94:95]
	v_pk_fma_f32 v[80:81], v[64:65], v[80:81], v[48:49]
	v_pk_fma_f32 v[82:83], v[66:67], v[82:83], v[50:51]
	v_pk_fma_f32 v[84:85], v[68:69], v[84:85], v[52:53]
	v_pk_fma_f32 v[86:87], v[70:71], v[86:87], v[54:55]
	v_pk_fma_f32 v[88:89], v[72:73], v[88:89], v[56:57]
	v_pk_fma_f32 v[90:91], v[74:75], v[90:91], v[58:59]
	v_pk_fma_f32 v[92:93], v[76:77], v[92:93], v[60:61]
	v_pk_fma_f32 v[94:95], v[78:79], v[94:95], v[62:63]
	v_cvt_pk_bf16_f32 v80, v80, v81
	v_cvt_pk_bf16_f32 v81, v82, v83
	v_cvt_pk_bf16_f32 v84, v84, v85
	v_cvt_pk_bf16_f32 v85, v86, v87
	v_cvt_pk_bf16_f32 v88, v88, v89
	v_cvt_pk_bf16_f32 v89, v90, v91
	v_cvt_pk_bf16_f32 v92, v92, v93
	v_cvt_pk_bf16_f32 v93, v94, v95
	global_store_dwordx2 v102, v[80:81], s[40:41]
	global_store_dwordx2 v102, v[84:85], s[40:41] offset:512
	global_store_dwordx2 v102, v[88:89], s[40:41] offset:1024
	global_store_dwordx2 v102, v[92:93], s[40:41] offset:1536
	s_add_u32 s40, s40, 0x400000
	s_addc_u32 s41, s41, 0
	s_waitcnt vmcnt(16)
	v_lshlrev_b32_e32 v80, 16, v174
	v_and_b32_e32 v81, 0xffff0000, v174
	v_lshlrev_b32_e32 v82, 16, v175
	v_and_b32_e32 v83, 0xffff0000, v175
	v_lshlrev_b32_e32 v84, 16, v176
	v_and_b32_e32 v85, 0xffff0000, v176
	v_lshlrev_b32_e32 v86, 16, v177
	v_and_b32_e32 v87, 0xffff0000, v177
	v_lshlrev_b32_e32 v88, 16, v178
	v_and_b32_e32 v89, 0xffff0000, v178
	v_lshlrev_b32_e32 v90, 16, v179
	v_and_b32_e32 v91, 0xffff0000, v179
	v_lshlrev_b32_e32 v92, 16, v180
	v_and_b32_e32 v93, 0xffff0000, v180
	v_lshlrev_b32_e32 v94, 16, v181
	v_and_b32_e32 v95, 0xffff0000, v181
	v_mul_f32_e32 v96, v81, v81
	v_mul_f32_e32 v97, v83, v83
	v_fmac_f32_e32 v96, v80, v80
	v_fmac_f32_e32 v97, v82, v82
	v_add_f32_e32 v98, v96, v97
	v_mul_f32_e32 v96, v85, v85
	v_mul_f32_e32 v97, v87, v87
	v_fmac_f32_e32 v96, v84, v84
	v_fmac_f32_e32 v97, v86, v86
	v_add_f32_e32 v96, v96, v97
	v_add_f32_e32 v98, v98, v96
	v_mul_f32_e32 v96, v89, v89
	v_mul_f32_e32 v97, v91, v91
	v_fmac_f32_e32 v96, v88, v88
	v_fmac_f32_e32 v97, v90, v90
	v_add_f32_e32 v96, v96, v97
	v_add_f32_e32 v98, v98, v96
	v_mul_f32_e32 v96, v93, v93
	v_mul_f32_e32 v97, v95, v95
	v_fmac_f32_e32 v96, v92, v92
	v_fmac_f32_e32 v97, v94, v94
	v_add_f32_e32 v96, v96, v97
	v_add_f32_e32 v98, v98, v96
	s_nop 1
	v_add_f32_dpp v98, v98, v98 quad_perm:[1,0,3,2] row_mask:0xf bank_mask:0xf bound_ctrl:1
	s_nop 1
	v_add_f32_dpp v98, v98, v98 quad_perm:[2,3,0,1] row_mask:0xf bank_mask:0xf bound_ctrl:1
	s_nop 1
	v_add_f32_dpp v98, v98, v98 row_half_mirror row_mask:0xf bank_mask:0xf bound_ctrl:1
	s_nop 1
	v_add_f32_dpp v98, v98, v98 row_mirror row_mask:0xf bank_mask:0xf bound_ctrl:1
	v_mov_b32_e32 v96, v98
	s_nop 1
	v_permlane16_swap_b32_e32 v98, v96
	v_add_f32_e32 v98, v98, v96
	v_mov_b32_e32 v96, v98
	s_nop 1
	v_permlane32_swap_b32_e32 v98, v96
	v_add_f32_e32 v98, v98, v96
	v_fmamk_f32 v100, v98, 0x3a800000, v153
	v_rsq_f32_e32 v100, v100
	s_nop 0
; __device__ __forceinline__ void norm_phase(const void* src_lat, int lat_f32, const float* src_ctx, int nrows, const float* gvec, const float* mods_l, int sh_off, int sc_off, bf16_t* U, const float* part, int nparts, float* ctx_out) {
;     ...
;     for (int row = gw; row < nrows; row += ngw) {
;         const int s = row < MLAT ? (row >> 13) : 4;
;         f32x4 v[4]; float ss = 0.f;
;         if (row < MLAT && !lat_f32) { const bf16_t* src = (const bf16_t*)src_lat + (size_t)row * DM + 4 * lane;
; #pragma unroll
;             for (int j = 0; j < 4; ++j) { const u32x2 w = *(const u32x2*)(src + 256 * j);
;                 v[j] = (f32x4){__uint_as_float(w.x << 16), __uint_as_float(w.x & 0xffff0000u), __uint_as_float(w.y << 16), __uint_as_float(w.y & 0xffff0000u)}; } }
;         else { const float* src = row < MLAT ? (const float*)src_lat + (size_t)row * DM : src_ctx + (size_t)(row - MLAT) * DM;
; #pragma unroll
;             for (int j = 0; j < 4; ++j) v[j] = *(const f32x4*)(src + 4 * lane + 256 * j); }
; #pragma unroll
;         for (int j = 0; j < 4; ++j) { ss += (v[j][0] * v[j][0] + v[j][1] * v[j][1]) + (v[j][2] * v[j][2] + v[j][3] * v[j][3]); }
;         if (nparts != 0 && row >= MLAT) {
;             for (int ch = 0; ch < nparts; ch += 4) {
;                 f32x4 pv[4][4];
; #pragma unroll
;                 for (int c4 = 0; c4 < 4; ++c4) { const float* pr = part + ((size_t)(ch + c4) * MCTX + (row - MLAT)) * DM + 4 * lane;
; #pragma unroll
;                     for (int j = 0; j < 4; ++j) pv[c4][j] = *(const f32x4*)(pr + 256 * j); }
; #pragma unroll
;                 for (int c4 = 0; c4 < 4; ++c4)
; #pragma unroll
;                     for (int j = 0; j < 4; ++j) v[j] = v[j] + pv[c4][j]; }
;             ss = 0.f;
; #pragma unroll
;             for (int j = 0; j < 4; ++j) { *(f32x4*)(ctx_out + (size_t)(row - MLAT) * DM + 4 * lane + 256 * j) = v[j]; ss += (v[j][0] * v[j][0] + v[j][1] * v[j][1]) + (v[j][2] * v[j][2] + v[j][3] * v[j][3]); }
;         }
;         const float rs = rsqrtf(wave_sum64(ss) * (1.0f / DM) + EPS);
;         const float* shp = mods_l + s * 6144 + sh_off + 4 * lane; const float* scp = mods_l + s * 6144 + sc_off + 4 * lane;
;         bf16_t* up = U + (size_t)row * DM + 4 * lane;
; #pragma unroll
;         for (int j = 0; j < 4; ++j) { const f32x4 sh = *(const f32x4*)(shp + 256 * j), sc = *(const f32x4*)(scp + 256 * j);
	v_pk_mul_f32 v[80:81], v[80:81], v[100:101] op_sel_hi:[1,0]
	v_pk_mul_f32 v[82:83], v[82:83], v[100:101] op_sel_hi:[1,0]
	v_pk_mul_f32 v[84:85], v[84:85], v[100:101] op_sel_hi:[1,0]
	v_pk_mul_f32 v[86:87], v[86:87], v[100:101] op_sel_hi:[1,0]
	v_pk_mul_f32 v[88:89], v[88:89], v[100:101] op_sel_hi:[1,0]
	v_pk_mul_f32 v[90:91], v[90:91], v[100:101] op_sel_hi:[1,0]
	v_pk_mul_f32 v[92:93], v[92:93], v[100:101] op_sel_hi:[1,0]
	v_pk_mul_f32 v[94:95], v[94:95], v[100:101] op_sel_hi:[1,0]
	v_pk_mul_f32 v[80:81], v[0:1], v[80:81]
	v_pk_mul_f32 v[82:83], v[2:3], v[82:83]
	v_pk_mul_f32 v[84:85], v[4:5], v[84:85]
	v_pk_mul_f32 v[86:87], v[6:7], v[86:87]
	v_pk_mul_f32 v[88:89], v[8:9], v[88:89]
	v_pk_mul_f32 v[90:91], v[10:11], v[90:91]
	v_pk_mul_f32 v[92:93], v[12:13], v[92:93]
	v_pk_mul_f32 v[94:95], v[14:15], v[94:95]
	v_pk_fma_f32 v[80:81], v[64:65], v[80:81], v[48:49]
	v_pk_fma_f32 v[82:83], v[66:67], v[82:83], v[50:51]
	v_pk_fma_f32 v[84:85], v[68:69], v[84:85], v[52:53]
	v_pk_fma_f32 v[86:87], v[70:71], v[86:87], v[54:55]
	v_pk_fma_f32 v[88:89], v[72:73], v[88:89], v[56:57]
	v_pk_fma_f32 v[90:91], v[74:75], v[90:91], v[58:59]
	v_pk_fma_f32 v[92:93], v[76:77], v[92:93], v[60:61]
	v_pk_fma_f32 v[94:95], v[78:79], v[94:95], v[62:63]
	v_cvt_pk_bf16_f32 v80, v80, v81
	v_cvt_pk_bf16_f32 v81, v82, v83
	v_cvt_pk_bf16_f32 v84, v84, v85
	v_cvt_pk_bf16_f32 v85, v86, v87
	v_cvt_pk_bf16_f32 v88, v88, v89
	v_cvt_pk_bf16_f32 v89, v90, v91
	v_cvt_pk_bf16_f32 v92, v92, v93
	v_cvt_pk_bf16_f32 v93, v94, v95
	global_store_dwordx2 v102, v[80:81], s[40:41]
	global_store_dwordx2 v102, v[84:85], s[40:41] offset:512
	global_store_dwordx2 v102, v[88:89], s[40:41] offset:1024
	global_store_dwordx2 v102, v[92:93], s[40:41] offset:1536
	s_add_u32 s40, s40, 0x400000
	s_addc_u32 s41, s41, 0
	s_waitcnt vmcnt(12)
	v_lshlrev_b32_e32 v80, 16, v182
	v_and_b32_e32 v81, 0xffff0000, v182
	v_lshlrev_b32_e32 v82, 16, v183
	v_and_b32_e32 v83, 0xffff0000, v183
	v_lshlrev_b32_e32 v84, 16, v184
	v_and_b32_e32 v85, 0xffff0000, v184
	v_lshlrev_b32_e32 v86, 16, v185
	v_and_b32_e32 v87, 0xffff0000, v185
	v_lshlrev_b32_e32 v88, 16, v186
	v_and_b32_e32 v89, 0xffff0000, v186
	v_lshlrev_b32_e32 v90, 16, v187
	v_and_b32_e32 v91, 0xffff0000, v187
	v_lshlrev_b32_e32 v92, 16, v188
	v_and_b32_e32 v93, 0xffff0000, v188
	v_lshlrev_b32_e32 v94, 16, v189
	v_and_b32_e32 v95, 0xffff0000, v189
	v_mul_f32_e32 v96, v81, v81
	v_mul_f32_e32 v97, v83, v83
	v_fmac_f32_e32 v96, v80, v80
	v_fmac_f32_e32 v97, v82, v82
	v_add_f32_e32 v98, v96, v97
	v_mul_f32_e32 v96, v85, v85
	v_mul_f32_e32 v97, v87, v87
	v_fmac_f32_e32 v96, v84, v84
	v_fmac_f32_e32 v97, v86, v86
	v_add_f32_e32 v96, v96, v97
	v_add_f32_e32 v98, v98, v96
	v_mul_f32_e32 v96, v89, v89
	v_mul_f32_e32 v97, v91, v91
	v_fmac_f32_e32 v96, v88, v88
	v_fmac_f32_e32 v97, v90, v90
	v_add_f32_e32 v96, v96, v97
	v_add_f32_e32 v98, v98, v96
	v_mul_f32_e32 v96, v93, v93
	v_mul_f32_e32 v97, v95, v95
	v_fmac_f32_e32 v96, v92, v92
	v_fmac_f32_e32 v97, v94, v94
	v_add_f32_e32 v96, v96, v97
	v_add_f32_e32 v98, v98, v96
	s_nop 1
	v_add_f32_dpp v98, v98, v98 quad_perm:[1,0,3,2] row_mask:0xf bank_mask:0xf bound_ctrl:1
	s_nop 1
	v_add_f32_dpp v98, v98, v98 quad_perm:[2,3,0,1] row_mask:0xf bank_mask:0xf bound_ctrl:1
	s_nop 1
	v_add_f32_dpp v98, v98, v98 row_half_mirror row_mask:0xf bank_mask:0xf bound_ctrl:1
	s_nop 1
	v_add_f32_dpp v98, v98, v98 row_mirror row_mask:0xf bank_mask:0xf bound_ctrl:1
	v_mov_b32_e32 v96, v98
	s_nop 1
	v_permlane16_swap_b32_e32 v98, v96
	v_add_f32_e32 v98, v98, v96
	v_mov_b32_e32 v96, v98
	s_nop 1
	v_permlane32_swap_b32_e32 v98, v96
	v_add_f32_e32 v98, v98, v96
	v_fmamk_f32 v100, v98, 0x3a800000, v153
	v_rsq_f32_e32 v100, v100
	s_nop 0
	v_pk_mul_f32 v[80:81], v[80:81], v[100:101] op_sel_hi:[1,0]
	v_pk_mul_f32 v[82:83], v[82:83], v[100:101] op_sel_hi:[1,0]
	v_pk_mul_f32 v[84:85], v[84:85], v[100:101] op_sel_hi:[1,0]
	v_pk_mul_f32 v[86:87], v[86:87], v[100:101] op_sel_hi:[1,0]
	v_pk_mul_f32 v[88:89], v[88:89], v[100:101] op_sel_hi:[1,0]
	v_pk_mul_f32 v[90:91], v[90:91], v[100:101] op_sel_hi:[1,0]
	v_pk_mul_f32 v[92:93], v[92:93], v[100:101] op_sel_hi:[1,0]
	v_pk_mul_f32 v[94:95], v[94:95], v[100:101] op_sel_hi:[1,0]
	v_pk_mul_f32 v[80:81], v[0:1], v[80:81]
	v_pk_mul_f32 v[82:83], v[2:3], v[82:83]
	v_pk_mul_f32 v[84:85], v[4:5], v[84:85]
	v_pk_mul_f32 v[86:87], v[6:7], v[86:87]
	v_pk_mul_f32 v[88:89], v[8:9], v[88:89]
	v_pk_mul_f32 v[90:91], v[10:11], v[90:91]
	v_pk_mul_f32 v[92:93], v[12:13], v[92:93]
	v_pk_mul_f32 v[94:95], v[14:15], v[94:95]
	v_pk_fma_f32 v[80:81], v[64:65], v[80:81], v[48:49]
	v_pk_fma_f32 v[82:83], v[66:67], v[82:83], v[50:51]
	v_pk_fma_f32 v[84:85], v[68:69], v[84:85], v[52:53]
	v_pk_fma_f32 v[86:87], v[70:71], v[86:87], v[54:55]
	v_pk_fma_f32 v[88:89], v[72:73], v[88:89], v[56:57]
	v_pk_fma_f32 v[90:91], v[74:75], v[90:91], v[58:59]
	v_pk_fma_f32 v[92:93], v[76:77], v[92:93], v[60:61]
	v_pk_fma_f32 v[94:95], v[78:79], v[94:95], v[62:63]
	v_cvt_pk_bf16_f32 v80, v80, v81
	v_cvt_pk_bf16_f32 v81, v82, v83
	v_cvt_pk_bf16_f32 v84, v84, v85
	v_cvt_pk_bf16_f32 v85, v86, v87
	v_cvt_pk_bf16_f32 v88, v88, v89
	v_cvt_pk_bf16_f32 v89, v90, v91
	v_cvt_pk_bf16_f32 v92, v92, v93
	v_cvt_pk_bf16_f32 v93, v94, v95
	global_store_dwordx2 v102, v[80:81], s[40:41]
	global_store_dwordx2 v102, v[84:85], s[40:41] offset:512
	global_store_dwordx2 v102, v[88:89], s[40:41] offset:1024
	global_store_dwordx2 v102, v[92:93], s[40:41] offset:1536
	s_add_u32 s40, s40, 0x400000
	s_addc_u32 s41, s41, 0
	s_add_i32 s0, s0, 0x8000
	s_add_i32 s82, s82, 0x8000
	s_cmp_lt_i32 s0, 0x8400
	s_cbranch_scc1 .LBB0_142
	s_branch .LBB0_150

; __device__ __forceinline__ void norm_phase(const void* src_lat, int lat_f32, const float* src_ctx, int nrows, const float* gvec, const float* mods_l, int sh_off, int sc_off, bf16_t* U, const float* part, int nparts, float* ctx_out) {
;     int tid_ = threadIdx.x; asm volatile("" : "+v"(tid_));
;     const int lane = tid_ & 63, w = __builtin_amdgcn_readfirstlane(tid_ >> 6);
;     const int gw = blockIdx.x * 8 + w, ngw = gridDim.x * 8;
;     f32x4 gv[4];
; #pragma unroll
;     for (int j = 0; j < 4; ++j) gv[j] = *(const f32x4*)(gvec + 4 * lane + 256 * j);
;     for (int row = gw; row < nrows; row += ngw) {
;         const int s = row < MLAT ? (row >> 13) : 4;
;         f32x4 v[4]; float ss = 0.f;
;         if (row < MLAT && !lat_f32) { const bf16_t* src = (const bf16_t*)src_lat + (size_t)row * DM + 4 * lane;
; #pragma unroll
;             for (int j = 0; j < 4; ++j) { const u32x2 w = *(const u32x2*)(src + 256 * j);
;                 v[j] = (f32x4){__uint_as_float(w.x << 16), __uint_as_float(w.x & 0xffff0000u), __uint_as_float(w.y << 16), __uint_as_float(w.y & 0xffff0000u)}; } }
;         else { const float* src = row < MLAT ? (const float*)src_lat + (size_t)row * DM : src_ctx + (size_t)(row - MLAT) * DM;
; #pragma unroll
;             for (int j = 0; j < 4; ++j) v[j] = *(const f32x4*)(src + 4 * lane + 256 * j); }
; #pragma unroll
;         for (int j = 0; j < 4; ++j) { ss += (v[j][0] * v[j][0] + v[j][1] * v[j][1]) + (v[j][2] * v[j][2] + v[j][3] * v[j][3]); }
;         if (nparts != 0 && row >= MLAT) {
;             for (int ch = 0; ch < nparts; ch += 4) {
;                 f32x4 pv[4][4];
; #pragma unroll
;                 for (int c4 = 0; c4 < 4; ++c4) { const float* pr = part + ((size_t)(ch + c4) * MCTX + (row - MLAT)) * DM + 4 * lane;
; #pragma unroll
;                     for (int j = 0; j < 4; ++j) pv[c4][j] = *(const f32x4*)(pr + 256 * j); }
; #pragma unroll
;                 for (int c4 = 0; c4 < 4; ++c4)
; #pragma unroll
;                     for (int j = 0; j < 4; ++j) v[j] = v[j] + pv[c4][j]; }
;             ss = 0.f;
; #pragma unroll
;             for (int j = 0; j < 4; ++j) { *(f32x4*)(ctx_out + (size_t)(row - MLAT) * DM + 4 * lane + 256 * j) = v[j]; ss += (v[j][0] * v[j][0] + v[j][1] * v[j][1]) + (v[j][2] * v[j][2] + v[j][3] * v[j][3]); }
;         }
;         const float rs = rsqrtf(wave_sum64(ss) * (1.0f / DM) + EPS);
.LBB0_728:
	global_load_dwordx2 v[0:1], v155, s[78:79] offset:56
	v_readlane_b32 s0, v240, 36
	v_readlane_b32 s1, v240, 37
	s_and_b64 s[0:1], exec, s[0:1]
	s_mov_b32 s0, 0x8400
	v_mov_b32_e32 v18, v152
	s_cselect_b32 s26, s0, 0x8000
	v_readlane_b32 s1, v241, 4
	v_readfirstlane_b32 s0, v18
	s_ashr_i32 s0, s0, 6
	s_add_i32 s0, s0, s1
	s_cmp_ge_i32 s0, s26
	s_cbranch_scc1 .LBB0_738
	v_readlane_b32 s8, v240, 44
	v_readlane_b32 s9, v240, 45
	v_lshlrev_b32_e32 v2, 2, v18
	s_lshl_b64 s[8:9], s[8:9], 2
	v_and_b32_e32 v20, 0xfc, v2
	s_waitcnt vmcnt(0)
	v_lshl_add_u64 v[0:1], v[0:1], 0, s[8:9]
	v_lshlrev_b32_e32 v154, 2, v20
	v_lshl_add_u64 v[12:13], v[0:1], 0, v[154:155]
	flat_load_dwordx4 v[0:3], v[12:13]
	flat_load_dwordx4 v[4:7], v[12:13] offset:1024
	flat_load_dwordx4 v[8:11], v[12:13] offset:2048
	s_nop 0
	flat_load_dwordx4 v[12:15], v[12:13] offset:3072
	v_readlane_b32 s8, v241, 7
	v_readlane_b32 s9, v241, 8
	s_ashr_i32 s1, s0, 31
	v_lshl_add_u64 v[36:37], v[16:17], 0, v[154:155]
	v_lshl_add_u64 v[32:33], s[8:9], 0, v[154:155]
	s_lshl_b64 s[8:9], s[0:1], 11
	v_and_b32_e32 v16, 63, v18
	s_add_u32 s8, s70, s8
	v_lshl_add_u64 v[34:35], s[72:73], 0, v[154:155]
	v_lshlrev_b32_e32 v154, 3, v16
	s_addc_u32 s9, s71, s9
	v_lshl_add_u64 v[38:39], s[8:9], 0, v[154:155]
	v_lshlrev_b32_e32 v154, 2, v20
	s_cmp_lg_u32 s56, 0x800
	s_cbranch_scc1 .LBB0_732
	v_and_b32_e32 v100, 63, v152
	v_lshlrev_b32_e32 v101, 4, v100
	v_lshlrev_b32_e32 v100, 3, v100
	v_readlane_b32 s34, v240, 42
	v_readlane_b32 s35, v240, 43
	s_lshl_b32 s36, s0, 11
	s_nop 0
	s_add_u32 s38, s70, s36
	s_addc_u32 s39, s71, 0
	s_add_u32 s40, s38, 0xe7600000
	s_addc_u32 s41, s39, -1
	s_add_u32 s42, s34, 0x3000
	s_addc_u32 s43, s35, 0
	s_add_u32 s44, s34, 0x4000
	s_addc_u32 s45, s35, 0
	global_load_dwordx4 v[198:201], v101, s[42:43]
	global_load_dwordx4 v[202:205], v101, s[42:43] offset:1024
	global_load_dwordx4 v[206:209], v101, s[42:43] offset:2048
	global_load_dwordx4 v[210:213], v101, s[42:43] offset:3072
	global_load_dwordx4 v[214:217], v101, s[44:45]
	global_load_dwordx4 v[218:221], v101, s[44:45] offset:1024
	global_load_dwordx4 v[222:225], v101, s[44:45] offset:2048
	global_load_dwordx4 v[226:229], v101, s[44:45] offset:3072
	s_add_u32 s42, s42, 0x6000
	s_addc_u32 s43, s43, 0
	s_add_u32 s44, s44, 0x6000
	s_addc_u32 s45, s45, 0
	global_load_dwordx2 v[104:105], v100, s[38:39]
	global_load_dwordx2 v[106:107], v100, s[38:39] offset:512
	global_load_dwordx2 v[108:109], v100, s[38:39] offset:1024
	global_load_dwordx2 v[110:111], v100, s[38:39] offset:1536
	s_add_u32 s38, s38, 0x400000
	s_addc_u32 s39, s39, 0
	global_load_dwordx2 v[112:113], v100, s[38:39]
	global_load_dwordx2 v[114:115], v100, s[38:39] offset:512
	global_load_dwordx2 v[116:117], v100, s[38:39] offset:1024
	global_load_dwordx2 v[118:119], v100, s[38:39] offset:1536
	s_add_u32 s38, s38, 0x400000
	s_addc_u32 s39, s39, 0
	global_load_dwordx2 v[120:121], v100, s[38:39]
	global_load_dwordx2 v[122:123], v100, s[38:39] offset:512
	global_load_dwordx2 v[124:125], v100, s[38:39] offset:1024
	global_load_dwordx2 v[126:127], v100, s[38:39] offset:1536
	s_add_u32 s38, s38, 0x400000
	s_addc_u32 s39, s39, 0
	global_load_dwordx2 v[128:129], v100, s[38:39]
	global_load_dwordx2 v[130:131], v100, s[38:39] offset:512
	global_load_dwordx2 v[132:133], v100, s[38:39] offset:1024
	global_load_dwordx2 v[134:135], v100, s[38:39] offset:1536
	s_add_u32 s38, s38, 0x400000
	s_addc_u32 s39, s39, 0
	s_waitcnt vmcnt(16)
	v_pk_add_f32 v[214:215], v[214:215], 1.0 op_sel_hi:[1,0]
	v_pk_add_f32 v[216:217], v[216:217], 1.0 op_sel_hi:[1,0]
	v_pk_add_f32 v[218:219], v[218:219], 1.0 op_sel_hi:[1,0]
	v_pk_add_f32 v[220:221], v[220:221], 1.0 op_sel_hi:[1,0]
	v_pk_add_f32 v[222:223], v[222:223], 1.0 op_sel_hi:[1,0]
	v_pk_add_f32 v[224:225], v[224:225], 1.0 op_sel_hi:[1,0]
	v_pk_add_f32 v[226:227], v[226:227], 1.0 op_sel_hi:[1,0]
	v_pk_add_f32 v[228:229], v[228:229], 1.0 op_sel_hi:[1,0]
	s_waitcnt vmcnt(12)
	v_lshlrev_b32_e32 v40, 16, v104
	v_and_b32_e32 v41, 0xffff0000, v104
	v_lshlrev_b32_e32 v42, 16, v105
	v_and_b32_e32 v43, 0xffff0000, v105
	v_lshlrev_b32_e32 v44, 16, v106
	v_and_b32_e32 v45, 0xffff0000, v106
	v_lshlrev_b32_e32 v46, 16, v107
	v_and_b32_e32 v47, 0xffff0000, v107
	v_lshlrev_b32_e32 v48, 16, v108
	v_and_b32_e32 v49, 0xffff0000, v108
	v_lshlrev_b32_e32 v50, 16, v109
	v_and_b32_e32 v51, 0xffff0000, v109
	v_lshlrev_b32_e32 v52, 16, v110
	v_and_b32_e32 v53, 0xffff0000, v110
	v_lshlrev_b32_e32 v54, 16, v111
	v_and_b32_e32 v55, 0xffff0000, v111
	v_mul_f32_e32 v56, v41, v41
	v_mul_f32_e32 v57, v43, v43
	v_fmac_f32_e32 v56, v40, v40
	v_fmac_f32_e32 v57, v42, v42
	v_add_f32_e32 v58, v56, v57
	v_mul_f32_e32 v56, v45, v45
	v_mul_f32_e32 v57, v47, v47
	v_fmac_f32_e32 v56, v44, v44
	v_fmac_f32_e32 v57, v46, v46
	v_add_f32_e32 v56, v56, v57
	v_add_f32_e32 v58, v58, v56
	v_mul_f32_e32 v56, v49, v49
	v_mul_f32_e32 v57, v51, v51
	v_fmac_f32_e32 v56, v48, v48
	v_fmac_f32_e32 v57, v50, v50
	v_add_f32_e32 v56, v56, v57
	v_add_f32_e32 v58, v58, v56
	v_mul_f32_e32 v56, v53, v53
	v_mul_f32_e32 v57, v55, v55
	v_fmac_f32_e32 v56, v52, v52
	v_fmac_f32_e32 v57, v54, v54
	v_add_f32_e32 v56, v56, v57
	v_add_f32_e32 v58, v58, v56
	s_nop 1
	v_add_f32_dpp v58, v58, v58 quad_perm:[1,0,3,2] row_mask:0xf bank_mask:0xf bound_ctrl:1
	s_nop 1
	v_add_f32_dpp v58, v58, v58 quad_perm:[2,3,0,1] row_mask:0xf bank_mask:0xf bound_ctrl:1
	s_nop 1
	v_add_f32_dpp v58, v58, v58 row_half_mirror row_mask:0xf bank_mask:0xf bound_ctrl:1
	s_nop 1
	v_add_f32_dpp v58, v58, v58 row_mirror row_mask:0xf bank_mask:0xf bound_ctrl:1
	v_mov_b32_e32 v56, v58
	s_nop 1
	v_permlane16_swap_b32_e32 v58, v56
; __device__ __forceinline__ void norm_phase(const void* src_lat, int lat_f32, const float* src_ctx, int nrows, const float* gvec, const float* mods_l, int sh_off, int sc_off, bf16_t* U, const float* part, int nparts, float* ctx_out) {
;     ...
;         if (row < MLAT && !lat_f32) { const bf16_t* src = (const bf16_t*)src_lat + (size_t)row * DM + 4 * lane;
; #pragma unroll
;             for (int j = 0; j < 4; ++j) { const u32x2 w = *(const u32x2*)(src + 256 * j);
;                 v[j] = (f32x4){__uint_as_float(w.x << 16), __uint_as_float(w.x & 0xffff0000u), __uint_as_float(w.y << 16), __uint_as_float(w.y & 0xffff0000u)}; } }
;         else { const float* src = row < MLAT ? (const float*)src_lat + (size_t)row * DM : src_ctx + (size_t)(row - MLAT) * DM;
; #pragma unroll
;             for (int j = 0; j < 4; ++j) v[j] = *(const f32x4*)(src + 4 * lane + 256 * j); }
; #pragma unroll
;         for (int j = 0; j < 4; ++j) { ss += (v[j][0] * v[j][0] + v[j][1] * v[j][1]) + (v[j][2] * v[j][2] + v[j][3] * v[j][3]); }
;         if (nparts != 0 && row >= MLAT) {
;             for (int ch = 0; ch < nparts; ch += 4) {
;                 f32x4 pv[4][4];
; #pragma unroll
;                 for (int c4 = 0; c4 < 4; ++c4) { const float* pr = part + ((size_t)(ch + c4) * MCTX + (row - MLAT)) * DM + 4 * lane;
; #pragma unroll
;                     for (int j = 0; j < 4; ++j) pv[c4][j] = *(const f32x4*)(pr + 256 * j); }
; #pragma unroll
;                 for (int c4 = 0; c4 < 4; ++c4)
; #pragma unroll
;                     for (int j = 0; j < 4; ++j) v[j] = v[j] + pv[c4][j]; }
;             ss = 0.f;
; #pragma unroll
;             for (int j = 0; j < 4; ++j) { *(f32x4*)(ctx_out + (size_t)(row - MLAT) * DM + 4 * lane + 256 * j) = v[j]; ss += (v[j][0] * v[j][0] + v[j][1] * v[j][1]) + (v[j][2] * v[j][2] + v[j][3] * v[j][3]); }
;         }
;         const float rs = rsqrtf(wave_sum64(ss) * (1.0f / DM) + EPS);
;         const float* shp = mods_l + s * 6144 + sh_off + 4 * lane; const float* scp = mods_l + s * 6144 + sc_off + 4 * lane;
;         bf16_t* up = U + (size_t)row * DM + 4 * lane;
; #pragma unroll
;         for (int j = 0; j < 4; ++j) { const f32x4 sh = *(const f32x4*)(shp + 256 * j), sc = *(const f32x4*)(scp + 256 * j);
;             const f32x4 y = v[j] * rs * gv[j] * (sc + 1.0f) + sh;
;             u32x2 o; o.x = pkbf(y[0], y[1]); o.y = pkbf(y[2], y[3]); *(u32x2*)(up + 256 * j) = o; }
	v_add_f32_e32 v58, v58, v56
	v_mov_b32_e32 v56, v58
	s_nop 1
	v_permlane32_swap_b32_e32 v58, v56
	v_add_f32_e32 v58, v58, v56
	v_fmamk_f32 v60, v58, 0x3a800000, v153
	v_rsq_f32_e32 v60, v60
	s_nop 0
	v_pk_mul_f32 v[40:41], v[40:41], v[60:61] op_sel_hi:[1,0]
	v_pk_mul_f32 v[42:43], v[42:43], v[60:61] op_sel_hi:[1,0]
	v_pk_mul_f32 v[44:45], v[44:45], v[60:61] op_sel_hi:[1,0]
	v_pk_mul_f32 v[46:47], v[46:47], v[60:61] op_sel_hi:[1,0]
	v_pk_mul_f32 v[48:49], v[48:49], v[60:61] op_sel_hi:[1,0]
	v_pk_mul_f32 v[50:51], v[50:51], v[60:61] op_sel_hi:[1,0]
	v_pk_mul_f32 v[52:53], v[52:53], v[60:61] op_sel_hi:[1,0]
	v_pk_mul_f32 v[54:55], v[54:55], v[60:61] op_sel_hi:[1,0]
	v_pk_mul_f32 v[40:41], v[0:1], v[40:41]
	v_pk_mul_f32 v[42:43], v[2:3], v[42:43]
	v_pk_mul_f32 v[44:45], v[4:5], v[44:45]
	v_pk_mul_f32 v[46:47], v[6:7], v[46:47]
	v_pk_mul_f32 v[48:49], v[8:9], v[48:49]
	v_pk_mul_f32 v[50:51], v[10:11], v[50:51]
	v_pk_mul_f32 v[52:53], v[12:13], v[52:53]
	v_pk_mul_f32 v[54:55], v[14:15], v[54:55]
	v_pk_fma_f32 v[40:41], v[214:215], v[40:41], v[198:199]
	v_pk_fma_f32 v[42:43], v[216:217], v[42:43], v[200:201]
	v_pk_fma_f32 v[44:45], v[218:219], v[44:45], v[202:203]
	v_pk_fma_f32 v[46:47], v[220:221], v[46:47], v[204:205]
	v_pk_fma_f32 v[48:49], v[222:223], v[48:49], v[206:207]
	v_pk_fma_f32 v[50:51], v[224:225], v[50:51], v[208:209]
	v_pk_fma_f32 v[52:53], v[226:227], v[52:53], v[210:211]
	v_pk_fma_f32 v[54:55], v[228:229], v[54:55], v[212:213]
	v_cvt_pk_bf16_f32 v40, v40, v41
	v_cvt_pk_bf16_f32 v41, v42, v43
	v_cvt_pk_bf16_f32 v44, v44, v45
	v_cvt_pk_bf16_f32 v45, v46, v47
	v_cvt_pk_bf16_f32 v48, v48, v49
	v_cvt_pk_bf16_f32 v49, v50, v51
	v_cvt_pk_bf16_f32 v52, v52, v53
	v_cvt_pk_bf16_f32 v53, v54, v55
	global_store_dwordx2 v100, v[40:41], s[40:41]
	global_store_dwordx2 v100, v[44:45], s[40:41] offset:512
	global_store_dwordx2 v100, v[48:49], s[40:41] offset:1024
	global_store_dwordx2 v100, v[52:53], s[40:41] offset:1536
	s_add_u32 s40, s40, 0x400000
	s_addc_u32 s41, s41, 0
	global_load_dwordx2 v[104:105], v100, s[38:39]
	global_load_dwordx2 v[106:107], v100, s[38:39] offset:512
	global_load_dwordx2 v[108:109], v100, s[38:39] offset:1024
	global_load_dwordx2 v[110:111], v100, s[38:39] offset:1536
	s_add_u32 s38, s38, 0x400000
	s_addc_u32 s39, s39, 0
	global_load_dwordx4 v[68:71], v101, s[42:43]
	global_load_dwordx4 v[72:75], v101, s[42:43] offset:1024
	global_load_dwordx4 v[76:79], v101, s[42:43] offset:2048
	global_load_dwordx4 v[80:83], v101, s[42:43] offset:3072
	global_load_dwordx4 v[84:87], v101, s[44:45]
	global_load_dwordx4 v[88:91], v101, s[44:45] offset:1024
	global_load_dwordx4 v[92:95], v101, s[44:45] offset:2048
	global_load_dwordx4 v[96:99], v101, s[44:45] offset:3072
	s_add_u32 s42, s42, 0x6000
	s_addc_u32 s43, s43, 0
	s_add_u32 s44, s44, 0x6000
	s_addc_u32 s45, s45, 0
	s_waitcnt vmcnt(24)
	v_lshlrev_b32_e32 v40, 16, v112
	v_and_b32_e32 v41, 0xffff0000, v112
	v_lshlrev_b32_e32 v42, 16, v113
	v_and_b32_e32 v43, 0xffff0000, v113
	v_lshlrev_b32_e32 v44, 16, v114
	v_and_b32_e32 v45, 0xffff0000, v114
	v_lshlrev_b32_e32 v46, 16, v115
	v_and_b32_e32 v47, 0xffff0000, v115
	v_lshlrev_b32_e32 v48, 16, v116
	v_and_b32_e32 v49, 0xffff0000, v116
	v_lshlrev_b32_e32 v50, 16, v117
	v_and_b32_e32 v51, 0xffff0000, v117
	v_lshlrev_b32_e32 v52, 16, v118
	v_and_b32_e32 v53, 0xffff0000, v118
	v_lshlrev_b32_e32 v54, 16, v119
	v_and_b32_e32 v55, 0xffff0000, v119
	v_mul_f32_e32 v56, v41, v41
	v_mul_f32_e32 v57, v43, v43
	v_fmac_f32_e32 v56, v40, v40
	v_fmac_f32_e32 v57, v42, v42
	v_add_f32_e32 v58, v56, v57
	v_mul_f32_e32 v56, v45, v45
	v_mul_f32_e32 v57, v47, v47
	v_fmac_f32_e32 v56, v44, v44
	v_fmac_f32_e32 v57, v46, v46
	v_add_f32_e32 v56, v56, v57
	v_add_f32_e32 v58, v58, v56
	v_mul_f32_e32 v56, v49, v49
	v_mul_f32_e32 v57, v51, v51
	v_fmac_f32_e32 v56, v48, v48
	v_fmac_f32_e32 v57, v50, v50
	v_add_f32_e32 v56, v56, v57
	v_add_f32_e32 v58, v58, v56
	v_mul_f32_e32 v56, v53, v53
	v_mul_f32_e32 v57, v55, v55
	v_fmac_f32_e32 v56, v52, v52
	v_fmac_f32_e32 v57, v54, v54
	v_add_f32_e32 v56, v56, v57
	v_add_f32_e32 v58, v58, v56
	s_nop 1
	v_add_f32_dpp v58, v58, v58 quad_perm:[1,0,3,2] row_mask:0xf bank_mask:0xf bound_ctrl:1
	s_nop 1
	v_add_f32_dpp v58, v58, v58 quad_perm:[2,3,0,1] row_mask:0xf bank_mask:0xf bound_ctrl:1
	s_nop 1
	v_add_f32_dpp v58, v58, v58 row_half_mirror row_mask:0xf bank_mask:0xf bound_ctrl:1
	s_nop 1
	v_add_f32_dpp v58, v58, v58 row_mirror row_mask:0xf bank_mask:0xf bound_ctrl:1
	v_mov_b32_e32 v56, v58
	s_nop 1
	v_permlane16_swap_b32_e32 v58, v56
	v_add_f32_e32 v58, v58, v56
	v_mov_b32_e32 v56, v58
	s_nop 1
	v_permlane32_swap_b32_e32 v58, v56
	v_add_f32_e32 v58, v58, v56
	v_fmamk_f32 v60, v58, 0x3a800000, v153
	v_rsq_f32_e32 v60, v60
	s_nop 0
	v_pk_mul_f32 v[40:41], v[40:41], v[60:61] op_sel_hi:[1,0]
	v_pk_mul_f32 v[42:43], v[42:43], v[60:61] op_sel_hi:[1,0]
	v_pk_mul_f32 v[44:45], v[44:45], v[60:61] op_sel_hi:[1,0]
	v_pk_mul_f32 v[46:47], v[46:47], v[60:61] op_sel_hi:[1,0]
	v_pk_mul_f32 v[48:49], v[48:49], v[60:61] op_sel_hi:[1,0]
	v_pk_mul_f32 v[50:51], v[50:51], v[60:61] op_sel_hi:[1,0]
	v_pk_mul_f32 v[52:53], v[52:53], v[60:61] op_sel_hi:[1,0]
	v_pk_mul_f32 v[54:55], v[54:55], v[60:61] op_sel_hi:[1,0]
	v_pk_mul_f32 v[40:41], v[0:1], v[40:41]
	v_pk_mul_f32 v[42:43], v[2:3], v[42:43]
	v_pk_mul_f32 v[44:45], v[4:5], v[44:45]
	v_pk_mul_f32 v[46:47], v[6:7], v[46:47]
	v_pk_mul_f32 v[48:49], v[8:9], v[48:49]
	v_pk_mul_f32 v[50:51], v[10:11], v[50:51]
	v_pk_mul_f32 v[52:53], v[12:13], v[52:53]
	v_pk_mul_f32 v[54:55], v[14:15], v[54:55]
	v_pk_fma_f32 v[40:41], v[214:215], v[40:41], v[198:199]
	v_pk_fma_f32 v[42:43], v[216:217], v[42:43], v[200:201]
	v_pk_fma_f32 v[44:45], v[218:219], v[44:45], v[202:203]
	v_pk_fma_f32 v[46:47], v[220:221], v[46:47], v[204:205]
	v_pk_fma_f32 v[48:49], v[222:223], v[48:49], v[206:207]
	v_pk_fma_f32 v[50:51], v[224:225], v[50:51], v[208:209]
	v_pk_fma_f32 v[52:53], v[226:227], v[52:53], v[210:211]
	v_pk_fma_f32 v[54:55], v[228:229], v[54:55], v[212:213]
	v_cvt_pk_bf16_f32 v40, v40, v41
	v_cvt_pk_bf16_f32 v41, v42, v43
	v_cvt_pk_bf16_f32 v44, v44, v45
	v_cvt_pk_bf16_f32 v45, v46, v47
	v_cvt_pk_bf16_f32 v48, v48, v49
	v_cvt_pk_bf16_f32 v49, v50, v51
	v_cvt_pk_bf16_f32 v52, v52, v53
	v_cvt_pk_bf16_f32 v53, v54, v55
	global_store_dwordx2 v100, v[40:41], s[40:41]
	global_store_dwordx2 v100, v[44:45], s[40:41] offset:512
	global_store_dwordx2 v100, v[48:49], s[40:41] offset:1024
	global_store_dwordx2 v100, v[52:53], s[40:41] offset:1536
	s_add_u32 s40, s40, 0x400000
	s_addc_u32 s41, s41, 0
	global_load_dwordx2 v[112:113], v100, s[38:39]
	global_load_dwordx2 v[114:115], v100, s[38:39] offset:512
	global_load_dwordx2 v[116:117], v100, s[38:39] offset:1024
	global_load_dwordx2 v[118:119], v100, s[38:39] offset:1536
	s_add_u32 s38, s38, 0x400000
	s_addc_u32 s39, s39, 0
	s_waitcnt vmcnt(28)
; __device__ __forceinline__ void norm_phase(const void* src_lat, int lat_f32, const float* src_ctx, int nrows, const float* gvec, const float* mods_l, int sh_off, int sc_off, bf16_t* U, const float* part, int nparts, float* ctx_out) {
;     ...
;         if (row < MLAT && !lat_f32) { const bf16_t* src = (const bf16_t*)src_lat + (size_t)row * DM + 4 * lane;
; #pragma unroll
;             for (int j = 0; j < 4; ++j) { const u32x2 w = *(const u32x2*)(src + 256 * j);
;                 v[j] = (f32x4){__uint_as_float(w.x << 16), __uint_as_float(w.x & 0xffff0000u), __uint_as_float(w.y << 16), __uint_as_float(w.y & 0xffff0000u)}; } }
;         else { const float* src = row < MLAT ? (const float*)src_lat + (size_t)row * DM : src_ctx + (size_t)(row - MLAT) * DM;
; #pragma unroll
;             for (int j = 0; j < 4; ++j) v[j] = *(const f32x4*)(src + 4 * lane + 256 * j); }
; #pragma unroll
;         for (int j = 0; j < 4; ++j) { ss += (v[j][0] * v[j][0] + v[j][1] * v[j][1]) + (v[j][2] * v[j][2] + v[j][3] * v[j][3]); }
;         if (nparts != 0 && row >= MLAT) {
;             for (int ch = 0; ch < nparts; ch += 4) {
;                 f32x4 pv[4][4];
; #pragma unroll
;                 for (int c4 = 0; c4 < 4; ++c4) { const float* pr = part + ((size_t)(ch + c4) * MCTX + (row - MLAT)) * DM + 4 * lane;
; #pragma unroll
;                     for (int j = 0; j < 4; ++j) pv[c4][j] = *(const f32x4*)(pr + 256 * j); }
; #pragma unroll
;                 for (int c4 = 0; c4 < 4; ++c4)
; #pragma unroll
;                     for (int j = 0; j < 4; ++j) v[j] = v[j] + pv[c4][j]; }
;             ss = 0.f;
; #pragma unroll
;             for (int j = 0; j < 4; ++j) { *(f32x4*)(ctx_out + (size_t)(row - MLAT) * DM + 4 * lane + 256 * j) = v[j]; ss += (v[j][0] * v[j][0] + v[j][1] * v[j][1]) + (v[j][2] * v[j][2] + v[j][3] * v[j][3]); }
;         }
;         const float rs = rsqrtf(wave_sum64(ss) * (1.0f / DM) + EPS);
;         const float* shp = mods_l + s * 6144 + sh_off + 4 * lane; const float* scp = mods_l + s * 6144 + sc_off + 4 * lane;
;         bf16_t* up = U + (size_t)row * DM + 4 * lane;
; #pragma unroll
;         for (int j = 0; j < 4; ++j) { const f32x4 sh = *(const f32x4*)(shp + 256 * j), sc = *(const f32x4*)(scp + 256 * j);
;             const f32x4 y = v[j] * rs * gv[j] * (sc + 1.0f) + sh;
;             u32x2 o; o.x = pkbf(y[0], y[1]); o.y = pkbf(y[2], y[3]); *(u32x2*)(up + 256 * j) = o; }
	v_lshlrev_b32_e32 v40, 16, v120
	v_and_b32_e32 v41, 0xffff0000, v120
	v_lshlrev_b32_e32 v42, 16, v121
	v_and_b32_e32 v43, 0xffff0000, v121
	v_lshlrev_b32_e32 v44, 16, v122
	v_and_b32_e32 v45, 0xffff0000, v122
	v_lshlrev_b32_e32 v46, 16, v123
	v_and_b32_e32 v47, 0xffff0000, v123
	v_lshlrev_b32_e32 v48, 16, v124
	v_and_b32_e32 v49, 0xffff0000, v124
	v_lshlrev_b32_e32 v50, 16, v125
	v_and_b32_e32 v51, 0xffff0000, v125
	v_lshlrev_b32_e32 v52, 16, v126
	v_and_b32_e32 v53, 0xffff0000, v126
	v_lshlrev_b32_e32 v54, 16, v127
	v_and_b32_e32 v55, 0xffff0000, v127
	v_mul_f32_e32 v56, v41, v41
	v_mul_f32_e32 v57, v43, v43
	v_fmac_f32_e32 v56, v40, v40
	v_fmac_f32_e32 v57, v42, v42
	v_add_f32_e32 v58, v56, v57
	v_mul_f32_e32 v56, v45, v45
	v_mul_f32_e32 v57, v47, v47
	v_fmac_f32_e32 v56, v44, v44
	v_fmac_f32_e32 v57, v46, v46
	v_add_f32_e32 v56, v56, v57
	v_add_f32_e32 v58, v58, v56
	v_mul_f32_e32 v56, v49, v49
	v_mul_f32_e32 v57, v51, v51
	v_fmac_f32_e32 v56, v48, v48
	v_fmac_f32_e32 v57, v50, v50
	v_add_f32_e32 v56, v56, v57
	v_add_f32_e32 v58, v58, v56
	v_mul_f32_e32 v56, v53, v53
	v_mul_f32_e32 v57, v55, v55
	v_fmac_f32_e32 v56, v52, v52
	v_fmac_f32_e32 v57, v54, v54
	v_add_f32_e32 v56, v56, v57
	v_add_f32_e32 v58, v58, v56
	s_nop 1
	v_add_f32_dpp v58, v58, v58 quad_perm:[1,0,3,2] row_mask:0xf bank_mask:0xf bound_ctrl:1
	s_nop 1
	v_add_f32_dpp v58, v58, v58 quad_perm:[2,3,0,1] row_mask:0xf bank_mask:0xf bound_ctrl:1
	s_nop 1
	v_add_f32_dpp v58, v58, v58 row_half_mirror row_mask:0xf bank_mask:0xf bound_ctrl:1
	s_nop 1
	v_add_f32_dpp v58, v58, v58 row_mirror row_mask:0xf bank_mask:0xf bound_ctrl:1
	v_mov_b32_e32 v56, v58
	s_nop 1
	v_permlane16_swap_b32_e32 v58, v56
	v_add_f32_e32 v58, v58, v56
	v_mov_b32_e32 v56, v58
	s_nop 1
	v_permlane32_swap_b32_e32 v58, v56
	v_add_f32_e32 v58, v58, v56
	v_fmamk_f32 v60, v58, 0x3a800000, v153
	v_rsq_f32_e32 v60, v60
	s_nop 0
	v_pk_mul_f32 v[40:41], v[40:41], v[60:61] op_sel_hi:[1,0]
	v_pk_mul_f32 v[42:43], v[42:43], v[60:61] op_sel_hi:[1,0]
	v_pk_mul_f32 v[44:45], v[44:45], v[60:61] op_sel_hi:[1,0]
	v_pk_mul_f32 v[46:47], v[46:47], v[60:61] op_sel_hi:[1,0]
	v_pk_mul_f32 v[48:49], v[48:49], v[60:61] op_sel_hi:[1,0]
	v_pk_mul_f32 v[50:51], v[50:51], v[60:61] op_sel_hi:[1,0]
	v_pk_mul_f32 v[52:53], v[52:53], v[60:61] op_sel_hi:[1,0]
	v_pk_mul_f32 v[54:55], v[54:55], v[60:61] op_sel_hi:[1,0]
	v_pk_mul_f32 v[40:41], v[0:1], v[40:41]
	v_pk_mul_f32 v[42:43], v[2:3], v[42:43]
	v_pk_mul_f32 v[44:45], v[4:5], v[44:45]
	v_pk_mul_f32 v[46:47], v[6:7], v[46:47]
	v_pk_mul_f32 v[48:49], v[8:9], v[48:49]
	v_pk_mul_f32 v[50:51], v[10:11], v[50:51]
	v_pk_mul_f32 v[52:53], v[12:13], v[52:53]
	v_pk_mul_f32 v[54:55], v[14:15], v[54:55]
	v_pk_fma_f32 v[40:41], v[214:215], v[40:41], v[198:199]
	v_pk_fma_f32 v[42:43], v[216:217], v[42:43], v[200:201]
	v_pk_fma_f32 v[44:45], v[218:219], v[44:45], v[202:203]
	v_pk_fma_f32 v[46:47], v[220:221], v[46:47], v[204:205]
	v_pk_fma_f32 v[48:49], v[222:223], v[48:49], v[206:207]
	v_pk_fma_f32 v[50:51], v[224:225], v[50:51], v[208:209]
	v_pk_fma_f32 v[52:53], v[226:227], v[52:53], v[210:211]
	v_pk_fma_f32 v[54:55], v[228:229], v[54:55], v[212:213]
	v_cvt_pk_bf16_f32 v40, v40, v41
	v_cvt_pk_bf16_f32 v41, v42, v43
	v_cvt_pk_bf16_f32 v44, v44, v45
	v_cvt_pk_bf16_f32 v45, v46, v47
	v_cvt_pk_bf16_f32 v48, v48, v49
	v_cvt_pk_bf16_f32 v49, v50, v51
	v_cvt_pk_bf16_f32 v52, v52, v53
	v_cvt_pk_bf16_f32 v53, v54, v55
	global_store_dwordx2 v100, v[40:41], s[40:41]
	global_store_dwordx2 v100, v[44:45], s[40:41] offset:512
	global_store_dwordx2 v100, v[48:49], s[40:41] offset:1024
	global_store_dwordx2 v100, v[52:53], s[40:41] offset:1536
	s_add_u32 s40, s40, 0x400000
	s_addc_u32 s41, s41, 0
	global_load_dwordx2 v[120:121], v100, s[38:39]
	global_load_dwordx2 v[122:123], v100, s[38:39] offset:512
	global_load_dwordx2 v[124:125], v100, s[38:39] offset:1024
	global_load_dwordx2 v[126:127], v100, s[38:39] offset:1536
	s_add_u32 s38, s38, 0x400000
	s_addc_u32 s39, s39, 0
	s_waitcnt vmcnt(32)
	v_lshlrev_b32_e32 v40, 16, v128
	v_and_b32_e32 v41, 0xffff0000, v128
	v_lshlrev_b32_e32 v42, 16, v129
	v_and_b32_e32 v43, 0xffff0000, v129
	v_lshlrev_b32_e32 v44, 16, v130
	v_and_b32_e32 v45, 0xffff0000, v130
	v_lshlrev_b32_e32 v46, 16, v131
	v_and_b32_e32 v47, 0xffff0000, v131
	v_lshlrev_b32_e32 v48, 16, v132
	v_and_b32_e32 v49, 0xffff0000, v132
	v_lshlrev_b32_e32 v50, 16, v133
	v_and_b32_e32 v51, 0xffff0000, v133
	v_lshlrev_b32_e32 v52, 16, v134
	v_and_b32_e32 v53, 0xffff0000, v134
	v_lshlrev_b32_e32 v54, 16, v135
	v_and_b32_e32 v55, 0xffff0000, v135
	v_mul_f32_e32 v56, v41, v41
	v_mul_f32_e32 v57, v43, v43
	v_fmac_f32_e32 v56, v40, v40
	v_fmac_f32_e32 v57, v42, v42
	v_add_f32_e32 v58, v56, v57
	v_mul_f32_e32 v56, v45, v45
	v_mul_f32_e32 v57, v47, v47
	v_fmac_f32_e32 v56, v44, v44
	v_fmac_f32_e32 v57, v46, v46
	v_add_f32_e32 v56, v56, v57
	v_add_f32_e32 v58, v58, v56
	v_mul_f32_e32 v56, v49, v49
	v_mul_f32_e32 v57, v51, v51
	v_fmac_f32_e32 v56, v48, v48
	v_fmac_f32_e32 v57, v50, v50
	v_add_f32_e32 v56, v56, v57
	v_add_f32_e32 v58, v58, v56
	v_mul_f32_e32 v56, v53, v53
	v_mul_f32_e32 v57, v55, v55
	v_fmac_f32_e32 v56, v52, v52
	v_fmac_f32_e32 v57, v54, v54
	v_add_f32_e32 v56, v56, v57
	v_add_f32_e32 v58, v58, v56
	s_nop 1
	v_add_f32_dpp v58, v58, v58 quad_perm:[1,0,3,2] row_mask:0xf bank_mask:0xf bound_ctrl:1
	s_nop 1
	v_add_f32_dpp v58, v58, v58 quad_perm:[2,3,0,1] row_mask:0xf bank_mask:0xf bound_ctrl:1
	s_nop 1
	v_add_f32_dpp v58, v58, v58 row_half_mirror row_mask:0xf bank_mask:0xf bound_ctrl:1
	s_nop 1
	v_add_f32_dpp v58, v58, v58 row_mirror row_mask:0xf bank_mask:0xf bound_ctrl:1
	v_mov_b32_e32 v56, v58
	s_nop 1
; __device__ __forceinline__ void norm_phase(const void* src_lat, int lat_f32, const float* src_ctx, int nrows, const float* gvec, const float* mods_l, int sh_off, int sc_off, bf16_t* U, const float* part, int nparts, float* ctx_out) {
;     ...
;         if (row < MLAT && !lat_f32) { const bf16_t* src = (const bf16_t*)src_lat + (size_t)row * DM + 4 * lane;
; #pragma unroll
;             for (int j = 0; j < 4; ++j) { const u32x2 w = *(const u32x2*)(src + 256 * j);
;                 v[j] = (f32x4){__uint_as_float(w.x << 16), __uint_as_float(w.x & 0xffff0000u), __uint_as_float(w.y << 16), __uint_as_float(w.y & 0xffff0000u)}; } }
;         else { const float* src = row < MLAT ? (const float*)src_lat + (size_t)row * DM : src_ctx + (size_t)(row - MLAT) * DM;
; #pragma unroll
;             for (int j = 0; j < 4; ++j) v[j] = *(const f32x4*)(src + 4 * lane + 256 * j); }
; #pragma unroll
;         for (int j = 0; j < 4; ++j) { ss += (v[j][0] * v[j][0] + v[j][1] * v[j][1]) + (v[j][2] * v[j][2] + v[j][3] * v[j][3]); }
;         if (nparts != 0 && row >= MLAT) {
;             for (int ch = 0; ch < nparts; ch += 4) {
;                 f32x4 pv[4][4];
; #pragma unroll
;                 for (int c4 = 0; c4 < 4; ++c4) { const float* pr = part + ((size_t)(ch + c4) * MCTX + (row - MLAT)) * DM + 4 * lane;
; #pragma unroll
;                     for (int j = 0; j < 4; ++j) pv[c4][j] = *(const f32x4*)(pr + 256 * j); }
; #pragma unroll
;                 for (int c4 = 0; c4 < 4; ++c4)
; #pragma unroll
;                     for (int j = 0; j < 4; ++j) v[j] = v[j] + pv[c4][j]; }
;             ss = 0.f;
; #pragma unroll
;             for (int j = 0; j < 4; ++j) { *(f32x4*)(ctx_out + (size_t)(row - MLAT) * DM + 4 * lane + 256 * j) = v[j]; ss += (v[j][0] * v[j][0] + v[j][1] * v[j][1]) + (v[j][2] * v[j][2] + v[j][3] * v[j][3]); }
;         }
;         const float rs = rsqrtf(wave_sum64(ss) * (1.0f / DM) + EPS);
;         const float* shp = mods_l + s * 6144 + sh_off + 4 * lane; const float* scp = mods_l + s * 6144 + sc_off + 4 * lane;
;         bf16_t* up = U + (size_t)row * DM + 4 * lane;
; #pragma unroll
;         for (int j = 0; j < 4; ++j) { const f32x4 sh = *(const f32x4*)(shp + 256 * j), sc = *(const f32x4*)(scp + 256 * j);
;             const f32x4 y = v[j] * rs * gv[j] * (sc + 1.0f) + sh;
;             u32x2 o; o.x = pkbf(y[0], y[1]); o.y = pkbf(y[2], y[3]); *(u32x2*)(up + 256 * j) = o; }
	v_permlane16_swap_b32_e32 v58, v56
	v_add_f32_e32 v58, v58, v56
	v_mov_b32_e32 v56, v58
	s_nop 1
	v_permlane32_swap_b32_e32 v58, v56
	v_add_f32_e32 v58, v58, v56
	v_fmamk_f32 v60, v58, 0x3a800000, v153
	v_rsq_f32_e32 v60, v60
	s_nop 0
	v_pk_mul_f32 v[40:41], v[40:41], v[60:61] op_sel_hi:[1,0]
	v_pk_mul_f32 v[42:43], v[42:43], v[60:61] op_sel_hi:[1,0]
	v_pk_mul_f32 v[44:45], v[44:45], v[60:61] op_sel_hi:[1,0]
	v_pk_mul_f32 v[46:47], v[46:47], v[60:61] op_sel_hi:[1,0]
	v_pk_mul_f32 v[48:49], v[48:49], v[60:61] op_sel_hi:[1,0]
	v_pk_mul_f32 v[50:51], v[50:51], v[60:61] op_sel_hi:[1,0]
	v_pk_mul_f32 v[52:53], v[52:53], v[60:61] op_sel_hi:[1,0]
	v_pk_mul_f32 v[54:55], v[54:55], v[60:61] op_sel_hi:[1,0]
	v_pk_mul_f32 v[40:41], v[0:1], v[40:41]
	v_pk_mul_f32 v[42:43], v[2:3], v[42:43]
	v_pk_mul_f32 v[44:45], v[4:5], v[44:45]
	v_pk_mul_f32 v[46:47], v[6:7], v[46:47]
	v_pk_mul_f32 v[48:49], v[8:9], v[48:49]
	v_pk_mul_f32 v[50:51], v[10:11], v[50:51]
	v_pk_mul_f32 v[52:53], v[12:13], v[52:53]
	v_pk_mul_f32 v[54:55], v[14:15], v[54:55]
	v_pk_fma_f32 v[40:41], v[214:215], v[40:41], v[198:199]
	v_pk_fma_f32 v[42:43], v[216:217], v[42:43], v[200:201]
	v_pk_fma_f32 v[44:45], v[218:219], v[44:45], v[202:203]
	v_pk_fma_f32 v[46:47], v[220:221], v[46:47], v[204:205]
	v_pk_fma_f32 v[48:49], v[222:223], v[48:49], v[206:207]
	v_pk_fma_f32 v[50:51], v[224:225], v[50:51], v[208:209]
	v_pk_fma_f32 v[52:53], v[226:227], v[52:53], v[210:211]
	v_pk_fma_f32 v[54:55], v[228:229], v[54:55], v[212:213]
	v_cvt_pk_bf16_f32 v40, v40, v41
	v_cvt_pk_bf16_f32 v41, v42, v43
	v_cvt_pk_bf16_f32 v44, v44, v45
	v_cvt_pk_bf16_f32 v45, v46, v47
	v_cvt_pk_bf16_f32 v48, v48, v49
	v_cvt_pk_bf16_f32 v49, v50, v51
	v_cvt_pk_bf16_f32 v52, v52, v53
	v_cvt_pk_bf16_f32 v53, v54, v55
	global_store_dwordx2 v100, v[40:41], s[40:41]
	global_store_dwordx2 v100, v[44:45], s[40:41] offset:512
	global_store_dwordx2 v100, v[48:49], s[40:41] offset:1024
	global_store_dwordx2 v100, v[52:53], s[40:41] offset:1536
	s_add_u32 s40, s40, 0x400000
	s_addc_u32 s41, s41, 0
	global_load_dwordx2 v[128:129], v100, s[38:39]
	global_load_dwordx2 v[130:131], v100, s[38:39] offset:512
	global_load_dwordx2 v[132:133], v100, s[38:39] offset:1024
	global_load_dwordx2 v[134:135], v100, s[38:39] offset:1536
	s_add_u32 s38, s38, 0x400000
	s_addc_u32 s39, s39, 0
	s_waitcnt vmcnt(24)
	v_pk_add_f32 v[84:85], v[84:85], 1.0 op_sel_hi:[1,0]
	v_pk_add_f32 v[86:87], v[86:87], 1.0 op_sel_hi:[1,0]
	v_pk_add_f32 v[88:89], v[88:89], 1.0 op_sel_hi:[1,0]
	v_pk_add_f32 v[90:91], v[90:91], 1.0 op_sel_hi:[1,0]
	v_pk_add_f32 v[92:93], v[92:93], 1.0 op_sel_hi:[1,0]
	v_pk_add_f32 v[94:95], v[94:95], 1.0 op_sel_hi:[1,0]
	v_pk_add_f32 v[96:97], v[96:97], 1.0 op_sel_hi:[1,0]
	v_pk_add_f32 v[98:99], v[98:99], 1.0 op_sel_hi:[1,0]
	v_lshlrev_b32_e32 v40, 16, v104
	v_and_b32_e32 v41, 0xffff0000, v104
	v_lshlrev_b32_e32 v42, 16, v105
	v_and_b32_e32 v43, 0xffff0000, v105
	v_lshlrev_b32_e32 v44, 16, v106
	v_and_b32_e32 v45, 0xffff0000, v106
	v_lshlrev_b32_e32 v46, 16, v107
	v_and_b32_e32 v47, 0xffff0000, v107
	v_lshlrev_b32_e32 v48, 16, v108
	v_and_b32_e32 v49, 0xffff0000, v108
	v_lshlrev_b32_e32 v50, 16, v109
	v_and_b32_e32 v51, 0xffff0000, v109
	v_lshlrev_b32_e32 v52, 16, v110
	v_and_b32_e32 v53, 0xffff0000, v110
	v_lshlrev_b32_e32 v54, 16, v111
	v_and_b32_e32 v55, 0xffff0000, v111
	v_mul_f32_e32 v56, v41, v41
	v_mul_f32_e32 v57, v43, v43
	v_fmac_f32_e32 v56, v40, v40
	v_fmac_f32_e32 v57, v42, v42
	v_add_f32_e32 v58, v56, v57
	v_mul_f32_e32 v56, v45, v45
	v_mul_f32_e32 v57, v47, v47
	v_fmac_f32_e32 v56, v44, v44
	v_fmac_f32_e32 v57, v46, v46
	v_add_f32_e32 v56, v56, v57
	v_add_f32_e32 v58, v58, v56
	v_mul_f32_e32 v56, v49, v49
	v_mul_f32_e32 v57, v51, v51
	v_fmac_f32_e32 v56, v48, v48
	v_fmac_f32_e32 v57, v50, v50
	v_add_f32_e32 v56, v56, v57
	v_add_f32_e32 v58, v58, v56
	v_mul_f32_e32 v56, v53, v53
	v_mul_f32_e32 v57, v55, v55
	v_fmac_f32_e32 v56, v52, v52
	v_fmac_f32_e32 v57, v54, v54
	v_add_f32_e32 v56, v56, v57
	v_add_f32_e32 v58, v58, v56
	s_nop 1
	v_add_f32_dpp v58, v58, v58 quad_perm:[1,0,3,2] row_mask:0xf bank_mask:0xf bound_ctrl:1
	s_nop 1
	v_add_f32_dpp v58, v58, v58 quad_perm:[2,3,0,1] row_mask:0xf bank_mask:0xf bound_ctrl:1
	s_nop 1
	v_add_f32_dpp v58, v58, v58 row_half_mirror row_mask:0xf bank_mask:0xf bound_ctrl:1
	s_nop 1
	v_add_f32_dpp v58, v58, v58 row_mirror row_mask:0xf bank_mask:0xf bound_ctrl:1
	v_mov_b32_e32 v56, v58
	s_nop 1
	v_permlane16_swap_b32_e32 v58, v56
	v_add_f32_e32 v58, v58, v56
	v_mov_b32_e32 v56, v58
	s_nop 1
	v_permlane32_swap_b32_e32 v58, v56
	v_add_f32_e32 v58, v58, v56
	v_fmamk_f32 v60, v58, 0x3a800000, v153
	v_rsq_f32_e32 v60, v60
	s_nop 0
	v_pk_mul_f32 v[40:41], v[40:41], v[60:61] op_sel_hi:[1,0]
	v_pk_mul_f32 v[42:43], v[42:43], v[60:61] op_sel_hi:[1,0]
	v_pk_mul_f32 v[44:45], v[44:45], v[60:61] op_sel_hi:[1,0]
	v_pk_mul_f32 v[46:47], v[46:47], v[60:61] op_sel_hi:[1,0]
	v_pk_mul_f32 v[48:49], v[48:49], v[60:61] op_sel_hi:[1,0]
	v_pk_mul_f32 v[50:51], v[50:51], v[60:61] op_sel_hi:[1,0]
	v_pk_mul_f32 v[52:53], v[52:53], v[60:61] op_sel_hi:[1,0]
	v_pk_mul_f32 v[54:55], v[54:55], v[60:61] op_sel_hi:[1,0]
	v_pk_mul_f32 v[40:41], v[0:1], v[40:41]
	v_pk_mul_f32 v[42:43], v[2:3], v[42:43]
	v_pk_mul_f32 v[44:45], v[4:5], v[44:45]
	v_pk_mul_f32 v[46:47], v[6:7], v[46:47]
	v_pk_mul_f32 v[48:49], v[8:9], v[48:49]
	v_pk_mul_f32 v[50:51], v[10:11], v[50:51]
	v_pk_mul_f32 v[52:53], v[12:13], v[52:53]
	v_pk_mul_f32 v[54:55], v[14:15], v[54:55]
	v_pk_fma_f32 v[40:41], v[84:85], v[40:41], v[68:69]
	v_pk_fma_f32 v[42:43], v[86:87], v[42:43], v[70:71]
	v_pk_fma_f32 v[44:45], v[88:89], v[44:45], v[72:73]
; __device__ __forceinline__ void norm_phase(const void* src_lat, int lat_f32, const float* src_ctx, int nrows, const float* gvec, const float* mods_l, int sh_off, int sc_off, bf16_t* U, const float* part, int nparts, float* ctx_out) {
;     ...
;         if (row < MLAT && !lat_f32) { const bf16_t* src = (const bf16_t*)src_lat + (size_t)row * DM + 4 * lane;
; #pragma unroll
;             for (int j = 0; j < 4; ++j) { const u32x2 w = *(const u32x2*)(src + 256 * j);
;                 v[j] = (f32x4){__uint_as_float(w.x << 16), __uint_as_float(w.x & 0xffff0000u), __uint_as_float(w.y << 16), __uint_as_float(w.y & 0xffff0000u)}; } }
;         else { const float* src = row < MLAT ? (const float*)src_lat + (size_t)row * DM : src_ctx + (size_t)(row - MLAT) * DM;
; #pragma unroll
;             for (int j = 0; j < 4; ++j) v[j] = *(const f32x4*)(src + 4 * lane + 256 * j); }
; #pragma unroll
;         for (int j = 0; j < 4; ++j) { ss += (v[j][0] * v[j][0] + v[j][1] * v[j][1]) + (v[j][2] * v[j][2] + v[j][3] * v[j][3]); }
;         if (nparts != 0 && row >= MLAT) {
;             for (int ch = 0; ch < nparts; ch += 4) {
;                 f32x4 pv[4][4];
; #pragma unroll
;                 for (int c4 = 0; c4 < 4; ++c4) { const float* pr = part + ((size_t)(ch + c4) * MCTX + (row - MLAT)) * DM + 4 * lane;
; #pragma unroll
;                     for (int j = 0; j < 4; ++j) pv[c4][j] = *(const f32x4*)(pr + 256 * j); }
; #pragma unroll
;                 for (int c4 = 0; c4 < 4; ++c4)
; #pragma unroll
;                     for (int j = 0; j < 4; ++j) v[j] = v[j] + pv[c4][j]; }
;             ss = 0.f;
; #pragma unroll
;             for (int j = 0; j < 4; ++j) { *(f32x4*)(ctx_out + (size_t)(row - MLAT) * DM + 4 * lane + 256 * j) = v[j]; ss += (v[j][0] * v[j][0] + v[j][1] * v[j][1]) + (v[j][2] * v[j][2] + v[j][3] * v[j][3]); }
;         }
;         const float rs = rsqrtf(wave_sum64(ss) * (1.0f / DM) + EPS);
;         const float* shp = mods_l + s * 6144 + sh_off + 4 * lane; const float* scp = mods_l + s * 6144 + sc_off + 4 * lane;
;         bf16_t* up = U + (size_t)row * DM + 4 * lane;
; #pragma unroll
;         for (int j = 0; j < 4; ++j) { const f32x4 sh = *(const f32x4*)(shp + 256 * j), sc = *(const f32x4*)(scp + 256 * j);
;             const f32x4 y = v[j] * rs * gv[j] * (sc + 1.0f) + sh;
;             u32x2 o; o.x = pkbf(y[0], y[1]); o.y = pkbf(y[2], y[3]); *(u32x2*)(up + 256 * j) = o; }
	v_pk_fma_f32 v[46:47], v[90:91], v[46:47], v[74:75]
	v_pk_fma_f32 v[48:49], v[92:93], v[48:49], v[76:77]
	v_pk_fma_f32 v[50:51], v[94:95], v[50:51], v[78:79]
	v_pk_fma_f32 v[52:53], v[96:97], v[52:53], v[80:81]
	v_pk_fma_f32 v[54:55], v[98:99], v[54:55], v[82:83]
	v_cvt_pk_bf16_f32 v40, v40, v41
	v_cvt_pk_bf16_f32 v41, v42, v43
	v_cvt_pk_bf16_f32 v44, v44, v45
	v_cvt_pk_bf16_f32 v45, v46, v47
	v_cvt_pk_bf16_f32 v48, v48, v49
	v_cvt_pk_bf16_f32 v49, v50, v51
	v_cvt_pk_bf16_f32 v52, v52, v53
	v_cvt_pk_bf16_f32 v53, v54, v55
	global_store_dwordx2 v100, v[40:41], s[40:41]
	global_store_dwordx2 v100, v[44:45], s[40:41] offset:512
	global_store_dwordx2 v100, v[48:49], s[40:41] offset:1024
	global_store_dwordx2 v100, v[52:53], s[40:41] offset:1536
	s_add_u32 s40, s40, 0x400000
	s_addc_u32 s41, s41, 0
	global_load_dwordx2 v[104:105], v100, s[38:39]
	global_load_dwordx2 v[106:107], v100, s[38:39] offset:512
	global_load_dwordx2 v[108:109], v100, s[38:39] offset:1024
	global_load_dwordx2 v[110:111], v100, s[38:39] offset:1536
	s_add_u32 s38, s38, 0x400000
	s_addc_u32 s39, s39, 0
	global_load_dwordx4 v[198:201], v101, s[42:43]
	global_load_dwordx4 v[202:205], v101, s[42:43] offset:1024
	global_load_dwordx4 v[206:209], v101, s[42:43] offset:2048
	global_load_dwordx4 v[210:213], v101, s[42:43] offset:3072
	global_load_dwordx4 v[214:217], v101, s[44:45]
	global_load_dwordx4 v[218:221], v101, s[44:45] offset:1024
	global_load_dwordx4 v[222:225], v101, s[44:45] offset:2048
	global_load_dwordx4 v[226:229], v101, s[44:45] offset:3072
	s_add_u32 s42, s42, 0x6000
	s_addc_u32 s43, s43, 0
	s_add_u32 s44, s44, 0x6000
	s_addc_u32 s45, s45, 0
	s_waitcnt vmcnt(32)
	v_lshlrev_b32_e32 v40, 16, v112
	v_and_b32_e32 v41, 0xffff0000, v112
	v_lshlrev_b32_e32 v42, 16, v113
	v_and_b32_e32 v43, 0xffff0000, v113
	v_lshlrev_b32_e32 v44, 16, v114
	v_and_b32_e32 v45, 0xffff0000, v114
	v_lshlrev_b32_e32 v46, 16, v115
	v_and_b32_e32 v47, 0xffff0000, v115
	v_lshlrev_b32_e32 v48, 16, v116
	v_and_b32_e32 v49, 0xffff0000, v116
	v_lshlrev_b32_e32 v50, 16, v117
	v_and_b32_e32 v51, 0xffff0000, v117
	v_lshlrev_b32_e32 v52, 16, v118
	v_and_b32_e32 v53, 0xffff0000, v118
	v_lshlrev_b32_e32 v54, 16, v119
	v_and_b32_e32 v55, 0xffff0000, v119
	v_mul_f32_e32 v56, v41, v41
	v_mul_f32_e32 v57, v43, v43
	v_fmac_f32_e32 v56, v40, v40
	v_fmac_f32_e32 v57, v42, v42
	v_add_f32_e32 v58, v56, v57
	v_mul_f32_e32 v56, v45, v45
	v_mul_f32_e32 v57, v47, v47
	v_fmac_f32_e32 v56, v44, v44
	v_fmac_f32_e32 v57, v46, v46
	v_add_f32_e32 v56, v56, v57
	v_add_f32_e32 v58, v58, v56
	v_mul_f32_e32 v56, v49, v49
	v_mul_f32_e32 v57, v51, v51
	v_fmac_f32_e32 v56, v48, v48
	v_fmac_f32_e32 v57, v50, v50
	v_add_f32_e32 v56, v56, v57
	v_add_f32_e32 v58, v58, v56
	v_mul_f32_e32 v56, v53, v53
	v_mul_f32_e32 v57, v55, v55
	v_fmac_f32_e32 v56, v52, v52
	v_fmac_f32_e32 v57, v54, v54
	v_add_f32_e32 v56, v56, v57
	v_add_f32_e32 v58, v58, v56
	s_nop 1
	v_add_f32_dpp v58, v58, v58 quad_perm:[1,0,3,2] row_mask:0xf bank_mask:0xf bound_ctrl:1
	s_nop 1
	v_add_f32_dpp v58, v58, v58 quad_perm:[2,3,0,1] row_mask:0xf bank_mask:0xf bound_ctrl:1
	s_nop 1
	v_add_f32_dpp v58, v58, v58 row_half_mirror row_mask:0xf bank_mask:0xf bound_ctrl:1
	s_nop 1
	v_add_f32_dpp v58, v58, v58 row_mirror row_mask:0xf bank_mask:0xf bound_ctrl:1
	v_mov_b32_e32 v56, v58
	s_nop 1
	v_permlane16_swap_b32_e32 v58, v56
	v_add_f32_e32 v58, v58, v56
	v_mov_b32_e32 v56, v58
	s_nop 1
	v_permlane32_swap_b32_e32 v58, v56
	v_add_f32_e32 v58, v58, v56
	v_fmamk_f32 v60, v58, 0x3a800000, v153
	v_rsq_f32_e32 v60, v60
	s_nop 0
	v_pk_mul_f32 v[40:41], v[40:41], v[60:61] op_sel_hi:[1,0]
	v_pk_mul_f32 v[42:43], v[42:43], v[60:61] op_sel_hi:[1,0]
	v_pk_mul_f32 v[44:45], v[44:45], v[60:61] op_sel_hi:[1,0]
	v_pk_mul_f32 v[46:47], v[46:47], v[60:61] op_sel_hi:[1,0]
	v_pk_mul_f32 v[48:49], v[48:49], v[60:61] op_sel_hi:[1,0]
	v_pk_mul_f32 v[50:51], v[50:51], v[60:61] op_sel_hi:[1,0]
	v_pk_mul_f32 v[52:53], v[52:53], v[60:61] op_sel_hi:[1,0]
	v_pk_mul_f32 v[54:55], v[54:55], v[60:61] op_sel_hi:[1,0]
	v_pk_mul_f32 v[40:41], v[0:1], v[40:41]
	v_pk_mul_f32 v[42:43], v[2:3], v[42:43]
	v_pk_mul_f32 v[44:45], v[4:5], v[44:45]
	v_pk_mul_f32 v[46:47], v[6:7], v[46:47]
	v_pk_mul_f32 v[48:49], v[8:9], v[48:49]
	v_pk_mul_f32 v[50:51], v[10:11], v[50:51]
	v_pk_mul_f32 v[52:53], v[12:13], v[52:53]
	v_pk_mul_f32 v[54:55], v[14:15], v[54:55]
	v_pk_fma_f32 v[40:41], v[84:85], v[40:41], v[68:69]
	v_pk_fma_f32 v[42:43], v[86:87], v[42:43], v[70:71]
	v_pk_fma_f32 v[44:45], v[88:89], v[44:45], v[72:73]
	v_pk_fma_f32 v[46:47], v[90:91], v[46:47], v[74:75]
	v_pk_fma_f32 v[48:49], v[92:93], v[48:49], v[76:77]
	v_pk_fma_f32 v[50:51], v[94:95], v[50:51], v[78:79]
	v_pk_fma_f32 v[52:53], v[96:97], v[52:53], v[80:81]
	v_pk_fma_f32 v[54:55], v[98:99], v[54:55], v[82:83]
	v_cvt_pk_bf16_f32 v40, v40, v41
	v_cvt_pk_bf16_f32 v41, v42, v43
	v_cvt_pk_bf16_f32 v44, v44, v45
	v_cvt_pk_bf16_f32 v45, v46, v47
	v_cvt_pk_bf16_f32 v48, v48, v49
	v_cvt_pk_bf16_f32 v49, v50, v51
	v_cvt_pk_bf16_f32 v52, v52, v53
	v_cvt_pk_bf16_f32 v53, v54, v55
	global_store_dwordx2 v100, v[40:41], s[40:41]
	global_store_dwordx2 v100, v[44:45], s[40:41] offset:512
	global_store_dwordx2 v100, v[48:49], s[40:41] offset:1024
	global_store_dwordx2 v100, v[52:53], s[40:41] offset:1536
	s_add_u32 s40, s40, 0x400000
	s_addc_u32 s41, s41, 0
	global_load_dwordx2 v[112:113], v100, s[38:39]
	global_load_dwordx2 v[114:115], v100, s[38:39] offset:512
	global_load_dwordx2 v[116:117], v100, s[38:39] offset:1024
	global_load_dwordx2 v[118:119], v100, s[38:39] offset:1536
	s_add_u32 s38, s38, 0x400000
	s_addc_u32 s39, s39, 0
	s_waitcnt vmcnt(32)
; __device__ __forceinline__ void norm_phase(const void* src_lat, int lat_f32, const float* src_ctx, int nrows, const float* gvec, const float* mods_l, int sh_off, int sc_off, bf16_t* U, const float* part, int nparts, float* ctx_out) {
;     ...
;         if (row < MLAT && !lat_f32) { const bf16_t* src = (const bf16_t*)src_lat + (size_t)row * DM + 4 * lane;
; #pragma unroll
;             for (int j = 0; j < 4; ++j) { const u32x2 w = *(const u32x2*)(src + 256 * j);
;                 v[j] = (f32x4){__uint_as_float(w.x << 16), __uint_as_float(w.x & 0xffff0000u), __uint_as_float(w.y << 16), __uint_as_float(w.y & 0xffff0000u)}; } }
;         else { const float* src = row < MLAT ? (const float*)src_lat + (size_t)row * DM : src_ctx + (size_t)(row - MLAT) * DM;
; #pragma unroll
;             for (int j = 0; j < 4; ++j) v[j] = *(const f32x4*)(src + 4 * lane + 256 * j); }
; #pragma unroll
;         for (int j = 0; j < 4; ++j) { ss += (v[j][0] * v[j][0] + v[j][1] * v[j][1]) + (v[j][2] * v[j][2] + v[j][3] * v[j][3]); }
;         if (nparts != 0 && row >= MLAT) {
;             for (int ch = 0; ch < nparts; ch += 4) {
;                 f32x4 pv[4][4];
; #pragma unroll
;                 for (int c4 = 0; c4 < 4; ++c4) { const float* pr = part + ((size_t)(ch + c4) * MCTX + (row - MLAT)) * DM + 4 * lane;
; #pragma unroll
;                     for (int j = 0; j < 4; ++j) pv[c4][j] = *(const f32x4*)(pr + 256 * j); }
; #pragma unroll
;                 for (int c4 = 0; c4 < 4; ++c4)
; #pragma unroll
;                     for (int j = 0; j < 4; ++j) v[j] = v[j] + pv[c4][j]; }
;             ss = 0.f;
; #pragma unroll
;             for (int j = 0; j < 4; ++j) { *(f32x4*)(ctx_out + (size_t)(row - MLAT) * DM + 4 * lane + 256 * j) = v[j]; ss += (v[j][0] * v[j][0] + v[j][1] * v[j][1]) + (v[j][2] * v[j][2] + v[j][3] * v[j][3]); }
;         }
;         const float rs = rsqrtf(wave_sum64(ss) * (1.0f / DM) + EPS);
;         const float* shp = mods_l + s * 6144 + sh_off + 4 * lane; const float* scp = mods_l + s * 6144 + sc_off + 4 * lane;
;         bf16_t* up = U + (size_t)row * DM + 4 * lane;
; #pragma unroll
;         for (int j = 0; j < 4; ++j) { const f32x4 sh = *(const f32x4*)(shp + 256 * j), sc = *(const f32x4*)(scp + 256 * j);
;             const f32x4 y = v[j] * rs * gv[j] * (sc + 1.0f) + sh;
;             u32x2 o; o.x = pkbf(y[0], y[1]); o.y = pkbf(y[2], y[3]); *(u32x2*)(up + 256 * j) = o; }
	v_lshlrev_b32_e32 v40, 16, v120
	v_and_b32_e32 v41, 0xffff0000, v120
	v_lshlrev_b32_e32 v42, 16, v121
	v_and_b32_e32 v43, 0xffff0000, v121
	v_lshlrev_b32_e32 v44, 16, v122
	v_and_b32_e32 v45, 0xffff0000, v122
	v_lshlrev_b32_e32 v46, 16, v123
	v_and_b32_e32 v47, 0xffff0000, v123
	v_lshlrev_b32_e32 v48, 16, v124
	v_and_b32_e32 v49, 0xffff0000, v124
	v_lshlrev_b32_e32 v50, 16, v125
	v_and_b32_e32 v51, 0xffff0000, v125
	v_lshlrev_b32_e32 v52, 16, v126
	v_and_b32_e32 v53, 0xffff0000, v126
	v_lshlrev_b32_e32 v54, 16, v127
	v_and_b32_e32 v55, 0xffff0000, v127
	v_mul_f32_e32 v56, v41, v41
	v_mul_f32_e32 v57, v43, v43
	v_fmac_f32_e32 v56, v40, v40
	v_fmac_f32_e32 v57, v42, v42
	v_add_f32_e32 v58, v56, v57
	v_mul_f32_e32 v56, v45, v45
	v_mul_f32_e32 v57, v47, v47
	v_fmac_f32_e32 v56, v44, v44
	v_fmac_f32_e32 v57, v46, v46
	v_add_f32_e32 v56, v56, v57
	v_add_f32_e32 v58, v58, v56
	v_mul_f32_e32 v56, v49, v49
	v_mul_f32_e32 v57, v51, v51
	v_fmac_f32_e32 v56, v48, v48
	v_fmac_f32_e32 v57, v50, v50
	v_add_f32_e32 v56, v56, v57
	v_add_f32_e32 v58, v58, v56
	v_mul_f32_e32 v56, v53, v53
	v_mul_f32_e32 v57, v55, v55
	v_fmac_f32_e32 v56, v52, v52
	v_fmac_f32_e32 v57, v54, v54
	v_add_f32_e32 v56, v56, v57
	v_add_f32_e32 v58, v58, v56
	s_nop 1
	v_add_f32_dpp v58, v58, v58 quad_perm:[1,0,3,2] row_mask:0xf bank_mask:0xf bound_ctrl:1
	s_nop 1
	v_add_f32_dpp v58, v58, v58 quad_perm:[2,3,0,1] row_mask:0xf bank_mask:0xf bound_ctrl:1
	s_nop 1
	v_add_f32_dpp v58, v58, v58 row_half_mirror row_mask:0xf bank_mask:0xf bound_ctrl:1
	s_nop 1
	v_add_f32_dpp v58, v58, v58 row_mirror row_mask:0xf bank_mask:0xf bound_ctrl:1
	v_mov_b32_e32 v56, v58
	s_nop 1
	v_permlane16_swap_b32_e32 v58, v56
	v_add_f32_e32 v58, v58, v56
	v_mov_b32_e32 v56, v58
	s_nop 1
	v_permlane32_swap_b32_e32 v58, v56
	v_add_f32_e32 v58, v58, v56
	v_fmamk_f32 v60, v58, 0x3a800000, v153
	v_rsq_f32_e32 v60, v60
	s_nop 0
	v_pk_mul_f32 v[40:41], v[40:41], v[60:61] op_sel_hi:[1,0]
	v_pk_mul_f32 v[42:43], v[42:43], v[60:61] op_sel_hi:[1,0]
	v_pk_mul_f32 v[44:45], v[44:45], v[60:61] op_sel_hi:[1,0]
	v_pk_mul_f32 v[46:47], v[46:47], v[60:61] op_sel_hi:[1,0]
	v_pk_mul_f32 v[48:49], v[48:49], v[60:61] op_sel_hi:[1,0]
	v_pk_mul_f32 v[50:51], v[50:51], v[60:61] op_sel_hi:[1,0]
	v_pk_mul_f32 v[52:53], v[52:53], v[60:61] op_sel_hi:[1,0]
	v_pk_mul_f32 v[54:55], v[54:55], v[60:61] op_sel_hi:[1,0]
	v_pk_mul_f32 v[40:41], v[0:1], v[40:41]
	v_pk_mul_f32 v[42:43], v[2:3], v[42:43]
	v_pk_mul_f32 v[44:45], v[4:5], v[44:45]
	v_pk_mul_f32 v[46:47], v[6:7], v[46:47]
	v_pk_mul_f32 v[48:49], v[8:9], v[48:49]
	v_pk_mul_f32 v[50:51], v[10:11], v[50:51]
	v_pk_mul_f32 v[52:53], v[12:13], v[52:53]
	v_pk_mul_f32 v[54:55], v[14:15], v[54:55]
	v_pk_fma_f32 v[40:41], v[84:85], v[40:41], v[68:69]
	v_pk_fma_f32 v[42:43], v[86:87], v[42:43], v[70:71]
	v_pk_fma_f32 v[44:45], v[88:89], v[44:45], v[72:73]
	v_pk_fma_f32 v[46:47], v[90:91], v[46:47], v[74:75]
	v_pk_fma_f32 v[48:49], v[92:93], v[48:49], v[76:77]
	v_pk_fma_f32 v[50:51], v[94:95], v[50:51], v[78:79]
	v_pk_fma_f32 v[52:53], v[96:97], v[52:53], v[80:81]
	v_pk_fma_f32 v[54:55], v[98:99], v[54:55], v[82:83]
	v_cvt_pk_bf16_f32 v40, v40, v41
	v_cvt_pk_bf16_f32 v41, v42, v43
	v_cvt_pk_bf16_f32 v44, v44, v45
	v_cvt_pk_bf16_f32 v45, v46, v47
	v_cvt_pk_bf16_f32 v48, v48, v49
	v_cvt_pk_bf16_f32 v49, v50, v51
	v_cvt_pk_bf16_f32 v52, v52, v53
	v_cvt_pk_bf16_f32 v53, v54, v55
	global_store_dwordx2 v100, v[40:41], s[40:41]
	global_store_dwordx2 v100, v[44:45], s[40:41] offset:512
	global_store_dwordx2 v100, v[48:49], s[40:41] offset:1024
	global_store_dwordx2 v100, v[52:53], s[40:41] offset:1536
	s_add_u32 s40, s40, 0x400000
	s_addc_u32 s41, s41, 0
	global_load_dwordx2 v[120:121], v100, s[38:39]
	global_load_dwordx2 v[122:123], v100, s[38:39] offset:512
	global_load_dwordx2 v[124:125], v100, s[38:39] offset:1024
	global_load_dwordx2 v[126:127], v100, s[38:39] offset:1536
	s_add_u32 s38, s38, 0x400000
	s_addc_u32 s39, s39, 0
	s_waitcnt vmcnt(32)
	v_lshlrev_b32_e32 v40, 16, v128
	v_and_b32_e32 v41, 0xffff0000, v128
	v_lshlrev_b32_e32 v42, 16, v129
	v_and_b32_e32 v43, 0xffff0000, v129
	v_lshlrev_b32_e32 v44, 16, v130
	v_and_b32_e32 v45, 0xffff0000, v130
	v_lshlrev_b32_e32 v46, 16, v131
	v_and_b32_e32 v47, 0xffff0000, v131
	v_lshlrev_b32_e32 v48, 16, v132
	v_and_b32_e32 v49, 0xffff0000, v132
	v_lshlrev_b32_e32 v50, 16, v133
	v_and_b32_e32 v51, 0xffff0000, v133
	v_lshlrev_b32_e32 v52, 16, v134
	v_and_b32_e32 v53, 0xffff0000, v134
	v_lshlrev_b32_e32 v54, 16, v135
	v_and_b32_e32 v55, 0xffff0000, v135
	v_mul_f32_e32 v56, v41, v41
	v_mul_f32_e32 v57, v43, v43
	v_fmac_f32_e32 v56, v40, v40
	v_fmac_f32_e32 v57, v42, v42
	v_add_f32_e32 v58, v56, v57
	v_mul_f32_e32 v56, v45, v45
	v_mul_f32_e32 v57, v47, v47
	v_fmac_f32_e32 v56, v44, v44
	v_fmac_f32_e32 v57, v46, v46
	v_add_f32_e32 v56, v56, v57
	v_add_f32_e32 v58, v58, v56
	v_mul_f32_e32 v56, v49, v49
	v_mul_f32_e32 v57, v51, v51
	v_fmac_f32_e32 v56, v48, v48
	v_fmac_f32_e32 v57, v50, v50
	v_add_f32_e32 v56, v56, v57
	v_add_f32_e32 v58, v58, v56
	v_mul_f32_e32 v56, v53, v53
	v_mul_f32_e32 v57, v55, v55
	v_fmac_f32_e32 v56, v52, v52
	v_fmac_f32_e32 v57, v54, v54
	v_add_f32_e32 v56, v56, v57
	v_add_f32_e32 v58, v58, v56
	s_nop 1
	v_add_f32_dpp v58, v58, v58 quad_perm:[1,0,3,2] row_mask:0xf bank_mask:0xf bound_ctrl:1
	s_nop 1
	v_add_f32_dpp v58, v58, v58 quad_perm:[2,3,0,1] row_mask:0xf bank_mask:0xf bound_ctrl:1
	s_nop 1
	v_add_f32_dpp v58, v58, v58 row_half_mirror row_mask:0xf bank_mask:0xf bound_ctrl:1
	s_nop 1
	v_add_f32_dpp v58, v58, v58 row_mirror row_mask:0xf bank_mask:0xf bound_ctrl:1
	v_mov_b32_e32 v56, v58
	s_nop 1
	v_permlane16_swap_b32_e32 v58, v56
; __device__ __forceinline__ void norm_phase(const void* src_lat, int lat_f32, const float* src_ctx, int nrows, const float* gvec, const float* mods_l, int sh_off, int sc_off, bf16_t* U, const float* part, int nparts, float* ctx_out) {
;     ...
;         if (row < MLAT && !lat_f32) { const bf16_t* src = (const bf16_t*)src_lat + (size_t)row * DM + 4 * lane;
; #pragma unroll
;             for (int j = 0; j < 4; ++j) { const u32x2 w = *(const u32x2*)(src + 256 * j);
;                 v[j] = (f32x4){__uint_as_float(w.x << 16), __uint_as_float(w.x & 0xffff0000u), __uint_as_float(w.y << 16), __uint_as_float(w.y & 0xffff0000u)}; } }
;         else { const float* src = row < MLAT ? (const float*)src_lat + (size_t)row * DM : src_ctx + (size_t)(row - MLAT) * DM;
; #pragma unroll
;             for (int j = 0; j < 4; ++j) v[j] = *(const f32x4*)(src + 4 * lane + 256 * j); }
; #pragma unroll
;         for (int j = 0; j < 4; ++j) { ss += (v[j][0] * v[j][0] + v[j][1] * v[j][1]) + (v[j][2] * v[j][2] + v[j][3] * v[j][3]); }
;         if (nparts != 0 && row >= MLAT) {
;             for (int ch = 0; ch < nparts; ch += 4) {
;                 f32x4 pv[4][4];
; #pragma unroll
;                 for (int c4 = 0; c4 < 4; ++c4) { const float* pr = part + ((size_t)(ch + c4) * MCTX + (row - MLAT)) * DM + 4 * lane;
; #pragma unroll
;                     for (int j = 0; j < 4; ++j) pv[c4][j] = *(const f32x4*)(pr + 256 * j); }
; #pragma unroll
;                 for (int c4 = 0; c4 < 4; ++c4)
; #pragma unroll
;                     for (int j = 0; j < 4; ++j) v[j] = v[j] + pv[c4][j]; }
;             ss = 0.f;
; #pragma unroll
;             for (int j = 0; j < 4; ++j) { *(f32x4*)(ctx_out + (size_t)(row - MLAT) * DM + 4 * lane + 256 * j) = v[j]; ss += (v[j][0] * v[j][0] + v[j][1] * v[j][1]) + (v[j][2] * v[j][2] + v[j][3] * v[j][3]); }
;         }
;         const float rs = rsqrtf(wave_sum64(ss) * (1.0f / DM) + EPS);
;         const float* shp = mods_l + s * 6144 + sh_off + 4 * lane; const float* scp = mods_l + s * 6144 + sc_off + 4 * lane;
;         bf16_t* up = U + (size_t)row * DM + 4 * lane;
; #pragma unroll
;         for (int j = 0; j < 4; ++j) { const f32x4 sh = *(const f32x4*)(shp + 256 * j), sc = *(const f32x4*)(scp + 256 * j);
;             const f32x4 y = v[j] * rs * gv[j] * (sc + 1.0f) + sh;
;             u32x2 o; o.x = pkbf(y[0], y[1]); o.y = pkbf(y[2], y[3]); *(u32x2*)(up + 256 * j) = o; }
	v_add_f32_e32 v58, v58, v56
	v_mov_b32_e32 v56, v58
	s_nop 1
	v_permlane32_swap_b32_e32 v58, v56
	v_add_f32_e32 v58, v58, v56
	v_fmamk_f32 v60, v58, 0x3a800000, v153
	v_rsq_f32_e32 v60, v60
	s_nop 0
	v_pk_mul_f32 v[40:41], v[40:41], v[60:61] op_sel_hi:[1,0]
	v_pk_mul_f32 v[42:43], v[42:43], v[60:61] op_sel_hi:[1,0]
	v_pk_mul_f32 v[44:45], v[44:45], v[60:61] op_sel_hi:[1,0]
	v_pk_mul_f32 v[46:47], v[46:47], v[60:61] op_sel_hi:[1,0]
	v_pk_mul_f32 v[48:49], v[48:49], v[60:61] op_sel_hi:[1,0]
	v_pk_mul_f32 v[50:51], v[50:51], v[60:61] op_sel_hi:[1,0]
	v_pk_mul_f32 v[52:53], v[52:53], v[60:61] op_sel_hi:[1,0]
	v_pk_mul_f32 v[54:55], v[54:55], v[60:61] op_sel_hi:[1,0]
	v_pk_mul_f32 v[40:41], v[0:1], v[40:41]
	v_pk_mul_f32 v[42:43], v[2:3], v[42:43]
	v_pk_mul_f32 v[44:45], v[4:5], v[44:45]
	v_pk_mul_f32 v[46:47], v[6:7], v[46:47]
	v_pk_mul_f32 v[48:49], v[8:9], v[48:49]
	v_pk_mul_f32 v[50:51], v[10:11], v[50:51]
	v_pk_mul_f32 v[52:53], v[12:13], v[52:53]
	v_pk_mul_f32 v[54:55], v[14:15], v[54:55]
	v_pk_fma_f32 v[40:41], v[84:85], v[40:41], v[68:69]
	v_pk_fma_f32 v[42:43], v[86:87], v[42:43], v[70:71]
	v_pk_fma_f32 v[44:45], v[88:89], v[44:45], v[72:73]
	v_pk_fma_f32 v[46:47], v[90:91], v[46:47], v[74:75]
	v_pk_fma_f32 v[48:49], v[92:93], v[48:49], v[76:77]
	v_pk_fma_f32 v[50:51], v[94:95], v[50:51], v[78:79]
	v_pk_fma_f32 v[52:53], v[96:97], v[52:53], v[80:81]
	v_pk_fma_f32 v[54:55], v[98:99], v[54:55], v[82:83]
	v_cvt_pk_bf16_f32 v40, v40, v41
	v_cvt_pk_bf16_f32 v41, v42, v43
	v_cvt_pk_bf16_f32 v44, v44, v45
	v_cvt_pk_bf16_f32 v45, v46, v47
	v_cvt_pk_bf16_f32 v48, v48, v49
	v_cvt_pk_bf16_f32 v49, v50, v51
	v_cvt_pk_bf16_f32 v52, v52, v53
	v_cvt_pk_bf16_f32 v53, v54, v55
	global_store_dwordx2 v100, v[40:41], s[40:41]
	global_store_dwordx2 v100, v[44:45], s[40:41] offset:512
	global_store_dwordx2 v100, v[48:49], s[40:41] offset:1024
	global_store_dwordx2 v100, v[52:53], s[40:41] offset:1536
	s_add_u32 s40, s40, 0x400000
	s_addc_u32 s41, s41, 0
	global_load_dwordx2 v[128:129], v100, s[38:39]
	global_load_dwordx2 v[130:131], v100, s[38:39] offset:512
	global_load_dwordx2 v[132:133], v100, s[38:39] offset:1024
	global_load_dwordx2 v[134:135], v100, s[38:39] offset:1536
	s_add_u32 s38, s38, 0x400000
	s_addc_u32 s39, s39, 0
	s_waitcnt vmcnt(24)
	v_pk_add_f32 v[214:215], v[214:215], 1.0 op_sel_hi:[1,0]
	v_pk_add_f32 v[216:217], v[216:217], 1.0 op_sel_hi:[1,0]
	v_pk_add_f32 v[218:219], v[218:219], 1.0 op_sel_hi:[1,0]
	v_pk_add_f32 v[220:221], v[220:221], 1.0 op_sel_hi:[1,0]
	v_pk_add_f32 v[222:223], v[222:223], 1.0 op_sel_hi:[1,0]
	v_pk_add_f32 v[224:225], v[224:225], 1.0 op_sel_hi:[1,0]
	v_pk_add_f32 v[226:227], v[226:227], 1.0 op_sel_hi:[1,0]
	v_pk_add_f32 v[228:229], v[228:229], 1.0 op_sel_hi:[1,0]
	v_lshlrev_b32_e32 v40, 16, v104
	v_and_b32_e32 v41, 0xffff0000, v104
	v_lshlrev_b32_e32 v42, 16, v105
	v_and_b32_e32 v43, 0xffff0000, v105
	v_lshlrev_b32_e32 v44, 16, v106
	v_and_b32_e32 v45, 0xffff0000, v106
	v_lshlrev_b32_e32 v46, 16, v107
	v_and_b32_e32 v47, 0xffff0000, v107
	v_lshlrev_b32_e32 v48, 16, v108
	v_and_b32_e32 v49, 0xffff0000, v108
	v_lshlrev_b32_e32 v50, 16, v109
	v_and_b32_e32 v51, 0xffff0000, v109
	v_lshlrev_b32_e32 v52, 16, v110
	v_and_b32_e32 v53, 0xffff0000, v110
	v_lshlrev_b32_e32 v54, 16, v111
	v_and_b32_e32 v55, 0xffff0000, v111
	v_mul_f32_e32 v56, v41, v41
	v_mul_f32_e32 v57, v43, v43
	v_fmac_f32_e32 v56, v40, v40
	v_fmac_f32_e32 v57, v42, v42
	v_add_f32_e32 v58, v56, v57
	v_mul_f32_e32 v56, v45, v45
	v_mul_f32_e32 v57, v47, v47
	v_fmac_f32_e32 v56, v44, v44
	v_fmac_f32_e32 v57, v46, v46
	v_add_f32_e32 v56, v56, v57
	v_add_f32_e32 v58, v58, v56
	v_mul_f32_e32 v56, v49, v49
	v_mul_f32_e32 v57, v51, v51
	v_fmac_f32_e32 v56, v48, v48
	v_fmac_f32_e32 v57, v50, v50
	v_add_f32_e32 v56, v56, v57
	v_add_f32_e32 v58, v58, v56
	v_mul_f32_e32 v56, v53, v53
	v_mul_f32_e32 v57, v55, v55
	v_fmac_f32_e32 v56, v52, v52
	v_fmac_f32_e32 v57, v54, v54
	v_add_f32_e32 v56, v56, v57
	v_add_f32_e32 v58, v58, v56
	s_nop 1
	v_add_f32_dpp v58, v58, v58 quad_perm:[1,0,3,2] row_mask:0xf bank_mask:0xf bound_ctrl:1
	s_nop 1
	v_add_f32_dpp v58, v58, v58 quad_perm:[2,3,0,1] row_mask:0xf bank_mask:0xf bound_ctrl:1
	s_nop 1
	v_add_f32_dpp v58, v58, v58 row_half_mirror row_mask:0xf bank_mask:0xf bound_ctrl:1
	s_nop 1
	v_add_f32_dpp v58, v58, v58 row_mirror row_mask:0xf bank_mask:0xf bound_ctrl:1
	v_mov_b32_e32 v56, v58
	s_nop 1
	v_permlane16_swap_b32_e32 v58, v56
	v_add_f32_e32 v58, v58, v56
	v_mov_b32_e32 v56, v58
	s_nop 1
	v_permlane32_swap_b32_e32 v58, v56
	v_add_f32_e32 v58, v58, v56
	v_fmamk_f32 v60, v58, 0x3a800000, v153
	v_rsq_f32_e32 v60, v60
	s_nop 0
	v_pk_mul_f32 v[40:41], v[40:41], v[60:61] op_sel_hi:[1,0]
	v_pk_mul_f32 v[42:43], v[42:43], v[60:61] op_sel_hi:[1,0]
	v_pk_mul_f32 v[44:45], v[44:45], v[60:61] op_sel_hi:[1,0]
	v_pk_mul_f32 v[46:47], v[46:47], v[60:61] op_sel_hi:[1,0]
	v_pk_mul_f32 v[48:49], v[48:49], v[60:61] op_sel_hi:[1,0]
	v_pk_mul_f32 v[50:51], v[50:51], v[60:61] op_sel_hi:[1,0]
	v_pk_mul_f32 v[52:53], v[52:53], v[60:61] op_sel_hi:[1,0]
	v_pk_mul_f32 v[54:55], v[54:55], v[60:61] op_sel_hi:[1,0]
	v_pk_mul_f32 v[40:41], v[0:1], v[40:41]
	v_pk_mul_f32 v[42:43], v[2:3], v[42:43]
	v_pk_mul_f32 v[44:45], v[4:5], v[44:45]
	v_pk_mul_f32 v[46:47], v[6:7], v[46:47]
	v_pk_mul_f32 v[48:49], v[8:9], v[48:49]
	v_pk_mul_f32 v[50:51], v[10:11], v[50:51]
	v_pk_mul_f32 v[52:53], v[12:13], v[52:53]
	v_pk_mul_f32 v[54:55], v[14:15], v[54:55]
	v_pk_fma_f32 v[40:41], v[214:215], v[40:41], v[198:199]
	v_pk_fma_f32 v[42:43], v[216:217], v[42:43], v[200:201]
	v_pk_fma_f32 v[44:45], v[218:219], v[44:45], v[202:203]
	v_pk_fma_f32 v[46:47], v[220:221], v[46:47], v[204:205]
; __device__ __forceinline__ void norm_phase(const void* src_lat, int lat_f32, const float* src_ctx, int nrows, const float* gvec, const float* mods_l, int sh_off, int sc_off, bf16_t* U, const float* part, int nparts, float* ctx_out) {
;     ...
;         if (row < MLAT && !lat_f32) { const bf16_t* src = (const bf16_t*)src_lat + (size_t)row * DM + 4 * lane;
; #pragma unroll
;             for (int j = 0; j < 4; ++j) { const u32x2 w = *(const u32x2*)(src + 256 * j);
;                 v[j] = (f32x4){__uint_as_float(w.x << 16), __uint_as_float(w.x & 0xffff0000u), __uint_as_float(w.y << 16), __uint_as_float(w.y & 0xffff0000u)}; } }
;         else { const float* src = row < MLAT ? (const float*)src_lat + (size_t)row * DM : src_ctx + (size_t)(row - MLAT) * DM;
; #pragma unroll
;             for (int j = 0; j < 4; ++j) v[j] = *(const f32x4*)(src + 4 * lane + 256 * j); }
; #pragma unroll
;         for (int j = 0; j < 4; ++j) { ss += (v[j][0] * v[j][0] + v[j][1] * v[j][1]) + (v[j][2] * v[j][2] + v[j][3] * v[j][3]); }
;         if (nparts != 0 && row >= MLAT) {
;             for (int ch = 0; ch < nparts; ch += 4) {
;                 f32x4 pv[4][4];
; #pragma unroll
;                 for (int c4 = 0; c4 < 4; ++c4) { const float* pr = part + ((size_t)(ch + c4) * MCTX + (row - MLAT)) * DM + 4 * lane;
; #pragma unroll
;                     for (int j = 0; j < 4; ++j) pv[c4][j] = *(const f32x4*)(pr + 256 * j); }
; #pragma unroll
;                 for (int c4 = 0; c4 < 4; ++c4)
; #pragma unroll
;                     for (int j = 0; j < 4; ++j) v[j] = v[j] + pv[c4][j]; }
;             ss = 0.f;
; #pragma unroll
;             for (int j = 0; j < 4; ++j) { *(f32x4*)(ctx_out + (size_t)(row - MLAT) * DM + 4 * lane + 256 * j) = v[j]; ss += (v[j][0] * v[j][0] + v[j][1] * v[j][1]) + (v[j][2] * v[j][2] + v[j][3] * v[j][3]); }
;         }
;         const float rs = rsqrtf(wave_sum64(ss) * (1.0f / DM) + EPS);
;         const float* shp = mods_l + s * 6144 + sh_off + 4 * lane; const float* scp = mods_l + s * 6144 + sc_off + 4 * lane;
;         bf16_t* up = U + (size_t)row * DM + 4 * lane;
; #pragma unroll
;         for (int j = 0; j < 4; ++j) { const f32x4 sh = *(const f32x4*)(shp + 256 * j), sc = *(const f32x4*)(scp + 256 * j);
;             const f32x4 y = v[j] * rs * gv[j] * (sc + 1.0f) + sh;
;             u32x2 o; o.x = pkbf(y[0], y[1]); o.y = pkbf(y[2], y[3]); *(u32x2*)(up + 256 * j) = o; }
	v_pk_fma_f32 v[48:49], v[222:223], v[48:49], v[206:207]
	v_pk_fma_f32 v[50:51], v[224:225], v[50:51], v[208:209]
	v_pk_fma_f32 v[52:53], v[226:227], v[52:53], v[210:211]
	v_pk_fma_f32 v[54:55], v[228:229], v[54:55], v[212:213]
	v_cvt_pk_bf16_f32 v40, v40, v41
	v_cvt_pk_bf16_f32 v41, v42, v43
	v_cvt_pk_bf16_f32 v44, v44, v45
	v_cvt_pk_bf16_f32 v45, v46, v47
	v_cvt_pk_bf16_f32 v48, v48, v49
	v_cvt_pk_bf16_f32 v49, v50, v51
	v_cvt_pk_bf16_f32 v52, v52, v53
	v_cvt_pk_bf16_f32 v53, v54, v55
	global_store_dwordx2 v100, v[40:41], s[40:41]
	global_store_dwordx2 v100, v[44:45], s[40:41] offset:512
	global_store_dwordx2 v100, v[48:49], s[40:41] offset:1024
	global_store_dwordx2 v100, v[52:53], s[40:41] offset:1536
	s_add_u32 s40, s40, 0x400000
	s_addc_u32 s41, s41, 0
	global_load_dwordx2 v[104:105], v100, s[38:39]
	global_load_dwordx2 v[106:107], v100, s[38:39] offset:512
	global_load_dwordx2 v[108:109], v100, s[38:39] offset:1024
	global_load_dwordx2 v[110:111], v100, s[38:39] offset:1536
	s_add_u32 s38, s38, 0x400000
	s_addc_u32 s39, s39, 0
	global_load_dwordx4 v[68:71], v101, s[42:43]
	global_load_dwordx4 v[72:75], v101, s[42:43] offset:1024
	global_load_dwordx4 v[76:79], v101, s[42:43] offset:2048
	global_load_dwordx4 v[80:83], v101, s[42:43] offset:3072
	global_load_dwordx4 v[84:87], v101, s[44:45]
	global_load_dwordx4 v[88:91], v101, s[44:45] offset:1024
	global_load_dwordx4 v[92:95], v101, s[44:45] offset:2048
	global_load_dwordx4 v[96:99], v101, s[44:45] offset:3072
	s_add_u32 s42, s42, 0x6000
	s_addc_u32 s43, s43, 0
	s_add_u32 s44, s44, 0x6000
	s_addc_u32 s45, s45, 0
	s_waitcnt vmcnt(32)
	v_lshlrev_b32_e32 v40, 16, v112
	v_and_b32_e32 v41, 0xffff0000, v112
	v_lshlrev_b32_e32 v42, 16, v113
	v_and_b32_e32 v43, 0xffff0000, v113
	v_lshlrev_b32_e32 v44, 16, v114
	v_and_b32_e32 v45, 0xffff0000, v114
	v_lshlrev_b32_e32 v46, 16, v115
	v_and_b32_e32 v47, 0xffff0000, v115
	v_lshlrev_b32_e32 v48, 16, v116
	v_and_b32_e32 v49, 0xffff0000, v116
	v_lshlrev_b32_e32 v50, 16, v117
	v_and_b32_e32 v51, 0xffff0000, v117
	v_lshlrev_b32_e32 v52, 16, v118
	v_and_b32_e32 v53, 0xffff0000, v118
	v_lshlrev_b32_e32 v54, 16, v119
	v_and_b32_e32 v55, 0xffff0000, v119
	v_mul_f32_e32 v56, v41, v41
	v_mul_f32_e32 v57, v43, v43
	v_fmac_f32_e32 v56, v40, v40
	v_fmac_f32_e32 v57, v42, v42
	v_add_f32_e32 v58, v56, v57
	v_mul_f32_e32 v56, v45, v45
	v_mul_f32_e32 v57, v47, v47
	v_fmac_f32_e32 v56, v44, v44
	v_fmac_f32_e32 v57, v46, v46
	v_add_f32_e32 v56, v56, v57
	v_add_f32_e32 v58, v58, v56
	v_mul_f32_e32 v56, v49, v49
	v_mul_f32_e32 v57, v51, v51
	v_fmac_f32_e32 v56, v48, v48
	v_fmac_f32_e32 v57, v50, v50
	v_add_f32_e32 v56, v56, v57
	v_add_f32_e32 v58, v58, v56
	v_mul_f32_e32 v56, v53, v53
	v_mul_f32_e32 v57, v55, v55
	v_fmac_f32_e32 v56, v52, v52
	v_fmac_f32_e32 v57, v54, v54
	v_add_f32_e32 v56, v56, v57
	v_add_f32_e32 v58, v58, v56
	s_nop 1
	v_add_f32_dpp v58, v58, v58 quad_perm:[1,0,3,2] row_mask:0xf bank_mask:0xf bound_ctrl:1
	s_nop 1
	v_add_f32_dpp v58, v58, v58 quad_perm:[2,3,0,1] row_mask:0xf bank_mask:0xf bound_ctrl:1
	s_nop 1
	v_add_f32_dpp v58, v58, v58 row_half_mirror row_mask:0xf bank_mask:0xf bound_ctrl:1
	s_nop 1
	v_add_f32_dpp v58, v58, v58 row_mirror row_mask:0xf bank_mask:0xf bound_ctrl:1
	v_mov_b32_e32 v56, v58
	s_nop 1
	v_permlane16_swap_b32_e32 v58, v56
	v_add_f32_e32 v58, v58, v56
	v_mov_b32_e32 v56, v58
	s_nop 1
	v_permlane32_swap_b32_e32 v58, v56
	v_add_f32_e32 v58, v58, v56
	v_fmamk_f32 v60, v58, 0x3a800000, v153
	v_rsq_f32_e32 v60, v60
	s_nop 0
	v_pk_mul_f32 v[40:41], v[40:41], v[60:61] op_sel_hi:[1,0]
	v_pk_mul_f32 v[42:43], v[42:43], v[60:61] op_sel_hi:[1,0]
	v_pk_mul_f32 v[44:45], v[44:45], v[60:61] op_sel_hi:[1,0]
	v_pk_mul_f32 v[46:47], v[46:47], v[60:61] op_sel_hi:[1,0]
	v_pk_mul_f32 v[48:49], v[48:49], v[60:61] op_sel_hi:[1,0]
	v_pk_mul_f32 v[50:51], v[50:51], v[60:61] op_sel_hi:[1,0]
	v_pk_mul_f32 v[52:53], v[52:53], v[60:61] op_sel_hi:[1,0]
	v_pk_mul_f32 v[54:55], v[54:55], v[60:61] op_sel_hi:[1,0]
	v_pk_mul_f32 v[40:41], v[0:1], v[40:41]
	v_pk_mul_f32 v[42:43], v[2:3], v[42:43]
	v_pk_mul_f32 v[44:45], v[4:5], v[44:45]
	v_pk_mul_f32 v[46:47], v[6:7], v[46:47]
	v_pk_mul_f32 v[48:49], v[8:9], v[48:49]
	v_pk_mul_f32 v[50:51], v[10:11], v[50:51]
	v_pk_mul_f32 v[52:53], v[12:13], v[52:53]
	v_pk_mul_f32 v[54:55], v[14:15], v[54:55]
	v_pk_fma_f32 v[40:41], v[214:215], v[40:41], v[198:199]
	v_pk_fma_f32 v[42:43], v[216:217], v[42:43], v[200:201]
	v_pk_fma_f32 v[44:45], v[218:219], v[44:45], v[202:203]
	v_pk_fma_f32 v[46:47], v[220:221], v[46:47], v[204:205]
	v_pk_fma_f32 v[48:49], v[222:223], v[48:49], v[206:207]
	v_pk_fma_f32 v[50:51], v[224:225], v[50:51], v[208:209]
	v_pk_fma_f32 v[52:53], v[226:227], v[52:53], v[210:211]
	v_pk_fma_f32 v[54:55], v[228:229], v[54:55], v[212:213]
	v_cvt_pk_bf16_f32 v40, v40, v41
	v_cvt_pk_bf16_f32 v41, v42, v43
	v_cvt_pk_bf16_f32 v44, v44, v45
	v_cvt_pk_bf16_f32 v45, v46, v47
	v_cvt_pk_bf16_f32 v48, v48, v49
	v_cvt_pk_bf16_f32 v49, v50, v51
	v_cvt_pk_bf16_f32 v52, v52, v53
	v_cvt_pk_bf16_f32 v53, v54, v55
	global_store_dwordx2 v100, v[40:41], s[40:41]
	global_store_dwordx2 v100, v[44:45], s[40:41] offset:512
	global_store_dwordx2 v100, v[48:49], s[40:41] offset:1024
	global_store_dwordx2 v100, v[52:53], s[40:41] offset:1536
	s_add_u32 s40, s40, 0x400000
	s_addc_u32 s41, s41, 0
	global_load_dwordx2 v[112:113], v100, s[38:39]
	global_load_dwordx2 v[114:115], v100, s[38:39] offset:512
	global_load_dwordx2 v[116:117], v100, s[38:39] offset:1024
	global_load_dwordx2 v[118:119], v100, s[38:39] offset:1536
	s_add_u32 s38, s38, 0x400000
	s_addc_u32 s39, s39, 0
	s_waitcnt vmcnt(32)
; __device__ __forceinline__ void norm_phase(const void* src_lat, int lat_f32, const float* src_ctx, int nrows, const float* gvec, const float* mods_l, int sh_off, int sc_off, bf16_t* U, const float* part, int nparts, float* ctx_out) {
;     ...
;         if (row < MLAT && !lat_f32) { const bf16_t* src = (const bf16_t*)src_lat + (size_t)row * DM + 4 * lane;
; #pragma unroll
;             for (int j = 0; j < 4; ++j) { const u32x2 w = *(const u32x2*)(src + 256 * j);
;                 v[j] = (f32x4){__uint_as_float(w.x << 16), __uint_as_float(w.x & 0xffff0000u), __uint_as_float(w.y << 16), __uint_as_float(w.y & 0xffff0000u)}; } }
;         else { const float* src = row < MLAT ? (const float*)src_lat + (size_t)row * DM : src_ctx + (size_t)(row - MLAT) * DM;
; #pragma unroll
;             for (int j = 0; j < 4; ++j) v[j] = *(const f32x4*)(src + 4 * lane + 256 * j); }
; #pragma unroll
;         for (int j = 0; j < 4; ++j) { ss += (v[j][0] * v[j][0] + v[j][1] * v[j][1]) + (v[j][2] * v[j][2] + v[j][3] * v[j][3]); }
;         if (nparts != 0 && row >= MLAT) {
;             for (int ch = 0; ch < nparts; ch += 4) {
;                 f32x4 pv[4][4];
; #pragma unroll
;                 for (int c4 = 0; c4 < 4; ++c4) { const float* pr = part + ((size_t)(ch + c4) * MCTX + (row - MLAT)) * DM + 4 * lane;
; #pragma unroll
;                     for (int j = 0; j < 4; ++j) pv[c4][j] = *(const f32x4*)(pr + 256 * j); }
; #pragma unroll
;                 for (int c4 = 0; c4 < 4; ++c4)
; #pragma unroll
;                     for (int j = 0; j < 4; ++j) v[j] = v[j] + pv[c4][j]; }
;             ss = 0.f;
; #pragma unroll
;             for (int j = 0; j < 4; ++j) { *(f32x4*)(ctx_out + (size_t)(row - MLAT) * DM + 4 * lane + 256 * j) = v[j]; ss += (v[j][0] * v[j][0] + v[j][1] * v[j][1]) + (v[j][2] * v[j][2] + v[j][3] * v[j][3]); }
;         }
;         const float rs = rsqrtf(wave_sum64(ss) * (1.0f / DM) + EPS);
;         const float* shp = mods_l + s * 6144 + sh_off + 4 * lane; const float* scp = mods_l + s * 6144 + sc_off + 4 * lane;
;         bf16_t* up = U + (size_t)row * DM + 4 * lane;
; #pragma unroll
;         for (int j = 0; j < 4; ++j) { const f32x4 sh = *(const f32x4*)(shp + 256 * j), sc = *(const f32x4*)(scp + 256 * j);
;             const f32x4 y = v[j] * rs * gv[j] * (sc + 1.0f) + sh;
;             u32x2 o; o.x = pkbf(y[0], y[1]); o.y = pkbf(y[2], y[3]); *(u32x2*)(up + 256 * j) = o; }
	v_lshlrev_b32_e32 v40, 16, v120
	v_and_b32_e32 v41, 0xffff0000, v120
	v_lshlrev_b32_e32 v42, 16, v121
	v_and_b32_e32 v43, 0xffff0000, v121
	v_lshlrev_b32_e32 v44, 16, v122
	v_and_b32_e32 v45, 0xffff0000, v122
	v_lshlrev_b32_e32 v46, 16, v123
	v_and_b32_e32 v47, 0xffff0000, v123
	v_lshlrev_b32_e32 v48, 16, v124
	v_and_b32_e32 v49, 0xffff0000, v124
	v_lshlrev_b32_e32 v50, 16, v125
	v_and_b32_e32 v51, 0xffff0000, v125
	v_lshlrev_b32_e32 v52, 16, v126
	v_and_b32_e32 v53, 0xffff0000, v126
	v_lshlrev_b32_e32 v54, 16, v127
	v_and_b32_e32 v55, 0xffff0000, v127
	v_mul_f32_e32 v56, v41, v41
	v_mul_f32_e32 v57, v43, v43
	v_fmac_f32_e32 v56, v40, v40
	v_fmac_f32_e32 v57, v42, v42
	v_add_f32_e32 v58, v56, v57
	v_mul_f32_e32 v56, v45, v45
	v_mul_f32_e32 v57, v47, v47
	v_fmac_f32_e32 v56, v44, v44
	v_fmac_f32_e32 v57, v46, v46
	v_add_f32_e32 v56, v56, v57
	v_add_f32_e32 v58, v58, v56
	v_mul_f32_e32 v56, v49, v49
	v_mul_f32_e32 v57, v51, v51
	v_fmac_f32_e32 v56, v48, v48
	v_fmac_f32_e32 v57, v50, v50
	v_add_f32_e32 v56, v56, v57
	v_add_f32_e32 v58, v58, v56
	v_mul_f32_e32 v56, v53, v53
	v_mul_f32_e32 v57, v55, v55
	v_fmac_f32_e32 v56, v52, v52
	v_fmac_f32_e32 v57, v54, v54
	v_add_f32_e32 v56, v56, v57
	v_add_f32_e32 v58, v58, v56
	s_nop 1
	v_add_f32_dpp v58, v58, v58 quad_perm:[1,0,3,2] row_mask:0xf bank_mask:0xf bound_ctrl:1
	s_nop 1
	v_add_f32_dpp v58, v58, v58 quad_perm:[2,3,0,1] row_mask:0xf bank_mask:0xf bound_ctrl:1
	s_nop 1
	v_add_f32_dpp v58, v58, v58 row_half_mirror row_mask:0xf bank_mask:0xf bound_ctrl:1
	s_nop 1
	v_add_f32_dpp v58, v58, v58 row_mirror row_mask:0xf bank_mask:0xf bound_ctrl:1
	v_mov_b32_e32 v56, v58
	s_nop 1
	v_permlane16_swap_b32_e32 v58, v56
	v_add_f32_e32 v58, v58, v56
	v_mov_b32_e32 v56, v58
	s_nop 1
	v_permlane32_swap_b32_e32 v58, v56
	v_add_f32_e32 v58, v58, v56
	v_fmamk_f32 v60, v58, 0x3a800000, v153
	v_rsq_f32_e32 v60, v60
	s_nop 0
	v_pk_mul_f32 v[40:41], v[40:41], v[60:61] op_sel_hi:[1,0]
	v_pk_mul_f32 v[42:43], v[42:43], v[60:61] op_sel_hi:[1,0]
	v_pk_mul_f32 v[44:45], v[44:45], v[60:61] op_sel_hi:[1,0]
	v_pk_mul_f32 v[46:47], v[46:47], v[60:61] op_sel_hi:[1,0]
	v_pk_mul_f32 v[48:49], v[48:49], v[60:61] op_sel_hi:[1,0]
	v_pk_mul_f32 v[50:51], v[50:51], v[60:61] op_sel_hi:[1,0]
	v_pk_mul_f32 v[52:53], v[52:53], v[60:61] op_sel_hi:[1,0]
	v_pk_mul_f32 v[54:55], v[54:55], v[60:61] op_sel_hi:[1,0]
	v_pk_mul_f32 v[40:41], v[0:1], v[40:41]
	v_pk_mul_f32 v[42:43], v[2:3], v[42:43]
	v_pk_mul_f32 v[44:45], v[4:5], v[44:45]
	v_pk_mul_f32 v[46:47], v[6:7], v[46:47]
	v_pk_mul_f32 v[48:49], v[8:9], v[48:49]
	v_pk_mul_f32 v[50:51], v[10:11], v[50:51]
	v_pk_mul_f32 v[52:53], v[12:13], v[52:53]
	v_pk_mul_f32 v[54:55], v[14:15], v[54:55]
	v_pk_fma_f32 v[40:41], v[214:215], v[40:41], v[198:199]
	v_pk_fma_f32 v[42:43], v[216:217], v[42:43], v[200:201]
	v_pk_fma_f32 v[44:45], v[218:219], v[44:45], v[202:203]
	v_pk_fma_f32 v[46:47], v[220:221], v[46:47], v[204:205]
	v_pk_fma_f32 v[48:49], v[222:223], v[48:49], v[206:207]
	v_pk_fma_f32 v[50:51], v[224:225], v[50:51], v[208:209]
	v_pk_fma_f32 v[52:53], v[226:227], v[52:53], v[210:211]
	v_pk_fma_f32 v[54:55], v[228:229], v[54:55], v[212:213]
	v_cvt_pk_bf16_f32 v40, v40, v41
	v_cvt_pk_bf16_f32 v41, v42, v43
	v_cvt_pk_bf16_f32 v44, v44, v45
	v_cvt_pk_bf16_f32 v45, v46, v47
	v_cvt_pk_bf16_f32 v48, v48, v49
	v_cvt_pk_bf16_f32 v49, v50, v51
	v_cvt_pk_bf16_f32 v52, v52, v53
	v_cvt_pk_bf16_f32 v53, v54, v55
	global_store_dwordx2 v100, v[40:41], s[40:41]
	global_store_dwordx2 v100, v[44:45], s[40:41] offset:512
	global_store_dwordx2 v100, v[48:49], s[40:41] offset:1024
	global_store_dwordx2 v100, v[52:53], s[40:41] offset:1536
	s_add_u32 s40, s40, 0x400000
	s_addc_u32 s41, s41, 0
	global_load_dwordx2 v[120:121], v100, s[38:39]
	global_load_dwordx2 v[122:123], v100, s[38:39] offset:512
	global_load_dwordx2 v[124:125], v100, s[38:39] offset:1024
	global_load_dwordx2 v[126:127], v100, s[38:39] offset:1536
	s_add_u32 s38, s38, 0x400000
	s_addc_u32 s39, s39, 0
	s_waitcnt vmcnt(32)
	v_lshlrev_b32_e32 v40, 16, v128
	v_and_b32_e32 v41, 0xffff0000, v128
	v_lshlrev_b32_e32 v42, 16, v129
	v_and_b32_e32 v43, 0xffff0000, v129
	v_lshlrev_b32_e32 v44, 16, v130
	v_and_b32_e32 v45, 0xffff0000, v130
	v_lshlrev_b32_e32 v46, 16, v131
	v_and_b32_e32 v47, 0xffff0000, v131
	v_lshlrev_b32_e32 v48, 16, v132
	v_and_b32_e32 v49, 0xffff0000, v132
	v_lshlrev_b32_e32 v50, 16, v133
	v_and_b32_e32 v51, 0xffff0000, v133
	v_lshlrev_b32_e32 v52, 16, v134
	v_and_b32_e32 v53, 0xffff0000, v134
	v_lshlrev_b32_e32 v54, 16, v135
	v_and_b32_e32 v55, 0xffff0000, v135
	v_mul_f32_e32 v56, v41, v41
	v_mul_f32_e32 v57, v43, v43
	v_fmac_f32_e32 v56, v40, v40
	v_fmac_f32_e32 v57, v42, v42
	v_add_f32_e32 v58, v56, v57
	v_mul_f32_e32 v56, v45, v45
	v_mul_f32_e32 v57, v47, v47
	v_fmac_f32_e32 v56, v44, v44
	v_fmac_f32_e32 v57, v46, v46
	v_add_f32_e32 v56, v56, v57
	v_add_f32_e32 v58, v58, v56
	v_mul_f32_e32 v56, v49, v49
	v_mul_f32_e32 v57, v51, v51
	v_fmac_f32_e32 v56, v48, v48
	v_fmac_f32_e32 v57, v50, v50
	v_add_f32_e32 v56, v56, v57
	v_add_f32_e32 v58, v58, v56
	v_mul_f32_e32 v56, v53, v53
	v_mul_f32_e32 v57, v55, v55
	v_fmac_f32_e32 v56, v52, v52
	v_fmac_f32_e32 v57, v54, v54
	v_add_f32_e32 v56, v56, v57
	v_add_f32_e32 v58, v58, v56
	s_nop 1
	v_add_f32_dpp v58, v58, v58 quad_perm:[1,0,3,2] row_mask:0xf bank_mask:0xf bound_ctrl:1
	s_nop 1
	v_add_f32_dpp v58, v58, v58 quad_perm:[2,3,0,1] row_mask:0xf bank_mask:0xf bound_ctrl:1
	s_nop 1
	v_add_f32_dpp v58, v58, v58 row_half_mirror row_mask:0xf bank_mask:0xf bound_ctrl:1
	s_nop 1
	v_add_f32_dpp v58, v58, v58 row_mirror row_mask:0xf bank_mask:0xf bound_ctrl:1
	v_mov_b32_e32 v56, v58
	s_nop 1
; __device__ __forceinline__ void norm_phase(const void* src_lat, int lat_f32, const float* src_ctx, int nrows, const float* gvec, const float* mods_l, int sh_off, int sc_off, bf16_t* U, const float* part, int nparts, float* ctx_out) {
;     ...
;         if (row < MLAT && !lat_f32) { const bf16_t* src = (const bf16_t*)src_lat + (size_t)row * DM + 4 * lane;
; #pragma unroll
;             for (int j = 0; j < 4; ++j) { const u32x2 w = *(const u32x2*)(src + 256 * j);
;                 v[j] = (f32x4){__uint_as_float(w.x << 16), __uint_as_float(w.x & 0xffff0000u), __uint_as_float(w.y << 16), __uint_as_float(w.y & 0xffff0000u)}; } }
;         else { const float* src = row < MLAT ? (const float*)src_lat + (size_t)row * DM : src_ctx + (size_t)(row - MLAT) * DM;
; #pragma unroll
;             for (int j = 0; j < 4; ++j) v[j] = *(const f32x4*)(src + 4 * lane + 256 * j); }
; #pragma unroll
;         for (int j = 0; j < 4; ++j) { ss += (v[j][0] * v[j][0] + v[j][1] * v[j][1]) + (v[j][2] * v[j][2] + v[j][3] * v[j][3]); }
;         if (nparts != 0 && row >= MLAT) {
;             for (int ch = 0; ch < nparts; ch += 4) {
;                 f32x4 pv[4][4];
; #pragma unroll
;                 for (int c4 = 0; c4 < 4; ++c4) { const float* pr = part + ((size_t)(ch + c4) * MCTX + (row - MLAT)) * DM + 4 * lane;
; #pragma unroll
;                     for (int j = 0; j < 4; ++j) pv[c4][j] = *(const f32x4*)(pr + 256 * j); }
; #pragma unroll
;                 for (int c4 = 0; c4 < 4; ++c4)
; #pragma unroll
;                     for (int j = 0; j < 4; ++j) v[j] = v[j] + pv[c4][j]; }
;             ss = 0.f;
; #pragma unroll
;             for (int j = 0; j < 4; ++j) { *(f32x4*)(ctx_out + (size_t)(row - MLAT) * DM + 4 * lane + 256 * j) = v[j]; ss += (v[j][0] * v[j][0] + v[j][1] * v[j][1]) + (v[j][2] * v[j][2] + v[j][3] * v[j][3]); }
;         }
;         const float rs = rsqrtf(wave_sum64(ss) * (1.0f / DM) + EPS);
;         const float* shp = mods_l + s * 6144 + sh_off + 4 * lane; const float* scp = mods_l + s * 6144 + sc_off + 4 * lane;
;         bf16_t* up = U + (size_t)row * DM + 4 * lane;
; #pragma unroll
;         for (int j = 0; j < 4; ++j) { const f32x4 sh = *(const f32x4*)(shp + 256 * j), sc = *(const f32x4*)(scp + 256 * j);
;             const f32x4 y = v[j] * rs * gv[j] * (sc + 1.0f) + sh;
;             u32x2 o; o.x = pkbf(y[0], y[1]); o.y = pkbf(y[2], y[3]); *(u32x2*)(up + 256 * j) = o; }
	v_permlane16_swap_b32_e32 v58, v56
	v_add_f32_e32 v58, v58, v56
	v_mov_b32_e32 v56, v58
	s_nop 1
	v_permlane32_swap_b32_e32 v58, v56
	v_add_f32_e32 v58, v58, v56
	v_fmamk_f32 v60, v58, 0x3a800000, v153
	v_rsq_f32_e32 v60, v60
	s_nop 0
	v_pk_mul_f32 v[40:41], v[40:41], v[60:61] op_sel_hi:[1,0]
	v_pk_mul_f32 v[42:43], v[42:43], v[60:61] op_sel_hi:[1,0]
	v_pk_mul_f32 v[44:45], v[44:45], v[60:61] op_sel_hi:[1,0]
	v_pk_mul_f32 v[46:47], v[46:47], v[60:61] op_sel_hi:[1,0]
	v_pk_mul_f32 v[48:49], v[48:49], v[60:61] op_sel_hi:[1,0]
	v_pk_mul_f32 v[50:51], v[50:51], v[60:61] op_sel_hi:[1,0]
	v_pk_mul_f32 v[52:53], v[52:53], v[60:61] op_sel_hi:[1,0]
	v_pk_mul_f32 v[54:55], v[54:55], v[60:61] op_sel_hi:[1,0]
	v_pk_mul_f32 v[40:41], v[0:1], v[40:41]
	v_pk_mul_f32 v[42:43], v[2:3], v[42:43]
	v_pk_mul_f32 v[44:45], v[4:5], v[44:45]
	v_pk_mul_f32 v[46:47], v[6:7], v[46:47]
	v_pk_mul_f32 v[48:49], v[8:9], v[48:49]
	v_pk_mul_f32 v[50:51], v[10:11], v[50:51]
	v_pk_mul_f32 v[52:53], v[12:13], v[52:53]
	v_pk_mul_f32 v[54:55], v[14:15], v[54:55]
	v_pk_fma_f32 v[40:41], v[214:215], v[40:41], v[198:199]
	v_pk_fma_f32 v[42:43], v[216:217], v[42:43], v[200:201]
	v_pk_fma_f32 v[44:45], v[218:219], v[44:45], v[202:203]
	v_pk_fma_f32 v[46:47], v[220:221], v[46:47], v[204:205]
	v_pk_fma_f32 v[48:49], v[222:223], v[48:49], v[206:207]
	v_pk_fma_f32 v[50:51], v[224:225], v[50:51], v[208:209]
	v_pk_fma_f32 v[52:53], v[226:227], v[52:53], v[210:211]
	v_pk_fma_f32 v[54:55], v[228:229], v[54:55], v[212:213]
	v_cvt_pk_bf16_f32 v40, v40, v41
	v_cvt_pk_bf16_f32 v41, v42, v43
	v_cvt_pk_bf16_f32 v44, v44, v45
	v_cvt_pk_bf16_f32 v45, v46, v47
	v_cvt_pk_bf16_f32 v48, v48, v49
	v_cvt_pk_bf16_f32 v49, v50, v51
	v_cvt_pk_bf16_f32 v52, v52, v53
	v_cvt_pk_bf16_f32 v53, v54, v55
	global_store_dwordx2 v100, v[40:41], s[40:41]
	global_store_dwordx2 v100, v[44:45], s[40:41] offset:512
	global_store_dwordx2 v100, v[48:49], s[40:41] offset:1024
	global_store_dwordx2 v100, v[52:53], s[40:41] offset:1536
	s_add_u32 s40, s40, 0x400000
	s_addc_u32 s41, s41, 0
	global_load_dwordx2 v[128:129], v100, s[38:39]
	global_load_dwordx2 v[130:131], v100, s[38:39] offset:512
	global_load_dwordx2 v[132:133], v100, s[38:39] offset:1024
	global_load_dwordx2 v[134:135], v100, s[38:39] offset:1536
	s_add_u32 s38, s38, 0x400000
	s_addc_u32 s39, s39, 0
	s_waitcnt vmcnt(24)
	v_pk_add_f32 v[84:85], v[84:85], 1.0 op_sel_hi:[1,0]
	v_pk_add_f32 v[86:87], v[86:87], 1.0 op_sel_hi:[1,0]
	v_pk_add_f32 v[88:89], v[88:89], 1.0 op_sel_hi:[1,0]
	v_pk_add_f32 v[90:91], v[90:91], 1.0 op_sel_hi:[1,0]
	v_pk_add_f32 v[92:93], v[92:93], 1.0 op_sel_hi:[1,0]
	v_pk_add_f32 v[94:95], v[94:95], 1.0 op_sel_hi:[1,0]
	v_pk_add_f32 v[96:97], v[96:97], 1.0 op_sel_hi:[1,0]
	v_pk_add_f32 v[98:99], v[98:99], 1.0 op_sel_hi:[1,0]
	v_lshlrev_b32_e32 v40, 16, v104
	v_and_b32_e32 v41, 0xffff0000, v104
	v_lshlrev_b32_e32 v42, 16, v105
	v_and_b32_e32 v43, 0xffff0000, v105
	v_lshlrev_b32_e32 v44, 16, v106
	v_and_b32_e32 v45, 0xffff0000, v106
	v_lshlrev_b32_e32 v46, 16, v107
	v_and_b32_e32 v47, 0xffff0000, v107
	v_lshlrev_b32_e32 v48, 16, v108
	v_and_b32_e32 v49, 0xffff0000, v108
	v_lshlrev_b32_e32 v50, 16, v109
	v_and_b32_e32 v51, 0xffff0000, v109
	v_lshlrev_b32_e32 v52, 16, v110
	v_and_b32_e32 v53, 0xffff0000, v110
	v_lshlrev_b32_e32 v54, 16, v111
	v_and_b32_e32 v55, 0xffff0000, v111
	v_mul_f32_e32 v56, v41, v41
	v_mul_f32_e32 v57, v43, v43
	v_fmac_f32_e32 v56, v40, v40
	v_fmac_f32_e32 v57, v42, v42
	v_add_f32_e32 v58, v56, v57
	v_mul_f32_e32 v56, v45, v45
	v_mul_f32_e32 v57, v47, v47
	v_fmac_f32_e32 v56, v44, v44
	v_fmac_f32_e32 v57, v46, v46
	v_add_f32_e32 v56, v56, v57
	v_add_f32_e32 v58, v58, v56
	v_mul_f32_e32 v56, v49, v49
	v_mul_f32_e32 v57, v51, v51
	v_fmac_f32_e32 v56, v48, v48
	v_fmac_f32_e32 v57, v50, v50
	v_add_f32_e32 v56, v56, v57
	v_add_f32_e32 v58, v58, v56
	v_mul_f32_e32 v56, v53, v53
	v_mul_f32_e32 v57, v55, v55
	v_fmac_f32_e32 v56, v52, v52
	v_fmac_f32_e32 v57, v54, v54
	v_add_f32_e32 v56, v56, v57
	v_add_f32_e32 v58, v58, v56
	s_nop 1
	v_add_f32_dpp v58, v58, v58 quad_perm:[1,0,3,2] row_mask:0xf bank_mask:0xf bound_ctrl:1
	s_nop 1
	v_add_f32_dpp v58, v58, v58 quad_perm:[2,3,0,1] row_mask:0xf bank_mask:0xf bound_ctrl:1
	s_nop 1
	v_add_f32_dpp v58, v58, v58 row_half_mirror row_mask:0xf bank_mask:0xf bound_ctrl:1
	s_nop 1
	v_add_f32_dpp v58, v58, v58 row_mirror row_mask:0xf bank_mask:0xf bound_ctrl:1
	v_mov_b32_e32 v56, v58
	s_nop 1
	v_permlane16_swap_b32_e32 v58, v56
	v_add_f32_e32 v58, v58, v56
	v_mov_b32_e32 v56, v58
	s_nop 1
	v_permlane32_swap_b32_e32 v58, v56
	v_add_f32_e32 v58, v58, v56
	v_fmamk_f32 v60, v58, 0x3a800000, v153
	v_rsq_f32_e32 v60, v60
	s_nop 0
	v_pk_mul_f32 v[40:41], v[40:41], v[60:61] op_sel_hi:[1,0]
	v_pk_mul_f32 v[42:43], v[42:43], v[60:61] op_sel_hi:[1,0]
	v_pk_mul_f32 v[44:45], v[44:45], v[60:61] op_sel_hi:[1,0]
	v_pk_mul_f32 v[46:47], v[46:47], v[60:61] op_sel_hi:[1,0]
	v_pk_mul_f32 v[48:49], v[48:49], v[60:61] op_sel_hi:[1,0]
	v_pk_mul_f32 v[50:51], v[50:51], v[60:61] op_sel_hi:[1,0]
	v_pk_mul_f32 v[52:53], v[52:53], v[60:61] op_sel_hi:[1,0]
	v_pk_mul_f32 v[54:55], v[54:55], v[60:61] op_sel_hi:[1,0]
	v_pk_mul_f32 v[40:41], v[0:1], v[40:41]
	v_pk_mul_f32 v[42:43], v[2:3], v[42:43]
	v_pk_mul_f32 v[44:45], v[4:5], v[44:45]
	v_pk_mul_f32 v[46:47], v[6:7], v[46:47]
	v_pk_mul_f32 v[48:49], v[8:9], v[48:49]
	v_pk_mul_f32 v[50:51], v[10:11], v[50:51]
	v_pk_mul_f32 v[52:53], v[12:13], v[52:53]
	v_pk_mul_f32 v[54:55], v[14:15], v[54:55]
	v_pk_fma_f32 v[40:41], v[84:85], v[40:41], v[68:69]
	v_pk_fma_f32 v[42:43], v[86:87], v[42:43], v[70:71]
	v_pk_fma_f32 v[44:45], v[88:89], v[44:45], v[72:73]
	v_pk_fma_f32 v[46:47], v[90:91], v[46:47], v[74:75]
	v_pk_fma_f32 v[48:49], v[92:93], v[48:49], v[76:77]
	v_pk_fma_f32 v[50:51], v[94:95], v[50:51], v[78:79]
	v_pk_fma_f32 v[52:53], v[96:97], v[52:53], v[80:81]
	v_pk_fma_f32 v[54:55], v[98:99], v[54:55], v[82:83]
	v_cvt_pk_bf16_f32 v40, v40, v41
	v_cvt_pk_bf16_f32 v41, v42, v43
	v_cvt_pk_bf16_f32 v44, v44, v45
	v_cvt_pk_bf16_f32 v45, v46, v47
	v_cvt_pk_bf16_f32 v48, v48, v49
	v_cvt_pk_bf16_f32 v49, v50, v51
	v_cvt_pk_bf16_f32 v52, v52, v53
	v_cvt_pk_bf16_f32 v53, v54, v55
	global_store_dwordx2 v100, v[40:41], s[40:41]
	global_store_dwordx2 v100, v[44:45], s[40:41] offset:512
	global_store_dwordx2 v100, v[48:49], s[40:41] offset:1024
	global_store_dwordx2 v100, v[52:53], s[40:41] offset:1536
	s_add_u32 s40, s40, 0x400000
	s_addc_u32 s41, s41, 0
	s_waitcnt vmcnt(20)
; __device__ __forceinline__ void norm_phase(const void* src_lat, int lat_f32, const float* src_ctx, int nrows, const float* gvec, const float* mods_l, int sh_off, int sc_off, bf16_t* U, const float* part, int nparts, float* ctx_out) {
;     ...
;         if (row < MLAT && !lat_f32) { const bf16_t* src = (const bf16_t*)src_lat + (size_t)row * DM + 4 * lane;
; #pragma unroll
;             for (int j = 0; j < 4; ++j) { const u32x2 w = *(const u32x2*)(src + 256 * j);
;                 v[j] = (f32x4){__uint_as_float(w.x << 16), __uint_as_float(w.x & 0xffff0000u), __uint_as_float(w.y << 16), __uint_as_float(w.y & 0xffff0000u)}; } }
;         else { const float* src = row < MLAT ? (const float*)src_lat + (size_t)row * DM : src_ctx + (size_t)(row - MLAT) * DM;
; #pragma unroll
;             for (int j = 0; j < 4; ++j) v[j] = *(const f32x4*)(src + 4 * lane + 256 * j); }
; #pragma unroll
;         for (int j = 0; j < 4; ++j) { ss += (v[j][0] * v[j][0] + v[j][1] * v[j][1]) + (v[j][2] * v[j][2] + v[j][3] * v[j][3]); }
;         if (nparts != 0 && row >= MLAT) {
;             for (int ch = 0; ch < nparts; ch += 4) {
;                 f32x4 pv[4][4];
; #pragma unroll
;                 for (int c4 = 0; c4 < 4; ++c4) { const float* pr = part + ((size_t)(ch + c4) * MCTX + (row - MLAT)) * DM + 4 * lane;
; #pragma unroll
;                     for (int j = 0; j < 4; ++j) pv[c4][j] = *(const f32x4*)(pr + 256 * j); }
; #pragma unroll
;                 for (int c4 = 0; c4 < 4; ++c4)
; #pragma unroll
;                     for (int j = 0; j < 4; ++j) v[j] = v[j] + pv[c4][j]; }
;             ss = 0.f;
; #pragma unroll
;             for (int j = 0; j < 4; ++j) { *(f32x4*)(ctx_out + (size_t)(row - MLAT) * DM + 4 * lane + 256 * j) = v[j]; ss += (v[j][0] * v[j][0] + v[j][1] * v[j][1]) + (v[j][2] * v[j][2] + v[j][3] * v[j][3]); }
;         }
;         const float rs = rsqrtf(wave_sum64(ss) * (1.0f / DM) + EPS);
;         const float* shp = mods_l + s * 6144 + sh_off + 4 * lane; const float* scp = mods_l + s * 6144 + sc_off + 4 * lane;
;         bf16_t* up = U + (size_t)row * DM + 4 * lane;
; #pragma unroll
;         for (int j = 0; j < 4; ++j) { const f32x4 sh = *(const f32x4*)(shp + 256 * j), sc = *(const f32x4*)(scp + 256 * j);
;             const f32x4 y = v[j] * rs * gv[j] * (sc + 1.0f) + sh;
;             u32x2 o; o.x = pkbf(y[0], y[1]); o.y = pkbf(y[2], y[3]); *(u32x2*)(up + 256 * j) = o; }
	v_lshlrev_b32_e32 v40, 16, v112
	v_and_b32_e32 v41, 0xffff0000, v112
	v_lshlrev_b32_e32 v42, 16, v113
	v_and_b32_e32 v43, 0xffff0000, v113
	v_lshlrev_b32_e32 v44, 16, v114
	v_and_b32_e32 v45, 0xffff0000, v114
	v_lshlrev_b32_e32 v46, 16, v115
	v_and_b32_e32 v47, 0xffff0000, v115
	v_lshlrev_b32_e32 v48, 16, v116
	v_and_b32_e32 v49, 0xffff0000, v116
	v_lshlrev_b32_e32 v50, 16, v117
	v_and_b32_e32 v51, 0xffff0000, v117
	v_lshlrev_b32_e32 v52, 16, v118
	v_and_b32_e32 v53, 0xffff0000, v118
	v_lshlrev_b32_e32 v54, 16, v119
	v_and_b32_e32 v55, 0xffff0000, v119
	v_mul_f32_e32 v56, v41, v41
	v_mul_f32_e32 v57, v43, v43
	v_fmac_f32_e32 v56, v40, v40
	v_fmac_f32_e32 v57, v42, v42
	v_add_f32_e32 v58, v56, v57
	v_mul_f32_e32 v56, v45, v45
	v_mul_f32_e32 v57, v47, v47
	v_fmac_f32_e32 v56, v44, v44
	v_fmac_f32_e32 v57, v46, v46
	v_add_f32_e32 v56, v56, v57
	v_add_f32_e32 v58, v58, v56
	v_mul_f32_e32 v56, v49, v49
	v_mul_f32_e32 v57, v51, v51
	v_fmac_f32_e32 v56, v48, v48
	v_fmac_f32_e32 v57, v50, v50
	v_add_f32_e32 v56, v56, v57
	v_add_f32_e32 v58, v58, v56
	v_mul_f32_e32 v56, v53, v53
	v_mul_f32_e32 v57, v55, v55
	v_fmac_f32_e32 v56, v52, v52
	v_fmac_f32_e32 v57, v54, v54
	v_add_f32_e32 v56, v56, v57
	v_add_f32_e32 v58, v58, v56
	s_nop 1
	v_add_f32_dpp v58, v58, v58 quad_perm:[1,0,3,2] row_mask:0xf bank_mask:0xf bound_ctrl:1
	s_nop 1
	v_add_f32_dpp v58, v58, v58 quad_perm:[2,3,0,1] row_mask:0xf bank_mask:0xf bound_ctrl:1
	s_nop 1
	v_add_f32_dpp v58, v58, v58 row_half_mirror row_mask:0xf bank_mask:0xf bound_ctrl:1
	s_nop 1
	v_add_f32_dpp v58, v58, v58 row_mirror row_mask:0xf bank_mask:0xf bound_ctrl:1
	v_mov_b32_e32 v56, v58
	s_nop 1
	v_permlane16_swap_b32_e32 v58, v56
	v_add_f32_e32 v58, v58, v56
	v_mov_b32_e32 v56, v58
	s_nop 1
	v_permlane32_swap_b32_e32 v58, v56
	v_add_f32_e32 v58, v58, v56
	v_fmamk_f32 v60, v58, 0x3a800000, v153
	v_rsq_f32_e32 v60, v60
	s_nop 0
	v_pk_mul_f32 v[40:41], v[40:41], v[60:61] op_sel_hi:[1,0]
	v_pk_mul_f32 v[42:43], v[42:43], v[60:61] op_sel_hi:[1,0]
	v_pk_mul_f32 v[44:45], v[44:45], v[60:61] op_sel_hi:[1,0]
	v_pk_mul_f32 v[46:47], v[46:47], v[60:61] op_sel_hi:[1,0]
	v_pk_mul_f32 v[48:49], v[48:49], v[60:61] op_sel_hi:[1,0]
	v_pk_mul_f32 v[50:51], v[50:51], v[60:61] op_sel_hi:[1,0]
	v_pk_mul_f32 v[52:53], v[52:53], v[60:61] op_sel_hi:[1,0]
	v_pk_mul_f32 v[54:55], v[54:55], v[60:61] op_sel_hi:[1,0]
	v_pk_mul_f32 v[40:41], v[0:1], v[40:41]
	v_pk_mul_f32 v[42:43], v[2:3], v[42:43]
	v_pk_mul_f32 v[44:45], v[4:5], v[44:45]
	v_pk_mul_f32 v[46:47], v[6:7], v[46:47]
	v_pk_mul_f32 v[48:49], v[8:9], v[48:49]
	v_pk_mul_f32 v[50:51], v[10:11], v[50:51]
	v_pk_mul_f32 v[52:53], v[12:13], v[52:53]
	v_pk_mul_f32 v[54:55], v[14:15], v[54:55]
	v_pk_fma_f32 v[40:41], v[84:85], v[40:41], v[68:69]
	v_pk_fma_f32 v[42:43], v[86:87], v[42:43], v[70:71]
	v_pk_fma_f32 v[44:45], v[88:89], v[44:45], v[72:73]
	v_pk_fma_f32 v[46:47], v[90:91], v[46:47], v[74:75]
	v_pk_fma_f32 v[48:49], v[92:93], v[48:49], v[76:77]
	v_pk_fma_f32 v[50:51], v[94:95], v[50:51], v[78:79]
	v_pk_fma_f32 v[52:53], v[96:97], v[52:53], v[80:81]
	v_pk_fma_f32 v[54:55], v[98:99], v[54:55], v[82:83]
	v_cvt_pk_bf16_f32 v40, v40, v41
	v_cvt_pk_bf16_f32 v41, v42, v43
	v_cvt_pk_bf16_f32 v44, v44, v45
	v_cvt_pk_bf16_f32 v45, v46, v47
	v_cvt_pk_bf16_f32 v48, v48, v49
	v_cvt_pk_bf16_f32 v49, v50, v51
	v_cvt_pk_bf16_f32 v52, v52, v53
	v_cvt_pk_bf16_f32 v53, v54, v55
	global_store_dwordx2 v100, v[40:41], s[40:41]
	global_store_dwordx2 v100, v[44:45], s[40:41] offset:512
	global_store_dwordx2 v100, v[48:49], s[40:41] offset:1024
	global_store_dwordx2 v100, v[52:53], s[40:41] offset:1536
	s_add_u32 s40, s40, 0x400000
	s_addc_u32 s41, s41, 0
	s_waitcnt vmcnt(16)
	v_lshlrev_b32_e32 v40, 16, v120
	v_and_b32_e32 v41, 0xffff0000, v120
	v_lshlrev_b32_e32 v42, 16, v121
	v_and_b32_e32 v43, 0xffff0000, v121
	v_lshlrev_b32_e32 v44, 16, v122
	v_and_b32_e32 v45, 0xffff0000, v122
	v_lshlrev_b32_e32 v46, 16, v123
	v_and_b32_e32 v47, 0xffff0000, v123
	v_lshlrev_b32_e32 v48, 16, v124
	v_and_b32_e32 v49, 0xffff0000, v124
	v_lshlrev_b32_e32 v50, 16, v125
	v_and_b32_e32 v51, 0xffff0000, v125
	v_lshlrev_b32_e32 v52, 16, v126
	v_and_b32_e32 v53, 0xffff0000, v126
	v_lshlrev_b32_e32 v54, 16, v127
	v_and_b32_e32 v55, 0xffff0000, v127
	v_mul_f32_e32 v56, v41, v41
	v_mul_f32_e32 v57, v43, v43
	v_fmac_f32_e32 v56, v40, v40
	v_fmac_f32_e32 v57, v42, v42
	v_add_f32_e32 v58, v56, v57
	v_mul_f32_e32 v56, v45, v45
	v_mul_f32_e32 v57, v47, v47
	v_fmac_f32_e32 v56, v44, v44
	v_fmac_f32_e32 v57, v46, v46
	v_add_f32_e32 v56, v56, v57
	v_add_f32_e32 v58, v58, v56
	v_mul_f32_e32 v56, v49, v49
	v_mul_f32_e32 v57, v51, v51
	v_fmac_f32_e32 v56, v48, v48
	v_fmac_f32_e32 v57, v50, v50
	v_add_f32_e32 v56, v56, v57
	v_add_f32_e32 v58, v58, v56
	v_mul_f32_e32 v56, v53, v53
	v_mul_f32_e32 v57, v55, v55
	v_fmac_f32_e32 v56, v52, v52
	v_fmac_f32_e32 v57, v54, v54
	v_add_f32_e32 v56, v56, v57
	v_add_f32_e32 v58, v58, v56
	s_nop 1
	v_add_f32_dpp v58, v58, v58 quad_perm:[1,0,3,2] row_mask:0xf bank_mask:0xf bound_ctrl:1
	s_nop 1
	v_add_f32_dpp v58, v58, v58 quad_perm:[2,3,0,1] row_mask:0xf bank_mask:0xf bound_ctrl:1
	s_nop 1
	v_add_f32_dpp v58, v58, v58 row_half_mirror row_mask:0xf bank_mask:0xf bound_ctrl:1
	s_nop 1
	v_add_f32_dpp v58, v58, v58 row_mirror row_mask:0xf bank_mask:0xf bound_ctrl:1
	v_mov_b32_e32 v56, v58
	s_nop 1
	v_permlane16_swap_b32_e32 v58, v56
	v_add_f32_e32 v58, v58, v56
	v_mov_b32_e32 v56, v58
	s_nop 1
	v_permlane32_swap_b32_e32 v58, v56
	v_add_f32_e32 v58, v58, v56
	v_fmamk_f32 v60, v58, 0x3a800000, v153
	v_rsq_f32_e32 v60, v60
	s_nop 0
	v_pk_mul_f32 v[40:41], v[40:41], v[60:61] op_sel_hi:[1,0]
; __device__ __forceinline__ void norm_phase(const void* src_lat, int lat_f32, const float* src_ctx, int nrows, const float* gvec, const float* mods_l, int sh_off, int sc_off, bf16_t* U, const float* part, int nparts, float* ctx_out) {
;     ...
;         if (row < MLAT && !lat_f32) { const bf16_t* src = (const bf16_t*)src_lat + (size_t)row * DM + 4 * lane;
; #pragma unroll
;             for (int j = 0; j < 4; ++j) { const u32x2 w = *(const u32x2*)(src + 256 * j);
;                 v[j] = (f32x4){__uint_as_float(w.x << 16), __uint_as_float(w.x & 0xffff0000u), __uint_as_float(w.y << 16), __uint_as_float(w.y & 0xffff0000u)}; } }
;         else { const float* src = row < MLAT ? (const float*)src_lat + (size_t)row * DM : src_ctx + (size_t)(row - MLAT) * DM;
; #pragma unroll
;             for (int j = 0; j < 4; ++j) v[j] = *(const f32x4*)(src + 4 * lane + 256 * j); }
; #pragma unroll
;         for (int j = 0; j < 4; ++j) { ss += (v[j][0] * v[j][0] + v[j][1] * v[j][1]) + (v[j][2] * v[j][2] + v[j][3] * v[j][3]); }
;         if (nparts != 0 && row >= MLAT) {
;             for (int ch = 0; ch < nparts; ch += 4) {
;                 f32x4 pv[4][4];
; #pragma unroll
;                 for (int c4 = 0; c4 < 4; ++c4) { const float* pr = part + ((size_t)(ch + c4) * MCTX + (row - MLAT)) * DM + 4 * lane;
; #pragma unroll
;                     for (int j = 0; j < 4; ++j) pv[c4][j] = *(const f32x4*)(pr + 256 * j); }
; #pragma unroll
;                 for (int c4 = 0; c4 < 4; ++c4)
; #pragma unroll
;                     for (int j = 0; j < 4; ++j) v[j] = v[j] + pv[c4][j]; }
;             ss = 0.f;
; #pragma unroll
;             for (int j = 0; j < 4; ++j) { *(f32x4*)(ctx_out + (size_t)(row - MLAT) * DM + 4 * lane + 256 * j) = v[j]; ss += (v[j][0] * v[j][0] + v[j][1] * v[j][1]) + (v[j][2] * v[j][2] + v[j][3] * v[j][3]); }
;         }
;         const float rs = rsqrtf(wave_sum64(ss) * (1.0f / DM) + EPS);
;         const float* shp = mods_l + s * 6144 + sh_off + 4 * lane; const float* scp = mods_l + s * 6144 + sc_off + 4 * lane;
;         bf16_t* up = U + (size_t)row * DM + 4 * lane;
; #pragma unroll
;         for (int j = 0; j < 4; ++j) { const f32x4 sh = *(const f32x4*)(shp + 256 * j), sc = *(const f32x4*)(scp + 256 * j);
;             const f32x4 y = v[j] * rs * gv[j] * (sc + 1.0f) + sh;
;             u32x2 o; o.x = pkbf(y[0], y[1]); o.y = pkbf(y[2], y[3]); *(u32x2*)(up + 256 * j) = o; }
	v_pk_mul_f32 v[42:43], v[42:43], v[60:61] op_sel_hi:[1,0]
	v_pk_mul_f32 v[44:45], v[44:45], v[60:61] op_sel_hi:[1,0]
	v_pk_mul_f32 v[46:47], v[46:47], v[60:61] op_sel_hi:[1,0]
	v_pk_mul_f32 v[48:49], v[48:49], v[60:61] op_sel_hi:[1,0]
	v_pk_mul_f32 v[50:51], v[50:51], v[60:61] op_sel_hi:[1,0]
	v_pk_mul_f32 v[52:53], v[52:53], v[60:61] op_sel_hi:[1,0]
	v_pk_mul_f32 v[54:55], v[54:55], v[60:61] op_sel_hi:[1,0]
	v_pk_mul_f32 v[40:41], v[0:1], v[40:41]
	v_pk_mul_f32 v[42:43], v[2:3], v[42:43]
	v_pk_mul_f32 v[44:45], v[4:5], v[44:45]
	v_pk_mul_f32 v[46:47], v[6:7], v[46:47]
	v_pk_mul_f32 v[48:49], v[8:9], v[48:49]
	v_pk_mul_f32 v[50:51], v[10:11], v[50:51]
	v_pk_mul_f32 v[52:53], v[12:13], v[52:53]
	v_pk_mul_f32 v[54:55], v[14:15], v[54:55]
	v_pk_fma_f32 v[40:41], v[84:85], v[40:41], v[68:69]
	v_pk_fma_f32 v[42:43], v[86:87], v[42:43], v[70:71]
	v_pk_fma_f32 v[44:45], v[88:89], v[44:45], v[72:73]
	v_pk_fma_f32 v[46:47], v[90:91], v[46:47], v[74:75]
	v_pk_fma_f32 v[48:49], v[92:93], v[48:49], v[76:77]
	v_pk_fma_f32 v[50:51], v[94:95], v[50:51], v[78:79]
	v_pk_fma_f32 v[52:53], v[96:97], v[52:53], v[80:81]
	v_pk_fma_f32 v[54:55], v[98:99], v[54:55], v[82:83]
	v_cvt_pk_bf16_f32 v40, v40, v41
	v_cvt_pk_bf16_f32 v41, v42, v43
	v_cvt_pk_bf16_f32 v44, v44, v45
	v_cvt_pk_bf16_f32 v45, v46, v47
	v_cvt_pk_bf16_f32 v48, v48, v49
	v_cvt_pk_bf16_f32 v49, v50, v51
	v_cvt_pk_bf16_f32 v52, v52, v53
	v_cvt_pk_bf16_f32 v53, v54, v55
	global_store_dwordx2 v100, v[40:41], s[40:41]
	global_store_dwordx2 v100, v[44:45], s[40:41] offset:512
	global_store_dwordx2 v100, v[48:49], s[40:41] offset:1024
	global_store_dwordx2 v100, v[52:53], s[40:41] offset:1536
	s_add_u32 s40, s40, 0x400000
	s_addc_u32 s41, s41, 0
	s_waitcnt vmcnt(12)
	v_lshlrev_b32_e32 v40, 16, v128
	v_and_b32_e32 v41, 0xffff0000, v128
	v_lshlrev_b32_e32 v42, 16, v129
	v_and_b32_e32 v43, 0xffff0000, v129
	v_lshlrev_b32_e32 v44, 16, v130
	v_and_b32_e32 v45, 0xffff0000, v130
	v_lshlrev_b32_e32 v46, 16, v131
	v_and_b32_e32 v47, 0xffff0000, v131
	v_lshlrev_b32_e32 v48, 16, v132
	v_and_b32_e32 v49, 0xffff0000, v132
	v_lshlrev_b32_e32 v50, 16, v133
	v_and_b32_e32 v51, 0xffff0000, v133
	v_lshlrev_b32_e32 v52, 16, v134
	v_and_b32_e32 v53, 0xffff0000, v134
	v_lshlrev_b32_e32 v54, 16, v135
	v_and_b32_e32 v55, 0xffff0000, v135
	v_mul_f32_e32 v56, v41, v41
	v_mul_f32_e32 v57, v43, v43
	v_fmac_f32_e32 v56, v40, v40
	v_fmac_f32_e32 v57, v42, v42
	v_add_f32_e32 v58, v56, v57
	v_mul_f32_e32 v56, v45, v45
	v_mul_f32_e32 v57, v47, v47
	v_fmac_f32_e32 v56, v44, v44
	v_fmac_f32_e32 v57, v46, v46
	v_add_f32_e32 v56, v56, v57
	v_add_f32_e32 v58, v58, v56
	v_mul_f32_e32 v56, v49, v49
	v_mul_f32_e32 v57, v51, v51
	v_fmac_f32_e32 v56, v48, v48
	v_fmac_f32_e32 v57, v50, v50
	v_add_f32_e32 v56, v56, v57
	v_add_f32_e32 v58, v58, v56
	v_mul_f32_e32 v56, v53, v53
	v_mul_f32_e32 v57, v55, v55
	v_fmac_f32_e32 v56, v52, v52
	v_fmac_f32_e32 v57, v54, v54
	v_add_f32_e32 v56, v56, v57
	v_add_f32_e32 v58, v58, v56
	s_nop 1
	v_add_f32_dpp v58, v58, v58 quad_perm:[1,0,3,2] row_mask:0xf bank_mask:0xf bound_ctrl:1
	s_nop 1
	v_add_f32_dpp v58, v58, v58 quad_perm:[2,3,0,1] row_mask:0xf bank_mask:0xf bound_ctrl:1
	s_nop 1
	v_add_f32_dpp v58, v58, v58 row_half_mirror row_mask:0xf bank_mask:0xf bound_ctrl:1
	s_nop 1
	v_add_f32_dpp v58, v58, v58 row_mirror row_mask:0xf bank_mask:0xf bound_ctrl:1
	v_mov_b32_e32 v56, v58
	s_nop 1
	v_permlane16_swap_b32_e32 v58, v56
	v_add_f32_e32 v58, v58, v56
	v_mov_b32_e32 v56, v58
	s_nop 1
	v_permlane32_swap_b32_e32 v58, v56
	v_add_f32_e32 v58, v58, v56
	v_fmamk_f32 v60, v58, 0x3a800000, v153
	v_rsq_f32_e32 v60, v60
	s_nop 0
	v_pk_mul_f32 v[40:41], v[40:41], v[60:61] op_sel_hi:[1,0]
	v_pk_mul_f32 v[42:43], v[42:43], v[60:61] op_sel_hi:[1,0]
	v_pk_mul_f32 v[44:45], v[44:45], v[60:61] op_sel_hi:[1,0]
	v_pk_mul_f32 v[46:47], v[46:47], v[60:61] op_sel_hi:[1,0]
	v_pk_mul_f32 v[48:49], v[48:49], v[60:61] op_sel_hi:[1,0]
	v_pk_mul_f32 v[50:51], v[50:51], v[60:61] op_sel_hi:[1,0]
	v_pk_mul_f32 v[52:53], v[52:53], v[60:61] op_sel_hi:[1,0]
	v_pk_mul_f32 v[54:55], v[54:55], v[60:61] op_sel_hi:[1,0]
	v_pk_mul_f32 v[40:41], v[0:1], v[40:41]
	v_pk_mul_f32 v[42:43], v[2:3], v[42:43]
	v_pk_mul_f32 v[44:45], v[4:5], v[44:45]
	v_pk_mul_f32 v[46:47], v[6:7], v[46:47]
	v_pk_mul_f32 v[48:49], v[8:9], v[48:49]
	v_pk_mul_f32 v[50:51], v[10:11], v[50:51]
	v_pk_mul_f32 v[52:53], v[12:13], v[52:53]
	v_pk_mul_f32 v[54:55], v[14:15], v[54:55]
	v_pk_fma_f32 v[40:41], v[84:85], v[40:41], v[68:69]
	v_pk_fma_f32 v[42:43], v[86:87], v[42:43], v[70:71]
	v_pk_fma_f32 v[44:45], v[88:89], v[44:45], v[72:73]
	v_pk_fma_f32 v[46:47], v[90:91], v[46:47], v[74:75]
	v_pk_fma_f32 v[48:49], v[92:93], v[48:49], v[76:77]
	v_pk_fma_f32 v[50:51], v[94:95], v[50:51], v[78:79]
	v_pk_fma_f32 v[52:53], v[96:97], v[52:53], v[80:81]
	v_pk_fma_f32 v[54:55], v[98:99], v[54:55], v[82:83]
	v_cvt_pk_bf16_f32 v40, v40, v41
	v_cvt_pk_bf16_f32 v41, v42, v43
	v_cvt_pk_bf16_f32 v44, v44, v45
	v_cvt_pk_bf16_f32 v45, v46, v47
	v_cvt_pk_bf16_f32 v48, v48, v49
	v_cvt_pk_bf16_f32 v49, v50, v51
	v_cvt_pk_bf16_f32 v52, v52, v53
	v_cvt_pk_bf16_f32 v53, v54, v55
	global_store_dwordx2 v100, v[40:41], s[40:41]
	global_store_dwordx2 v100, v[44:45], s[40:41] offset:512
	global_store_dwordx2 v100, v[48:49], s[40:41] offset:1024
	global_store_dwordx2 v100, v[52:53], s[40:41] offset:1536
	s_add_u32 s40, s40, 0x400000
	s_addc_u32 s41, s41, 0
	s_add_i32 s0, s0, 0x8000
	v_add_co_u32_e32 v38, vcc, 0x4000000, v38
	s_nop 1
	v_addc_co_u32_e32 v39, vcc, 0, v39, vcc
	s_cmp_lt_i32 s0, s26
	s_cbranch_scc1 .LBB0_732
	s_branch .LBB0_738
